# g2 + PEER gather: dot chains start with v_dot2_f32_bf16 src2=0 (no zero-init mov), row loads use SGPR row base + lane offset (saddr) instead of a 64-bit VALU add per row
# speedup vs baseline: 1.0090x; 1.0057x over previous
; #define P4_FOR16(M) M(0) M(1) M(2) M(3) M(4) M(5) M(6) M(7) M(8) M(9) M(10) M(11) M(12) M(13) M(14) M(15)
; #define P4_U(i) { P4_DOT(b##i, part[i]); const int nk_ = __builtin_amdgcn_readlane(ksel, nb + i); P4_LOAD(b##i, Ug, nk_); }
; #define P4_U(i) { P4_DOT(b##i, part[i]); const int nk_ = __builtin_amdgcn_readlane(kn, i); P4_LOAD(b##i, nbase, nk_); }
; __device__ __forceinline__ void peer_gather_f4p(const float* X, const int* __restrict__ IDX, const float* __restrict__ G, ...
;     ...
;         for (int bt = 0; bt < 7; ++bt) {
;             const int ksel = (bt + 1 < 4) ? k0 : k1;
;             const int nb = (16 * (bt + 1)) & 63;
;     ...
;             P4_FOR16(P4_U)
.LBB0_533:
	s_mov_b32 s87, s86
	s_waitcnt vmcnt(15)
	v_cvt_scalef32_pk_bf16_fp4 v48, v64, 1.0
	v_cvt_scalef32_pk_bf16_fp4 v50, v64, 1.0 op_sel:[1,0,0]
	v_cvt_scalef32_pk_bf16_fp4 v52, v64, 1.0 op_sel:[0,1,0]
	v_cvt_scalef32_pk_bf16_fp4 v54, v64, 1.0 op_sel:[1,1,0]
	v_dot2_f32_bf16 v56, v48, v6, 0
	v_dot2_f32_bf16 v48, v50, v4, 0
	v_dot2_f32_bf16 v56, v52, v10, v56
	s_cmp_lt_u32 s29, 3
	v_dot2_f32_bf16 v48, v54, v8, v48
	v_cvt_scalef32_pk_bf16_fp4 v50, v65, 1.0
	v_cvt_scalef32_pk_bf16_fp4 v52, v65, 1.0 op_sel:[1,0,0]
	v_cvt_scalef32_pk_bf16_fp4 v54, v65, 1.0 op_sel:[0,1,0]
	v_cvt_scalef32_pk_bf16_fp4 v58, v65, 1.0 op_sel:[1,1,0]
	s_cselect_b64 s[50:51], -1, 0
	v_dot2_f32_bf16 v56, v50, v14, v56
	v_dot2_f32_bf16 v48, v52, v12, v48
	s_waitcnt lgkmcnt(1)
	v_cndmask_b32_e64 v46, v39, v38, s[50:51]
	v_dot2_f32_bf16 v56, v54, v18, v56
	v_dot2_f32_bf16 v48, v58, v16, v48
	v_cvt_scalef32_pk_bf16_fp4 v50, v66, 1.0
	v_cvt_scalef32_pk_bf16_fp4 v52, v66, 1.0 op_sel:[1,0,0]
	v_cvt_scalef32_pk_bf16_fp4 v54, v66, 1.0 op_sel:[0,1,0]
	v_cvt_scalef32_pk_bf16_fp4 v58, v66, 1.0 op_sel:[1,1,0]
	s_add_i32 s12, s28, -15
	v_dot2_f32_bf16 v56, v50, v22, v56
	v_dot2_f32_bf16 v48, v52, v20, v48
	v_readlane_b32 s12, v46, s12
	v_dot2_f32_bf16 v56, v54, v26, v56
	v_dot2_f32_bf16 v48, v58, v24, v48
	v_cvt_scalef32_pk_bf16_fp4 v50, v67, 1.0
	v_cvt_scalef32_pk_bf16_fp4 v52, v67, 1.0 op_sel:[1,0,0]
	v_cvt_scalef32_pk_bf16_fp4 v54, v67, 1.0 op_sel:[0,1,0]
	v_cvt_scalef32_pk_bf16_fp4 v58, v67, 1.0 op_sel:[1,1,0]
	s_lshr_b32 s12, s12, 7
	v_dot2_f32_bf16 v56, v50, v30, v56
	v_dot2_f32_bf16 v48, v52, v28, v48
	s_mov_b32 s13, s86
	v_dot2_f32_bf16 v56, v54, v36, v56
	v_dot2_f32_bf16 v48, v58, v34, v48
	s_lshl_b64 s[12:13], s[12:13], 10
	s_nop 2
	v_readfirstlane_b32 s100, v40
	v_readfirstlane_b32 s101, v41
	v_subrev_u32_e32 v207, s100, v40
	v_add_f32_e32 v47, v56, v48
	s_add_u32 s12, s12, s100
	s_addc_u32 s13, s13, s101
	global_load_dwordx4 v[64:67], v207, s[12:13]
	s_waitcnt vmcnt(15)
	v_cvt_scalef32_pk_bf16_fp4 v48, v68, 1.0
	v_cvt_scalef32_pk_bf16_fp4 v50, v68, 1.0 op_sel:[1,0,0]
	v_cvt_scalef32_pk_bf16_fp4 v52, v68, 1.0 op_sel:[0,1,0]
	v_cvt_scalef32_pk_bf16_fp4 v54, v68, 1.0 op_sel:[1,1,0]
	v_dot2_f32_bf16 v56, v48, v6, 0
	v_dot2_f32_bf16 v48, v50, v4, 0
	v_dot2_f32_bf16 v56, v52, v10, v56
	s_add_i32 s12, s28, -14
	v_dot2_f32_bf16 v48, v54, v8, v48
	v_cvt_scalef32_pk_bf16_fp4 v50, v69, 1.0
	v_cvt_scalef32_pk_bf16_fp4 v52, v69, 1.0 op_sel:[1,0,0]
	v_cvt_scalef32_pk_bf16_fp4 v54, v69, 1.0 op_sel:[0,1,0]
	v_cvt_scalef32_pk_bf16_fp4 v58, v69, 1.0 op_sel:[1,1,0]
	v_readlane_b32 s12, v46, s12
	v_dot2_f32_bf16 v56, v50, v14, v56
	v_dot2_f32_bf16 v48, v52, v12, v48
	s_lshr_b32 s12, s12, 7
	v_dot2_f32_bf16 v56, v54, v18, v56
	v_dot2_f32_bf16 v48, v58, v16, v48
	v_cvt_scalef32_pk_bf16_fp4 v50, v70, 1.0
	v_cvt_scalef32_pk_bf16_fp4 v52, v70, 1.0 op_sel:[1,0,0]
	v_cvt_scalef32_pk_bf16_fp4 v54, v70, 1.0 op_sel:[0,1,0]
	v_cvt_scalef32_pk_bf16_fp4 v58, v70, 1.0 op_sel:[1,1,0]
	s_mov_b32 s13, s86
	v_dot2_f32_bf16 v56, v50, v22, v56
	v_dot2_f32_bf16 v48, v52, v20, v48
	s_lshl_b64 s[12:13], s[12:13], 10
	v_dot2_f32_bf16 v56, v54, v26, v56
	v_dot2_f32_bf16 v48, v58, v24, v48
	v_cvt_scalef32_pk_bf16_fp4 v50, v71, 1.0
	v_cvt_scalef32_pk_bf16_fp4 v52, v71, 1.0 op_sel:[1,0,0]
	v_cvt_scalef32_pk_bf16_fp4 v54, v71, 1.0 op_sel:[0,1,0]
	v_cvt_scalef32_pk_bf16_fp4 v58, v71, 1.0 op_sel:[1,1,0]
	v_mov_b32_e32 v100, 0
	v_dot2_f32_bf16 v56, v50, v30, v56
	v_dot2_f32_bf16 v48, v52, v28, v48
	v_mov_b32_e32 v42, 0
	v_dot2_f32_bf16 v56, v54, v36, v56
	v_dot2_f32_bf16 v48, v58, v34, v48
	s_nop 2
	v_add_f32_e32 v48, v56, v48
	s_add_u32 s12, s12, s100
	s_addc_u32 s13, s13, s101
	global_load_dwordx4 v[68:71], v207, s[12:13]
	s_waitcnt vmcnt(15)
	v_cvt_scalef32_pk_bf16_fp4 v50, v72, 1.0
	v_cvt_scalef32_pk_bf16_fp4 v52, v72, 1.0 op_sel:[1,0,0]
	v_cvt_scalef32_pk_bf16_fp4 v54, v72, 1.0 op_sel:[0,1,0]
	v_cvt_scalef32_pk_bf16_fp4 v56, v72, 1.0 op_sel:[1,1,0]
	s_add_i32 s12, s28, -13
	v_dot2_f32_bf16 v58, v50, v6, 0
	v_dot2_f32_bf16 v50, v52, v4, 0
	v_dot2_f32_bf16 v58, v54, v10, v58
	v_readlane_b32 s12, v46, s12
	v_dot2_f32_bf16 v50, v56, v8, v50
	v_cvt_scalef32_pk_bf16_fp4 v52, v73, 1.0
	v_cvt_scalef32_pk_bf16_fp4 v54, v73, 1.0 op_sel:[1,0,0]
	v_cvt_scalef32_pk_bf16_fp4 v56, v73, 1.0 op_sel:[0,1,0]
	v_cvt_scalef32_pk_bf16_fp4 v60, v73, 1.0 op_sel:[1,1,0]
	s_lshr_b32 s12, s12, 7
	v_dot2_f32_bf16 v58, v52, v14, v58
	v_dot2_f32_bf16 v50, v54, v12, v50
	s_mov_b32 s13, s86
	v_dot2_f32_bf16 v58, v56, v18, v58
	v_dot2_f32_bf16 v50, v60, v16, v50
	v_cvt_scalef32_pk_bf16_fp4 v52, v74, 1.0
	v_cvt_scalef32_pk_bf16_fp4 v54, v74, 1.0 op_sel:[1,0,0]
	v_cvt_scalef32_pk_bf16_fp4 v56, v74, 1.0 op_sel:[0,1,0]
	v_cvt_scalef32_pk_bf16_fp4 v60, v74, 1.0 op_sel:[1,1,0]
	s_lshl_b64 s[12:13], s[12:13], 10
	v_dot2_f32_bf16 v58, v52, v22, v58
	v_dot2_f32_bf16 v50, v54, v20, v50
	s_nop 0
	v_dot2_f32_bf16 v58, v56, v26, v58
	v_dot2_f32_bf16 v50, v60, v24, v50
	v_cvt_scalef32_pk_bf16_fp4 v52, v75, 1.0
	v_cvt_scalef32_pk_bf16_fp4 v54, v75, 1.0 op_sel:[1,0,0]
	v_cvt_scalef32_pk_bf16_fp4 v56, v75, 1.0 op_sel:[0,1,0]
	v_cvt_scalef32_pk_bf16_fp4 v60, v75, 1.0 op_sel:[1,1,0]
	s_nop 0
	v_dot2_f32_bf16 v58, v52, v30, v58
	v_dot2_f32_bf16 v50, v54, v28, v50
	s_nop 0
	v_dot2_f32_bf16 v58, v56, v36, v58
	v_dot2_f32_bf16 v50, v60, v34, v50
	s_nop 0
	s_nop 2
	v_add_f32_e32 v49, v58, v50
	s_add_u32 s12, s12, s100
	s_addc_u32 s13, s13, s101
	global_load_dwordx4 v[72:75], v207, s[12:13]
	s_waitcnt vmcnt(15)
; #define P4_FOR16(M) M(0) M(1) M(2) M(3) M(4) M(5) M(6) M(7) M(8) M(9) M(10) M(11) M(12) M(13) M(14) M(15)
; #define P4_U(i) { P4_DOT(b##i, part[i]); const int nk_ = __builtin_amdgcn_readlane(ksel, nb + i); P4_LOAD(b##i, Ug, nk_); }
; #define P4_U(i) { P4_DOT(b##i, part[i]); const int nk_ = __builtin_amdgcn_readlane(kn, i); P4_LOAD(b##i, nbase, nk_); }
; __device__ __forceinline__ void peer_gather_f4p(const float* X, const int* __restrict__ IDX, const float* __restrict__ G, ...
;     ...
;         for (int bt = 0; bt < 7; ++bt) {
;             const int ksel = (bt + 1 < 4) ? k0 : k1;
;             const int nb = (16 * (bt + 1)) & 63;
;     ...
;             P4_FOR16(P4_U)
	v_cvt_scalef32_pk_bf16_fp4 v50, v76, 1.0
	v_cvt_scalef32_pk_bf16_fp4 v52, v76, 1.0 op_sel:[1,0,0]
	v_cvt_scalef32_pk_bf16_fp4 v54, v76, 1.0 op_sel:[0,1,0]
	v_cvt_scalef32_pk_bf16_fp4 v56, v76, 1.0 op_sel:[1,1,0]
	v_dot2_f32_bf16 v58, v50, v6, 0
	v_dot2_f32_bf16 v50, v52, v4, 0
	v_dot2_f32_bf16 v58, v54, v10, v58
	s_add_i32 s12, s28, -12
	v_dot2_f32_bf16 v50, v56, v8, v50
	v_cvt_scalef32_pk_bf16_fp4 v52, v77, 1.0
	v_cvt_scalef32_pk_bf16_fp4 v54, v77, 1.0 op_sel:[1,0,0]
	v_cvt_scalef32_pk_bf16_fp4 v56, v77, 1.0 op_sel:[0,1,0]
	v_cvt_scalef32_pk_bf16_fp4 v60, v77, 1.0 op_sel:[1,1,0]
	v_readlane_b32 s12, v46, s12
	v_dot2_f32_bf16 v58, v52, v14, v58
	v_dot2_f32_bf16 v50, v54, v12, v50
	s_lshr_b32 s12, s12, 7
	v_dot2_f32_bf16 v58, v56, v18, v58
	v_dot2_f32_bf16 v50, v60, v16, v50
	v_cvt_scalef32_pk_bf16_fp4 v52, v78, 1.0
	v_cvt_scalef32_pk_bf16_fp4 v54, v78, 1.0 op_sel:[1,0,0]
	v_cvt_scalef32_pk_bf16_fp4 v56, v78, 1.0 op_sel:[0,1,0]
	v_cvt_scalef32_pk_bf16_fp4 v60, v78, 1.0 op_sel:[1,1,0]
	s_mov_b32 s13, s86
	v_dot2_f32_bf16 v58, v52, v22, v58
	v_dot2_f32_bf16 v50, v54, v20, v50
	s_lshl_b64 s[12:13], s[12:13], 10
	v_dot2_f32_bf16 v58, v56, v26, v58
	v_dot2_f32_bf16 v50, v60, v24, v50
	v_cvt_scalef32_pk_bf16_fp4 v52, v79, 1.0
	v_cvt_scalef32_pk_bf16_fp4 v54, v79, 1.0 op_sel:[1,0,0]
	v_cvt_scalef32_pk_bf16_fp4 v56, v79, 1.0 op_sel:[0,1,0]
	v_cvt_scalef32_pk_bf16_fp4 v60, v79, 1.0 op_sel:[1,1,0]
	s_nop 0
	v_dot2_f32_bf16 v58, v52, v30, v58
	v_dot2_f32_bf16 v50, v54, v28, v50
	s_nop 0
	v_dot2_f32_bf16 v58, v56, v36, v58
	v_dot2_f32_bf16 v50, v60, v34, v50
	s_nop 2
	v_add_f32_e32 v50, v58, v50
	s_add_u32 s12, s12, s100
	s_addc_u32 s13, s13, s101
	global_load_dwordx4 v[76:79], v207, s[12:13]
	s_waitcnt vmcnt(15)
	v_cvt_scalef32_pk_bf16_fp4 v52, v80, 1.0
	v_cvt_scalef32_pk_bf16_fp4 v54, v80, 1.0 op_sel:[1,0,0]
	v_cvt_scalef32_pk_bf16_fp4 v56, v80, 1.0 op_sel:[0,1,0]
	v_cvt_scalef32_pk_bf16_fp4 v58, v80, 1.0 op_sel:[1,1,0]
	s_add_i32 s12, s28, -11
	v_dot2_f32_bf16 v60, v52, v6, 0
	v_dot2_f32_bf16 v52, v54, v4, 0
	v_dot2_f32_bf16 v60, v56, v10, v60
	v_readlane_b32 s12, v46, s12
	v_dot2_f32_bf16 v52, v58, v8, v52
	v_cvt_scalef32_pk_bf16_fp4 v54, v81, 1.0
	v_cvt_scalef32_pk_bf16_fp4 v56, v81, 1.0 op_sel:[1,0,0]
	v_cvt_scalef32_pk_bf16_fp4 v58, v81, 1.0 op_sel:[0,1,0]
	v_cvt_scalef32_pk_bf16_fp4 v62, v81, 1.0 op_sel:[1,1,0]
	s_lshr_b32 s12, s12, 7
	v_dot2_f32_bf16 v60, v54, v14, v60
	v_dot2_f32_bf16 v52, v56, v12, v52
	s_mov_b32 s13, s86
	v_dot2_f32_bf16 v60, v58, v18, v60
	v_dot2_f32_bf16 v52, v62, v16, v52
	v_cvt_scalef32_pk_bf16_fp4 v54, v82, 1.0
	v_cvt_scalef32_pk_bf16_fp4 v56, v82, 1.0 op_sel:[1,0,0]
	v_cvt_scalef32_pk_bf16_fp4 v58, v82, 1.0 op_sel:[0,1,0]
	v_cvt_scalef32_pk_bf16_fp4 v62, v82, 1.0 op_sel:[1,1,0]
	s_lshl_b64 s[12:13], s[12:13], 10
	v_dot2_f32_bf16 v60, v54, v22, v60
	v_dot2_f32_bf16 v52, v56, v20, v52
	s_nop 0
	v_dot2_f32_bf16 v60, v58, v26, v60
	v_dot2_f32_bf16 v52, v62, v24, v52
	v_cvt_scalef32_pk_bf16_fp4 v54, v83, 1.0
	v_cvt_scalef32_pk_bf16_fp4 v56, v83, 1.0 op_sel:[1,0,0]
	v_cvt_scalef32_pk_bf16_fp4 v58, v83, 1.0 op_sel:[0,1,0]
	v_cvt_scalef32_pk_bf16_fp4 v62, v83, 1.0 op_sel:[1,1,0]
	s_nop 0
	v_dot2_f32_bf16 v60, v54, v30, v60
	v_dot2_f32_bf16 v52, v56, v28, v52
	s_nop 0
	v_dot2_f32_bf16 v60, v58, v36, v60
	v_dot2_f32_bf16 v52, v62, v34, v52
	s_nop 0
	s_nop 2
	v_add_f32_e32 v51, v60, v52
	s_add_u32 s12, s12, s100
	s_addc_u32 s13, s13, s101
	global_load_dwordx4 v[80:83], v207, s[12:13]
	s_waitcnt vmcnt(15)
	v_cvt_scalef32_pk_bf16_fp4 v52, v84, 1.0
	v_cvt_scalef32_pk_bf16_fp4 v54, v84, 1.0 op_sel:[1,0,0]
	v_cvt_scalef32_pk_bf16_fp4 v56, v84, 1.0 op_sel:[0,1,0]
	v_cvt_scalef32_pk_bf16_fp4 v58, v84, 1.0 op_sel:[1,1,0]
	v_dot2_f32_bf16 v60, v52, v6, 0
	v_dot2_f32_bf16 v52, v54, v4, 0
	v_dot2_f32_bf16 v60, v56, v10, v60
	s_add_i32 s12, s28, -10
	v_dot2_f32_bf16 v52, v58, v8, v52
	v_cvt_scalef32_pk_bf16_fp4 v54, v85, 1.0
	v_cvt_scalef32_pk_bf16_fp4 v56, v85, 1.0 op_sel:[1,0,0]
	v_cvt_scalef32_pk_bf16_fp4 v58, v85, 1.0 op_sel:[0,1,0]
	v_cvt_scalef32_pk_bf16_fp4 v62, v85, 1.0 op_sel:[1,1,0]
	v_readlane_b32 s12, v46, s12
	v_dot2_f32_bf16 v60, v54, v14, v60
	v_dot2_f32_bf16 v52, v56, v12, v52
	s_lshr_b32 s12, s12, 7
	v_dot2_f32_bf16 v60, v58, v18, v60
	v_dot2_f32_bf16 v52, v62, v16, v52
	v_cvt_scalef32_pk_bf16_fp4 v54, v86, 1.0
	v_cvt_scalef32_pk_bf16_fp4 v56, v86, 1.0 op_sel:[1,0,0]
	v_cvt_scalef32_pk_bf16_fp4 v58, v86, 1.0 op_sel:[0,1,0]
	v_cvt_scalef32_pk_bf16_fp4 v62, v86, 1.0 op_sel:[1,1,0]
	s_mov_b32 s13, s86
	v_dot2_f32_bf16 v60, v54, v22, v60
	v_dot2_f32_bf16 v52, v56, v20, v52
	s_lshl_b64 s[12:13], s[12:13], 10
	v_dot2_f32_bf16 v60, v58, v26, v60
	v_dot2_f32_bf16 v52, v62, v24, v52
	v_cvt_scalef32_pk_bf16_fp4 v54, v87, 1.0
	v_cvt_scalef32_pk_bf16_fp4 v56, v87, 1.0 op_sel:[1,0,0]
	v_cvt_scalef32_pk_bf16_fp4 v58, v87, 1.0 op_sel:[0,1,0]
	v_cvt_scalef32_pk_bf16_fp4 v62, v87, 1.0 op_sel:[1,1,0]
	s_nop 0
	v_dot2_f32_bf16 v60, v54, v30, v60
	v_dot2_f32_bf16 v52, v56, v28, v52
	s_nop 0
	v_dot2_f32_bf16 v60, v58, v36, v60
	v_dot2_f32_bf16 v52, v62, v34, v52
	s_nop 2
	v_add_f32_e32 v52, v60, v52
	s_add_u32 s12, s12, s100
	s_addc_u32 s13, s13, s101
	global_load_dwordx4 v[84:87], v207, s[12:13]
	s_waitcnt vmcnt(15)
; #define P4_FOR16(M) M(0) M(1) M(2) M(3) M(4) M(5) M(6) M(7) M(8) M(9) M(10) M(11) M(12) M(13) M(14) M(15)
; #define P4_U(i) { P4_DOT(b##i, part[i]); const int nk_ = __builtin_amdgcn_readlane(ksel, nb + i); P4_LOAD(b##i, Ug, nk_); }
; #define P4_U(i) { P4_DOT(b##i, part[i]); const int nk_ = __builtin_amdgcn_readlane(kn, i); P4_LOAD(b##i, nbase, nk_); }
; __device__ __forceinline__ void peer_gather_f4p(const float* X, const int* __restrict__ IDX, const float* __restrict__ G, ...
;     ...
;         for (int bt = 0; bt < 7; ++bt) {
;             const int ksel = (bt + 1 < 4) ? k0 : k1;
;             const int nb = (16 * (bt + 1)) & 63;
;     ...
;             P4_FOR16(P4_U)
	v_cvt_scalef32_pk_bf16_fp4 v54, v88, 1.0
	v_cvt_scalef32_pk_bf16_fp4 v56, v88, 1.0 op_sel:[1,0,0]
	v_cvt_scalef32_pk_bf16_fp4 v58, v88, 1.0 op_sel:[0,1,0]
	v_cvt_scalef32_pk_bf16_fp4 v60, v88, 1.0 op_sel:[1,1,0]
	s_add_i32 s12, s28, -9
	v_dot2_f32_bf16 v62, v54, v6, 0
	v_dot2_f32_bf16 v54, v56, v4, 0
	v_dot2_f32_bf16 v62, v58, v10, v62
	v_readlane_b32 s12, v46, s12
	v_dot2_f32_bf16 v54, v60, v8, v54
	v_cvt_scalef32_pk_bf16_fp4 v56, v89, 1.0
	v_cvt_scalef32_pk_bf16_fp4 v58, v89, 1.0 op_sel:[1,0,0]
	v_cvt_scalef32_pk_bf16_fp4 v60, v89, 1.0 op_sel:[0,1,0]
	v_cvt_scalef32_pk_bf16_fp4 v88, v89, 1.0 op_sel:[1,1,0]
	s_lshr_b32 s12, s12, 7
	v_dot2_f32_bf16 v62, v56, v14, v62
	v_dot2_f32_bf16 v54, v58, v12, v54
	s_mov_b32 s13, s86
	v_dot2_f32_bf16 v62, v60, v18, v62
	v_dot2_f32_bf16 v54, v88, v16, v54
	v_cvt_scalef32_pk_bf16_fp4 v56, v90, 1.0
	v_cvt_scalef32_pk_bf16_fp4 v58, v90, 1.0 op_sel:[1,0,0]
	v_cvt_scalef32_pk_bf16_fp4 v60, v90, 1.0 op_sel:[0,1,0]
	v_cvt_scalef32_pk_bf16_fp4 v88, v90, 1.0 op_sel:[1,1,0]
	s_lshl_b64 s[12:13], s[12:13], 10
	v_dot2_f32_bf16 v62, v56, v22, v62
	v_dot2_f32_bf16 v54, v58, v20, v54
	s_nop 0
	v_dot2_f32_bf16 v62, v60, v26, v62
	v_dot2_f32_bf16 v54, v88, v24, v54
	v_cvt_scalef32_pk_bf16_fp4 v56, v91, 1.0
	v_cvt_scalef32_pk_bf16_fp4 v58, v91, 1.0 op_sel:[1,0,0]
	v_cvt_scalef32_pk_bf16_fp4 v60, v91, 1.0 op_sel:[0,1,0]
	v_cvt_scalef32_pk_bf16_fp4 v88, v91, 1.0 op_sel:[1,1,0]
	s_nop 0
	v_dot2_f32_bf16 v62, v56, v30, v62
	v_dot2_f32_bf16 v54, v58, v28, v54
	s_nop 0
	v_dot2_f32_bf16 v62, v60, v36, v62
	v_dot2_f32_bf16 v54, v88, v34, v54
	s_nop 0
	s_nop 2
	v_add_f32_e32 v53, v62, v54
	s_add_u32 s12, s12, s100
	s_addc_u32 s13, s13, s101
	global_load_dwordx4 v[88:91], v207, s[12:13]
	s_waitcnt vmcnt(15)
	v_cvt_scalef32_pk_bf16_fp4 v54, v92, 1.0
	v_cvt_scalef32_pk_bf16_fp4 v56, v92, 1.0 op_sel:[1,0,0]
	v_cvt_scalef32_pk_bf16_fp4 v58, v92, 1.0 op_sel:[0,1,0]
	v_cvt_scalef32_pk_bf16_fp4 v60, v92, 1.0 op_sel:[1,1,0]
	v_dot2_f32_bf16 v62, v54, v6, 0
	v_dot2_f32_bf16 v54, v56, v4, 0
	v_dot2_f32_bf16 v62, v58, v10, v62
	s_add_i32 s12, s28, -8
	v_dot2_f32_bf16 v54, v60, v8, v54
	v_cvt_scalef32_pk_bf16_fp4 v56, v93, 1.0
	v_cvt_scalef32_pk_bf16_fp4 v58, v93, 1.0 op_sel:[1,0,0]
	v_cvt_scalef32_pk_bf16_fp4 v60, v93, 1.0 op_sel:[0,1,0]
	v_cvt_scalef32_pk_bf16_fp4 v92, v93, 1.0 op_sel:[1,1,0]
	v_readlane_b32 s12, v46, s12
	v_dot2_f32_bf16 v62, v56, v14, v62
	v_dot2_f32_bf16 v54, v58, v12, v54
	s_lshr_b32 s12, s12, 7
	v_dot2_f32_bf16 v62, v60, v18, v62
	v_dot2_f32_bf16 v54, v92, v16, v54
	v_cvt_scalef32_pk_bf16_fp4 v56, v94, 1.0
	v_cvt_scalef32_pk_bf16_fp4 v58, v94, 1.0 op_sel:[1,0,0]
	v_cvt_scalef32_pk_bf16_fp4 v60, v94, 1.0 op_sel:[0,1,0]
	v_cvt_scalef32_pk_bf16_fp4 v92, v94, 1.0 op_sel:[1,1,0]
	s_mov_b32 s13, s86
	v_dot2_f32_bf16 v62, v56, v22, v62
	v_dot2_f32_bf16 v54, v58, v20, v54
	s_lshl_b64 s[12:13], s[12:13], 10
	v_dot2_f32_bf16 v62, v60, v26, v62
	v_dot2_f32_bf16 v54, v92, v24, v54
	v_cvt_scalef32_pk_bf16_fp4 v56, v95, 1.0
	v_cvt_scalef32_pk_bf16_fp4 v58, v95, 1.0 op_sel:[1,0,0]
	v_cvt_scalef32_pk_bf16_fp4 v60, v95, 1.0 op_sel:[0,1,0]
	v_cvt_scalef32_pk_bf16_fp4 v92, v95, 1.0 op_sel:[1,1,0]
	s_nop 0
	v_dot2_f32_bf16 v62, v56, v30, v62
	v_dot2_f32_bf16 v54, v58, v28, v54
	s_nop 0
	v_dot2_f32_bf16 v62, v60, v36, v62
	v_dot2_f32_bf16 v54, v92, v34, v54
	s_nop 0
	s_nop 2
	v_add_f32_e32 v54, v62, v54
	s_add_u32 s12, s12, s100
	s_addc_u32 s13, s13, s101
	global_load_dwordx4 v[92:95], v207, s[12:13]
	s_waitcnt vmcnt(15)
	v_cvt_scalef32_pk_bf16_fp4 v56, v96, 1.0
	v_cvt_scalef32_pk_bf16_fp4 v58, v96, 1.0 op_sel:[1,0,0]
	v_cvt_scalef32_pk_bf16_fp4 v60, v96, 1.0 op_sel:[0,1,0]
	v_cvt_scalef32_pk_bf16_fp4 v62, v96, 1.0 op_sel:[1,1,0]
	s_add_i32 s12, s28, -7
	v_dot2c_f32_bf16_e32 v100, v56, v6
	v_dot2_f32_bf16 v56, v58, v4, 0
	v_dot2c_f32_bf16_e32 v100, v60, v10
	v_readlane_b32 s12, v46, s12
	v_dot2_f32_bf16 v56, v62, v8, v56
	v_cvt_scalef32_pk_bf16_fp4 v58, v97, 1.0
	v_cvt_scalef32_pk_bf16_fp4 v60, v97, 1.0 op_sel:[1,0,0]
	v_cvt_scalef32_pk_bf16_fp4 v62, v97, 1.0 op_sel:[0,1,0]
	v_cvt_scalef32_pk_bf16_fp4 v96, v97, 1.0 op_sel:[1,1,0]
	s_lshr_b32 s12, s12, 7
	v_dot2c_f32_bf16_e32 v100, v58, v14
	v_dot2_f32_bf16 v56, v60, v12, v56
	s_mov_b32 s13, s86
	v_dot2c_f32_bf16_e32 v100, v62, v18
	v_dot2_f32_bf16 v56, v96, v16, v56
	v_cvt_scalef32_pk_bf16_fp4 v58, v98, 1.0
	v_cvt_scalef32_pk_bf16_fp4 v60, v98, 1.0 op_sel:[1,0,0]
	v_cvt_scalef32_pk_bf16_fp4 v62, v98, 1.0 op_sel:[0,1,0]
	v_cvt_scalef32_pk_bf16_fp4 v96, v98, 1.0 op_sel:[1,1,0]
	s_lshl_b64 s[12:13], s[12:13], 10
	v_dot2c_f32_bf16_e32 v100, v58, v22
	v_dot2_f32_bf16 v56, v60, v20, v56
	s_nop 0
	v_dot2c_f32_bf16_e32 v100, v62, v26
	v_dot2_f32_bf16 v56, v96, v24, v56
	v_cvt_scalef32_pk_bf16_fp4 v58, v99, 1.0
	v_cvt_scalef32_pk_bf16_fp4 v60, v99, 1.0 op_sel:[1,0,0]
	v_cvt_scalef32_pk_bf16_fp4 v62, v99, 1.0 op_sel:[0,1,0]
	v_cvt_scalef32_pk_bf16_fp4 v96, v99, 1.0 op_sel:[1,1,0]
	s_nop 0
	v_dot2c_f32_bf16_e32 v100, v58, v30
	v_dot2_f32_bf16 v56, v60, v28, v56
	s_nop 0
	v_dot2c_f32_bf16_e32 v100, v62, v36
	v_dot2_f32_bf16 v56, v96, v34, v56
	s_nop 0
	s_nop 2
	v_add_f32_e32 v55, v100, v56
	s_add_u32 s12, s12, s100
	s_addc_u32 s13, s13, s101
	global_load_dwordx4 v[96:99], v207, s[12:13]
	s_waitcnt vmcnt(15)
; #define P4_FOR16(M) M(0) M(1) M(2) M(3) M(4) M(5) M(6) M(7) M(8) M(9) M(10) M(11) M(12) M(13) M(14) M(15)
; #define P4_U(i) { P4_DOT(b##i, part[i]); const int nk_ = __builtin_amdgcn_readlane(ksel, nb + i); P4_LOAD(b##i, Ug, nk_); }
; #define P4_U(i) { P4_DOT(b##i, part[i]); const int nk_ = __builtin_amdgcn_readlane(kn, i); P4_LOAD(b##i, nbase, nk_); }
; __device__ __forceinline__ void peer_gather_f4p(const float* X, const int* __restrict__ IDX, const float* __restrict__ G, ...
;     ...
;         for (int bt = 0; bt < 7; ++bt) {
;             const int ksel = (bt + 1 < 4) ? k0 : k1;
;             const int nb = (16 * (bt + 1)) & 63;
;     ...
;             P4_FOR16(P4_U)
	v_cvt_scalef32_pk_bf16_fp4 v56, v104, 1.0
	v_cvt_scalef32_pk_bf16_fp4 v58, v104, 1.0 op_sel:[1,0,0]
	v_cvt_scalef32_pk_bf16_fp4 v60, v104, 1.0 op_sel:[0,1,0]
	v_cvt_scalef32_pk_bf16_fp4 v62, v104, 1.0 op_sel:[1,1,0]
	v_dot2_f32_bf16 v100, v56, v6, 0
	v_dot2_f32_bf16 v56, v58, v4, 0
	v_dot2_f32_bf16 v100, v60, v10, v100
	s_add_i32 s12, s28, -6
	v_dot2_f32_bf16 v56, v62, v8, v56
	v_cvt_scalef32_pk_bf16_fp4 v58, v105, 1.0
	v_cvt_scalef32_pk_bf16_fp4 v60, v105, 1.0 op_sel:[1,0,0]
	v_cvt_scalef32_pk_bf16_fp4 v62, v105, 1.0 op_sel:[0,1,0]
	v_cvt_scalef32_pk_bf16_fp4 v102, v105, 1.0 op_sel:[1,1,0]
	v_readlane_b32 s12, v46, s12
	v_dot2_f32_bf16 v100, v58, v14, v100
	v_dot2_f32_bf16 v56, v60, v12, v56
	s_lshr_b32 s12, s12, 7
	v_dot2_f32_bf16 v100, v62, v18, v100
	v_dot2_f32_bf16 v56, v102, v16, v56
	v_cvt_scalef32_pk_bf16_fp4 v58, v106, 1.0
	v_cvt_scalef32_pk_bf16_fp4 v60, v106, 1.0 op_sel:[1,0,0]
	v_cvt_scalef32_pk_bf16_fp4 v62, v106, 1.0 op_sel:[0,1,0]
	v_cvt_scalef32_pk_bf16_fp4 v102, v106, 1.0 op_sel:[1,1,0]
	s_mov_b32 s13, s86
	v_dot2_f32_bf16 v100, v58, v22, v100
	v_dot2_f32_bf16 v56, v60, v20, v56
	s_lshl_b64 s[12:13], s[12:13], 10
	v_dot2_f32_bf16 v100, v62, v26, v100
	v_dot2_f32_bf16 v56, v102, v24, v56
	v_cvt_scalef32_pk_bf16_fp4 v58, v107, 1.0
	v_cvt_scalef32_pk_bf16_fp4 v60, v107, 1.0 op_sel:[1,0,0]
	v_cvt_scalef32_pk_bf16_fp4 v62, v107, 1.0 op_sel:[0,1,0]
	v_cvt_scalef32_pk_bf16_fp4 v102, v107, 1.0 op_sel:[1,1,0]
	s_nop 0
	v_dot2_f32_bf16 v100, v58, v30, v100
	v_dot2_f32_bf16 v56, v60, v28, v56
	s_nop 0
	v_dot2_f32_bf16 v100, v62, v36, v100
	v_dot2_f32_bf16 v56, v102, v34, v56
	s_nop 2
	v_add_f32_e32 v56, v100, v56
	s_add_u32 s12, s12, s100
	s_addc_u32 s13, s13, s101
	global_load_dwordx4 v[104:107], v207, s[12:13]
	s_waitcnt vmcnt(15)
	v_cvt_scalef32_pk_bf16_fp4 v58, v108, 1.0
	v_cvt_scalef32_pk_bf16_fp4 v60, v108, 1.0 op_sel:[1,0,0]
	v_cvt_scalef32_pk_bf16_fp4 v62, v108, 1.0 op_sel:[0,1,0]
	v_cvt_scalef32_pk_bf16_fp4 v100, v108, 1.0 op_sel:[1,1,0]
	s_add_i32 s12, s28, -5
	v_dot2_f32_bf16 v102, v58, v6, 0
	v_dot2_f32_bf16 v58, v60, v4, 0
	v_dot2_f32_bf16 v102, v62, v10, v102
	v_readlane_b32 s12, v46, s12
	v_dot2_f32_bf16 v58, v100, v8, v58
	v_cvt_scalef32_pk_bf16_fp4 v60, v109, 1.0
	v_cvt_scalef32_pk_bf16_fp4 v62, v109, 1.0 op_sel:[1,0,0]
	v_cvt_scalef32_pk_bf16_fp4 v100, v109, 1.0 op_sel:[0,1,0]
	v_cvt_scalef32_pk_bf16_fp4 v108, v109, 1.0 op_sel:[1,1,0]
	s_lshr_b32 s12, s12, 7
	v_dot2_f32_bf16 v102, v60, v14, v102
	v_dot2_f32_bf16 v58, v62, v12, v58
	s_mov_b32 s13, s86
	v_dot2_f32_bf16 v102, v100, v18, v102
	v_dot2_f32_bf16 v58, v108, v16, v58
	v_cvt_scalef32_pk_bf16_fp4 v60, v110, 1.0
	v_cvt_scalef32_pk_bf16_fp4 v62, v110, 1.0 op_sel:[1,0,0]
	v_cvt_scalef32_pk_bf16_fp4 v100, v110, 1.0 op_sel:[0,1,0]
	v_cvt_scalef32_pk_bf16_fp4 v108, v110, 1.0 op_sel:[1,1,0]
	s_lshl_b64 s[12:13], s[12:13], 10
	v_dot2_f32_bf16 v102, v60, v22, v102
	v_dot2_f32_bf16 v58, v62, v20, v58
	s_nop 0
	v_dot2_f32_bf16 v102, v100, v26, v102
	v_dot2_f32_bf16 v58, v108, v24, v58
	v_cvt_scalef32_pk_bf16_fp4 v60, v111, 1.0
	v_cvt_scalef32_pk_bf16_fp4 v62, v111, 1.0 op_sel:[1,0,0]
	v_cvt_scalef32_pk_bf16_fp4 v100, v111, 1.0 op_sel:[0,1,0]
	v_cvt_scalef32_pk_bf16_fp4 v108, v111, 1.0 op_sel:[1,1,0]
	s_nop 0
	v_dot2_f32_bf16 v102, v60, v30, v102
	v_dot2_f32_bf16 v58, v62, v28, v58
	s_nop 0
	v_dot2_f32_bf16 v102, v100, v36, v102
	v_dot2_f32_bf16 v58, v108, v34, v58
	s_nop 0
	s_nop 2
	v_add_f32_e32 v57, v102, v58
	s_add_u32 s12, s12, s100
	s_addc_u32 s13, s13, s101
	global_load_dwordx4 v[108:111], v207, s[12:13]
	s_waitcnt vmcnt(15)
	v_cvt_scalef32_pk_bf16_fp4 v58, v112, 1.0
	v_cvt_scalef32_pk_bf16_fp4 v60, v112, 1.0 op_sel:[1,0,0]
	v_cvt_scalef32_pk_bf16_fp4 v62, v112, 1.0 op_sel:[0,1,0]
	v_cvt_scalef32_pk_bf16_fp4 v100, v112, 1.0 op_sel:[1,1,0]
	v_dot2_f32_bf16 v102, v58, v6, 0
	v_dot2_f32_bf16 v58, v60, v4, 0
	v_dot2_f32_bf16 v102, v62, v10, v102
	s_add_i32 s12, s28, -4
	v_dot2_f32_bf16 v58, v100, v8, v58
	v_cvt_scalef32_pk_bf16_fp4 v60, v113, 1.0
	v_cvt_scalef32_pk_bf16_fp4 v62, v113, 1.0 op_sel:[1,0,0]
	v_cvt_scalef32_pk_bf16_fp4 v100, v113, 1.0 op_sel:[0,1,0]
	v_cvt_scalef32_pk_bf16_fp4 v112, v113, 1.0 op_sel:[1,1,0]
	v_readlane_b32 s12, v46, s12
	v_dot2_f32_bf16 v102, v60, v14, v102
	v_dot2_f32_bf16 v58, v62, v12, v58
	s_lshr_b32 s12, s12, 7
	v_dot2_f32_bf16 v102, v100, v18, v102
	v_dot2_f32_bf16 v58, v112, v16, v58
	v_cvt_scalef32_pk_bf16_fp4 v60, v114, 1.0
	v_cvt_scalef32_pk_bf16_fp4 v62, v114, 1.0 op_sel:[1,0,0]
	v_cvt_scalef32_pk_bf16_fp4 v100, v114, 1.0 op_sel:[0,1,0]
	v_cvt_scalef32_pk_bf16_fp4 v112, v114, 1.0 op_sel:[1,1,0]
	s_mov_b32 s13, s86
	v_dot2_f32_bf16 v102, v60, v22, v102
	v_dot2_f32_bf16 v58, v62, v20, v58
	s_lshl_b64 s[12:13], s[12:13], 10
	v_dot2_f32_bf16 v102, v100, v26, v102
	v_dot2_f32_bf16 v58, v112, v24, v58
	v_cvt_scalef32_pk_bf16_fp4 v60, v115, 1.0
	v_cvt_scalef32_pk_bf16_fp4 v62, v115, 1.0 op_sel:[1,0,0]
	v_cvt_scalef32_pk_bf16_fp4 v100, v115, 1.0 op_sel:[0,1,0]
	v_cvt_scalef32_pk_bf16_fp4 v112, v115, 1.0 op_sel:[1,1,0]
	s_nop 0
	v_dot2_f32_bf16 v102, v60, v30, v102
	v_dot2_f32_bf16 v58, v62, v28, v58
	s_nop 0
	v_dot2_f32_bf16 v102, v100, v36, v102
	v_dot2_f32_bf16 v58, v112, v34, v58
	s_nop 0
	s_nop 2
	v_add_f32_e32 v132, v102, v58
	s_add_u32 s12, s12, s100
	s_addc_u32 s13, s13, s101
	global_load_dwordx4 v[112:115], v207, s[12:13]
	s_waitcnt vmcnt(15)
; #define P4_FOR16(M) M(0) M(1) M(2) M(3) M(4) M(5) M(6) M(7) M(8) M(9) M(10) M(11) M(12) M(13) M(14) M(15)
; #define P4_U(i) { P4_DOT(b##i, part[i]); const int nk_ = __builtin_amdgcn_readlane(ksel, nb + i); P4_LOAD(b##i, Ug, nk_); }
; #define P4_U(i) { P4_DOT(b##i, part[i]); const int nk_ = __builtin_amdgcn_readlane(kn, i); P4_LOAD(b##i, nbase, nk_); }
; __device__ __forceinline__ void peer_gather_f4p(const float* X, const int* __restrict__ IDX, const float* __restrict__ G, ...
;     ...
;         for (int bt = 0; bt < 7; ++bt) {
;             const int ksel = (bt + 1 < 4) ? k0 : k1;
;             const int nb = (16 * (bt + 1)) & 63;
;     ...
;             P4_FOR16(P4_U)
	v_cvt_scalef32_pk_bf16_fp4 v58, v116, 1.0
	v_cvt_scalef32_pk_bf16_fp4 v60, v116, 1.0 op_sel:[1,0,0]
	v_cvt_scalef32_pk_bf16_fp4 v62, v116, 1.0 op_sel:[0,1,0]
	v_cvt_scalef32_pk_bf16_fp4 v100, v116, 1.0 op_sel:[1,1,0]
	v_dot2_f32_bf16 v102, v58, v6, 0
	v_dot2_f32_bf16 v58, v60, v4, 0
	v_dot2_f32_bf16 v102, v62, v10, v102
	s_add_i32 s12, s28, -3
	v_dot2_f32_bf16 v58, v100, v8, v58
	v_cvt_scalef32_pk_bf16_fp4 v60, v117, 1.0
	v_cvt_scalef32_pk_bf16_fp4 v62, v117, 1.0 op_sel:[1,0,0]
	v_cvt_scalef32_pk_bf16_fp4 v100, v117, 1.0 op_sel:[0,1,0]
	v_cvt_scalef32_pk_bf16_fp4 v116, v117, 1.0 op_sel:[1,1,0]
	v_readlane_b32 s12, v46, s12
	v_dot2_f32_bf16 v102, v60, v14, v102
	v_dot2_f32_bf16 v58, v62, v12, v58
	s_lshr_b32 s12, s12, 7
	v_dot2_f32_bf16 v102, v100, v18, v102
	v_dot2_f32_bf16 v58, v116, v16, v58
	v_cvt_scalef32_pk_bf16_fp4 v60, v118, 1.0
	v_cvt_scalef32_pk_bf16_fp4 v62, v118, 1.0 op_sel:[1,0,0]
	v_cvt_scalef32_pk_bf16_fp4 v100, v118, 1.0 op_sel:[0,1,0]
	v_cvt_scalef32_pk_bf16_fp4 v116, v118, 1.0 op_sel:[1,1,0]
	s_mov_b32 s13, s86
	v_dot2_f32_bf16 v102, v60, v22, v102
	v_dot2_f32_bf16 v58, v62, v20, v58
	s_lshl_b64 s[12:13], s[12:13], 10
	v_dot2_f32_bf16 v102, v100, v26, v102
	v_dot2_f32_bf16 v58, v116, v24, v58
	v_cvt_scalef32_pk_bf16_fp4 v60, v119, 1.0
	v_cvt_scalef32_pk_bf16_fp4 v62, v119, 1.0 op_sel:[1,0,0]
	v_cvt_scalef32_pk_bf16_fp4 v100, v119, 1.0 op_sel:[0,1,0]
	v_cvt_scalef32_pk_bf16_fp4 v116, v119, 1.0 op_sel:[1,1,0]
	s_nop 0
	v_dot2_f32_bf16 v102, v60, v30, v102
	v_dot2_f32_bf16 v58, v62, v28, v58
	s_nop 0
	v_dot2_f32_bf16 v102, v100, v36, v102
	v_dot2_f32_bf16 v58, v116, v34, v58
	s_nop 0
	s_nop 2
	v_add_f32_e32 v133, v102, v58
	s_add_u32 s12, s12, s100
	s_addc_u32 s13, s13, s101
	global_load_dwordx4 v[116:119], v207, s[12:13]
	s_waitcnt vmcnt(15)
	v_cvt_scalef32_pk_bf16_fp4 v58, v120, 1.0
	v_cvt_scalef32_pk_bf16_fp4 v60, v120, 1.0 op_sel:[1,0,0]
	v_cvt_scalef32_pk_bf16_fp4 v62, v120, 1.0 op_sel:[0,1,0]
	v_cvt_scalef32_pk_bf16_fp4 v100, v120, 1.0 op_sel:[1,1,0]
	v_dot2_f32_bf16 v102, v58, v6, 0
	v_dot2_f32_bf16 v58, v60, v4, 0
	v_dot2_f32_bf16 v102, v62, v10, v102
	s_add_i32 s12, s28, -2
	v_dot2_f32_bf16 v58, v100, v8, v58
	v_cvt_scalef32_pk_bf16_fp4 v60, v121, 1.0
	v_cvt_scalef32_pk_bf16_fp4 v62, v121, 1.0 op_sel:[1,0,0]
	v_cvt_scalef32_pk_bf16_fp4 v100, v121, 1.0 op_sel:[0,1,0]
	v_cvt_scalef32_pk_bf16_fp4 v120, v121, 1.0 op_sel:[1,1,0]
	v_readlane_b32 s12, v46, s12
	v_dot2_f32_bf16 v102, v60, v14, v102
	v_dot2_f32_bf16 v58, v62, v12, v58
	s_lshr_b32 s12, s12, 7
	v_dot2_f32_bf16 v102, v100, v18, v102
	v_dot2_f32_bf16 v58, v120, v16, v58
	v_cvt_scalef32_pk_bf16_fp4 v60, v122, 1.0
	v_cvt_scalef32_pk_bf16_fp4 v62, v122, 1.0 op_sel:[1,0,0]
	v_cvt_scalef32_pk_bf16_fp4 v100, v122, 1.0 op_sel:[0,1,0]
	v_cvt_scalef32_pk_bf16_fp4 v120, v122, 1.0 op_sel:[1,1,0]
	s_mov_b32 s13, s86
	v_dot2_f32_bf16 v102, v60, v22, v102
	v_dot2_f32_bf16 v58, v62, v20, v58
	s_lshl_b64 s[12:13], s[12:13], 10
	v_dot2_f32_bf16 v102, v100, v26, v102
	v_dot2_f32_bf16 v58, v120, v24, v58
	v_cvt_scalef32_pk_bf16_fp4 v60, v123, 1.0
	v_cvt_scalef32_pk_bf16_fp4 v62, v123, 1.0 op_sel:[1,0,0]
	v_cvt_scalef32_pk_bf16_fp4 v100, v123, 1.0 op_sel:[0,1,0]
	v_cvt_scalef32_pk_bf16_fp4 v120, v123, 1.0 op_sel:[1,1,0]
	s_nop 0
	v_dot2_f32_bf16 v102, v60, v30, v102
	v_dot2_f32_bf16 v58, v62, v28, v58
	s_nop 0
	v_dot2_f32_bf16 v102, v100, v36, v102
	v_dot2_f32_bf16 v58, v120, v34, v58
	s_nop 0
	s_nop 2
	v_add_f32_e32 v134, v102, v58
	s_add_u32 s12, s12, s100
	s_addc_u32 s13, s13, s101
	global_load_dwordx4 v[120:123], v207, s[12:13]
	s_waitcnt vmcnt(15)
	v_cvt_scalef32_pk_bf16_fp4 v58, v124, 1.0
	v_cvt_scalef32_pk_bf16_fp4 v60, v124, 1.0 op_sel:[1,0,0]
	v_cvt_scalef32_pk_bf16_fp4 v62, v124, 1.0 op_sel:[0,1,0]
	v_cvt_scalef32_pk_bf16_fp4 v100, v124, 1.0 op_sel:[1,1,0]
	v_dot2_f32_bf16 v102, v58, v6, 0
	v_dot2_f32_bf16 v58, v60, v4, 0
	v_dot2_f32_bf16 v102, v62, v10, v102
	s_add_i32 s12, s28, -1
	v_dot2_f32_bf16 v58, v100, v8, v58
	v_cvt_scalef32_pk_bf16_fp4 v60, v125, 1.0
	v_cvt_scalef32_pk_bf16_fp4 v62, v125, 1.0 op_sel:[1,0,0]
	v_cvt_scalef32_pk_bf16_fp4 v100, v125, 1.0 op_sel:[0,1,0]
	v_cvt_scalef32_pk_bf16_fp4 v124, v125, 1.0 op_sel:[1,1,0]
	v_readlane_b32 s12, v46, s12
	v_dot2_f32_bf16 v102, v60, v14, v102
	v_dot2_f32_bf16 v58, v62, v12, v58
	s_lshr_b32 s12, s12, 7
	v_dot2_f32_bf16 v102, v100, v18, v102
	v_dot2_f32_bf16 v58, v124, v16, v58
	v_cvt_scalef32_pk_bf16_fp4 v60, v126, 1.0
	v_cvt_scalef32_pk_bf16_fp4 v62, v126, 1.0 op_sel:[1,0,0]
	v_cvt_scalef32_pk_bf16_fp4 v100, v126, 1.0 op_sel:[0,1,0]
	v_cvt_scalef32_pk_bf16_fp4 v124, v126, 1.0 op_sel:[1,1,0]
	s_mov_b32 s13, s86
	v_dot2_f32_bf16 v102, v60, v22, v102
	v_dot2_f32_bf16 v58, v62, v20, v58
	s_lshl_b64 s[12:13], s[12:13], 10
	v_dot2_f32_bf16 v102, v100, v26, v102
	v_dot2_f32_bf16 v58, v124, v24, v58
	v_cvt_scalef32_pk_bf16_fp4 v60, v127, 1.0
	v_cvt_scalef32_pk_bf16_fp4 v62, v127, 1.0 op_sel:[1,0,0]
	v_cvt_scalef32_pk_bf16_fp4 v100, v127, 1.0 op_sel:[0,1,0]
	v_cvt_scalef32_pk_bf16_fp4 v124, v127, 1.0 op_sel:[1,1,0]
	s_nop 0
	v_dot2_f32_bf16 v102, v60, v30, v102
	v_dot2_f32_bf16 v58, v62, v28, v58
	s_nop 0
	v_dot2_f32_bf16 v102, v100, v36, v102
	v_dot2_f32_bf16 v58, v124, v34, v58
	s_nop 0
	s_nop 2
	v_add_f32_e32 v135, v102, v58
	s_add_u32 s12, s12, s100
	s_addc_u32 s13, s13, s101
	global_load_dwordx4 v[124:127], v207, s[12:13]
	s_waitcnt vmcnt(15)
; __device__ __forceinline__ float gelu_tanh(float h) {
;     return 0.5f * h * (1.f + tanhf(0.7978845608028654f * (h + 0.044715f * h * h * h)));
; }
	v_cvt_scalef32_pk_bf16_fp4 v58, v128, 1.0
	v_cvt_scalef32_pk_bf16_fp4 v60, v128, 1.0 op_sel:[1,0,0]
	v_cvt_scalef32_pk_bf16_fp4 v62, v128, 1.0 op_sel:[0,1,0]
	v_cvt_scalef32_pk_bf16_fp4 v100, v128, 1.0 op_sel:[1,1,0]
	v_readlane_b32 s12, v46, s28
	v_dot2_f32_bf16 v102, v58, v6, 0
	v_dot2c_f32_bf16_e32 v42, v60, v4
	s_lshr_b32 s12, s12, 7
	v_dot2_f32_bf16 v102, v62, v10, v102
	v_dot2c_f32_bf16_e32 v42, v100, v8
	v_cvt_scalef32_pk_bf16_fp4 v58, v129, 1.0
	v_cvt_scalef32_pk_bf16_fp4 v60, v129, 1.0 op_sel:[1,0,0]
	v_cvt_scalef32_pk_bf16_fp4 v62, v129, 1.0 op_sel:[0,1,0]
	v_cvt_scalef32_pk_bf16_fp4 v100, v129, 1.0 op_sel:[1,1,0]
	s_mov_b32 s13, s86
	v_dot2_f32_bf16 v102, v58, v14, v102
	v_dot2c_f32_bf16_e32 v42, v60, v12
	s_lshl_b64 s[12:13], s[12:13], 10
	v_dot2_f32_bf16 v102, v62, v18, v102
	v_dot2c_f32_bf16_e32 v42, v100, v16
	v_cvt_scalef32_pk_bf16_fp4 v58, v130, 1.0
	v_cvt_scalef32_pk_bf16_fp4 v60, v130, 1.0 op_sel:[1,0,0]
	v_cvt_scalef32_pk_bf16_fp4 v62, v130, 1.0 op_sel:[0,1,0]
	v_cvt_scalef32_pk_bf16_fp4 v100, v130, 1.0 op_sel:[1,1,0]
	v_cndmask_b32_e64 v46, v48, v56, s[48:49]
	v_dot2_f32_bf16 v102, v58, v22, v102
	v_dot2c_f32_bf16_e32 v42, v60, v20
	ds_swizzle_b32 v46, v46 offset:swizzle(SWAP,8)
	v_dot2_f32_bf16 v102, v62, v26, v102
	v_dot2c_f32_bf16_e32 v42, v100, v24
	v_cvt_scalef32_pk_bf16_fp4 v58, v131, 1.0
	v_cvt_scalef32_pk_bf16_fp4 v60, v131, 1.0 op_sel:[1,0,0]
	v_cvt_scalef32_pk_bf16_fp4 v62, v131, 1.0 op_sel:[0,1,0]
	v_cvt_scalef32_pk_bf16_fp4 v100, v131, 1.0 op_sel:[1,1,0]
	s_nop 0
	v_dot2_f32_bf16 v102, v58, v30, v102
	v_dot2c_f32_bf16_e32 v42, v60, v28
	s_nop 0
	v_dot2_f32_bf16 v102, v62, v36, v102
	v_dot2c_f32_bf16_e32 v42, v100, v34
	s_nop 0
	s_nop 2
	v_add_f32_e32 v58, v102, v42
	v_lshl_add_u64 v[42:43], v[40:41], 0, s[12:13]
	global_load_dwordx4 v[128:131], v[42:43], off
	v_cndmask_b32_e64 v43, v47, v55, s[48:49]
	ds_swizzle_b32 v43, v43 offset:swizzle(SWAP,8)
	v_cndmask_b32_e64 v42, v55, v47, s[48:49]
	v_cndmask_b32_e64 v47, v49, v57, s[48:49]
	ds_swizzle_b32 v47, v47 offset:swizzle(SWAP,8)
	s_waitcnt lgkmcnt(1)
	v_add_f32_e32 v42, v42, v43
	v_cndmask_b32_e64 v43, v56, v48, s[48:49]
	v_cndmask_b32_e64 v48, v50, v132, s[48:49]
	v_add_f32_e32 v43, v43, v46
	v_cndmask_b32_e64 v46, v57, v49, s[48:49]
	ds_swizzle_b32 v48, v48 offset:swizzle(SWAP,8)
	v_cndmask_b32_e64 v49, v51, v133, s[48:49]
	ds_swizzle_b32 v49, v49 offset:swizzle(SWAP,8)
	s_waitcnt lgkmcnt(2)
	v_add_f32_e32 v46, v46, v47
	v_cndmask_b32_e64 v47, v132, v50, s[48:49]
	v_cndmask_b32_e64 v50, v52, v134, s[48:49]
	ds_swizzle_b32 v50, v50 offset:swizzle(SWAP,8)
	s_waitcnt lgkmcnt(2)
	v_add_f32_e32 v47, v47, v48
	v_cndmask_b32_e64 v48, v133, v51, s[48:49]
	v_cndmask_b32_e64 v51, v53, v135, s[48:49]
	s_waitcnt lgkmcnt(1)
	v_add_f32_e32 v48, v48, v49
	v_cndmask_b32_e64 v49, v134, v52, s[48:49]
	ds_swizzle_b32 v51, v51 offset:swizzle(SWAP,8)
	v_cndmask_b32_e64 v52, v54, v58, s[48:49]
	ds_swizzle_b32 v52, v52 offset:swizzle(SWAP,8)
	s_waitcnt lgkmcnt(2)
	v_add_f32_e32 v49, v49, v50
	v_cndmask_b32_e64 v50, v135, v53, s[48:49]
	s_waitcnt lgkmcnt(1)
	v_add_f32_e32 v50, v50, v51
	v_cndmask_b32_e64 v51, v58, v54, s[48:49]
	s_waitcnt lgkmcnt(0)
	v_add_f32_e32 v51, v51, v52
	v_cndmask_b32_e64 v53, v42, v48, s[46:47]
	v_cndmask_b32_e64 v42, v48, v42, s[46:47]
	v_cndmask_b32_e64 v48, v49, v43, s[46:47]
	v_cndmask_b32_e64 v43, v43, v49, s[46:47]
	v_cndmask_b32_e64 v49, v46, v50, s[46:47]
	v_cndmask_b32_e64 v52, v47, v51, s[46:47]
	ds_swizzle_b32 v53, v53 offset:swizzle(SWAP,4)
	ds_swizzle_b32 v43, v43 offset:swizzle(SWAP,4)
	ds_swizzle_b32 v49, v49 offset:swizzle(SWAP,4)
	ds_swizzle_b32 v52, v52 offset:swizzle(SWAP,4)
	v_cndmask_b32_e64 v46, v50, v46, s[46:47]
	v_cndmask_b32_e64 v47, v51, v47, s[46:47]
	s_waitcnt lgkmcnt(3)
	v_add_f32_e32 v42, v42, v53
	s_waitcnt lgkmcnt(2)
	v_add_f32_e32 v43, v48, v43
	s_waitcnt lgkmcnt(1)
	v_add_f32_e32 v46, v46, v49
	s_waitcnt lgkmcnt(0)
	v_add_f32_e32 v47, v47, v52
	v_cndmask_b32_e64 v48, v42, v46, s[44:45]
	v_cndmask_b32_e64 v49, v43, v47, s[44:45]
	ds_swizzle_b32 v48, v48 offset:swizzle(SWAP,2)
	ds_swizzle_b32 v49, v49 offset:swizzle(SWAP,2)
	v_cndmask_b32_e64 v42, v46, v42, s[44:45]
	v_cndmask_b32_e64 v43, v47, v43, s[44:45]
	s_waitcnt lgkmcnt(1)
	v_add_f32_e32 v42, v42, v48
	s_waitcnt lgkmcnt(0)
	v_add_f32_e32 v43, v43, v49
	v_cndmask_b32_e64 v46, v42, v43, s[42:43]
	ds_swizzle_b32 v46, v46 offset:swizzle(SWAP,1)
	v_cndmask_b32_e64 v42, v43, v42, s[42:43]
	s_waitcnt lgkmcnt(0)
	v_add_f32_e32 v42, v42, v46
	ds_swizzle_b32 v43, v42 offset:swizzle(SWAP,16)
	s_waitcnt lgkmcnt(0)
	v_add_f32_e32 v46, v42, v43
	ds_read2st64_b32 v[42:43], v45 offset1:8
	v_mov_b32_e32 v47, v46
	s_nop 1
	v_permlane32_swap_b32_e32 v46, v47
	v_add_f32_e32 v46, v46, v47
	s_waitcnt lgkmcnt(0)
	v_mul_f32_e32 v42, v42, v46
	v_mul_f32_e32 v46, 0x3d372713, v42
	v_mul_f32_e32 v46, v42, v46
	v_fma_f32 v46, v42, v46, v42
	v_mul_f32_e32 v46, 0x3f4c422a, v46
	v_cmp_nlt_f32_e64 s[12:13], |v46|, s25
	s_and_saveexec_b64 s[40:41], s[12:13]
	s_xor_b64 s[12:13], exec, s[40:41]
	s_cbranch_execz .LBB0_536
	v_add_f32_e64 v47, |v46|, |v46|
	v_mul_f32_e32 v48, 0x3fb8aa3b, v47
	v_rndne_f32_e32 v49, v48
	v_sub_f32_e32 v50, v48, v49
	v_fma_f32 v48, v47, s70, -v48
	v_fmac_f32_e32 v48, 0x32a5705f, v47
	v_add_f32_e32 v48, v50, v48
	v_cvt_i32_f32_e32 v49, v49
	v_exp_f32_e32 v48, v48
	v_cmp_ngt_f32_e64 s[50:51], s67, v47
	v_ldexp_f32 v48, v48, v49
	s_nop 0
	v_cndmask_b32_e64 v48, 0, v48, s[50:51]
	v_cmp_nlt_f32_e64 s[50:51], s68, v47
	s_nop 1
	v_cndmask_b32_e64 v47, v205, v48, s[50:51]
	v_add_f32_e32 v47, 1.0, v47
	v_rcp_f32_e32 v47, v47
	s_nop 0
	v_fma_f32 v47, v47, -2.0, 1.0
	s_andn2_saveexec_b64 s[12:13], s[12:13]
	s_cbranch_execnz .LBB0_537

; #define P4_FOR16(M) M(0) M(1) M(2) M(3) M(4) M(5) M(6) M(7) M(8) M(9) M(10) M(11) M(12) M(13) M(14) M(15)
; #define P4_V(i) { const unsigned wu_ = (unsigned)__builtin_amdgcn_readlane((int)__float_as_uint(wreg), i); const unsigned long long wp_ = ((unsigned long long)wu_ << 32) | wu_; \
;               P4_ACC(b##i, wp_); const int nk_ = __builtin_amdgcn_readlane(ksel, nb + i); P4_LOAD(b##i, Vg, nk_); }
; #define P4_V(i) { const unsigned wu_ = (unsigned)__builtin_amdgcn_readlane((int)__float_as_uint(wreg), i); const unsigned long long wp_ = ((unsigned long long)wu_ << 32) | wu_; \
;               P4_ACC(b##i, wp_); const int nk_ = __builtin_amdgcn_readlane(kn, i); P4_LOAD(b##i, Vg, nk_); }
; #define P4_V(i) { const unsigned wu_ = (unsigned)__builtin_amdgcn_readlane((int)__float_as_uint(wreg), i); const unsigned long long wp_ = ((unsigned long long)wu_ << 32) | wu_; \
;               P4_ACC(b##i, wp_); }
; __device__ __forceinline__ void peer_gather_f4p(const float* X, const int* __restrict__ IDX, const float* __restrict__ G, ...
;     ...
;         for (int bt = 0; bt < 7; ++bt) {
;             const int ksel = (bt + 1 < 4) ? k0 : k1;
;             const int nb = (16 * (bt + 1)) & 63;
;             const float wreg = wbuf[kt * 128 + bt * 16 + (lane & 15)];
;     ...
;             P4_FOR16(P4_V)
.LBB0_550:
	ds_read_b32 v65, v171
	s_waitcnt vmcnt(15)
	v_cvt_scalef32_pk_f32_fp4 v[66:67], v4, 1.0
	v_cvt_scalef32_pk_f32_fp4 v[68:69], v4, 1.0 op_sel:[1,0,0]
	v_cvt_scalef32_pk_f32_fp4 v[70:71], v4, 1.0 op_sel:[0,1,0]
	s_cmp_lt_u32 s28, 3
	s_waitcnt lgkmcnt(0)
	v_readlane_b32 s16, v65, 0
	s_mov_b32 s17, s16
	v_cvt_scalef32_pk_f32_fp4 v[72:73], v4, 1.0 op_sel:[1,1,0]
	v_pk_fma_f32 v[132:133], s[16:17], v[66:67], v[132:133]
	v_pk_fma_f32 v[162:163], s[16:17], v[68:69], v[162:163]
	v_pk_fma_f32 v[160:161], s[16:17], v[70:71], v[160:161]
	s_cselect_b64 vcc, -1, 0
	v_pk_fma_f32 v[158:159], s[16:17], v[72:73], v[158:159]
	v_cvt_scalef32_pk_f32_fp4 v[66:67], v5, 1.0
	v_cvt_scalef32_pk_f32_fp4 v[68:69], v5, 1.0 op_sel:[1,0,0]
	v_cvt_scalef32_pk_f32_fp4 v[70:71], v5, 1.0 op_sel:[0,1,0]
	v_cvt_scalef32_pk_f32_fp4 v[4:5], v5, 1.0 op_sel:[1,1,0]
	v_cndmask_b32_e32 v64, v167, v166, vcc
	v_pk_fma_f32 v[156:157], s[16:17], v[66:67], v[156:157]
	v_pk_fma_f32 v[154:155], s[16:17], v[68:69], v[154:155]
	v_pk_fma_f32 v[152:153], s[16:17], v[70:71], v[152:153]
	v_pk_fma_f32 v[150:151], s[16:17], v[4:5], v[150:151]
	v_cvt_scalef32_pk_f32_fp4 v[4:5], v6, 1.0
	v_cvt_scalef32_pk_f32_fp4 v[66:67], v6, 1.0 op_sel:[1,0,0]
	v_cvt_scalef32_pk_f32_fp4 v[68:69], v6, 1.0 op_sel:[0,1,0]
	v_cvt_scalef32_pk_f32_fp4 v[70:71], v6, 1.0 op_sel:[1,1,0]
	s_mov_b32 s41, s86
	v_pk_fma_f32 v[148:149], s[16:17], v[4:5], v[148:149]
	v_pk_fma_f32 v[146:147], s[16:17], v[66:67], v[146:147]
	v_pk_fma_f32 v[144:145], s[16:17], v[68:69], v[144:145]
	v_pk_fma_f32 v[142:143], s[16:17], v[70:71], v[142:143]
	v_cvt_scalef32_pk_f32_fp4 v[4:5], v7, 1.0
	v_cvt_scalef32_pk_f32_fp4 v[66:67], v7, 1.0 op_sel:[1,0,0]
	v_cvt_scalef32_pk_f32_fp4 v[68:69], v7, 1.0 op_sel:[0,1,0]
	v_cvt_scalef32_pk_f32_fp4 v[6:7], v7, 1.0 op_sel:[1,1,0]
	s_add_i32 s28, s28, 1
	v_pk_fma_f32 v[140:141], s[16:17], v[4:5], v[140:141]
	v_pk_fma_f32 v[138:139], s[16:17], v[66:67], v[138:139]
	v_pk_fma_f32 v[136:137], s[16:17], v[68:69], v[136:137]
	v_pk_fma_f32 v[134:135], s[16:17], v[6:7], v[134:135]
	s_add_i32 s16, s27, -15
	v_readlane_b32 s16, v64, s16
	s_lshr_b32 s40, s16, 7
	v_readfirstlane_b32 s100, v168
	v_readfirstlane_b32 s101, v169
	v_subrev_u32_e32 v207, s100, v168
	s_lshl_b64 s[16:17], s[40:41], 10
	s_add_u32 s16, s16, s100
	s_addc_u32 s17, s17, s101
	global_load_dwordx4 v[4:7], v207, s[16:17]
	v_readlane_b32 s16, v65, 1
	s_waitcnt vmcnt(15)
	v_cvt_scalef32_pk_f32_fp4 v[66:67], v8, 1.0
	v_cvt_scalef32_pk_f32_fp4 v[68:69], v8, 1.0 op_sel:[1,0,0]
	v_cvt_scalef32_pk_f32_fp4 v[70:71], v8, 1.0 op_sel:[0,1,0]
	s_mov_b32 s17, s16
	v_cvt_scalef32_pk_f32_fp4 v[72:73], v8, 1.0 op_sel:[1,1,0]
	v_pk_fma_f32 v[132:133], s[16:17], v[66:67], v[132:133]
	v_pk_fma_f32 v[162:163], s[16:17], v[68:69], v[162:163]
	v_pk_fma_f32 v[160:161], s[16:17], v[70:71], v[160:161]
	v_add_u32_e32 v171, 64, v171
	v_pk_fma_f32 v[158:159], s[16:17], v[72:73], v[158:159]
	v_cvt_scalef32_pk_f32_fp4 v[66:67], v9, 1.0
	v_cvt_scalef32_pk_f32_fp4 v[68:69], v9, 1.0 op_sel:[1,0,0]
	v_cvt_scalef32_pk_f32_fp4 v[70:71], v9, 1.0 op_sel:[0,1,0]
	v_cvt_scalef32_pk_f32_fp4 v[8:9], v9, 1.0 op_sel:[1,1,0]
	s_nop 0
	v_pk_fma_f32 v[156:157], s[16:17], v[66:67], v[156:157]
	v_pk_fma_f32 v[154:155], s[16:17], v[68:69], v[154:155]
	v_pk_fma_f32 v[152:153], s[16:17], v[70:71], v[152:153]
	v_pk_fma_f32 v[150:151], s[16:17], v[8:9], v[150:151]
	v_cvt_scalef32_pk_f32_fp4 v[8:9], v10, 1.0
	v_cvt_scalef32_pk_f32_fp4 v[66:67], v10, 1.0 op_sel:[1,0,0]
	v_cvt_scalef32_pk_f32_fp4 v[68:69], v10, 1.0 op_sel:[0,1,0]
	v_cvt_scalef32_pk_f32_fp4 v[70:71], v10, 1.0 op_sel:[1,1,0]
	s_nop 0
	v_pk_fma_f32 v[148:149], s[16:17], v[8:9], v[148:149]
	v_pk_fma_f32 v[146:147], s[16:17], v[66:67], v[146:147]
	v_pk_fma_f32 v[144:145], s[16:17], v[68:69], v[144:145]
	v_pk_fma_f32 v[142:143], s[16:17], v[70:71], v[142:143]
	v_cvt_scalef32_pk_f32_fp4 v[8:9], v11, 1.0
	v_cvt_scalef32_pk_f32_fp4 v[66:67], v11, 1.0 op_sel:[1,0,0]
	v_cvt_scalef32_pk_f32_fp4 v[68:69], v11, 1.0 op_sel:[0,1,0]
	v_cvt_scalef32_pk_f32_fp4 v[10:11], v11, 1.0 op_sel:[1,1,0]
	s_nop 0
	v_pk_fma_f32 v[140:141], s[16:17], v[8:9], v[140:141]
	v_pk_fma_f32 v[138:139], s[16:17], v[66:67], v[138:139]
	v_pk_fma_f32 v[136:137], s[16:17], v[68:69], v[136:137]
	v_pk_fma_f32 v[134:135], s[16:17], v[10:11], v[134:135]
	s_add_i32 s16, s27, -14
	v_readlane_b32 s16, v64, s16
	s_lshr_b32 s40, s16, 7
	s_lshl_b64 s[16:17], s[40:41], 10
	s_add_u32 s16, s16, s100
	s_addc_u32 s17, s17, s101
	global_load_dwordx4 v[8:11], v207, s[16:17]
	v_readlane_b32 s16, v65, 2
	s_waitcnt vmcnt(15)
	v_cvt_scalef32_pk_f32_fp4 v[66:67], v12, 1.0
	v_cvt_scalef32_pk_f32_fp4 v[68:69], v12, 1.0 op_sel:[1,0,0]
	v_cvt_scalef32_pk_f32_fp4 v[70:71], v12, 1.0 op_sel:[0,1,0]
	s_mov_b32 s17, s16
	v_cvt_scalef32_pk_f32_fp4 v[72:73], v12, 1.0 op_sel:[1,1,0]
	v_pk_fma_f32 v[132:133], s[16:17], v[66:67], v[132:133]
	v_pk_fma_f32 v[162:163], s[16:17], v[68:69], v[162:163]
	v_pk_fma_f32 v[160:161], s[16:17], v[70:71], v[160:161]
	s_nop 0
	v_pk_fma_f32 v[158:159], s[16:17], v[72:73], v[158:159]
	v_cvt_scalef32_pk_f32_fp4 v[66:67], v13, 1.0
	v_cvt_scalef32_pk_f32_fp4 v[68:69], v13, 1.0 op_sel:[1,0,0]
	v_cvt_scalef32_pk_f32_fp4 v[70:71], v13, 1.0 op_sel:[0,1,0]
	v_cvt_scalef32_pk_f32_fp4 v[12:13], v13, 1.0 op_sel:[1,1,0]
	s_nop 0
	v_pk_fma_f32 v[156:157], s[16:17], v[66:67], v[156:157]
	v_pk_fma_f32 v[154:155], s[16:17], v[68:69], v[154:155]
	v_pk_fma_f32 v[152:153], s[16:17], v[70:71], v[152:153]
	v_pk_fma_f32 v[150:151], s[16:17], v[12:13], v[150:151]
	v_cvt_scalef32_pk_f32_fp4 v[12:13], v14, 1.0
	v_cvt_scalef32_pk_f32_fp4 v[66:67], v14, 1.0 op_sel:[1,0,0]
	v_cvt_scalef32_pk_f32_fp4 v[68:69], v14, 1.0 op_sel:[0,1,0]
	v_cvt_scalef32_pk_f32_fp4 v[70:71], v14, 1.0 op_sel:[1,1,0]
	s_nop 0
	v_pk_fma_f32 v[148:149], s[16:17], v[12:13], v[148:149]
	v_pk_fma_f32 v[146:147], s[16:17], v[66:67], v[146:147]
	v_pk_fma_f32 v[144:145], s[16:17], v[68:69], v[144:145]
	v_pk_fma_f32 v[142:143], s[16:17], v[70:71], v[142:143]
	v_cvt_scalef32_pk_f32_fp4 v[12:13], v15, 1.0
	v_cvt_scalef32_pk_f32_fp4 v[66:67], v15, 1.0 op_sel:[1,0,0]
	v_cvt_scalef32_pk_f32_fp4 v[68:69], v15, 1.0 op_sel:[0,1,0]
	v_cvt_scalef32_pk_f32_fp4 v[14:15], v15, 1.0 op_sel:[1,1,0]
	s_nop 0
	v_pk_fma_f32 v[140:141], s[16:17], v[12:13], v[140:141]
	v_pk_fma_f32 v[138:139], s[16:17], v[66:67], v[138:139]
	v_pk_fma_f32 v[136:137], s[16:17], v[68:69], v[136:137]
	v_pk_fma_f32 v[134:135], s[16:17], v[14:15], v[134:135]
	s_add_i32 s16, s27, -13
	v_readlane_b32 s16, v64, s16
	s_lshr_b32 s40, s16, 7
	s_lshl_b64 s[16:17], s[40:41], 10
	s_add_u32 s16, s16, s100
	s_addc_u32 s17, s17, s101
	global_load_dwordx4 v[12:15], v207, s[16:17]
	v_readlane_b32 s16, v65, 3
	s_waitcnt vmcnt(15)
; #define P4_FOR16(M) M(0) M(1) M(2) M(3) M(4) M(5) M(6) M(7) M(8) M(9) M(10) M(11) M(12) M(13) M(14) M(15)
; #define P4_V(i) { const unsigned wu_ = (unsigned)__builtin_amdgcn_readlane((int)__float_as_uint(wreg), i); const unsigned long long wp_ = ((unsigned long long)wu_ << 32) | wu_; \
;               P4_ACC(b##i, wp_); const int nk_ = __builtin_amdgcn_readlane(ksel, nb + i); P4_LOAD(b##i, Vg, nk_); }
; #define P4_V(i) { const unsigned wu_ = (unsigned)__builtin_amdgcn_readlane((int)__float_as_uint(wreg), i); const unsigned long long wp_ = ((unsigned long long)wu_ << 32) | wu_; \
;               P4_ACC(b##i, wp_); const int nk_ = __builtin_amdgcn_readlane(kn, i); P4_LOAD(b##i, Vg, nk_); }
; #define P4_V(i) { const unsigned wu_ = (unsigned)__builtin_amdgcn_readlane((int)__float_as_uint(wreg), i); const unsigned long long wp_ = ((unsigned long long)wu_ << 32) | wu_; \
;               P4_ACC(b##i, wp_); }
; __device__ __forceinline__ void peer_gather_f4p(const float* X, const int* __restrict__ IDX, const float* __restrict__ G, ...
;     ...
;         for (int bt = 0; bt < 7; ++bt) {
;             const int ksel = (bt + 1 < 4) ? k0 : k1;
;             const int nb = (16 * (bt + 1)) & 63;
;             const float wreg = wbuf[kt * 128 + bt * 16 + (lane & 15)];
;     ...
;             P4_FOR16(P4_V)
	v_cvt_scalef32_pk_f32_fp4 v[66:67], v16, 1.0
	v_cvt_scalef32_pk_f32_fp4 v[68:69], v16, 1.0 op_sel:[1,0,0]
	v_cvt_scalef32_pk_f32_fp4 v[70:71], v16, 1.0 op_sel:[0,1,0]
	s_mov_b32 s17, s16
	v_cvt_scalef32_pk_f32_fp4 v[72:73], v16, 1.0 op_sel:[1,1,0]
	v_pk_fma_f32 v[132:133], s[16:17], v[66:67], v[132:133]
	v_pk_fma_f32 v[162:163], s[16:17], v[68:69], v[162:163]
	v_pk_fma_f32 v[160:161], s[16:17], v[70:71], v[160:161]
	s_nop 0
	v_pk_fma_f32 v[158:159], s[16:17], v[72:73], v[158:159]
	v_cvt_scalef32_pk_f32_fp4 v[66:67], v17, 1.0
	v_cvt_scalef32_pk_f32_fp4 v[68:69], v17, 1.0 op_sel:[1,0,0]
	v_cvt_scalef32_pk_f32_fp4 v[70:71], v17, 1.0 op_sel:[0,1,0]
	v_cvt_scalef32_pk_f32_fp4 v[16:17], v17, 1.0 op_sel:[1,1,0]
	s_nop 0
	v_pk_fma_f32 v[156:157], s[16:17], v[66:67], v[156:157]
	v_pk_fma_f32 v[154:155], s[16:17], v[68:69], v[154:155]
	v_pk_fma_f32 v[152:153], s[16:17], v[70:71], v[152:153]
	v_pk_fma_f32 v[150:151], s[16:17], v[16:17], v[150:151]
	v_cvt_scalef32_pk_f32_fp4 v[16:17], v18, 1.0
	v_cvt_scalef32_pk_f32_fp4 v[66:67], v18, 1.0 op_sel:[1,0,0]
	v_cvt_scalef32_pk_f32_fp4 v[68:69], v18, 1.0 op_sel:[0,1,0]
	v_cvt_scalef32_pk_f32_fp4 v[70:71], v18, 1.0 op_sel:[1,1,0]
	s_nop 0
	v_pk_fma_f32 v[148:149], s[16:17], v[16:17], v[148:149]
	v_pk_fma_f32 v[146:147], s[16:17], v[66:67], v[146:147]
	v_pk_fma_f32 v[144:145], s[16:17], v[68:69], v[144:145]
	v_pk_fma_f32 v[142:143], s[16:17], v[70:71], v[142:143]
	v_cvt_scalef32_pk_f32_fp4 v[16:17], v19, 1.0
	v_cvt_scalef32_pk_f32_fp4 v[66:67], v19, 1.0 op_sel:[1,0,0]
	v_cvt_scalef32_pk_f32_fp4 v[68:69], v19, 1.0 op_sel:[0,1,0]
	v_cvt_scalef32_pk_f32_fp4 v[18:19], v19, 1.0 op_sel:[1,1,0]
	s_nop 0
	v_pk_fma_f32 v[140:141], s[16:17], v[16:17], v[140:141]
	v_pk_fma_f32 v[138:139], s[16:17], v[66:67], v[138:139]
	v_pk_fma_f32 v[136:137], s[16:17], v[68:69], v[136:137]
	v_pk_fma_f32 v[134:135], s[16:17], v[18:19], v[134:135]
	s_add_i32 s16, s27, -12
	v_readlane_b32 s16, v64, s16
	s_lshr_b32 s40, s16, 7
	s_lshl_b64 s[16:17], s[40:41], 10
	s_add_u32 s16, s16, s100
	s_addc_u32 s17, s17, s101
	global_load_dwordx4 v[16:19], v207, s[16:17]
	v_readlane_b32 s16, v65, 4
	s_waitcnt vmcnt(15)
	v_cvt_scalef32_pk_f32_fp4 v[66:67], v20, 1.0
	v_cvt_scalef32_pk_f32_fp4 v[68:69], v20, 1.0 op_sel:[1,0,0]
	v_cvt_scalef32_pk_f32_fp4 v[70:71], v20, 1.0 op_sel:[0,1,0]
	s_mov_b32 s17, s16
	v_cvt_scalef32_pk_f32_fp4 v[72:73], v20, 1.0 op_sel:[1,1,0]
	v_pk_fma_f32 v[132:133], s[16:17], v[66:67], v[132:133]
	v_pk_fma_f32 v[162:163], s[16:17], v[68:69], v[162:163]
	v_pk_fma_f32 v[160:161], s[16:17], v[70:71], v[160:161]
	s_nop 0
	v_pk_fma_f32 v[158:159], s[16:17], v[72:73], v[158:159]
	v_cvt_scalef32_pk_f32_fp4 v[66:67], v21, 1.0
	v_cvt_scalef32_pk_f32_fp4 v[68:69], v21, 1.0 op_sel:[1,0,0]
	v_cvt_scalef32_pk_f32_fp4 v[70:71], v21, 1.0 op_sel:[0,1,0]
	v_cvt_scalef32_pk_f32_fp4 v[20:21], v21, 1.0 op_sel:[1,1,0]
	s_nop 0
	v_pk_fma_f32 v[156:157], s[16:17], v[66:67], v[156:157]
	v_pk_fma_f32 v[154:155], s[16:17], v[68:69], v[154:155]
	v_pk_fma_f32 v[152:153], s[16:17], v[70:71], v[152:153]
	v_pk_fma_f32 v[150:151], s[16:17], v[20:21], v[150:151]
	v_cvt_scalef32_pk_f32_fp4 v[20:21], v22, 1.0
	v_cvt_scalef32_pk_f32_fp4 v[66:67], v22, 1.0 op_sel:[1,0,0]
	v_cvt_scalef32_pk_f32_fp4 v[68:69], v22, 1.0 op_sel:[0,1,0]
	v_cvt_scalef32_pk_f32_fp4 v[70:71], v22, 1.0 op_sel:[1,1,0]
	s_nop 0
	v_pk_fma_f32 v[148:149], s[16:17], v[20:21], v[148:149]
	v_pk_fma_f32 v[146:147], s[16:17], v[66:67], v[146:147]
	v_pk_fma_f32 v[144:145], s[16:17], v[68:69], v[144:145]
	v_pk_fma_f32 v[142:143], s[16:17], v[70:71], v[142:143]
	v_cvt_scalef32_pk_f32_fp4 v[20:21], v23, 1.0
	v_cvt_scalef32_pk_f32_fp4 v[66:67], v23, 1.0 op_sel:[1,0,0]
	v_cvt_scalef32_pk_f32_fp4 v[68:69], v23, 1.0 op_sel:[0,1,0]
	v_cvt_scalef32_pk_f32_fp4 v[22:23], v23, 1.0 op_sel:[1,1,0]
	s_nop 0
	v_pk_fma_f32 v[140:141], s[16:17], v[20:21], v[140:141]
	v_pk_fma_f32 v[138:139], s[16:17], v[66:67], v[138:139]
	v_pk_fma_f32 v[136:137], s[16:17], v[68:69], v[136:137]
	v_pk_fma_f32 v[134:135], s[16:17], v[22:23], v[134:135]
	s_add_i32 s16, s27, -11
	v_readlane_b32 s16, v64, s16
	s_lshr_b32 s40, s16, 7
	s_lshl_b64 s[16:17], s[40:41], 10
	s_add_u32 s16, s16, s100
	s_addc_u32 s17, s17, s101
	global_load_dwordx4 v[20:23], v207, s[16:17]
	v_readlane_b32 s16, v65, 5
	s_waitcnt vmcnt(15)
	v_cvt_scalef32_pk_f32_fp4 v[66:67], v24, 1.0
	v_cvt_scalef32_pk_f32_fp4 v[68:69], v24, 1.0 op_sel:[1,0,0]
	v_cvt_scalef32_pk_f32_fp4 v[70:71], v24, 1.0 op_sel:[0,1,0]
	s_mov_b32 s17, s16
	v_cvt_scalef32_pk_f32_fp4 v[72:73], v24, 1.0 op_sel:[1,1,0]
	v_pk_fma_f32 v[132:133], s[16:17], v[66:67], v[132:133]
	v_pk_fma_f32 v[162:163], s[16:17], v[68:69], v[162:163]
	v_pk_fma_f32 v[160:161], s[16:17], v[70:71], v[160:161]
	s_nop 0
	v_pk_fma_f32 v[158:159], s[16:17], v[72:73], v[158:159]
	v_cvt_scalef32_pk_f32_fp4 v[66:67], v25, 1.0
	v_cvt_scalef32_pk_f32_fp4 v[68:69], v25, 1.0 op_sel:[1,0,0]
	v_cvt_scalef32_pk_f32_fp4 v[70:71], v25, 1.0 op_sel:[0,1,0]
	v_cvt_scalef32_pk_f32_fp4 v[24:25], v25, 1.0 op_sel:[1,1,0]
	s_nop 0
	v_pk_fma_f32 v[156:157], s[16:17], v[66:67], v[156:157]
	v_pk_fma_f32 v[154:155], s[16:17], v[68:69], v[154:155]
	v_pk_fma_f32 v[152:153], s[16:17], v[70:71], v[152:153]
	v_pk_fma_f32 v[150:151], s[16:17], v[24:25], v[150:151]
	v_cvt_scalef32_pk_f32_fp4 v[24:25], v26, 1.0
	v_cvt_scalef32_pk_f32_fp4 v[66:67], v26, 1.0 op_sel:[1,0,0]
	v_cvt_scalef32_pk_f32_fp4 v[68:69], v26, 1.0 op_sel:[0,1,0]
	v_cvt_scalef32_pk_f32_fp4 v[70:71], v26, 1.0 op_sel:[1,1,0]
	s_nop 0
	v_pk_fma_f32 v[148:149], s[16:17], v[24:25], v[148:149]
	v_pk_fma_f32 v[146:147], s[16:17], v[66:67], v[146:147]
	v_pk_fma_f32 v[144:145], s[16:17], v[68:69], v[144:145]
	v_pk_fma_f32 v[142:143], s[16:17], v[70:71], v[142:143]
	v_cvt_scalef32_pk_f32_fp4 v[24:25], v27, 1.0
	v_cvt_scalef32_pk_f32_fp4 v[66:67], v27, 1.0 op_sel:[1,0,0]
	v_cvt_scalef32_pk_f32_fp4 v[68:69], v27, 1.0 op_sel:[0,1,0]
	v_cvt_scalef32_pk_f32_fp4 v[26:27], v27, 1.0 op_sel:[1,1,0]
	s_nop 0
	v_pk_fma_f32 v[140:141], s[16:17], v[24:25], v[140:141]
	v_pk_fma_f32 v[138:139], s[16:17], v[66:67], v[138:139]
	v_pk_fma_f32 v[136:137], s[16:17], v[68:69], v[136:137]
	v_pk_fma_f32 v[134:135], s[16:17], v[26:27], v[134:135]
	s_add_i32 s16, s27, -10
	v_readlane_b32 s16, v64, s16
	s_lshr_b32 s40, s16, 7
	s_lshl_b64 s[16:17], s[40:41], 10
	s_add_u32 s16, s16, s100
	s_addc_u32 s17, s17, s101
	global_load_dwordx4 v[24:27], v207, s[16:17]
	v_readlane_b32 s16, v65, 6
	s_waitcnt vmcnt(15)
; #define P4_FOR16(M) M(0) M(1) M(2) M(3) M(4) M(5) M(6) M(7) M(8) M(9) M(10) M(11) M(12) M(13) M(14) M(15)
; #define P4_V(i) { const unsigned wu_ = (unsigned)__builtin_amdgcn_readlane((int)__float_as_uint(wreg), i); const unsigned long long wp_ = ((unsigned long long)wu_ << 32) | wu_; \
;               P4_ACC(b##i, wp_); const int nk_ = __builtin_amdgcn_readlane(ksel, nb + i); P4_LOAD(b##i, Vg, nk_); }
; #define P4_V(i) { const unsigned wu_ = (unsigned)__builtin_amdgcn_readlane((int)__float_as_uint(wreg), i); const unsigned long long wp_ = ((unsigned long long)wu_ << 32) | wu_; \
;               P4_ACC(b##i, wp_); const int nk_ = __builtin_amdgcn_readlane(kn, i); P4_LOAD(b##i, Vg, nk_); }
; #define P4_V(i) { const unsigned wu_ = (unsigned)__builtin_amdgcn_readlane((int)__float_as_uint(wreg), i); const unsigned long long wp_ = ((unsigned long long)wu_ << 32) | wu_; \
;               P4_ACC(b##i, wp_); }
; __device__ __forceinline__ void peer_gather_f4p(const float* X, const int* __restrict__ IDX, const float* __restrict__ G, ...
;     ...
;         for (int bt = 0; bt < 7; ++bt) {
;             const int ksel = (bt + 1 < 4) ? k0 : k1;
;             const int nb = (16 * (bt + 1)) & 63;
;             const float wreg = wbuf[kt * 128 + bt * 16 + (lane & 15)];
;     ...
;             P4_FOR16(P4_V)
	v_cvt_scalef32_pk_f32_fp4 v[66:67], v28, 1.0
	v_cvt_scalef32_pk_f32_fp4 v[68:69], v28, 1.0 op_sel:[1,0,0]
	v_cvt_scalef32_pk_f32_fp4 v[70:71], v28, 1.0 op_sel:[0,1,0]
	s_mov_b32 s17, s16
	v_cvt_scalef32_pk_f32_fp4 v[72:73], v28, 1.0 op_sel:[1,1,0]
	v_pk_fma_f32 v[132:133], s[16:17], v[66:67], v[132:133]
	v_pk_fma_f32 v[162:163], s[16:17], v[68:69], v[162:163]
	v_pk_fma_f32 v[160:161], s[16:17], v[70:71], v[160:161]
	s_nop 0
	v_pk_fma_f32 v[158:159], s[16:17], v[72:73], v[158:159]
	v_cvt_scalef32_pk_f32_fp4 v[66:67], v29, 1.0
	v_cvt_scalef32_pk_f32_fp4 v[68:69], v29, 1.0 op_sel:[1,0,0]
	v_cvt_scalef32_pk_f32_fp4 v[70:71], v29, 1.0 op_sel:[0,1,0]
	v_cvt_scalef32_pk_f32_fp4 v[28:29], v29, 1.0 op_sel:[1,1,0]
	s_nop 0
	v_pk_fma_f32 v[156:157], s[16:17], v[66:67], v[156:157]
	v_pk_fma_f32 v[154:155], s[16:17], v[68:69], v[154:155]
	v_pk_fma_f32 v[152:153], s[16:17], v[70:71], v[152:153]
	v_pk_fma_f32 v[150:151], s[16:17], v[28:29], v[150:151]
	v_cvt_scalef32_pk_f32_fp4 v[28:29], v30, 1.0
	v_cvt_scalef32_pk_f32_fp4 v[66:67], v30, 1.0 op_sel:[1,0,0]
	v_cvt_scalef32_pk_f32_fp4 v[68:69], v30, 1.0 op_sel:[0,1,0]
	v_cvt_scalef32_pk_f32_fp4 v[70:71], v30, 1.0 op_sel:[1,1,0]
	s_nop 0
	v_pk_fma_f32 v[148:149], s[16:17], v[28:29], v[148:149]
	v_pk_fma_f32 v[146:147], s[16:17], v[66:67], v[146:147]
	v_pk_fma_f32 v[144:145], s[16:17], v[68:69], v[144:145]
	v_pk_fma_f32 v[142:143], s[16:17], v[70:71], v[142:143]
	v_cvt_scalef32_pk_f32_fp4 v[28:29], v31, 1.0
	v_cvt_scalef32_pk_f32_fp4 v[66:67], v31, 1.0 op_sel:[1,0,0]
	v_cvt_scalef32_pk_f32_fp4 v[68:69], v31, 1.0 op_sel:[0,1,0]
	v_cvt_scalef32_pk_f32_fp4 v[30:31], v31, 1.0 op_sel:[1,1,0]
	s_nop 0
	v_pk_fma_f32 v[140:141], s[16:17], v[28:29], v[140:141]
	v_pk_fma_f32 v[138:139], s[16:17], v[66:67], v[138:139]
	v_pk_fma_f32 v[136:137], s[16:17], v[68:69], v[136:137]
	v_pk_fma_f32 v[134:135], s[16:17], v[30:31], v[134:135]
	s_add_i32 s16, s27, -9
	v_readlane_b32 s16, v64, s16
	s_lshr_b32 s40, s16, 7
	s_lshl_b64 s[16:17], s[40:41], 10
	s_add_u32 s16, s16, s100
	s_addc_u32 s17, s17, s101
	global_load_dwordx4 v[28:31], v207, s[16:17]
	v_readlane_b32 s16, v65, 7
	s_waitcnt vmcnt(15)
	v_cvt_scalef32_pk_f32_fp4 v[66:67], v32, 1.0
	v_cvt_scalef32_pk_f32_fp4 v[68:69], v32, 1.0 op_sel:[1,0,0]
	v_cvt_scalef32_pk_f32_fp4 v[70:71], v32, 1.0 op_sel:[0,1,0]
	s_mov_b32 s17, s16
	v_cvt_scalef32_pk_f32_fp4 v[72:73], v32, 1.0 op_sel:[1,1,0]
	v_pk_fma_f32 v[132:133], s[16:17], v[66:67], v[132:133]
	v_pk_fma_f32 v[162:163], s[16:17], v[68:69], v[162:163]
	v_pk_fma_f32 v[160:161], s[16:17], v[70:71], v[160:161]
	s_nop 0
	v_pk_fma_f32 v[158:159], s[16:17], v[72:73], v[158:159]
	v_cvt_scalef32_pk_f32_fp4 v[66:67], v33, 1.0
	v_cvt_scalef32_pk_f32_fp4 v[68:69], v33, 1.0 op_sel:[1,0,0]
	v_cvt_scalef32_pk_f32_fp4 v[70:71], v33, 1.0 op_sel:[0,1,0]
	v_cvt_scalef32_pk_f32_fp4 v[32:33], v33, 1.0 op_sel:[1,1,0]
	s_nop 0
	v_pk_fma_f32 v[156:157], s[16:17], v[66:67], v[156:157]
	v_pk_fma_f32 v[154:155], s[16:17], v[68:69], v[154:155]
	v_pk_fma_f32 v[152:153], s[16:17], v[70:71], v[152:153]
	v_pk_fma_f32 v[150:151], s[16:17], v[32:33], v[150:151]
	v_cvt_scalef32_pk_f32_fp4 v[32:33], v34, 1.0
	v_cvt_scalef32_pk_f32_fp4 v[66:67], v34, 1.0 op_sel:[1,0,0]
	v_cvt_scalef32_pk_f32_fp4 v[68:69], v34, 1.0 op_sel:[0,1,0]
	v_cvt_scalef32_pk_f32_fp4 v[70:71], v34, 1.0 op_sel:[1,1,0]
	s_nop 0
	v_pk_fma_f32 v[148:149], s[16:17], v[32:33], v[148:149]
	v_pk_fma_f32 v[146:147], s[16:17], v[66:67], v[146:147]
	v_pk_fma_f32 v[144:145], s[16:17], v[68:69], v[144:145]
	v_pk_fma_f32 v[142:143], s[16:17], v[70:71], v[142:143]
	v_cvt_scalef32_pk_f32_fp4 v[32:33], v35, 1.0
	v_cvt_scalef32_pk_f32_fp4 v[66:67], v35, 1.0 op_sel:[1,0,0]
	v_cvt_scalef32_pk_f32_fp4 v[68:69], v35, 1.0 op_sel:[0,1,0]
	v_cvt_scalef32_pk_f32_fp4 v[34:35], v35, 1.0 op_sel:[1,1,0]
	s_nop 0
	v_pk_fma_f32 v[140:141], s[16:17], v[32:33], v[140:141]
	v_pk_fma_f32 v[138:139], s[16:17], v[66:67], v[138:139]
	v_pk_fma_f32 v[136:137], s[16:17], v[68:69], v[136:137]
	v_pk_fma_f32 v[134:135], s[16:17], v[34:35], v[134:135]
	s_add_i32 s16, s27, -8
	v_readlane_b32 s16, v64, s16
	s_lshr_b32 s40, s16, 7
	s_lshl_b64 s[16:17], s[40:41], 10
	s_add_u32 s16, s16, s100
	s_addc_u32 s17, s17, s101
	global_load_dwordx4 v[32:35], v207, s[16:17]
	v_readlane_b32 s16, v65, 8
	s_waitcnt vmcnt(15)
	v_cvt_scalef32_pk_f32_fp4 v[66:67], v36, 1.0
	v_cvt_scalef32_pk_f32_fp4 v[68:69], v36, 1.0 op_sel:[1,0,0]
	v_cvt_scalef32_pk_f32_fp4 v[70:71], v36, 1.0 op_sel:[0,1,0]
	s_mov_b32 s17, s16
	v_cvt_scalef32_pk_f32_fp4 v[72:73], v36, 1.0 op_sel:[1,1,0]
	v_pk_fma_f32 v[132:133], s[16:17], v[66:67], v[132:133]
	v_pk_fma_f32 v[162:163], s[16:17], v[68:69], v[162:163]
	v_pk_fma_f32 v[160:161], s[16:17], v[70:71], v[160:161]
	s_nop 0
	v_pk_fma_f32 v[158:159], s[16:17], v[72:73], v[158:159]
	v_cvt_scalef32_pk_f32_fp4 v[66:67], v37, 1.0
	v_cvt_scalef32_pk_f32_fp4 v[68:69], v37, 1.0 op_sel:[1,0,0]
	v_cvt_scalef32_pk_f32_fp4 v[70:71], v37, 1.0 op_sel:[0,1,0]
	v_cvt_scalef32_pk_f32_fp4 v[36:37], v37, 1.0 op_sel:[1,1,0]
	s_nop 0
	v_pk_fma_f32 v[156:157], s[16:17], v[66:67], v[156:157]
	v_pk_fma_f32 v[154:155], s[16:17], v[68:69], v[154:155]
	v_pk_fma_f32 v[152:153], s[16:17], v[70:71], v[152:153]
	v_pk_fma_f32 v[150:151], s[16:17], v[36:37], v[150:151]
	v_cvt_scalef32_pk_f32_fp4 v[36:37], v38, 1.0
	v_cvt_scalef32_pk_f32_fp4 v[66:67], v38, 1.0 op_sel:[1,0,0]
	v_cvt_scalef32_pk_f32_fp4 v[68:69], v38, 1.0 op_sel:[0,1,0]
	v_cvt_scalef32_pk_f32_fp4 v[70:71], v38, 1.0 op_sel:[1,1,0]
	s_nop 0
	v_pk_fma_f32 v[148:149], s[16:17], v[36:37], v[148:149]
	v_pk_fma_f32 v[146:147], s[16:17], v[66:67], v[146:147]
	v_pk_fma_f32 v[144:145], s[16:17], v[68:69], v[144:145]
	v_pk_fma_f32 v[142:143], s[16:17], v[70:71], v[142:143]
	v_cvt_scalef32_pk_f32_fp4 v[36:37], v39, 1.0
	v_cvt_scalef32_pk_f32_fp4 v[66:67], v39, 1.0 op_sel:[1,0,0]
	v_cvt_scalef32_pk_f32_fp4 v[68:69], v39, 1.0 op_sel:[0,1,0]
	v_cvt_scalef32_pk_f32_fp4 v[38:39], v39, 1.0 op_sel:[1,1,0]
	s_nop 0
	v_pk_fma_f32 v[140:141], s[16:17], v[36:37], v[140:141]
	v_pk_fma_f32 v[138:139], s[16:17], v[66:67], v[138:139]
	v_pk_fma_f32 v[136:137], s[16:17], v[68:69], v[136:137]
	v_pk_fma_f32 v[134:135], s[16:17], v[38:39], v[134:135]
	s_add_i32 s16, s27, -7
	v_readlane_b32 s16, v64, s16
	s_lshr_b32 s40, s16, 7
	s_lshl_b64 s[16:17], s[40:41], 10
	s_add_u32 s16, s16, s100
	s_addc_u32 s17, s17, s101
	global_load_dwordx4 v[36:39], v207, s[16:17]
	v_readlane_b32 s16, v65, 9
	s_waitcnt vmcnt(15)
; #define P4_FOR16(M) M(0) M(1) M(2) M(3) M(4) M(5) M(6) M(7) M(8) M(9) M(10) M(11) M(12) M(13) M(14) M(15)
; #define P4_V(i) { const unsigned wu_ = (unsigned)__builtin_amdgcn_readlane((int)__float_as_uint(wreg), i); const unsigned long long wp_ = ((unsigned long long)wu_ << 32) | wu_; \
;               P4_ACC(b##i, wp_); const int nk_ = __builtin_amdgcn_readlane(ksel, nb + i); P4_LOAD(b##i, Vg, nk_); }
; #define P4_V(i) { const unsigned wu_ = (unsigned)__builtin_amdgcn_readlane((int)__float_as_uint(wreg), i); const unsigned long long wp_ = ((unsigned long long)wu_ << 32) | wu_; \
;               P4_ACC(b##i, wp_); const int nk_ = __builtin_amdgcn_readlane(kn, i); P4_LOAD(b##i, Vg, nk_); }
; #define P4_V(i) { const unsigned wu_ = (unsigned)__builtin_amdgcn_readlane((int)__float_as_uint(wreg), i); const unsigned long long wp_ = ((unsigned long long)wu_ << 32) | wu_; \
;               P4_ACC(b##i, wp_); }
; __device__ __forceinline__ void peer_gather_f4p(const float* X, const int* __restrict__ IDX, const float* __restrict__ G, ...
;     ...
;         for (int bt = 0; bt < 7; ++bt) {
;             const int ksel = (bt + 1 < 4) ? k0 : k1;
;             const int nb = (16 * (bt + 1)) & 63;
;             const float wreg = wbuf[kt * 128 + bt * 16 + (lane & 15)];
;     ...
;             P4_FOR16(P4_V)
	v_cvt_scalef32_pk_f32_fp4 v[66:67], v40, 1.0
	v_cvt_scalef32_pk_f32_fp4 v[68:69], v40, 1.0 op_sel:[1,0,0]
	v_cvt_scalef32_pk_f32_fp4 v[70:71], v40, 1.0 op_sel:[0,1,0]
	s_mov_b32 s17, s16
	v_cvt_scalef32_pk_f32_fp4 v[72:73], v40, 1.0 op_sel:[1,1,0]
	v_pk_fma_f32 v[132:133], s[16:17], v[66:67], v[132:133]
	v_pk_fma_f32 v[162:163], s[16:17], v[68:69], v[162:163]
	v_pk_fma_f32 v[160:161], s[16:17], v[70:71], v[160:161]
	s_nop 0
	v_pk_fma_f32 v[158:159], s[16:17], v[72:73], v[158:159]
	v_cvt_scalef32_pk_f32_fp4 v[66:67], v41, 1.0
	v_cvt_scalef32_pk_f32_fp4 v[68:69], v41, 1.0 op_sel:[1,0,0]
	v_cvt_scalef32_pk_f32_fp4 v[70:71], v41, 1.0 op_sel:[0,1,0]
	v_cvt_scalef32_pk_f32_fp4 v[40:41], v41, 1.0 op_sel:[1,1,0]
	s_nop 0
	v_pk_fma_f32 v[156:157], s[16:17], v[66:67], v[156:157]
	v_pk_fma_f32 v[154:155], s[16:17], v[68:69], v[154:155]
	v_pk_fma_f32 v[152:153], s[16:17], v[70:71], v[152:153]
	v_pk_fma_f32 v[150:151], s[16:17], v[40:41], v[150:151]
	v_cvt_scalef32_pk_f32_fp4 v[40:41], v42, 1.0
	v_cvt_scalef32_pk_f32_fp4 v[66:67], v42, 1.0 op_sel:[1,0,0]
	v_cvt_scalef32_pk_f32_fp4 v[68:69], v42, 1.0 op_sel:[0,1,0]
	v_cvt_scalef32_pk_f32_fp4 v[70:71], v42, 1.0 op_sel:[1,1,0]
	s_nop 0
	v_pk_fma_f32 v[148:149], s[16:17], v[40:41], v[148:149]
	v_pk_fma_f32 v[146:147], s[16:17], v[66:67], v[146:147]
	v_pk_fma_f32 v[144:145], s[16:17], v[68:69], v[144:145]
	v_pk_fma_f32 v[142:143], s[16:17], v[70:71], v[142:143]
	v_cvt_scalef32_pk_f32_fp4 v[40:41], v43, 1.0
	v_cvt_scalef32_pk_f32_fp4 v[66:67], v43, 1.0 op_sel:[1,0,0]
	v_cvt_scalef32_pk_f32_fp4 v[68:69], v43, 1.0 op_sel:[0,1,0]
	v_cvt_scalef32_pk_f32_fp4 v[42:43], v43, 1.0 op_sel:[1,1,0]
	s_nop 0
	v_pk_fma_f32 v[140:141], s[16:17], v[40:41], v[140:141]
	v_pk_fma_f32 v[138:139], s[16:17], v[66:67], v[138:139]
	v_pk_fma_f32 v[136:137], s[16:17], v[68:69], v[136:137]
	v_pk_fma_f32 v[134:135], s[16:17], v[42:43], v[134:135]
	s_add_i32 s16, s27, -6
	v_readlane_b32 s16, v64, s16
	s_lshr_b32 s40, s16, 7
	s_lshl_b64 s[16:17], s[40:41], 10
	s_add_u32 s16, s16, s100
	s_addc_u32 s17, s17, s101
	global_load_dwordx4 v[40:43], v207, s[16:17]
	v_readlane_b32 s16, v65, 10
	s_waitcnt vmcnt(15)
	v_cvt_scalef32_pk_f32_fp4 v[66:67], v44, 1.0
	v_cvt_scalef32_pk_f32_fp4 v[68:69], v44, 1.0 op_sel:[1,0,0]
	v_cvt_scalef32_pk_f32_fp4 v[70:71], v44, 1.0 op_sel:[0,1,0]
	s_mov_b32 s17, s16
	v_cvt_scalef32_pk_f32_fp4 v[72:73], v44, 1.0 op_sel:[1,1,0]
	v_pk_fma_f32 v[132:133], s[16:17], v[66:67], v[132:133]
	v_pk_fma_f32 v[162:163], s[16:17], v[68:69], v[162:163]
	v_pk_fma_f32 v[160:161], s[16:17], v[70:71], v[160:161]
	s_nop 0
	v_pk_fma_f32 v[158:159], s[16:17], v[72:73], v[158:159]
	v_cvt_scalef32_pk_f32_fp4 v[66:67], v45, 1.0
	v_cvt_scalef32_pk_f32_fp4 v[68:69], v45, 1.0 op_sel:[1,0,0]
	v_cvt_scalef32_pk_f32_fp4 v[70:71], v45, 1.0 op_sel:[0,1,0]
	v_cvt_scalef32_pk_f32_fp4 v[44:45], v45, 1.0 op_sel:[1,1,0]
	s_nop 0
	v_pk_fma_f32 v[156:157], s[16:17], v[66:67], v[156:157]
	v_pk_fma_f32 v[154:155], s[16:17], v[68:69], v[154:155]
	v_pk_fma_f32 v[152:153], s[16:17], v[70:71], v[152:153]
	v_pk_fma_f32 v[150:151], s[16:17], v[44:45], v[150:151]
	v_cvt_scalef32_pk_f32_fp4 v[44:45], v46, 1.0
	v_cvt_scalef32_pk_f32_fp4 v[66:67], v46, 1.0 op_sel:[1,0,0]
	v_cvt_scalef32_pk_f32_fp4 v[68:69], v46, 1.0 op_sel:[0,1,0]
	v_cvt_scalef32_pk_f32_fp4 v[70:71], v46, 1.0 op_sel:[1,1,0]
	s_nop 0
	v_pk_fma_f32 v[148:149], s[16:17], v[44:45], v[148:149]
	v_pk_fma_f32 v[146:147], s[16:17], v[66:67], v[146:147]
	v_pk_fma_f32 v[144:145], s[16:17], v[68:69], v[144:145]
	v_pk_fma_f32 v[142:143], s[16:17], v[70:71], v[142:143]
	v_cvt_scalef32_pk_f32_fp4 v[44:45], v47, 1.0
	v_cvt_scalef32_pk_f32_fp4 v[66:67], v47, 1.0 op_sel:[1,0,0]
	v_cvt_scalef32_pk_f32_fp4 v[68:69], v47, 1.0 op_sel:[0,1,0]
	v_cvt_scalef32_pk_f32_fp4 v[46:47], v47, 1.0 op_sel:[1,1,0]
	s_nop 0
	v_pk_fma_f32 v[140:141], s[16:17], v[44:45], v[140:141]
	v_pk_fma_f32 v[138:139], s[16:17], v[66:67], v[138:139]
	v_pk_fma_f32 v[136:137], s[16:17], v[68:69], v[136:137]
	v_pk_fma_f32 v[134:135], s[16:17], v[46:47], v[134:135]
	s_add_i32 s16, s27, -5
	v_readlane_b32 s16, v64, s16
	s_lshr_b32 s40, s16, 7
	s_lshl_b64 s[16:17], s[40:41], 10
	s_add_u32 s16, s16, s100
	s_addc_u32 s17, s17, s101
	global_load_dwordx4 v[44:47], v207, s[16:17]
	v_readlane_b32 s16, v65, 11
	s_waitcnt vmcnt(15)
	v_cvt_scalef32_pk_f32_fp4 v[66:67], v48, 1.0
	v_cvt_scalef32_pk_f32_fp4 v[68:69], v48, 1.0 op_sel:[1,0,0]
	v_cvt_scalef32_pk_f32_fp4 v[70:71], v48, 1.0 op_sel:[0,1,0]
	s_mov_b32 s17, s16
	v_cvt_scalef32_pk_f32_fp4 v[72:73], v48, 1.0 op_sel:[1,1,0]
	v_pk_fma_f32 v[132:133], s[16:17], v[66:67], v[132:133]
	v_pk_fma_f32 v[162:163], s[16:17], v[68:69], v[162:163]
	v_pk_fma_f32 v[160:161], s[16:17], v[70:71], v[160:161]
	s_nop 0
	v_pk_fma_f32 v[158:159], s[16:17], v[72:73], v[158:159]
	v_cvt_scalef32_pk_f32_fp4 v[66:67], v49, 1.0
	v_cvt_scalef32_pk_f32_fp4 v[68:69], v49, 1.0 op_sel:[1,0,0]
	v_cvt_scalef32_pk_f32_fp4 v[70:71], v49, 1.0 op_sel:[0,1,0]
	v_cvt_scalef32_pk_f32_fp4 v[48:49], v49, 1.0 op_sel:[1,1,0]
	s_nop 0
	v_pk_fma_f32 v[156:157], s[16:17], v[66:67], v[156:157]
	v_pk_fma_f32 v[154:155], s[16:17], v[68:69], v[154:155]
	v_pk_fma_f32 v[152:153], s[16:17], v[70:71], v[152:153]
	v_pk_fma_f32 v[150:151], s[16:17], v[48:49], v[150:151]
	v_cvt_scalef32_pk_f32_fp4 v[48:49], v50, 1.0
	v_cvt_scalef32_pk_f32_fp4 v[66:67], v50, 1.0 op_sel:[1,0,0]
	v_cvt_scalef32_pk_f32_fp4 v[68:69], v50, 1.0 op_sel:[0,1,0]
	v_cvt_scalef32_pk_f32_fp4 v[70:71], v50, 1.0 op_sel:[1,1,0]
	s_nop 0
	v_pk_fma_f32 v[148:149], s[16:17], v[48:49], v[148:149]
	v_pk_fma_f32 v[146:147], s[16:17], v[66:67], v[146:147]
	v_pk_fma_f32 v[144:145], s[16:17], v[68:69], v[144:145]
	v_pk_fma_f32 v[142:143], s[16:17], v[70:71], v[142:143]
	v_cvt_scalef32_pk_f32_fp4 v[48:49], v51, 1.0
	v_cvt_scalef32_pk_f32_fp4 v[66:67], v51, 1.0 op_sel:[1,0,0]
	v_cvt_scalef32_pk_f32_fp4 v[68:69], v51, 1.0 op_sel:[0,1,0]
	v_cvt_scalef32_pk_f32_fp4 v[50:51], v51, 1.0 op_sel:[1,1,0]
	s_nop 0
	v_pk_fma_f32 v[140:141], s[16:17], v[48:49], v[140:141]
	v_pk_fma_f32 v[138:139], s[16:17], v[66:67], v[138:139]
	v_pk_fma_f32 v[136:137], s[16:17], v[68:69], v[136:137]
	v_pk_fma_f32 v[134:135], s[16:17], v[50:51], v[134:135]
	s_add_i32 s16, s27, -4
	v_readlane_b32 s16, v64, s16
	s_lshr_b32 s40, s16, 7
	s_lshl_b64 s[16:17], s[40:41], 10
	s_add_u32 s16, s16, s100
	s_addc_u32 s17, s17, s101
	global_load_dwordx4 v[48:51], v207, s[16:17]
	v_readlane_b32 s16, v65, 12
	s_waitcnt vmcnt(15)
; #define P4_FOR16(M) M(0) M(1) M(2) M(3) M(4) M(5) M(6) M(7) M(8) M(9) M(10) M(11) M(12) M(13) M(14) M(15)
; #define P4_V(i) { const unsigned wu_ = (unsigned)__builtin_amdgcn_readlane((int)__float_as_uint(wreg), i); const unsigned long long wp_ = ((unsigned long long)wu_ << 32) | wu_; \
;               P4_ACC(b##i, wp_); const int nk_ = __builtin_amdgcn_readlane(ksel, nb + i); P4_LOAD(b##i, Vg, nk_); }
; #define P4_V(i) { const unsigned wu_ = (unsigned)__builtin_amdgcn_readlane((int)__float_as_uint(wreg), i); const unsigned long long wp_ = ((unsigned long long)wu_ << 32) | wu_; \
;               P4_ACC(b##i, wp_); const int nk_ = __builtin_amdgcn_readlane(kn, i); P4_LOAD(b##i, Vg, nk_); }
; #define P4_V(i) { const unsigned wu_ = (unsigned)__builtin_amdgcn_readlane((int)__float_as_uint(wreg), i); const unsigned long long wp_ = ((unsigned long long)wu_ << 32) | wu_; \
;               P4_ACC(b##i, wp_); }
; __device__ __forceinline__ void peer_gather_f4p(const float* X, const int* __restrict__ IDX, const float* __restrict__ G, ...
;     ...
;         for (int bt = 0; bt < 7; ++bt) {
;             const int ksel = (bt + 1 < 4) ? k0 : k1;
;             const int nb = (16 * (bt + 1)) & 63;
;             const float wreg = wbuf[kt * 128 + bt * 16 + (lane & 15)];
;     ...
;             P4_FOR16(P4_V)
	v_cvt_scalef32_pk_f32_fp4 v[66:67], v52, 1.0
	v_cvt_scalef32_pk_f32_fp4 v[68:69], v52, 1.0 op_sel:[1,0,0]
	v_cvt_scalef32_pk_f32_fp4 v[70:71], v52, 1.0 op_sel:[0,1,0]
	s_mov_b32 s17, s16
	v_cvt_scalef32_pk_f32_fp4 v[72:73], v52, 1.0 op_sel:[1,1,0]
	v_pk_fma_f32 v[132:133], s[16:17], v[66:67], v[132:133]
	v_pk_fma_f32 v[162:163], s[16:17], v[68:69], v[162:163]
	v_pk_fma_f32 v[160:161], s[16:17], v[70:71], v[160:161]
	s_nop 0
	v_pk_fma_f32 v[158:159], s[16:17], v[72:73], v[158:159]
	v_cvt_scalef32_pk_f32_fp4 v[66:67], v53, 1.0
	v_cvt_scalef32_pk_f32_fp4 v[68:69], v53, 1.0 op_sel:[1,0,0]
	v_cvt_scalef32_pk_f32_fp4 v[70:71], v53, 1.0 op_sel:[0,1,0]
	v_cvt_scalef32_pk_f32_fp4 v[52:53], v53, 1.0 op_sel:[1,1,0]
	s_nop 0
	v_pk_fma_f32 v[156:157], s[16:17], v[66:67], v[156:157]
	v_pk_fma_f32 v[154:155], s[16:17], v[68:69], v[154:155]
	v_pk_fma_f32 v[152:153], s[16:17], v[70:71], v[152:153]
	v_pk_fma_f32 v[150:151], s[16:17], v[52:53], v[150:151]
	v_cvt_scalef32_pk_f32_fp4 v[52:53], v54, 1.0
	v_cvt_scalef32_pk_f32_fp4 v[66:67], v54, 1.0 op_sel:[1,0,0]
	v_cvt_scalef32_pk_f32_fp4 v[68:69], v54, 1.0 op_sel:[0,1,0]
	v_cvt_scalef32_pk_f32_fp4 v[70:71], v54, 1.0 op_sel:[1,1,0]
	s_nop 0
	v_pk_fma_f32 v[148:149], s[16:17], v[52:53], v[148:149]
	v_pk_fma_f32 v[146:147], s[16:17], v[66:67], v[146:147]
	v_pk_fma_f32 v[144:145], s[16:17], v[68:69], v[144:145]
	v_pk_fma_f32 v[142:143], s[16:17], v[70:71], v[142:143]
	v_cvt_scalef32_pk_f32_fp4 v[52:53], v55, 1.0
	v_cvt_scalef32_pk_f32_fp4 v[66:67], v55, 1.0 op_sel:[1,0,0]
	v_cvt_scalef32_pk_f32_fp4 v[68:69], v55, 1.0 op_sel:[0,1,0]
	v_cvt_scalef32_pk_f32_fp4 v[54:55], v55, 1.0 op_sel:[1,1,0]
	s_nop 0
	v_pk_fma_f32 v[140:141], s[16:17], v[52:53], v[140:141]
	v_pk_fma_f32 v[138:139], s[16:17], v[66:67], v[138:139]
	v_pk_fma_f32 v[136:137], s[16:17], v[68:69], v[136:137]
	v_pk_fma_f32 v[134:135], s[16:17], v[54:55], v[134:135]
	s_add_i32 s16, s27, -3
	v_readlane_b32 s16, v64, s16
	s_lshr_b32 s40, s16, 7
	s_lshl_b64 s[16:17], s[40:41], 10
	s_add_u32 s16, s16, s100
	s_addc_u32 s17, s17, s101
	global_load_dwordx4 v[52:55], v207, s[16:17]
	v_readlane_b32 s16, v65, 13
	s_waitcnt vmcnt(15)
	v_cvt_scalef32_pk_f32_fp4 v[66:67], v56, 1.0
	v_cvt_scalef32_pk_f32_fp4 v[68:69], v56, 1.0 op_sel:[1,0,0]
	v_cvt_scalef32_pk_f32_fp4 v[70:71], v56, 1.0 op_sel:[0,1,0]
	s_mov_b32 s17, s16
	v_cvt_scalef32_pk_f32_fp4 v[72:73], v56, 1.0 op_sel:[1,1,0]
	v_pk_fma_f32 v[132:133], s[16:17], v[66:67], v[132:133]
	v_pk_fma_f32 v[162:163], s[16:17], v[68:69], v[162:163]
	v_pk_fma_f32 v[160:161], s[16:17], v[70:71], v[160:161]
	s_nop 0
	v_pk_fma_f32 v[158:159], s[16:17], v[72:73], v[158:159]
	v_cvt_scalef32_pk_f32_fp4 v[66:67], v57, 1.0
	v_cvt_scalef32_pk_f32_fp4 v[68:69], v57, 1.0 op_sel:[1,0,0]
	v_cvt_scalef32_pk_f32_fp4 v[70:71], v57, 1.0 op_sel:[0,1,0]
	v_cvt_scalef32_pk_f32_fp4 v[56:57], v57, 1.0 op_sel:[1,1,0]
	s_nop 0
	v_pk_fma_f32 v[156:157], s[16:17], v[66:67], v[156:157]
	v_pk_fma_f32 v[154:155], s[16:17], v[68:69], v[154:155]
	v_pk_fma_f32 v[152:153], s[16:17], v[70:71], v[152:153]
	v_pk_fma_f32 v[150:151], s[16:17], v[56:57], v[150:151]
	v_cvt_scalef32_pk_f32_fp4 v[56:57], v58, 1.0
	v_cvt_scalef32_pk_f32_fp4 v[66:67], v58, 1.0 op_sel:[1,0,0]
	v_cvt_scalef32_pk_f32_fp4 v[68:69], v58, 1.0 op_sel:[0,1,0]
	v_cvt_scalef32_pk_f32_fp4 v[70:71], v58, 1.0 op_sel:[1,1,0]
	s_nop 0
	v_pk_fma_f32 v[148:149], s[16:17], v[56:57], v[148:149]
	v_pk_fma_f32 v[146:147], s[16:17], v[66:67], v[146:147]
	v_pk_fma_f32 v[144:145], s[16:17], v[68:69], v[144:145]
	v_pk_fma_f32 v[142:143], s[16:17], v[70:71], v[142:143]
	v_cvt_scalef32_pk_f32_fp4 v[56:57], v59, 1.0
	v_cvt_scalef32_pk_f32_fp4 v[66:67], v59, 1.0 op_sel:[1,0,0]
	v_cvt_scalef32_pk_f32_fp4 v[68:69], v59, 1.0 op_sel:[0,1,0]
	v_cvt_scalef32_pk_f32_fp4 v[58:59], v59, 1.0 op_sel:[1,1,0]
	s_nop 0
	v_pk_fma_f32 v[140:141], s[16:17], v[56:57], v[140:141]
	v_pk_fma_f32 v[138:139], s[16:17], v[66:67], v[138:139]
	v_pk_fma_f32 v[136:137], s[16:17], v[68:69], v[136:137]
	v_pk_fma_f32 v[134:135], s[16:17], v[58:59], v[134:135]
	s_add_i32 s16, s27, -2
	v_readlane_b32 s16, v64, s16
	s_lshr_b32 s40, s16, 7
	s_lshl_b64 s[16:17], s[40:41], 10
	s_add_u32 s16, s16, s100
	s_addc_u32 s17, s17, s101
	global_load_dwordx4 v[56:59], v207, s[16:17]
	v_readlane_b32 s16, v65, 14
	s_waitcnt vmcnt(15)
	v_cvt_scalef32_pk_f32_fp4 v[66:67], v60, 1.0
	v_cvt_scalef32_pk_f32_fp4 v[68:69], v60, 1.0 op_sel:[1,0,0]
	v_cvt_scalef32_pk_f32_fp4 v[70:71], v60, 1.0 op_sel:[0,1,0]
	s_mov_b32 s17, s16
	v_cvt_scalef32_pk_f32_fp4 v[72:73], v60, 1.0 op_sel:[1,1,0]
	v_pk_fma_f32 v[132:133], s[16:17], v[66:67], v[132:133]
	v_pk_fma_f32 v[162:163], s[16:17], v[68:69], v[162:163]
	v_pk_fma_f32 v[160:161], s[16:17], v[70:71], v[160:161]
	s_nop 0
	v_pk_fma_f32 v[158:159], s[16:17], v[72:73], v[158:159]
	v_cvt_scalef32_pk_f32_fp4 v[66:67], v61, 1.0
	v_cvt_scalef32_pk_f32_fp4 v[68:69], v61, 1.0 op_sel:[1,0,0]
	v_cvt_scalef32_pk_f32_fp4 v[70:71], v61, 1.0 op_sel:[0,1,0]
	v_cvt_scalef32_pk_f32_fp4 v[60:61], v61, 1.0 op_sel:[1,1,0]
	s_nop 0
	v_pk_fma_f32 v[156:157], s[16:17], v[66:67], v[156:157]
	v_pk_fma_f32 v[154:155], s[16:17], v[68:69], v[154:155]
	v_pk_fma_f32 v[152:153], s[16:17], v[70:71], v[152:153]
	v_pk_fma_f32 v[150:151], s[16:17], v[60:61], v[150:151]
	v_cvt_scalef32_pk_f32_fp4 v[60:61], v62, 1.0
	v_cvt_scalef32_pk_f32_fp4 v[66:67], v62, 1.0 op_sel:[1,0,0]
	v_cvt_scalef32_pk_f32_fp4 v[68:69], v62, 1.0 op_sel:[0,1,0]
	v_cvt_scalef32_pk_f32_fp4 v[70:71], v62, 1.0 op_sel:[1,1,0]
	s_nop 0
	v_pk_fma_f32 v[148:149], s[16:17], v[60:61], v[148:149]
	v_pk_fma_f32 v[146:147], s[16:17], v[66:67], v[146:147]
	v_pk_fma_f32 v[144:145], s[16:17], v[68:69], v[144:145]
	v_pk_fma_f32 v[142:143], s[16:17], v[70:71], v[142:143]
	v_cvt_scalef32_pk_f32_fp4 v[60:61], v63, 1.0
	v_cvt_scalef32_pk_f32_fp4 v[66:67], v63, 1.0 op_sel:[1,0,0]
	v_cvt_scalef32_pk_f32_fp4 v[68:69], v63, 1.0 op_sel:[0,1,0]
	v_cvt_scalef32_pk_f32_fp4 v[62:63], v63, 1.0 op_sel:[1,1,0]
	s_nop 0
	v_pk_fma_f32 v[140:141], s[16:17], v[60:61], v[140:141]
	v_pk_fma_f32 v[138:139], s[16:17], v[66:67], v[138:139]
	v_pk_fma_f32 v[136:137], s[16:17], v[68:69], v[136:137]
	v_pk_fma_f32 v[134:135], s[16:17], v[62:63], v[134:135]
	s_add_i32 s16, s27, -1
	v_readlane_b32 s16, v64, s16
	s_lshr_b32 s40, s16, 7
	s_lshl_b64 s[16:17], s[40:41], 10
	s_add_u32 s16, s16, s100
	s_addc_u32 s17, s17, s101
	global_load_dwordx4 v[60:63], v207, s[16:17]
	v_readlane_b32 s16, v65, 15
	s_waitcnt vmcnt(15)
; #define P4_FOR16(M) M(0) M(1) M(2) M(3) M(4) M(5) M(6) M(7) M(8) M(9) M(10) M(11) M(12) M(13) M(14) M(15)
; #define P4_V(i) { const unsigned wu_ = (unsigned)__builtin_amdgcn_readlane((int)__float_as_uint(wreg), i); const unsigned long long wp_ = ((unsigned long long)wu_ << 32) | wu_; \
;               P4_ACC(b##i, wp_); const int nk_ = __builtin_amdgcn_readlane(ksel, nb + i); P4_LOAD(b##i, Vg, nk_); }
; #define P4_V(i) { const unsigned wu_ = (unsigned)__builtin_amdgcn_readlane((int)__float_as_uint(wreg), i); const unsigned long long wp_ = ((unsigned long long)wu_ << 32) | wu_; \
;               P4_ACC(b##i, wp_); const int nk_ = __builtin_amdgcn_readlane(kn, i); P4_LOAD(b##i, Vg, nk_); }
; #define P4_V(i) { const unsigned wu_ = (unsigned)__builtin_amdgcn_readlane((int)__float_as_uint(wreg), i); const unsigned long long wp_ = ((unsigned long long)wu_ << 32) | wu_; \
;               P4_ACC(b##i, wp_); }
; __device__ __forceinline__ void peer_gather_f4p(const float* X, const int* __restrict__ IDX, const float* __restrict__ G, ...
;     ...
;         for (int bt = 0; bt < 7; ++bt) {
;             const int ksel = (bt + 1 < 4) ? k0 : k1;
;             const int nb = (16 * (bt + 1)) & 63;
;             const float wreg = wbuf[kt * 128 + bt * 16 + (lane & 15)];
;     ...
;             P4_FOR16(P4_V)
;     ...
;         }
;         {
;             const float wreg = wbuf[kt * 128 + 7 * 16 + (lane & 15)];
;             if (kt < 3) {
;     ...
;                 P4_FOR16(P4_V)
	v_cvt_scalef32_pk_f32_fp4 v[66:67], v100, 1.0
	v_cvt_scalef32_pk_f32_fp4 v[68:69], v100, 1.0 op_sel:[1,0,0]
	v_cvt_scalef32_pk_f32_fp4 v[70:71], v100, 1.0 op_sel:[0,1,0]
	v_cvt_scalef32_pk_f32_fp4 v[72:73], v100, 1.0 op_sel:[1,1,0]
	s_mov_b32 s17, s16
	v_pk_fma_f32 v[132:133], s[16:17], v[66:67], v[132:133]
	v_pk_fma_f32 v[162:163], s[16:17], v[68:69], v[162:163]
	v_pk_fma_f32 v[160:161], s[16:17], v[70:71], v[160:161]
	v_pk_fma_f32 v[158:159], s[16:17], v[72:73], v[158:159]
	v_cvt_scalef32_pk_f32_fp4 v[66:67], v101, 1.0
	v_cvt_scalef32_pk_f32_fp4 v[68:69], v101, 1.0 op_sel:[1,0,0]
	v_cvt_scalef32_pk_f32_fp4 v[70:71], v101, 1.0 op_sel:[0,1,0]
	v_cvt_scalef32_pk_f32_fp4 v[72:73], v101, 1.0 op_sel:[1,1,0]
	s_nop 0
	v_pk_fma_f32 v[156:157], s[16:17], v[66:67], v[156:157]
	v_pk_fma_f32 v[154:155], s[16:17], v[68:69], v[154:155]
	v_pk_fma_f32 v[152:153], s[16:17], v[70:71], v[152:153]
	v_pk_fma_f32 v[150:151], s[16:17], v[72:73], v[150:151]
	v_cvt_scalef32_pk_f32_fp4 v[66:67], v102, 1.0
	v_cvt_scalef32_pk_f32_fp4 v[68:69], v102, 1.0 op_sel:[1,0,0]
	v_cvt_scalef32_pk_f32_fp4 v[70:71], v102, 1.0 op_sel:[0,1,0]
	v_cvt_scalef32_pk_f32_fp4 v[72:73], v102, 1.0 op_sel:[1,1,0]
	s_nop 0
	v_pk_fma_f32 v[148:149], s[16:17], v[66:67], v[148:149]
	v_pk_fma_f32 v[146:147], s[16:17], v[68:69], v[146:147]
	v_pk_fma_f32 v[144:145], s[16:17], v[70:71], v[144:145]
	v_pk_fma_f32 v[142:143], s[16:17], v[72:73], v[142:143]
	v_cvt_scalef32_pk_f32_fp4 v[66:67], v103, 1.0
	v_cvt_scalef32_pk_f32_fp4 v[68:69], v103, 1.0 op_sel:[1,0,0]
	v_cvt_scalef32_pk_f32_fp4 v[70:71], v103, 1.0 op_sel:[0,1,0]
	v_cvt_scalef32_pk_f32_fp4 v[72:73], v103, 1.0 op_sel:[1,1,0]
	s_nop 0
	v_pk_fma_f32 v[140:141], s[16:17], v[66:67], v[140:141]
	v_pk_fma_f32 v[138:139], s[16:17], v[68:69], v[138:139]
	v_pk_fma_f32 v[136:137], s[16:17], v[70:71], v[136:137]
	v_pk_fma_f32 v[134:135], s[16:17], v[72:73], v[134:135]
	v_readlane_b32 s16, v64, s27
	s_lshr_b32 s40, s16, 7
	s_lshl_b64 s[40:41], s[40:41], 10
	s_add_u32 s40, s40, s100
	s_addc_u32 s41, s41, s101
	global_load_dwordx4 v[100:103], v207, s[40:41]
	s_add_i32 s27, s27, 16
	s_cmpk_eq_i32 s27, 0x8f
	s_cbranch_scc0 .LBB0_550
	v_lshl_add_u32 v64, v170, 2, s26
	ds_read_b32 v209, v64 offset:4544
	s_cmp_lg_u32 s19, 3
	s_mov_b64 s[40:41], -1
	s_cbranch_scc0 .LBB0_553
	v_readlane_b32 s16, v208, 0
	s_waitcnt lgkmcnt(0)
	v_readlane_b32 s40, v209, 0
	s_waitcnt vmcnt(15)
	v_cvt_scalef32_pk_f32_fp4 v[64:65], v4, 1.0
	v_mov_b64_e32 v[194:195], v[132:133]
	v_mov_b64_e32 v[196:197], v[162:163]
	v_mov_b64_e32 v[190:191], v[160:161]
	v_mov_b64_e32 v[192:193], v[158:159]
	s_lshr_b32 s16, s16, 7
	s_mov_b32 s17, s86
	s_mov_b32 s41, s40
	v_cvt_scalef32_pk_f32_fp4 v[66:67], v4, 1.0 op_sel:[1,0,0]
	v_cvt_scalef32_pk_f32_fp4 v[68:69], v4, 1.0 op_sel:[0,1,0]
	v_cvt_scalef32_pk_f32_fp4 v[70:71], v4, 1.0 op_sel:[1,1,0]
	v_pk_fma_f32 v[194:195], s[40:41], v[64:65], v[194:195]
	v_mov_b64_e32 v[186:187], v[156:157]
	v_pk_fma_f32 v[196:197], s[40:41], v[66:67], v[196:197]
	v_pk_fma_f32 v[190:191], s[40:41], v[68:69], v[190:191]
	v_pk_fma_f32 v[192:193], s[40:41], v[70:71], v[192:193]
	v_cvt_scalef32_pk_f32_fp4 v[64:65], v5, 1.0
	v_mov_b64_e32 v[188:189], v[154:155]
	v_mov_b64_e32 v[182:183], v[152:153]
	v_mov_b64_e32 v[184:185], v[150:151]
	s_lshl_b64 s[16:17], s[16:17], 10
	v_cvt_scalef32_pk_f32_fp4 v[66:67], v5, 1.0 op_sel:[1,0,0]
	v_cvt_scalef32_pk_f32_fp4 v[68:69], v5, 1.0 op_sel:[0,1,0]
	v_cvt_scalef32_pk_f32_fp4 v[70:71], v5, 1.0 op_sel:[1,1,0]
	v_pk_fma_f32 v[186:187], s[40:41], v[64:65], v[186:187]
	v_mov_b64_e32 v[178:179], v[148:149]
	v_pk_fma_f32 v[188:189], s[40:41], v[66:67], v[188:189]
	v_pk_fma_f32 v[182:183], s[40:41], v[68:69], v[182:183]
	v_pk_fma_f32 v[184:185], s[40:41], v[70:71], v[184:185]
	v_cvt_scalef32_pk_f32_fp4 v[64:65], v6, 1.0
	v_mov_b64_e32 v[180:181], v[146:147]
	v_mov_b64_e32 v[174:175], v[144:145]
	v_mov_b64_e32 v[176:177], v[142:143]
	s_add_u32 s16, s52, s16
	v_cvt_scalef32_pk_f32_fp4 v[66:67], v6, 1.0 op_sel:[1,0,0]
	v_cvt_scalef32_pk_f32_fp4 v[68:69], v6, 1.0 op_sel:[0,1,0]
	v_cvt_scalef32_pk_f32_fp4 v[70:71], v6, 1.0 op_sel:[1,1,0]
	v_pk_fma_f32 v[178:179], s[40:41], v[64:65], v[178:179]
	v_mov_b64_e32 v[170:171], v[140:141]
	v_pk_fma_f32 v[180:181], s[40:41], v[66:67], v[180:181]
	v_pk_fma_f32 v[174:175], s[40:41], v[68:69], v[174:175]
	v_pk_fma_f32 v[176:177], s[40:41], v[70:71], v[176:177]
	v_cvt_scalef32_pk_f32_fp4 v[64:65], v7, 1.0
	s_addc_u32 s17, s53, s17
	v_cvt_scalef32_pk_f32_fp4 v[66:67], v7, 1.0 op_sel:[1,0,0]
	v_cvt_scalef32_pk_f32_fp4 v[68:69], v7, 1.0 op_sel:[0,1,0]
	v_cvt_scalef32_pk_f32_fp4 v[70:71], v7, 1.0 op_sel:[1,1,0]
	v_pk_fma_f32 v[170:171], s[40:41], v[64:65], v[170:171]
	v_mov_b64_e32 v[172:173], v[138:139]
	v_mov_b64_e32 v[166:167], v[136:137]
	v_mov_b64_e32 v[168:169], v[134:135]
	v_lshl_add_u64 v[64:65], s[16:17], 0, v[164:165]
	v_readlane_b32 s16, v208, 1
	v_pk_fma_f32 v[172:173], s[40:41], v[66:67], v[172:173]
	v_pk_fma_f32 v[166:167], s[40:41], v[68:69], v[166:167]
	v_pk_fma_f32 v[168:169], s[40:41], v[70:71], v[168:169]
	global_load_dwordx4 v[64:67], v[64:65], off
	v_readlane_b32 s40, v209, 1
	s_waitcnt vmcnt(15)
; #define P4_FOR16(M) M(0) M(1) M(2) M(3) M(4) M(5) M(6) M(7) M(8) M(9) M(10) M(11) M(12) M(13) M(14) M(15)
; #define P4_V(i) { const unsigned wu_ = (unsigned)__builtin_amdgcn_readlane((int)__float_as_uint(wreg), i); const unsigned long long wp_ = ((unsigned long long)wu_ << 32) | wu_; \
;               P4_ACC(b##i, wp_); const int nk_ = __builtin_amdgcn_readlane(ksel, nb + i); P4_LOAD(b##i, Vg, nk_); }
; #define P4_V(i) { const unsigned wu_ = (unsigned)__builtin_amdgcn_readlane((int)__float_as_uint(wreg), i); const unsigned long long wp_ = ((unsigned long long)wu_ << 32) | wu_; \
;               P4_ACC(b##i, wp_); const int nk_ = __builtin_amdgcn_readlane(kn, i); P4_LOAD(b##i, Vg, nk_); }
; #define P4_V(i) { const unsigned wu_ = (unsigned)__builtin_amdgcn_readlane((int)__float_as_uint(wreg), i); const unsigned long long wp_ = ((unsigned long long)wu_ << 32) | wu_; \
;               P4_ACC(b##i, wp_); }
; __device__ __forceinline__ void peer_gather_f4p(const float* X, const int* __restrict__ IDX, const float* __restrict__ G, ...
;     ...
;         {
;             const float wreg = wbuf[kt * 128 + 7 * 16 + (lane & 15)];
;             if (kt < 3) {
;     ...
;                 P4_FOR16(P4_V)
	v_cvt_scalef32_pk_f32_fp4 v[68:69], v8, 1.0
	s_lshr_b32 s16, s16, 7
	s_mov_b32 s17, s86
	s_mov_b32 s41, s40
	v_cvt_scalef32_pk_f32_fp4 v[70:71], v8, 1.0 op_sel:[1,0,0]
	v_cvt_scalef32_pk_f32_fp4 v[72:73], v8, 1.0 op_sel:[0,1,0]
	v_cvt_scalef32_pk_f32_fp4 v[74:75], v8, 1.0 op_sel:[1,1,0]
	v_pk_fma_f32 v[194:195], s[40:41], v[68:69], v[194:195]
	s_lshl_b64 s[16:17], s[16:17], 10
	v_pk_fma_f32 v[196:197], s[40:41], v[70:71], v[196:197]
	v_pk_fma_f32 v[190:191], s[40:41], v[72:73], v[190:191]
	v_pk_fma_f32 v[192:193], s[40:41], v[74:75], v[192:193]
	v_cvt_scalef32_pk_f32_fp4 v[68:69], v9, 1.0
	v_cvt_scalef32_pk_f32_fp4 v[70:71], v9, 1.0 op_sel:[1,0,0]
	v_cvt_scalef32_pk_f32_fp4 v[72:73], v9, 1.0 op_sel:[0,1,0]
	v_cvt_scalef32_pk_f32_fp4 v[74:75], v9, 1.0 op_sel:[1,1,0]
	s_add_u32 s16, s52, s16
	v_pk_fma_f32 v[186:187], s[40:41], v[68:69], v[186:187]
	v_pk_fma_f32 v[188:189], s[40:41], v[70:71], v[188:189]
	v_pk_fma_f32 v[182:183], s[40:41], v[72:73], v[182:183]
	v_pk_fma_f32 v[184:185], s[40:41], v[74:75], v[184:185]
	v_cvt_scalef32_pk_f32_fp4 v[68:69], v10, 1.0
	v_cvt_scalef32_pk_f32_fp4 v[70:71], v10, 1.0 op_sel:[1,0,0]
	v_cvt_scalef32_pk_f32_fp4 v[72:73], v10, 1.0 op_sel:[0,1,0]
	v_cvt_scalef32_pk_f32_fp4 v[74:75], v10, 1.0 op_sel:[1,1,0]
	s_addc_u32 s17, s53, s17
	v_pk_fma_f32 v[178:179], s[40:41], v[68:69], v[178:179]
	v_pk_fma_f32 v[180:181], s[40:41], v[70:71], v[180:181]
	v_pk_fma_f32 v[174:175], s[40:41], v[72:73], v[174:175]
	v_pk_fma_f32 v[176:177], s[40:41], v[74:75], v[176:177]
	v_cvt_scalef32_pk_f32_fp4 v[68:69], v11, 1.0
	v_cvt_scalef32_pk_f32_fp4 v[70:71], v11, 1.0 op_sel:[1,0,0]
	v_cvt_scalef32_pk_f32_fp4 v[72:73], v11, 1.0 op_sel:[0,1,0]
	v_cvt_scalef32_pk_f32_fp4 v[74:75], v11, 1.0 op_sel:[1,1,0]
	s_nop 0
	v_pk_fma_f32 v[170:171], s[40:41], v[68:69], v[170:171]
	v_lshl_add_u64 v[68:69], s[16:17], 0, v[164:165]
	v_readlane_b32 s16, v208, 2
	v_pk_fma_f32 v[172:173], s[40:41], v[70:71], v[172:173]
	v_pk_fma_f32 v[166:167], s[40:41], v[72:73], v[166:167]
	v_pk_fma_f32 v[168:169], s[40:41], v[74:75], v[168:169]
	global_load_dwordx4 v[68:71], v[68:69], off
	v_readlane_b32 s40, v209, 2
	s_waitcnt vmcnt(15)
	v_cvt_scalef32_pk_f32_fp4 v[72:73], v12, 1.0
	s_lshr_b32 s16, s16, 7
	s_mov_b32 s17, s86
	s_mov_b32 s41, s40
	v_cvt_scalef32_pk_f32_fp4 v[74:75], v12, 1.0 op_sel:[1,0,0]
	v_cvt_scalef32_pk_f32_fp4 v[76:77], v12, 1.0 op_sel:[0,1,0]
	v_cvt_scalef32_pk_f32_fp4 v[78:79], v12, 1.0 op_sel:[1,1,0]
	v_pk_fma_f32 v[194:195], s[40:41], v[72:73], v[194:195]
	s_lshl_b64 s[16:17], s[16:17], 10
	v_pk_fma_f32 v[196:197], s[40:41], v[74:75], v[196:197]
	v_pk_fma_f32 v[190:191], s[40:41], v[76:77], v[190:191]
	v_pk_fma_f32 v[192:193], s[40:41], v[78:79], v[192:193]
	v_cvt_scalef32_pk_f32_fp4 v[72:73], v13, 1.0
	v_cvt_scalef32_pk_f32_fp4 v[74:75], v13, 1.0 op_sel:[1,0,0]
	v_cvt_scalef32_pk_f32_fp4 v[76:77], v13, 1.0 op_sel:[0,1,0]
	v_cvt_scalef32_pk_f32_fp4 v[78:79], v13, 1.0 op_sel:[1,1,0]
	s_add_u32 s16, s52, s16
	v_pk_fma_f32 v[186:187], s[40:41], v[72:73], v[186:187]
	v_pk_fma_f32 v[188:189], s[40:41], v[74:75], v[188:189]
	v_pk_fma_f32 v[182:183], s[40:41], v[76:77], v[182:183]
	v_pk_fma_f32 v[184:185], s[40:41], v[78:79], v[184:185]
	v_cvt_scalef32_pk_f32_fp4 v[72:73], v14, 1.0
	v_cvt_scalef32_pk_f32_fp4 v[74:75], v14, 1.0 op_sel:[1,0,0]
	v_cvt_scalef32_pk_f32_fp4 v[76:77], v14, 1.0 op_sel:[0,1,0]
	v_cvt_scalef32_pk_f32_fp4 v[78:79], v14, 1.0 op_sel:[1,1,0]
	s_addc_u32 s17, s53, s17
	v_pk_fma_f32 v[178:179], s[40:41], v[72:73], v[178:179]
	v_pk_fma_f32 v[180:181], s[40:41], v[74:75], v[180:181]
	v_pk_fma_f32 v[174:175], s[40:41], v[76:77], v[174:175]
	v_pk_fma_f32 v[176:177], s[40:41], v[78:79], v[176:177]
	v_cvt_scalef32_pk_f32_fp4 v[72:73], v15, 1.0
	v_cvt_scalef32_pk_f32_fp4 v[74:75], v15, 1.0 op_sel:[1,0,0]
	v_cvt_scalef32_pk_f32_fp4 v[76:77], v15, 1.0 op_sel:[0,1,0]
	v_cvt_scalef32_pk_f32_fp4 v[78:79], v15, 1.0 op_sel:[1,1,0]
	s_nop 0
	v_pk_fma_f32 v[170:171], s[40:41], v[72:73], v[170:171]
	v_lshl_add_u64 v[72:73], s[16:17], 0, v[164:165]
	v_readlane_b32 s16, v208, 3
	v_pk_fma_f32 v[172:173], s[40:41], v[74:75], v[172:173]
	v_pk_fma_f32 v[166:167], s[40:41], v[76:77], v[166:167]
	v_pk_fma_f32 v[168:169], s[40:41], v[78:79], v[168:169]
	global_load_dwordx4 v[72:75], v[72:73], off
	v_readlane_b32 s40, v209, 3
	s_waitcnt vmcnt(15)
	v_cvt_scalef32_pk_f32_fp4 v[76:77], v16, 1.0
	s_lshr_b32 s16, s16, 7
	s_mov_b32 s17, s86
	s_mov_b32 s41, s40
	v_cvt_scalef32_pk_f32_fp4 v[78:79], v16, 1.0 op_sel:[1,0,0]
	v_cvt_scalef32_pk_f32_fp4 v[80:81], v16, 1.0 op_sel:[0,1,0]
	v_cvt_scalef32_pk_f32_fp4 v[82:83], v16, 1.0 op_sel:[1,1,0]
	v_pk_fma_f32 v[194:195], s[40:41], v[76:77], v[194:195]
	s_lshl_b64 s[16:17], s[16:17], 10
	v_pk_fma_f32 v[196:197], s[40:41], v[78:79], v[196:197]
	v_pk_fma_f32 v[190:191], s[40:41], v[80:81], v[190:191]
	v_pk_fma_f32 v[192:193], s[40:41], v[82:83], v[192:193]
	v_cvt_scalef32_pk_f32_fp4 v[76:77], v17, 1.0
	v_cvt_scalef32_pk_f32_fp4 v[78:79], v17, 1.0 op_sel:[1,0,0]
	v_cvt_scalef32_pk_f32_fp4 v[80:81], v17, 1.0 op_sel:[0,1,0]
	v_cvt_scalef32_pk_f32_fp4 v[82:83], v17, 1.0 op_sel:[1,1,0]
	s_add_u32 s16, s52, s16
	v_pk_fma_f32 v[186:187], s[40:41], v[76:77], v[186:187]
	v_pk_fma_f32 v[188:189], s[40:41], v[78:79], v[188:189]
	v_pk_fma_f32 v[182:183], s[40:41], v[80:81], v[182:183]
	v_pk_fma_f32 v[184:185], s[40:41], v[82:83], v[184:185]
	v_cvt_scalef32_pk_f32_fp4 v[76:77], v18, 1.0
	v_cvt_scalef32_pk_f32_fp4 v[78:79], v18, 1.0 op_sel:[1,0,0]
	v_cvt_scalef32_pk_f32_fp4 v[80:81], v18, 1.0 op_sel:[0,1,0]
	v_cvt_scalef32_pk_f32_fp4 v[82:83], v18, 1.0 op_sel:[1,1,0]
	s_addc_u32 s17, s53, s17
	v_pk_fma_f32 v[178:179], s[40:41], v[76:77], v[178:179]
	v_pk_fma_f32 v[180:181], s[40:41], v[78:79], v[180:181]
	v_pk_fma_f32 v[174:175], s[40:41], v[80:81], v[174:175]
	v_pk_fma_f32 v[176:177], s[40:41], v[82:83], v[176:177]
	v_cvt_scalef32_pk_f32_fp4 v[76:77], v19, 1.0
	v_cvt_scalef32_pk_f32_fp4 v[78:79], v19, 1.0 op_sel:[1,0,0]
	v_cvt_scalef32_pk_f32_fp4 v[80:81], v19, 1.0 op_sel:[0,1,0]
	v_cvt_scalef32_pk_f32_fp4 v[82:83], v19, 1.0 op_sel:[1,1,0]
	s_nop 0
	v_pk_fma_f32 v[170:171], s[40:41], v[76:77], v[170:171]
	v_lshl_add_u64 v[76:77], s[16:17], 0, v[164:165]
	v_readlane_b32 s16, v208, 4
	v_pk_fma_f32 v[172:173], s[40:41], v[78:79], v[172:173]
	v_pk_fma_f32 v[166:167], s[40:41], v[80:81], v[166:167]
	v_pk_fma_f32 v[168:169], s[40:41], v[82:83], v[168:169]
	global_load_dwordx4 v[76:79], v[76:77], off
	v_readlane_b32 s40, v209, 4
	s_waitcnt vmcnt(15)
; #define P4_FOR16(M) M(0) M(1) M(2) M(3) M(4) M(5) M(6) M(7) M(8) M(9) M(10) M(11) M(12) M(13) M(14) M(15)
; #define P4_V(i) { const unsigned wu_ = (unsigned)__builtin_amdgcn_readlane((int)__float_as_uint(wreg), i); const unsigned long long wp_ = ((unsigned long long)wu_ << 32) | wu_; \
;               P4_ACC(b##i, wp_); const int nk_ = __builtin_amdgcn_readlane(ksel, nb + i); P4_LOAD(b##i, Vg, nk_); }
; #define P4_V(i) { const unsigned wu_ = (unsigned)__builtin_amdgcn_readlane((int)__float_as_uint(wreg), i); const unsigned long long wp_ = ((unsigned long long)wu_ << 32) | wu_; \
;               P4_ACC(b##i, wp_); const int nk_ = __builtin_amdgcn_readlane(kn, i); P4_LOAD(b##i, Vg, nk_); }
; #define P4_V(i) { const unsigned wu_ = (unsigned)__builtin_amdgcn_readlane((int)__float_as_uint(wreg), i); const unsigned long long wp_ = ((unsigned long long)wu_ << 32) | wu_; \
;               P4_ACC(b##i, wp_); }
; __device__ __forceinline__ void peer_gather_f4p(const float* X, const int* __restrict__ IDX, const float* __restrict__ G, ...
;     ...
;         {
;             const float wreg = wbuf[kt * 128 + 7 * 16 + (lane & 15)];
;             if (kt < 3) {
;     ...
;                 P4_FOR16(P4_V)
	v_cvt_scalef32_pk_f32_fp4 v[80:81], v20, 1.0
	s_lshr_b32 s16, s16, 7
	s_mov_b32 s17, s86
	s_mov_b32 s41, s40
	v_cvt_scalef32_pk_f32_fp4 v[82:83], v20, 1.0 op_sel:[1,0,0]
	v_cvt_scalef32_pk_f32_fp4 v[84:85], v20, 1.0 op_sel:[0,1,0]
	v_cvt_scalef32_pk_f32_fp4 v[86:87], v20, 1.0 op_sel:[1,1,0]
	v_pk_fma_f32 v[194:195], s[40:41], v[80:81], v[194:195]
	s_lshl_b64 s[16:17], s[16:17], 10
	v_pk_fma_f32 v[196:197], s[40:41], v[82:83], v[196:197]
	v_pk_fma_f32 v[190:191], s[40:41], v[84:85], v[190:191]
	v_pk_fma_f32 v[192:193], s[40:41], v[86:87], v[192:193]
	v_cvt_scalef32_pk_f32_fp4 v[80:81], v21, 1.0
	v_cvt_scalef32_pk_f32_fp4 v[82:83], v21, 1.0 op_sel:[1,0,0]
	v_cvt_scalef32_pk_f32_fp4 v[84:85], v21, 1.0 op_sel:[0,1,0]
	v_cvt_scalef32_pk_f32_fp4 v[86:87], v21, 1.0 op_sel:[1,1,0]
	s_add_u32 s16, s52, s16
	v_pk_fma_f32 v[186:187], s[40:41], v[80:81], v[186:187]
	v_pk_fma_f32 v[188:189], s[40:41], v[82:83], v[188:189]
	v_pk_fma_f32 v[182:183], s[40:41], v[84:85], v[182:183]
	v_pk_fma_f32 v[184:185], s[40:41], v[86:87], v[184:185]
	v_cvt_scalef32_pk_f32_fp4 v[80:81], v22, 1.0
	v_cvt_scalef32_pk_f32_fp4 v[82:83], v22, 1.0 op_sel:[1,0,0]
	v_cvt_scalef32_pk_f32_fp4 v[84:85], v22, 1.0 op_sel:[0,1,0]
	v_cvt_scalef32_pk_f32_fp4 v[86:87], v22, 1.0 op_sel:[1,1,0]
	s_addc_u32 s17, s53, s17
	v_pk_fma_f32 v[178:179], s[40:41], v[80:81], v[178:179]
	v_pk_fma_f32 v[180:181], s[40:41], v[82:83], v[180:181]
	v_pk_fma_f32 v[174:175], s[40:41], v[84:85], v[174:175]
	v_pk_fma_f32 v[176:177], s[40:41], v[86:87], v[176:177]
	v_cvt_scalef32_pk_f32_fp4 v[80:81], v23, 1.0
	v_cvt_scalef32_pk_f32_fp4 v[82:83], v23, 1.0 op_sel:[1,0,0]
	v_cvt_scalef32_pk_f32_fp4 v[84:85], v23, 1.0 op_sel:[0,1,0]
	v_cvt_scalef32_pk_f32_fp4 v[86:87], v23, 1.0 op_sel:[1,1,0]
	s_nop 0
	v_pk_fma_f32 v[170:171], s[40:41], v[80:81], v[170:171]
	v_lshl_add_u64 v[80:81], s[16:17], 0, v[164:165]
	v_readlane_b32 s16, v208, 5
	v_pk_fma_f32 v[172:173], s[40:41], v[82:83], v[172:173]
	v_pk_fma_f32 v[166:167], s[40:41], v[84:85], v[166:167]
	v_pk_fma_f32 v[168:169], s[40:41], v[86:87], v[168:169]
	global_load_dwordx4 v[80:83], v[80:81], off
	v_readlane_b32 s40, v209, 5
	s_waitcnt vmcnt(15)
	v_cvt_scalef32_pk_f32_fp4 v[84:85], v24, 1.0
	s_lshr_b32 s16, s16, 7
	s_mov_b32 s17, s86
	s_mov_b32 s41, s40
	v_cvt_scalef32_pk_f32_fp4 v[86:87], v24, 1.0 op_sel:[1,0,0]
	v_cvt_scalef32_pk_f32_fp4 v[88:89], v24, 1.0 op_sel:[0,1,0]
	v_cvt_scalef32_pk_f32_fp4 v[90:91], v24, 1.0 op_sel:[1,1,0]
	v_pk_fma_f32 v[194:195], s[40:41], v[84:85], v[194:195]
	s_lshl_b64 s[16:17], s[16:17], 10
	v_pk_fma_f32 v[196:197], s[40:41], v[86:87], v[196:197]
	v_pk_fma_f32 v[190:191], s[40:41], v[88:89], v[190:191]
	v_pk_fma_f32 v[192:193], s[40:41], v[90:91], v[192:193]
	v_cvt_scalef32_pk_f32_fp4 v[84:85], v25, 1.0
	v_cvt_scalef32_pk_f32_fp4 v[86:87], v25, 1.0 op_sel:[1,0,0]
	v_cvt_scalef32_pk_f32_fp4 v[88:89], v25, 1.0 op_sel:[0,1,0]
	v_cvt_scalef32_pk_f32_fp4 v[90:91], v25, 1.0 op_sel:[1,1,0]
	s_add_u32 s16, s52, s16
	v_pk_fma_f32 v[186:187], s[40:41], v[84:85], v[186:187]
	v_pk_fma_f32 v[188:189], s[40:41], v[86:87], v[188:189]
	v_pk_fma_f32 v[182:183], s[40:41], v[88:89], v[182:183]
	v_pk_fma_f32 v[184:185], s[40:41], v[90:91], v[184:185]
	v_cvt_scalef32_pk_f32_fp4 v[84:85], v26, 1.0
	v_cvt_scalef32_pk_f32_fp4 v[86:87], v26, 1.0 op_sel:[1,0,0]
	v_cvt_scalef32_pk_f32_fp4 v[88:89], v26, 1.0 op_sel:[0,1,0]
	v_cvt_scalef32_pk_f32_fp4 v[90:91], v26, 1.0 op_sel:[1,1,0]
	s_addc_u32 s17, s53, s17
	v_pk_fma_f32 v[178:179], s[40:41], v[84:85], v[178:179]
	v_pk_fma_f32 v[180:181], s[40:41], v[86:87], v[180:181]
	v_pk_fma_f32 v[174:175], s[40:41], v[88:89], v[174:175]
	v_pk_fma_f32 v[176:177], s[40:41], v[90:91], v[176:177]
	v_cvt_scalef32_pk_f32_fp4 v[84:85], v27, 1.0
	v_cvt_scalef32_pk_f32_fp4 v[86:87], v27, 1.0 op_sel:[1,0,0]
	v_cvt_scalef32_pk_f32_fp4 v[88:89], v27, 1.0 op_sel:[0,1,0]
	v_cvt_scalef32_pk_f32_fp4 v[90:91], v27, 1.0 op_sel:[1,1,0]
	s_nop 0
	v_pk_fma_f32 v[170:171], s[40:41], v[84:85], v[170:171]
	v_lshl_add_u64 v[84:85], s[16:17], 0, v[164:165]
	v_readlane_b32 s16, v208, 6
	v_pk_fma_f32 v[172:173], s[40:41], v[86:87], v[172:173]
	v_pk_fma_f32 v[166:167], s[40:41], v[88:89], v[166:167]
	v_pk_fma_f32 v[168:169], s[40:41], v[90:91], v[168:169]
	global_load_dwordx4 v[84:87], v[84:85], off
	v_readlane_b32 s40, v209, 6
	s_waitcnt vmcnt(15)
	v_cvt_scalef32_pk_f32_fp4 v[88:89], v28, 1.0
	s_lshr_b32 s16, s16, 7
	s_mov_b32 s17, s86
	s_mov_b32 s41, s40
	v_cvt_scalef32_pk_f32_fp4 v[90:91], v28, 1.0 op_sel:[1,0,0]
	v_cvt_scalef32_pk_f32_fp4 v[92:93], v28, 1.0 op_sel:[0,1,0]
	v_cvt_scalef32_pk_f32_fp4 v[94:95], v28, 1.0 op_sel:[1,1,0]
	v_pk_fma_f32 v[194:195], s[40:41], v[88:89], v[194:195]
	s_lshl_b64 s[16:17], s[16:17], 10
	v_pk_fma_f32 v[196:197], s[40:41], v[90:91], v[196:197]
	v_pk_fma_f32 v[190:191], s[40:41], v[92:93], v[190:191]
	v_pk_fma_f32 v[192:193], s[40:41], v[94:95], v[192:193]
	v_cvt_scalef32_pk_f32_fp4 v[88:89], v29, 1.0
	v_cvt_scalef32_pk_f32_fp4 v[90:91], v29, 1.0 op_sel:[1,0,0]
	v_cvt_scalef32_pk_f32_fp4 v[92:93], v29, 1.0 op_sel:[0,1,0]
	v_cvt_scalef32_pk_f32_fp4 v[94:95], v29, 1.0 op_sel:[1,1,0]
	s_add_u32 s16, s52, s16
	v_pk_fma_f32 v[186:187], s[40:41], v[88:89], v[186:187]
	v_pk_fma_f32 v[188:189], s[40:41], v[90:91], v[188:189]
	v_pk_fma_f32 v[182:183], s[40:41], v[92:93], v[182:183]
	v_pk_fma_f32 v[184:185], s[40:41], v[94:95], v[184:185]
	v_cvt_scalef32_pk_f32_fp4 v[88:89], v30, 1.0
	v_cvt_scalef32_pk_f32_fp4 v[90:91], v30, 1.0 op_sel:[1,0,0]
	v_cvt_scalef32_pk_f32_fp4 v[92:93], v30, 1.0 op_sel:[0,1,0]
	v_cvt_scalef32_pk_f32_fp4 v[94:95], v30, 1.0 op_sel:[1,1,0]
	s_addc_u32 s17, s53, s17
	v_pk_fma_f32 v[178:179], s[40:41], v[88:89], v[178:179]
	v_pk_fma_f32 v[180:181], s[40:41], v[90:91], v[180:181]
	v_pk_fma_f32 v[174:175], s[40:41], v[92:93], v[174:175]
	v_pk_fma_f32 v[176:177], s[40:41], v[94:95], v[176:177]
	v_cvt_scalef32_pk_f32_fp4 v[88:89], v31, 1.0
	v_cvt_scalef32_pk_f32_fp4 v[90:91], v31, 1.0 op_sel:[1,0,0]
	v_cvt_scalef32_pk_f32_fp4 v[92:93], v31, 1.0 op_sel:[0,1,0]
	v_cvt_scalef32_pk_f32_fp4 v[94:95], v31, 1.0 op_sel:[1,1,0]
	s_nop 0
	v_pk_fma_f32 v[170:171], s[40:41], v[88:89], v[170:171]
	v_lshl_add_u64 v[88:89], s[16:17], 0, v[164:165]
	v_readlane_b32 s16, v208, 7
	v_pk_fma_f32 v[172:173], s[40:41], v[90:91], v[172:173]
	v_pk_fma_f32 v[166:167], s[40:41], v[92:93], v[166:167]
	v_pk_fma_f32 v[168:169], s[40:41], v[94:95], v[168:169]
	global_load_dwordx4 v[88:91], v[88:89], off
	v_readlane_b32 s40, v209, 7
	s_waitcnt vmcnt(15)
; #define P4_FOR16(M) M(0) M(1) M(2) M(3) M(4) M(5) M(6) M(7) M(8) M(9) M(10) M(11) M(12) M(13) M(14) M(15)
; #define P4_V(i) { const unsigned wu_ = (unsigned)__builtin_amdgcn_readlane((int)__float_as_uint(wreg), i); const unsigned long long wp_ = ((unsigned long long)wu_ << 32) | wu_; \
;               P4_ACC(b##i, wp_); const int nk_ = __builtin_amdgcn_readlane(ksel, nb + i); P4_LOAD(b##i, Vg, nk_); }
; #define P4_V(i) { const unsigned wu_ = (unsigned)__builtin_amdgcn_readlane((int)__float_as_uint(wreg), i); const unsigned long long wp_ = ((unsigned long long)wu_ << 32) | wu_; \
;               P4_ACC(b##i, wp_); const int nk_ = __builtin_amdgcn_readlane(kn, i); P4_LOAD(b##i, Vg, nk_); }
; #define P4_V(i) { const unsigned wu_ = (unsigned)__builtin_amdgcn_readlane((int)__float_as_uint(wreg), i); const unsigned long long wp_ = ((unsigned long long)wu_ << 32) | wu_; \
;               P4_ACC(b##i, wp_); }
; __device__ __forceinline__ void peer_gather_f4p(const float* X, const int* __restrict__ IDX, const float* __restrict__ G, ...
;     ...
;         {
;             const float wreg = wbuf[kt * 128 + 7 * 16 + (lane & 15)];
;             if (kt < 3) {
;     ...
;                 P4_FOR16(P4_V)
	v_cvt_scalef32_pk_f32_fp4 v[92:93], v32, 1.0
	s_lshr_b32 s16, s16, 7
	s_mov_b32 s17, s86
	s_mov_b32 s41, s40
	v_cvt_scalef32_pk_f32_fp4 v[94:95], v32, 1.0 op_sel:[1,0,0]
	v_cvt_scalef32_pk_f32_fp4 v[96:97], v32, 1.0 op_sel:[0,1,0]
	v_cvt_scalef32_pk_f32_fp4 v[98:99], v32, 1.0 op_sel:[1,1,0]
	v_pk_fma_f32 v[194:195], s[40:41], v[92:93], v[194:195]
	s_lshl_b64 s[16:17], s[16:17], 10
	v_pk_fma_f32 v[196:197], s[40:41], v[94:95], v[196:197]
	v_pk_fma_f32 v[190:191], s[40:41], v[96:97], v[190:191]
	v_pk_fma_f32 v[192:193], s[40:41], v[98:99], v[192:193]
	v_cvt_scalef32_pk_f32_fp4 v[92:93], v33, 1.0
	v_cvt_scalef32_pk_f32_fp4 v[94:95], v33, 1.0 op_sel:[1,0,0]
	v_cvt_scalef32_pk_f32_fp4 v[96:97], v33, 1.0 op_sel:[0,1,0]
	v_cvt_scalef32_pk_f32_fp4 v[98:99], v33, 1.0 op_sel:[1,1,0]
	s_add_u32 s16, s52, s16
	v_pk_fma_f32 v[186:187], s[40:41], v[92:93], v[186:187]
	v_pk_fma_f32 v[188:189], s[40:41], v[94:95], v[188:189]
	v_pk_fma_f32 v[182:183], s[40:41], v[96:97], v[182:183]
	v_pk_fma_f32 v[184:185], s[40:41], v[98:99], v[184:185]
	v_cvt_scalef32_pk_f32_fp4 v[92:93], v34, 1.0
	v_cvt_scalef32_pk_f32_fp4 v[94:95], v34, 1.0 op_sel:[1,0,0]
	v_cvt_scalef32_pk_f32_fp4 v[96:97], v34, 1.0 op_sel:[0,1,0]
	v_cvt_scalef32_pk_f32_fp4 v[98:99], v34, 1.0 op_sel:[1,1,0]
	s_addc_u32 s17, s53, s17
	v_pk_fma_f32 v[178:179], s[40:41], v[92:93], v[178:179]
	v_pk_fma_f32 v[180:181], s[40:41], v[94:95], v[180:181]
	v_pk_fma_f32 v[174:175], s[40:41], v[96:97], v[174:175]
	v_pk_fma_f32 v[176:177], s[40:41], v[98:99], v[176:177]
	v_cvt_scalef32_pk_f32_fp4 v[92:93], v35, 1.0
	v_cvt_scalef32_pk_f32_fp4 v[94:95], v35, 1.0 op_sel:[1,0,0]
	v_cvt_scalef32_pk_f32_fp4 v[96:97], v35, 1.0 op_sel:[0,1,0]
	v_cvt_scalef32_pk_f32_fp4 v[98:99], v35, 1.0 op_sel:[1,1,0]
	s_nop 0
	v_pk_fma_f32 v[170:171], s[40:41], v[92:93], v[170:171]
	v_lshl_add_u64 v[92:93], s[16:17], 0, v[164:165]
	v_readlane_b32 s16, v208, 8
	v_pk_fma_f32 v[172:173], s[40:41], v[94:95], v[172:173]
	v_pk_fma_f32 v[166:167], s[40:41], v[96:97], v[166:167]
	v_pk_fma_f32 v[168:169], s[40:41], v[98:99], v[168:169]
	global_load_dwordx4 v[92:95], v[92:93], off
	v_readlane_b32 s40, v209, 8
	s_waitcnt vmcnt(15)
	v_cvt_scalef32_pk_f32_fp4 v[96:97], v36, 1.0
	s_lshr_b32 s16, s16, 7
	s_mov_b32 s17, s86
	s_mov_b32 s41, s40
	v_cvt_scalef32_pk_f32_fp4 v[98:99], v36, 1.0 op_sel:[1,0,0]
	v_cvt_scalef32_pk_f32_fp4 v[104:105], v36, 1.0 op_sel:[0,1,0]
	v_cvt_scalef32_pk_f32_fp4 v[106:107], v36, 1.0 op_sel:[1,1,0]
	v_pk_fma_f32 v[194:195], s[40:41], v[96:97], v[194:195]
	s_lshl_b64 s[16:17], s[16:17], 10
	v_pk_fma_f32 v[196:197], s[40:41], v[98:99], v[196:197]
	v_pk_fma_f32 v[190:191], s[40:41], v[104:105], v[190:191]
	v_pk_fma_f32 v[192:193], s[40:41], v[106:107], v[192:193]
	v_cvt_scalef32_pk_f32_fp4 v[96:97], v37, 1.0
	v_cvt_scalef32_pk_f32_fp4 v[98:99], v37, 1.0 op_sel:[1,0,0]
	v_cvt_scalef32_pk_f32_fp4 v[104:105], v37, 1.0 op_sel:[0,1,0]
	v_cvt_scalef32_pk_f32_fp4 v[106:107], v37, 1.0 op_sel:[1,1,0]
	s_add_u32 s16, s52, s16
	v_pk_fma_f32 v[186:187], s[40:41], v[96:97], v[186:187]
	v_pk_fma_f32 v[188:189], s[40:41], v[98:99], v[188:189]
	v_pk_fma_f32 v[182:183], s[40:41], v[104:105], v[182:183]
	v_pk_fma_f32 v[184:185], s[40:41], v[106:107], v[184:185]
	v_cvt_scalef32_pk_f32_fp4 v[96:97], v38, 1.0
	v_cvt_scalef32_pk_f32_fp4 v[98:99], v38, 1.0 op_sel:[1,0,0]
	v_cvt_scalef32_pk_f32_fp4 v[104:105], v38, 1.0 op_sel:[0,1,0]
	v_cvt_scalef32_pk_f32_fp4 v[106:107], v38, 1.0 op_sel:[1,1,0]
	s_addc_u32 s17, s53, s17
	v_pk_fma_f32 v[178:179], s[40:41], v[96:97], v[178:179]
	v_pk_fma_f32 v[180:181], s[40:41], v[98:99], v[180:181]
	v_pk_fma_f32 v[174:175], s[40:41], v[104:105], v[174:175]
	v_pk_fma_f32 v[176:177], s[40:41], v[106:107], v[176:177]
	v_cvt_scalef32_pk_f32_fp4 v[96:97], v39, 1.0
	v_cvt_scalef32_pk_f32_fp4 v[98:99], v39, 1.0 op_sel:[1,0,0]
	v_cvt_scalef32_pk_f32_fp4 v[104:105], v39, 1.0 op_sel:[0,1,0]
	v_cvt_scalef32_pk_f32_fp4 v[106:107], v39, 1.0 op_sel:[1,1,0]
	s_nop 0
	v_pk_fma_f32 v[170:171], s[40:41], v[96:97], v[170:171]
	v_lshl_add_u64 v[96:97], s[16:17], 0, v[164:165]
	v_readlane_b32 s16, v208, 9
	v_pk_fma_f32 v[172:173], s[40:41], v[98:99], v[172:173]
	v_pk_fma_f32 v[166:167], s[40:41], v[104:105], v[166:167]
	v_pk_fma_f32 v[168:169], s[40:41], v[106:107], v[168:169]
	global_load_dwordx4 v[96:99], v[96:97], off
	v_readlane_b32 s40, v209, 9
	s_waitcnt vmcnt(15)
	v_cvt_scalef32_pk_f32_fp4 v[104:105], v40, 1.0
	s_lshr_b32 s16, s16, 7
	s_mov_b32 s17, s86
	s_mov_b32 s41, s40
	v_cvt_scalef32_pk_f32_fp4 v[106:107], v40, 1.0 op_sel:[1,0,0]
	v_cvt_scalef32_pk_f32_fp4 v[108:109], v40, 1.0 op_sel:[0,1,0]
	v_cvt_scalef32_pk_f32_fp4 v[110:111], v40, 1.0 op_sel:[1,1,0]
	v_pk_fma_f32 v[194:195], s[40:41], v[104:105], v[194:195]
	s_lshl_b64 s[16:17], s[16:17], 10
	v_pk_fma_f32 v[196:197], s[40:41], v[106:107], v[196:197]
	v_pk_fma_f32 v[190:191], s[40:41], v[108:109], v[190:191]
	v_pk_fma_f32 v[192:193], s[40:41], v[110:111], v[192:193]
	v_cvt_scalef32_pk_f32_fp4 v[104:105], v41, 1.0
	v_cvt_scalef32_pk_f32_fp4 v[106:107], v41, 1.0 op_sel:[1,0,0]
	v_cvt_scalef32_pk_f32_fp4 v[108:109], v41, 1.0 op_sel:[0,1,0]
	v_cvt_scalef32_pk_f32_fp4 v[110:111], v41, 1.0 op_sel:[1,1,0]
	s_add_u32 s16, s52, s16
	v_pk_fma_f32 v[186:187], s[40:41], v[104:105], v[186:187]
	v_pk_fma_f32 v[188:189], s[40:41], v[106:107], v[188:189]
	v_pk_fma_f32 v[182:183], s[40:41], v[108:109], v[182:183]
	v_pk_fma_f32 v[184:185], s[40:41], v[110:111], v[184:185]
	v_cvt_scalef32_pk_f32_fp4 v[104:105], v42, 1.0
	v_cvt_scalef32_pk_f32_fp4 v[106:107], v42, 1.0 op_sel:[1,0,0]
	v_cvt_scalef32_pk_f32_fp4 v[108:109], v42, 1.0 op_sel:[0,1,0]
	v_cvt_scalef32_pk_f32_fp4 v[110:111], v42, 1.0 op_sel:[1,1,0]
	s_addc_u32 s17, s53, s17
	v_pk_fma_f32 v[178:179], s[40:41], v[104:105], v[178:179]
	v_pk_fma_f32 v[180:181], s[40:41], v[106:107], v[180:181]
	v_pk_fma_f32 v[174:175], s[40:41], v[108:109], v[174:175]
	v_pk_fma_f32 v[176:177], s[40:41], v[110:111], v[176:177]
	v_cvt_scalef32_pk_f32_fp4 v[104:105], v43, 1.0
	v_cvt_scalef32_pk_f32_fp4 v[106:107], v43, 1.0 op_sel:[1,0,0]
	v_cvt_scalef32_pk_f32_fp4 v[108:109], v43, 1.0 op_sel:[0,1,0]
	v_cvt_scalef32_pk_f32_fp4 v[110:111], v43, 1.0 op_sel:[1,1,0]
	s_nop 0
	v_pk_fma_f32 v[170:171], s[40:41], v[104:105], v[170:171]
	v_lshl_add_u64 v[104:105], s[16:17], 0, v[164:165]
	v_readlane_b32 s16, v208, 10
	v_pk_fma_f32 v[172:173], s[40:41], v[106:107], v[172:173]
	v_pk_fma_f32 v[166:167], s[40:41], v[108:109], v[166:167]
	v_pk_fma_f32 v[168:169], s[40:41], v[110:111], v[168:169]
	global_load_dwordx4 v[104:107], v[104:105], off
	v_readlane_b32 s40, v209, 10
	s_waitcnt vmcnt(15)
; #define P4_FOR16(M) M(0) M(1) M(2) M(3) M(4) M(5) M(6) M(7) M(8) M(9) M(10) M(11) M(12) M(13) M(14) M(15)
; #define P4_V(i) { const unsigned wu_ = (unsigned)__builtin_amdgcn_readlane((int)__float_as_uint(wreg), i); const unsigned long long wp_ = ((unsigned long long)wu_ << 32) | wu_; \
;               P4_ACC(b##i, wp_); const int nk_ = __builtin_amdgcn_readlane(ksel, nb + i); P4_LOAD(b##i, Vg, nk_); }
; #define P4_V(i) { const unsigned wu_ = (unsigned)__builtin_amdgcn_readlane((int)__float_as_uint(wreg), i); const unsigned long long wp_ = ((unsigned long long)wu_ << 32) | wu_; \
;               P4_ACC(b##i, wp_); const int nk_ = __builtin_amdgcn_readlane(kn, i); P4_LOAD(b##i, Vg, nk_); }
; #define P4_V(i) { const unsigned wu_ = (unsigned)__builtin_amdgcn_readlane((int)__float_as_uint(wreg), i); const unsigned long long wp_ = ((unsigned long long)wu_ << 32) | wu_; \
;               P4_ACC(b##i, wp_); }
; __device__ __forceinline__ void peer_gather_f4p(const float* X, const int* __restrict__ IDX, const float* __restrict__ G, ...
;     ...
;             if (kt < 3) {
;     ...
;                 P4_FOR16(P4_V)
	v_cvt_scalef32_pk_f32_fp4 v[108:109], v44, 1.0
	s_lshr_b32 s16, s16, 7
	s_mov_b32 s17, s86
	s_mov_b32 s41, s40
	v_cvt_scalef32_pk_f32_fp4 v[110:111], v44, 1.0 op_sel:[1,0,0]
	v_cvt_scalef32_pk_f32_fp4 v[112:113], v44, 1.0 op_sel:[0,1,0]
	v_cvt_scalef32_pk_f32_fp4 v[114:115], v44, 1.0 op_sel:[1,1,0]
	v_pk_fma_f32 v[194:195], s[40:41], v[108:109], v[194:195]
	s_lshl_b64 s[16:17], s[16:17], 10
	v_pk_fma_f32 v[196:197], s[40:41], v[110:111], v[196:197]
	v_pk_fma_f32 v[190:191], s[40:41], v[112:113], v[190:191]
	v_pk_fma_f32 v[192:193], s[40:41], v[114:115], v[192:193]
	v_cvt_scalef32_pk_f32_fp4 v[108:109], v45, 1.0
	v_cvt_scalef32_pk_f32_fp4 v[110:111], v45, 1.0 op_sel:[1,0,0]
	v_cvt_scalef32_pk_f32_fp4 v[112:113], v45, 1.0 op_sel:[0,1,0]
	v_cvt_scalef32_pk_f32_fp4 v[114:115], v45, 1.0 op_sel:[1,1,0]
	s_add_u32 s16, s52, s16
	v_pk_fma_f32 v[186:187], s[40:41], v[108:109], v[186:187]
	v_pk_fma_f32 v[188:189], s[40:41], v[110:111], v[188:189]
	v_pk_fma_f32 v[182:183], s[40:41], v[112:113], v[182:183]
	v_pk_fma_f32 v[184:185], s[40:41], v[114:115], v[184:185]
	v_cvt_scalef32_pk_f32_fp4 v[108:109], v46, 1.0
	v_cvt_scalef32_pk_f32_fp4 v[110:111], v46, 1.0 op_sel:[1,0,0]
	v_cvt_scalef32_pk_f32_fp4 v[112:113], v46, 1.0 op_sel:[0,1,0]
	v_cvt_scalef32_pk_f32_fp4 v[114:115], v46, 1.0 op_sel:[1,1,0]
	s_addc_u32 s17, s53, s17
	v_pk_fma_f32 v[178:179], s[40:41], v[108:109], v[178:179]
	v_pk_fma_f32 v[180:181], s[40:41], v[110:111], v[180:181]
	v_pk_fma_f32 v[174:175], s[40:41], v[112:113], v[174:175]
	v_pk_fma_f32 v[176:177], s[40:41], v[114:115], v[176:177]
	v_cvt_scalef32_pk_f32_fp4 v[108:109], v47, 1.0
	v_cvt_scalef32_pk_f32_fp4 v[110:111], v47, 1.0 op_sel:[1,0,0]
	v_cvt_scalef32_pk_f32_fp4 v[112:113], v47, 1.0 op_sel:[0,1,0]
	v_cvt_scalef32_pk_f32_fp4 v[114:115], v47, 1.0 op_sel:[1,1,0]
	s_nop 0
	v_pk_fma_f32 v[170:171], s[40:41], v[108:109], v[170:171]
	v_lshl_add_u64 v[108:109], s[16:17], 0, v[164:165]
	v_readlane_b32 s16, v208, 11
	v_pk_fma_f32 v[172:173], s[40:41], v[110:111], v[172:173]
	v_pk_fma_f32 v[166:167], s[40:41], v[112:113], v[166:167]
	v_pk_fma_f32 v[168:169], s[40:41], v[114:115], v[168:169]
	global_load_dwordx4 v[108:111], v[108:109], off
	v_readlane_b32 s40, v209, 11
	s_waitcnt vmcnt(15)
	v_cvt_scalef32_pk_f32_fp4 v[112:113], v48, 1.0
	s_lshr_b32 s16, s16, 7
	s_mov_b32 s17, s86
	s_mov_b32 s41, s40
	v_cvt_scalef32_pk_f32_fp4 v[114:115], v48, 1.0 op_sel:[1,0,0]
	v_cvt_scalef32_pk_f32_fp4 v[116:117], v48, 1.0 op_sel:[0,1,0]
	v_cvt_scalef32_pk_f32_fp4 v[118:119], v48, 1.0 op_sel:[1,1,0]
	v_pk_fma_f32 v[194:195], s[40:41], v[112:113], v[194:195]
	s_lshl_b64 s[16:17], s[16:17], 10
	v_pk_fma_f32 v[196:197], s[40:41], v[114:115], v[196:197]
	v_pk_fma_f32 v[190:191], s[40:41], v[116:117], v[190:191]
	v_pk_fma_f32 v[192:193], s[40:41], v[118:119], v[192:193]
	v_cvt_scalef32_pk_f32_fp4 v[112:113], v49, 1.0
	v_cvt_scalef32_pk_f32_fp4 v[114:115], v49, 1.0 op_sel:[1,0,0]
	v_cvt_scalef32_pk_f32_fp4 v[116:117], v49, 1.0 op_sel:[0,1,0]
	v_cvt_scalef32_pk_f32_fp4 v[118:119], v49, 1.0 op_sel:[1,1,0]
	s_add_u32 s16, s52, s16
	v_pk_fma_f32 v[186:187], s[40:41], v[112:113], v[186:187]
	v_pk_fma_f32 v[188:189], s[40:41], v[114:115], v[188:189]
	v_pk_fma_f32 v[182:183], s[40:41], v[116:117], v[182:183]
	v_pk_fma_f32 v[184:185], s[40:41], v[118:119], v[184:185]
	v_cvt_scalef32_pk_f32_fp4 v[112:113], v50, 1.0
	v_cvt_scalef32_pk_f32_fp4 v[114:115], v50, 1.0 op_sel:[1,0,0]
	v_cvt_scalef32_pk_f32_fp4 v[116:117], v50, 1.0 op_sel:[0,1,0]
	v_cvt_scalef32_pk_f32_fp4 v[118:119], v50, 1.0 op_sel:[1,1,0]
	s_addc_u32 s17, s53, s17
	v_pk_fma_f32 v[178:179], s[40:41], v[112:113], v[178:179]
	v_pk_fma_f32 v[180:181], s[40:41], v[114:115], v[180:181]
	v_pk_fma_f32 v[174:175], s[40:41], v[116:117], v[174:175]
	v_pk_fma_f32 v[176:177], s[40:41], v[118:119], v[176:177]
	v_cvt_scalef32_pk_f32_fp4 v[112:113], v51, 1.0
	v_cvt_scalef32_pk_f32_fp4 v[114:115], v51, 1.0 op_sel:[1,0,0]
	v_cvt_scalef32_pk_f32_fp4 v[116:117], v51, 1.0 op_sel:[0,1,0]
	v_cvt_scalef32_pk_f32_fp4 v[118:119], v51, 1.0 op_sel:[1,1,0]
	s_nop 0
	v_pk_fma_f32 v[170:171], s[40:41], v[112:113], v[170:171]
	v_lshl_add_u64 v[112:113], s[16:17], 0, v[164:165]
	v_readlane_b32 s16, v208, 12
	v_pk_fma_f32 v[172:173], s[40:41], v[114:115], v[172:173]
	v_pk_fma_f32 v[166:167], s[40:41], v[116:117], v[166:167]
	v_pk_fma_f32 v[168:169], s[40:41], v[118:119], v[168:169]
	global_load_dwordx4 v[112:115], v[112:113], off
	v_readlane_b32 s40, v209, 12
	s_waitcnt vmcnt(15)
	v_cvt_scalef32_pk_f32_fp4 v[116:117], v52, 1.0
	s_lshr_b32 s16, s16, 7
	s_mov_b32 s17, s86
	s_mov_b32 s41, s40
	v_cvt_scalef32_pk_f32_fp4 v[118:119], v52, 1.0 op_sel:[1,0,0]
	v_cvt_scalef32_pk_f32_fp4 v[120:121], v52, 1.0 op_sel:[0,1,0]
	v_cvt_scalef32_pk_f32_fp4 v[122:123], v52, 1.0 op_sel:[1,1,0]
	v_pk_fma_f32 v[194:195], s[40:41], v[116:117], v[194:195]
	s_lshl_b64 s[16:17], s[16:17], 10
	v_pk_fma_f32 v[196:197], s[40:41], v[118:119], v[196:197]
	v_pk_fma_f32 v[190:191], s[40:41], v[120:121], v[190:191]
	v_pk_fma_f32 v[192:193], s[40:41], v[122:123], v[192:193]
	v_cvt_scalef32_pk_f32_fp4 v[116:117], v53, 1.0
	v_cvt_scalef32_pk_f32_fp4 v[118:119], v53, 1.0 op_sel:[1,0,0]
	v_cvt_scalef32_pk_f32_fp4 v[120:121], v53, 1.0 op_sel:[0,1,0]
	v_cvt_scalef32_pk_f32_fp4 v[122:123], v53, 1.0 op_sel:[1,1,0]
	s_add_u32 s16, s52, s16
	v_pk_fma_f32 v[186:187], s[40:41], v[116:117], v[186:187]
	v_pk_fma_f32 v[188:189], s[40:41], v[118:119], v[188:189]
	v_pk_fma_f32 v[182:183], s[40:41], v[120:121], v[182:183]
	v_pk_fma_f32 v[184:185], s[40:41], v[122:123], v[184:185]
	v_cvt_scalef32_pk_f32_fp4 v[116:117], v54, 1.0
	v_cvt_scalef32_pk_f32_fp4 v[118:119], v54, 1.0 op_sel:[1,0,0]
	v_cvt_scalef32_pk_f32_fp4 v[120:121], v54, 1.0 op_sel:[0,1,0]
	v_cvt_scalef32_pk_f32_fp4 v[122:123], v54, 1.0 op_sel:[1,1,0]
	s_addc_u32 s17, s53, s17
	v_pk_fma_f32 v[178:179], s[40:41], v[116:117], v[178:179]
	v_pk_fma_f32 v[180:181], s[40:41], v[118:119], v[180:181]
	v_pk_fma_f32 v[174:175], s[40:41], v[120:121], v[174:175]
	v_pk_fma_f32 v[176:177], s[40:41], v[122:123], v[176:177]
	v_cvt_scalef32_pk_f32_fp4 v[116:117], v55, 1.0
	v_cvt_scalef32_pk_f32_fp4 v[118:119], v55, 1.0 op_sel:[1,0,0]
	v_cvt_scalef32_pk_f32_fp4 v[120:121], v55, 1.0 op_sel:[0,1,0]
	v_cvt_scalef32_pk_f32_fp4 v[122:123], v55, 1.0 op_sel:[1,1,0]
	s_nop 0
	v_pk_fma_f32 v[170:171], s[40:41], v[116:117], v[170:171]
	v_lshl_add_u64 v[116:117], s[16:17], 0, v[164:165]
	v_readlane_b32 s16, v208, 13
	v_pk_fma_f32 v[172:173], s[40:41], v[118:119], v[172:173]
	v_pk_fma_f32 v[166:167], s[40:41], v[120:121], v[166:167]
	v_pk_fma_f32 v[168:169], s[40:41], v[122:123], v[168:169]
	global_load_dwordx4 v[116:119], v[116:117], off
	v_readlane_b32 s40, v209, 13
	s_waitcnt vmcnt(15)
; #define P4_FOR16(M) M(0) M(1) M(2) M(3) M(4) M(5) M(6) M(7) M(8) M(9) M(10) M(11) M(12) M(13) M(14) M(15)
; #define P4_V(i) { const unsigned wu_ = (unsigned)__builtin_amdgcn_readlane((int)__float_as_uint(wreg), i); const unsigned long long wp_ = ((unsigned long long)wu_ << 32) | wu_; \
;               P4_ACC(b##i, wp_); const int nk_ = __builtin_amdgcn_readlane(ksel, nb + i); P4_LOAD(b##i, Vg, nk_); }
; #define P4_V(i) { const unsigned wu_ = (unsigned)__builtin_amdgcn_readlane((int)__float_as_uint(wreg), i); const unsigned long long wp_ = ((unsigned long long)wu_ << 32) | wu_; \
;               P4_ACC(b##i, wp_); const int nk_ = __builtin_amdgcn_readlane(kn, i); P4_LOAD(b##i, Vg, nk_); }
; #define P4_V(i) { const unsigned wu_ = (unsigned)__builtin_amdgcn_readlane((int)__float_as_uint(wreg), i); const unsigned long long wp_ = ((unsigned long long)wu_ << 32) | wu_; \
;               P4_ACC(b##i, wp_); }
; __device__ __forceinline__ void peer_gather_f4p(const float* X, const int* __restrict__ IDX, const float* __restrict__ G, ...
;     ...
;             if (kt < 3) {
;     ...
;                 P4_FOR16(P4_V)
	v_cvt_scalef32_pk_f32_fp4 v[120:121], v56, 1.0
	s_lshr_b32 s16, s16, 7
	s_mov_b32 s17, s86
	s_mov_b32 s41, s40
	v_cvt_scalef32_pk_f32_fp4 v[122:123], v56, 1.0 op_sel:[1,0,0]
	v_cvt_scalef32_pk_f32_fp4 v[124:125], v56, 1.0 op_sel:[0,1,0]
	v_cvt_scalef32_pk_f32_fp4 v[126:127], v56, 1.0 op_sel:[1,1,0]
	v_pk_fma_f32 v[194:195], s[40:41], v[120:121], v[194:195]
	s_lshl_b64 s[16:17], s[16:17], 10
	v_pk_fma_f32 v[196:197], s[40:41], v[122:123], v[196:197]
	v_pk_fma_f32 v[190:191], s[40:41], v[124:125], v[190:191]
	v_pk_fma_f32 v[192:193], s[40:41], v[126:127], v[192:193]
	v_cvt_scalef32_pk_f32_fp4 v[120:121], v57, 1.0
	v_cvt_scalef32_pk_f32_fp4 v[122:123], v57, 1.0 op_sel:[1,0,0]
	v_cvt_scalef32_pk_f32_fp4 v[124:125], v57, 1.0 op_sel:[0,1,0]
	v_cvt_scalef32_pk_f32_fp4 v[126:127], v57, 1.0 op_sel:[1,1,0]
	s_add_u32 s16, s52, s16
	v_pk_fma_f32 v[186:187], s[40:41], v[120:121], v[186:187]
	v_pk_fma_f32 v[188:189], s[40:41], v[122:123], v[188:189]
	v_pk_fma_f32 v[182:183], s[40:41], v[124:125], v[182:183]
	v_pk_fma_f32 v[184:185], s[40:41], v[126:127], v[184:185]
	v_cvt_scalef32_pk_f32_fp4 v[120:121], v58, 1.0
	v_cvt_scalef32_pk_f32_fp4 v[122:123], v58, 1.0 op_sel:[1,0,0]
	v_cvt_scalef32_pk_f32_fp4 v[124:125], v58, 1.0 op_sel:[0,1,0]
	v_cvt_scalef32_pk_f32_fp4 v[126:127], v58, 1.0 op_sel:[1,1,0]
	s_addc_u32 s17, s53, s17
	v_pk_fma_f32 v[178:179], s[40:41], v[120:121], v[178:179]
	v_pk_fma_f32 v[180:181], s[40:41], v[122:123], v[180:181]
	v_pk_fma_f32 v[174:175], s[40:41], v[124:125], v[174:175]
	v_pk_fma_f32 v[176:177], s[40:41], v[126:127], v[176:177]
	v_cvt_scalef32_pk_f32_fp4 v[120:121], v59, 1.0
	v_cvt_scalef32_pk_f32_fp4 v[122:123], v59, 1.0 op_sel:[1,0,0]
	v_cvt_scalef32_pk_f32_fp4 v[124:125], v59, 1.0 op_sel:[0,1,0]
	v_cvt_scalef32_pk_f32_fp4 v[126:127], v59, 1.0 op_sel:[1,1,0]
	s_nop 0
	v_pk_fma_f32 v[170:171], s[40:41], v[120:121], v[170:171]
	v_lshl_add_u64 v[120:121], s[16:17], 0, v[164:165]
	v_readlane_b32 s16, v208, 14
	v_pk_fma_f32 v[172:173], s[40:41], v[122:123], v[172:173]
	v_pk_fma_f32 v[166:167], s[40:41], v[124:125], v[166:167]
	v_pk_fma_f32 v[168:169], s[40:41], v[126:127], v[168:169]
	global_load_dwordx4 v[120:123], v[120:121], off
	v_readlane_b32 s40, v209, 14
	s_waitcnt vmcnt(15)
	v_cvt_scalef32_pk_f32_fp4 v[124:125], v60, 1.0
	s_lshr_b32 s16, s16, 7
	s_mov_b32 s17, s86
	s_mov_b32 s41, s40
	v_cvt_scalef32_pk_f32_fp4 v[126:127], v60, 1.0 op_sel:[1,0,0]
	v_cvt_scalef32_pk_f32_fp4 v[128:129], v60, 1.0 op_sel:[0,1,0]
	v_cvt_scalef32_pk_f32_fp4 v[130:131], v60, 1.0 op_sel:[1,1,0]
	v_pk_fma_f32 v[194:195], s[40:41], v[124:125], v[194:195]
	s_lshl_b64 s[16:17], s[16:17], 10
	v_pk_fma_f32 v[196:197], s[40:41], v[126:127], v[196:197]
	v_pk_fma_f32 v[190:191], s[40:41], v[128:129], v[190:191]
	v_pk_fma_f32 v[192:193], s[40:41], v[130:131], v[192:193]
	v_cvt_scalef32_pk_f32_fp4 v[124:125], v61, 1.0
	v_cvt_scalef32_pk_f32_fp4 v[126:127], v61, 1.0 op_sel:[1,0,0]
	v_cvt_scalef32_pk_f32_fp4 v[128:129], v61, 1.0 op_sel:[0,1,0]
	v_cvt_scalef32_pk_f32_fp4 v[130:131], v61, 1.0 op_sel:[1,1,0]
	s_add_u32 s16, s52, s16
	v_pk_fma_f32 v[186:187], s[40:41], v[124:125], v[186:187]
	v_pk_fma_f32 v[188:189], s[40:41], v[126:127], v[188:189]
	v_pk_fma_f32 v[182:183], s[40:41], v[128:129], v[182:183]
	v_pk_fma_f32 v[184:185], s[40:41], v[130:131], v[184:185]
	v_cvt_scalef32_pk_f32_fp4 v[124:125], v62, 1.0
	v_cvt_scalef32_pk_f32_fp4 v[126:127], v62, 1.0 op_sel:[1,0,0]
	v_cvt_scalef32_pk_f32_fp4 v[128:129], v62, 1.0 op_sel:[0,1,0]
	v_cvt_scalef32_pk_f32_fp4 v[130:131], v62, 1.0 op_sel:[1,1,0]
	s_addc_u32 s17, s53, s17
	v_pk_fma_f32 v[178:179], s[40:41], v[124:125], v[178:179]
	v_pk_fma_f32 v[180:181], s[40:41], v[126:127], v[180:181]
	v_pk_fma_f32 v[174:175], s[40:41], v[128:129], v[174:175]
	v_pk_fma_f32 v[176:177], s[40:41], v[130:131], v[176:177]
	v_cvt_scalef32_pk_f32_fp4 v[124:125], v63, 1.0
	v_cvt_scalef32_pk_f32_fp4 v[126:127], v63, 1.0 op_sel:[1,0,0]
	v_cvt_scalef32_pk_f32_fp4 v[128:129], v63, 1.0 op_sel:[0,1,0]
	v_cvt_scalef32_pk_f32_fp4 v[130:131], v63, 1.0 op_sel:[1,1,0]
	s_nop 0
	v_pk_fma_f32 v[170:171], s[40:41], v[124:125], v[170:171]
	v_lshl_add_u64 v[124:125], s[16:17], 0, v[164:165]
	v_readlane_b32 s16, v208, 15
	v_pk_fma_f32 v[172:173], s[40:41], v[126:127], v[172:173]
	v_pk_fma_f32 v[166:167], s[40:41], v[128:129], v[166:167]
	v_pk_fma_f32 v[168:169], s[40:41], v[130:131], v[168:169]
	global_load_dwordx4 v[124:127], v[124:125], off
	v_readlane_b32 s40, v209, 15
	s_waitcnt vmcnt(15)
	v_cvt_scalef32_pk_f32_fp4 v[128:129], v100, 1.0
	s_lshr_b32 s16, s16, 7
	s_mov_b32 s17, s86
	s_mov_b32 s41, s40
	v_cvt_scalef32_pk_f32_fp4 v[130:131], v100, 1.0 op_sel:[1,0,0]
	v_cvt_scalef32_pk_f32_fp4 v[210:211], v100, 1.0 op_sel:[0,1,0]
	v_cvt_scalef32_pk_f32_fp4 v[212:213], v100, 1.0 op_sel:[1,1,0]
	v_pk_fma_f32 v[194:195], s[40:41], v[128:129], v[194:195]
	s_lshl_b64 s[16:17], s[16:17], 10
	v_pk_fma_f32 v[196:197], s[40:41], v[130:131], v[196:197]
	v_pk_fma_f32 v[190:191], s[40:41], v[210:211], v[190:191]
	v_pk_fma_f32 v[192:193], s[40:41], v[212:213], v[192:193]
	v_cvt_scalef32_pk_f32_fp4 v[128:129], v101, 1.0
	v_cvt_scalef32_pk_f32_fp4 v[130:131], v101, 1.0 op_sel:[1,0,0]
	v_cvt_scalef32_pk_f32_fp4 v[210:211], v101, 1.0 op_sel:[0,1,0]
	v_cvt_scalef32_pk_f32_fp4 v[212:213], v101, 1.0 op_sel:[1,1,0]
	s_add_u32 s16, s52, s16
	v_pk_fma_f32 v[186:187], s[40:41], v[128:129], v[186:187]
	v_pk_fma_f32 v[188:189], s[40:41], v[130:131], v[188:189]
	v_pk_fma_f32 v[182:183], s[40:41], v[210:211], v[182:183]
	v_pk_fma_f32 v[184:185], s[40:41], v[212:213], v[184:185]
	v_cvt_scalef32_pk_f32_fp4 v[128:129], v102, 1.0
	v_cvt_scalef32_pk_f32_fp4 v[130:131], v102, 1.0 op_sel:[1,0,0]
	v_cvt_scalef32_pk_f32_fp4 v[210:211], v102, 1.0 op_sel:[0,1,0]
	v_cvt_scalef32_pk_f32_fp4 v[212:213], v102, 1.0 op_sel:[1,1,0]
	s_addc_u32 s17, s53, s17
	v_pk_fma_f32 v[178:179], s[40:41], v[128:129], v[178:179]
	v_pk_fma_f32 v[180:181], s[40:41], v[130:131], v[180:181]
	v_pk_fma_f32 v[174:175], s[40:41], v[210:211], v[174:175]
	v_pk_fma_f32 v[176:177], s[40:41], v[212:213], v[176:177]
	v_cvt_scalef32_pk_f32_fp4 v[128:129], v103, 1.0
	v_cvt_scalef32_pk_f32_fp4 v[130:131], v103, 1.0 op_sel:[1,0,0]
	v_cvt_scalef32_pk_f32_fp4 v[210:211], v103, 1.0 op_sel:[0,1,0]
	v_cvt_scalef32_pk_f32_fp4 v[212:213], v103, 1.0 op_sel:[1,1,0]
	s_nop 0
	v_pk_fma_f32 v[170:171], s[40:41], v[128:129], v[170:171]
	v_lshl_add_u64 v[128:129], s[16:17], 0, v[164:165]
	v_pk_fma_f32 v[172:173], s[40:41], v[130:131], v[172:173]
	v_pk_fma_f32 v[166:167], s[40:41], v[210:211], v[166:167]
	v_pk_fma_f32 v[168:169], s[40:41], v[212:213], v[168:169]
	global_load_dwordx4 v[128:131], v[128:129], off
	s_mov_b64 s[40:41], 0

; #define P4_FOR16(M) M(0) M(1) M(2) M(3) M(4) M(5) M(6) M(7) M(8) M(9) M(10) M(11) M(12) M(13) M(14) M(15)
; #define P4_U(i) { P4_DOT(b##i, part[i]); const int nk_ = __builtin_amdgcn_readlane(ksel, nb + i); P4_LOAD(b##i, Ug, nk_); }
; #define P4_U(i) { P4_DOT(b##i, part[i]); const int nk_ = __builtin_amdgcn_readlane(kn, i); P4_LOAD(b##i, nbase, nk_); }
; __device__ __forceinline__ void peer_gather_f4p(const float* X, const int* __restrict__ IDX, const float* __restrict__ G, ...
;     ...
; #pragma unroll 1
;         for (int bt = 0; bt < 7; ++bt) {
;             const int ksel = (bt + 1 < 4) ? k0 : k1;
;             const int nb = (16 * (bt + 1)) & 63;
;     ...
;             P4_FOR16(P4_U)
;     ...
;             P4_RED(bt);
;         }
.LBB0_1230:
	s_mov_b32 s87, s86
	s_waitcnt vmcnt(15)
	v_cvt_scalef32_pk_bf16_fp4 v48, v64, 1.0
	v_cvt_scalef32_pk_bf16_fp4 v50, v64, 1.0 op_sel:[1,0,0]
	v_cvt_scalef32_pk_bf16_fp4 v52, v64, 1.0 op_sel:[0,1,0]
	v_cvt_scalef32_pk_bf16_fp4 v54, v64, 1.0 op_sel:[1,1,0]
	v_dot2_f32_bf16 v56, v48, v6, 0
	v_dot2_f32_bf16 v48, v50, v4, 0
	v_dot2_f32_bf16 v56, v52, v10, v56
	s_cmp_lt_u32 s29, 3
	v_dot2_f32_bf16 v48, v54, v8, v48
	v_cvt_scalef32_pk_bf16_fp4 v50, v65, 1.0
	v_cvt_scalef32_pk_bf16_fp4 v52, v65, 1.0 op_sel:[1,0,0]
	v_cvt_scalef32_pk_bf16_fp4 v54, v65, 1.0 op_sel:[0,1,0]
	v_cvt_scalef32_pk_bf16_fp4 v58, v65, 1.0 op_sel:[1,1,0]
	s_cselect_b64 s[48:49], -1, 0
	v_dot2_f32_bf16 v56, v50, v14, v56
	v_dot2_f32_bf16 v48, v52, v12, v48
	s_waitcnt lgkmcnt(1)
	v_cndmask_b32_e64 v46, v39, v38, s[48:49]
	v_dot2_f32_bf16 v56, v54, v18, v56
	v_dot2_f32_bf16 v48, v58, v16, v48
	v_cvt_scalef32_pk_bf16_fp4 v50, v66, 1.0
	v_cvt_scalef32_pk_bf16_fp4 v52, v66, 1.0 op_sel:[1,0,0]
	v_cvt_scalef32_pk_bf16_fp4 v54, v66, 1.0 op_sel:[0,1,0]
	v_cvt_scalef32_pk_bf16_fp4 v58, v66, 1.0 op_sel:[1,1,0]
	s_add_i32 s12, s28, -15
	v_dot2_f32_bf16 v56, v50, v22, v56
	v_dot2_f32_bf16 v48, v52, v20, v48
	v_readlane_b32 s12, v46, s12
	v_dot2_f32_bf16 v56, v54, v26, v56
	v_dot2_f32_bf16 v48, v58, v24, v48
	v_cvt_scalef32_pk_bf16_fp4 v50, v67, 1.0
	v_cvt_scalef32_pk_bf16_fp4 v52, v67, 1.0 op_sel:[1,0,0]
	v_cvt_scalef32_pk_bf16_fp4 v54, v67, 1.0 op_sel:[0,1,0]
	v_cvt_scalef32_pk_bf16_fp4 v58, v67, 1.0 op_sel:[1,1,0]
	s_lshr_b32 s12, s12, 7
	v_dot2_f32_bf16 v56, v50, v30, v56
	v_dot2_f32_bf16 v48, v52, v28, v48
	s_mov_b32 s13, s86
	v_dot2_f32_bf16 v56, v54, v36, v56
	v_dot2_f32_bf16 v48, v58, v34, v48
	s_lshl_b64 s[12:13], s[12:13], 10
	s_nop 2
	v_readfirstlane_b32 s100, v40
	v_readfirstlane_b32 s101, v41
	v_subrev_u32_e32 v207, s100, v40
	v_add_f32_e32 v47, v56, v48
	s_add_u32 s12, s12, s100
	s_addc_u32 s13, s13, s101
	global_load_dwordx4 v[64:67], v207, s[12:13]
	s_waitcnt vmcnt(15)
	v_cvt_scalef32_pk_bf16_fp4 v48, v68, 1.0
	v_cvt_scalef32_pk_bf16_fp4 v50, v68, 1.0 op_sel:[1,0,0]
	v_cvt_scalef32_pk_bf16_fp4 v52, v68, 1.0 op_sel:[0,1,0]
	v_cvt_scalef32_pk_bf16_fp4 v54, v68, 1.0 op_sel:[1,1,0]
	v_dot2_f32_bf16 v56, v48, v6, 0
	v_dot2_f32_bf16 v48, v50, v4, 0
	v_dot2_f32_bf16 v56, v52, v10, v56
	s_add_i32 s12, s28, -14
	v_dot2_f32_bf16 v48, v54, v8, v48
	v_cvt_scalef32_pk_bf16_fp4 v50, v69, 1.0
	v_cvt_scalef32_pk_bf16_fp4 v52, v69, 1.0 op_sel:[1,0,0]
	v_cvt_scalef32_pk_bf16_fp4 v54, v69, 1.0 op_sel:[0,1,0]
	v_cvt_scalef32_pk_bf16_fp4 v58, v69, 1.0 op_sel:[1,1,0]
	v_readlane_b32 s12, v46, s12
	v_dot2_f32_bf16 v56, v50, v14, v56
	v_dot2_f32_bf16 v48, v52, v12, v48
	s_lshr_b32 s12, s12, 7
	v_dot2_f32_bf16 v56, v54, v18, v56
	v_dot2_f32_bf16 v48, v58, v16, v48
	v_cvt_scalef32_pk_bf16_fp4 v50, v70, 1.0
	v_cvt_scalef32_pk_bf16_fp4 v52, v70, 1.0 op_sel:[1,0,0]
	v_cvt_scalef32_pk_bf16_fp4 v54, v70, 1.0 op_sel:[0,1,0]
	v_cvt_scalef32_pk_bf16_fp4 v58, v70, 1.0 op_sel:[1,1,0]
	s_mov_b32 s13, s86
	v_dot2_f32_bf16 v56, v50, v22, v56
	v_dot2_f32_bf16 v48, v52, v20, v48
	s_lshl_b64 s[12:13], s[12:13], 10
	v_dot2_f32_bf16 v56, v54, v26, v56
	v_dot2_f32_bf16 v48, v58, v24, v48
	v_cvt_scalef32_pk_bf16_fp4 v50, v71, 1.0
	v_cvt_scalef32_pk_bf16_fp4 v52, v71, 1.0 op_sel:[1,0,0]
	v_cvt_scalef32_pk_bf16_fp4 v54, v71, 1.0 op_sel:[0,1,0]
	v_cvt_scalef32_pk_bf16_fp4 v58, v71, 1.0 op_sel:[1,1,0]
	v_mov_b32_e32 v42, 0
	v_dot2_f32_bf16 v56, v50, v30, v56
	v_dot2_f32_bf16 v48, v52, v28, v48
	s_nop 0
	v_dot2_f32_bf16 v56, v54, v36, v56
	v_dot2_f32_bf16 v48, v58, v34, v48
	s_nop 2
	v_add_f32_e32 v48, v56, v48
	s_add_u32 s12, s12, s100
	s_addc_u32 s13, s13, s101
	global_load_dwordx4 v[68:71], v207, s[12:13]
	s_waitcnt vmcnt(15)
	v_cvt_scalef32_pk_bf16_fp4 v50, v72, 1.0
	v_cvt_scalef32_pk_bf16_fp4 v52, v72, 1.0 op_sel:[1,0,0]
	v_cvt_scalef32_pk_bf16_fp4 v54, v72, 1.0 op_sel:[0,1,0]
	v_cvt_scalef32_pk_bf16_fp4 v56, v72, 1.0 op_sel:[1,1,0]
	s_add_i32 s12, s28, -13
	v_dot2_f32_bf16 v58, v50, v6, 0
	v_dot2_f32_bf16 v50, v52, v4, 0
	v_dot2_f32_bf16 v58, v54, v10, v58
	v_readlane_b32 s12, v46, s12
	v_dot2_f32_bf16 v50, v56, v8, v50
	v_cvt_scalef32_pk_bf16_fp4 v52, v73, 1.0
	v_cvt_scalef32_pk_bf16_fp4 v54, v73, 1.0 op_sel:[1,0,0]
	v_cvt_scalef32_pk_bf16_fp4 v56, v73, 1.0 op_sel:[0,1,0]
	v_cvt_scalef32_pk_bf16_fp4 v60, v73, 1.0 op_sel:[1,1,0]
	s_lshr_b32 s12, s12, 7
	v_dot2_f32_bf16 v58, v52, v14, v58
	v_dot2_f32_bf16 v50, v54, v12, v50
	s_mov_b32 s13, s86
	v_dot2_f32_bf16 v58, v56, v18, v58
	v_dot2_f32_bf16 v50, v60, v16, v50
	v_cvt_scalef32_pk_bf16_fp4 v52, v74, 1.0
	v_cvt_scalef32_pk_bf16_fp4 v54, v74, 1.0 op_sel:[1,0,0]
	v_cvt_scalef32_pk_bf16_fp4 v56, v74, 1.0 op_sel:[0,1,0]
	v_cvt_scalef32_pk_bf16_fp4 v60, v74, 1.0 op_sel:[1,1,0]
	s_lshl_b64 s[12:13], s[12:13], 10
	v_dot2_f32_bf16 v58, v52, v22, v58
	v_dot2_f32_bf16 v50, v54, v20, v50
	s_nop 0
	v_dot2_f32_bf16 v58, v56, v26, v58
	v_dot2_f32_bf16 v50, v60, v24, v50
	v_cvt_scalef32_pk_bf16_fp4 v52, v75, 1.0
	v_cvt_scalef32_pk_bf16_fp4 v54, v75, 1.0 op_sel:[1,0,0]
	v_cvt_scalef32_pk_bf16_fp4 v56, v75, 1.0 op_sel:[0,1,0]
	v_cvt_scalef32_pk_bf16_fp4 v60, v75, 1.0 op_sel:[1,1,0]
	s_nop 0
	v_dot2_f32_bf16 v58, v52, v30, v58
	v_dot2_f32_bf16 v50, v54, v28, v50
	s_nop 0
	v_dot2_f32_bf16 v58, v56, v36, v58
	v_dot2_f32_bf16 v50, v60, v34, v50
	s_nop 0
	s_nop 2
	v_add_f32_e32 v49, v58, v50
	s_add_u32 s12, s12, s100
	s_addc_u32 s13, s13, s101
	global_load_dwordx4 v[72:75], v207, s[12:13]
	s_waitcnt vmcnt(15)
; #define P4_FOR16(M) M(0) M(1) M(2) M(3) M(4) M(5) M(6) M(7) M(8) M(9) M(10) M(11) M(12) M(13) M(14) M(15)
; #define P4_U(i) { P4_DOT(b##i, part[i]); const int nk_ = __builtin_amdgcn_readlane(ksel, nb + i); P4_LOAD(b##i, Ug, nk_); }
; #define P4_U(i) { P4_DOT(b##i, part[i]); const int nk_ = __builtin_amdgcn_readlane(kn, i); P4_LOAD(b##i, nbase, nk_); }
; __device__ __forceinline__ void peer_gather_f4p(const float* X, const int* __restrict__ IDX, const float* __restrict__ G, ...
;     ...
; #pragma unroll 1
;         for (int bt = 0; bt < 7; ++bt) {
;             const int ksel = (bt + 1 < 4) ? k0 : k1;
;             const int nb = (16 * (bt + 1)) & 63;
;     ...
;             P4_FOR16(P4_U)
;     ...
;             P4_RED(bt);
;         }
	v_cvt_scalef32_pk_bf16_fp4 v50, v76, 1.0
	v_cvt_scalef32_pk_bf16_fp4 v52, v76, 1.0 op_sel:[1,0,0]
	v_cvt_scalef32_pk_bf16_fp4 v54, v76, 1.0 op_sel:[0,1,0]
	v_cvt_scalef32_pk_bf16_fp4 v56, v76, 1.0 op_sel:[1,1,0]
	v_dot2_f32_bf16 v58, v50, v6, 0
	v_dot2_f32_bf16 v50, v52, v4, 0
	v_dot2_f32_bf16 v58, v54, v10, v58
	s_add_i32 s12, s28, -12
	v_dot2_f32_bf16 v50, v56, v8, v50
	v_cvt_scalef32_pk_bf16_fp4 v52, v77, 1.0
	v_cvt_scalef32_pk_bf16_fp4 v54, v77, 1.0 op_sel:[1,0,0]
	v_cvt_scalef32_pk_bf16_fp4 v56, v77, 1.0 op_sel:[0,1,0]
	v_cvt_scalef32_pk_bf16_fp4 v60, v77, 1.0 op_sel:[1,1,0]
	v_readlane_b32 s12, v46, s12
	v_dot2_f32_bf16 v58, v52, v14, v58
	v_dot2_f32_bf16 v50, v54, v12, v50
	s_lshr_b32 s12, s12, 7
	v_dot2_f32_bf16 v58, v56, v18, v58
	v_dot2_f32_bf16 v50, v60, v16, v50
	v_cvt_scalef32_pk_bf16_fp4 v52, v78, 1.0
	v_cvt_scalef32_pk_bf16_fp4 v54, v78, 1.0 op_sel:[1,0,0]
	v_cvt_scalef32_pk_bf16_fp4 v56, v78, 1.0 op_sel:[0,1,0]
	v_cvt_scalef32_pk_bf16_fp4 v60, v78, 1.0 op_sel:[1,1,0]
	s_mov_b32 s13, s86
	v_dot2_f32_bf16 v58, v52, v22, v58
	v_dot2_f32_bf16 v50, v54, v20, v50
	s_lshl_b64 s[12:13], s[12:13], 10
	v_dot2_f32_bf16 v58, v56, v26, v58
	v_dot2_f32_bf16 v50, v60, v24, v50
	v_cvt_scalef32_pk_bf16_fp4 v52, v79, 1.0
	v_cvt_scalef32_pk_bf16_fp4 v54, v79, 1.0 op_sel:[1,0,0]
	v_cvt_scalef32_pk_bf16_fp4 v56, v79, 1.0 op_sel:[0,1,0]
	v_cvt_scalef32_pk_bf16_fp4 v60, v79, 1.0 op_sel:[1,1,0]
	s_nop 0
	v_dot2_f32_bf16 v58, v52, v30, v58
	v_dot2_f32_bf16 v50, v54, v28, v50
	s_nop 0
	v_dot2_f32_bf16 v58, v56, v36, v58
	v_dot2_f32_bf16 v50, v60, v34, v50
	s_nop 2
	v_add_f32_e32 v50, v58, v50
	s_add_u32 s12, s12, s100
	s_addc_u32 s13, s13, s101
	global_load_dwordx4 v[76:79], v207, s[12:13]
	s_waitcnt vmcnt(15)
	v_cvt_scalef32_pk_bf16_fp4 v52, v84, 1.0
	v_cvt_scalef32_pk_bf16_fp4 v54, v84, 1.0 op_sel:[1,0,0]
	v_cvt_scalef32_pk_bf16_fp4 v56, v84, 1.0 op_sel:[0,1,0]
	v_cvt_scalef32_pk_bf16_fp4 v58, v84, 1.0 op_sel:[1,1,0]
	s_add_i32 s12, s28, -11
	v_dot2_f32_bf16 v60, v52, v6, 0
	v_dot2_f32_bf16 v52, v54, v4, 0
	v_dot2_f32_bf16 v60, v56, v10, v60
	v_readlane_b32 s12, v46, s12
	v_dot2_f32_bf16 v52, v58, v8, v52
	v_cvt_scalef32_pk_bf16_fp4 v54, v85, 1.0
	v_cvt_scalef32_pk_bf16_fp4 v56, v85, 1.0 op_sel:[1,0,0]
	v_cvt_scalef32_pk_bf16_fp4 v58, v85, 1.0 op_sel:[0,1,0]
	v_cvt_scalef32_pk_bf16_fp4 v62, v85, 1.0 op_sel:[1,1,0]
	s_lshr_b32 s12, s12, 7
	v_dot2_f32_bf16 v60, v54, v14, v60
	v_dot2_f32_bf16 v52, v56, v12, v52
	s_mov_b32 s13, s86
	v_dot2_f32_bf16 v60, v58, v18, v60
	v_dot2_f32_bf16 v52, v62, v16, v52
	v_cvt_scalef32_pk_bf16_fp4 v54, v86, 1.0
	v_cvt_scalef32_pk_bf16_fp4 v56, v86, 1.0 op_sel:[1,0,0]
	v_cvt_scalef32_pk_bf16_fp4 v58, v86, 1.0 op_sel:[0,1,0]
	v_cvt_scalef32_pk_bf16_fp4 v62, v86, 1.0 op_sel:[1,1,0]
	s_lshl_b64 s[12:13], s[12:13], 10
	v_dot2_f32_bf16 v60, v54, v22, v60
	v_dot2_f32_bf16 v52, v56, v20, v52
	s_nop 0
	v_dot2_f32_bf16 v60, v58, v26, v60
	v_dot2_f32_bf16 v52, v62, v24, v52
	v_cvt_scalef32_pk_bf16_fp4 v54, v87, 1.0
	v_cvt_scalef32_pk_bf16_fp4 v56, v87, 1.0 op_sel:[1,0,0]
	v_cvt_scalef32_pk_bf16_fp4 v58, v87, 1.0 op_sel:[0,1,0]
	v_cvt_scalef32_pk_bf16_fp4 v62, v87, 1.0 op_sel:[1,1,0]
	s_nop 0
	v_dot2_f32_bf16 v60, v54, v30, v60
	v_dot2_f32_bf16 v52, v56, v28, v52
	s_nop 0
	v_dot2_f32_bf16 v60, v58, v36, v60
	v_dot2_f32_bf16 v52, v62, v34, v52
	s_nop 0
	s_nop 2
	v_add_f32_e32 v51, v60, v52
	s_add_u32 s12, s12, s100
	s_addc_u32 s13, s13, s101
	global_load_dwordx4 v[84:87], v207, s[12:13]
	s_waitcnt vmcnt(15)
	v_cvt_scalef32_pk_bf16_fp4 v52, v88, 1.0
	v_cvt_scalef32_pk_bf16_fp4 v54, v88, 1.0 op_sel:[1,0,0]
	v_cvt_scalef32_pk_bf16_fp4 v56, v88, 1.0 op_sel:[0,1,0]
	v_cvt_scalef32_pk_bf16_fp4 v58, v88, 1.0 op_sel:[1,1,0]
	v_dot2_f32_bf16 v60, v52, v6, 0
	v_dot2_f32_bf16 v52, v54, v4, 0
	v_dot2_f32_bf16 v60, v56, v10, v60
	s_add_i32 s12, s28, -10
	v_dot2_f32_bf16 v52, v58, v8, v52
	v_cvt_scalef32_pk_bf16_fp4 v54, v89, 1.0
	v_cvt_scalef32_pk_bf16_fp4 v56, v89, 1.0 op_sel:[1,0,0]
	v_cvt_scalef32_pk_bf16_fp4 v58, v89, 1.0 op_sel:[0,1,0]
	v_cvt_scalef32_pk_bf16_fp4 v62, v89, 1.0 op_sel:[1,1,0]
	v_readlane_b32 s12, v46, s12
	v_dot2_f32_bf16 v60, v54, v14, v60
	v_dot2_f32_bf16 v52, v56, v12, v52
	s_lshr_b32 s12, s12, 7
	v_dot2_f32_bf16 v60, v58, v18, v60
	v_dot2_f32_bf16 v52, v62, v16, v52
	v_cvt_scalef32_pk_bf16_fp4 v54, v90, 1.0
	v_cvt_scalef32_pk_bf16_fp4 v56, v90, 1.0 op_sel:[1,0,0]
	v_cvt_scalef32_pk_bf16_fp4 v58, v90, 1.0 op_sel:[0,1,0]
	v_cvt_scalef32_pk_bf16_fp4 v62, v90, 1.0 op_sel:[1,1,0]
	s_mov_b32 s13, s86
	v_dot2_f32_bf16 v60, v54, v22, v60
	v_dot2_f32_bf16 v52, v56, v20, v52
	s_lshl_b64 s[12:13], s[12:13], 10
	v_dot2_f32_bf16 v60, v58, v26, v60
	v_dot2_f32_bf16 v52, v62, v24, v52
	v_cvt_scalef32_pk_bf16_fp4 v54, v91, 1.0
	v_cvt_scalef32_pk_bf16_fp4 v56, v91, 1.0 op_sel:[1,0,0]
	v_cvt_scalef32_pk_bf16_fp4 v58, v91, 1.0 op_sel:[0,1,0]
	v_cvt_scalef32_pk_bf16_fp4 v62, v91, 1.0 op_sel:[1,1,0]
	s_nop 0
	v_dot2_f32_bf16 v60, v54, v30, v60
	v_dot2_f32_bf16 v52, v56, v28, v52
	s_nop 0
	v_dot2_f32_bf16 v60, v58, v36, v60
	v_dot2_f32_bf16 v52, v62, v34, v52
	s_nop 2
	v_add_f32_e32 v52, v60, v52
	s_add_u32 s12, s12, s100
	s_addc_u32 s13, s13, s101
	global_load_dwordx4 v[88:91], v207, s[12:13]
	s_waitcnt vmcnt(15)
; #define P4_FOR16(M) M(0) M(1) M(2) M(3) M(4) M(5) M(6) M(7) M(8) M(9) M(10) M(11) M(12) M(13) M(14) M(15)
; #define P4_U(i) { P4_DOT(b##i, part[i]); const int nk_ = __builtin_amdgcn_readlane(ksel, nb + i); P4_LOAD(b##i, Ug, nk_); }
; #define P4_U(i) { P4_DOT(b##i, part[i]); const int nk_ = __builtin_amdgcn_readlane(kn, i); P4_LOAD(b##i, nbase, nk_); }
; __device__ __forceinline__ void peer_gather_f4p(const float* X, const int* __restrict__ IDX, const float* __restrict__ G, ...
;     ...
; #pragma unroll 1
;         for (int bt = 0; bt < 7; ++bt) {
;             const int ksel = (bt + 1 < 4) ? k0 : k1;
;             const int nb = (16 * (bt + 1)) & 63;
;     ...
;             P4_FOR16(P4_U)
;     ...
;             P4_RED(bt);
;         }
	v_cvt_scalef32_pk_bf16_fp4 v54, v92, 1.0
	v_cvt_scalef32_pk_bf16_fp4 v56, v92, 1.0 op_sel:[1,0,0]
	v_cvt_scalef32_pk_bf16_fp4 v58, v92, 1.0 op_sel:[0,1,0]
	v_cvt_scalef32_pk_bf16_fp4 v60, v92, 1.0 op_sel:[1,1,0]
	s_add_i32 s12, s28, -9
	v_dot2_f32_bf16 v62, v54, v6, 0
	v_dot2_f32_bf16 v54, v56, v4, 0
	v_dot2_f32_bf16 v62, v58, v10, v62
	v_readlane_b32 s12, v46, s12
	v_dot2_f32_bf16 v54, v60, v8, v54
	v_cvt_scalef32_pk_bf16_fp4 v56, v93, 1.0
	v_cvt_scalef32_pk_bf16_fp4 v58, v93, 1.0 op_sel:[1,0,0]
	v_cvt_scalef32_pk_bf16_fp4 v60, v93, 1.0 op_sel:[0,1,0]
	v_cvt_scalef32_pk_bf16_fp4 v80, v93, 1.0 op_sel:[1,1,0]
	s_lshr_b32 s12, s12, 7
	v_dot2_f32_bf16 v62, v56, v14, v62
	v_dot2_f32_bf16 v54, v58, v12, v54
	s_mov_b32 s13, s86
	v_dot2_f32_bf16 v62, v60, v18, v62
	v_dot2_f32_bf16 v54, v80, v16, v54
	v_cvt_scalef32_pk_bf16_fp4 v56, v94, 1.0
	v_cvt_scalef32_pk_bf16_fp4 v58, v94, 1.0 op_sel:[1,0,0]
	v_cvt_scalef32_pk_bf16_fp4 v60, v94, 1.0 op_sel:[0,1,0]
	v_cvt_scalef32_pk_bf16_fp4 v80, v94, 1.0 op_sel:[1,1,0]
	s_lshl_b64 s[12:13], s[12:13], 10
	v_dot2_f32_bf16 v62, v56, v22, v62
	v_dot2_f32_bf16 v54, v58, v20, v54
	s_nop 0
	v_dot2_f32_bf16 v62, v60, v26, v62
	v_dot2_f32_bf16 v54, v80, v24, v54
	v_cvt_scalef32_pk_bf16_fp4 v56, v95, 1.0
	v_cvt_scalef32_pk_bf16_fp4 v58, v95, 1.0 op_sel:[1,0,0]
	v_cvt_scalef32_pk_bf16_fp4 v60, v95, 1.0 op_sel:[0,1,0]
	v_cvt_scalef32_pk_bf16_fp4 v80, v95, 1.0 op_sel:[1,1,0]
	s_nop 0
	v_dot2_f32_bf16 v62, v56, v30, v62
	v_dot2_f32_bf16 v54, v58, v28, v54
	s_nop 0
	v_dot2_f32_bf16 v62, v60, v36, v62
	v_dot2_f32_bf16 v54, v80, v34, v54
	s_nop 0
	s_nop 2
	v_add_f32_e32 v53, v62, v54
	s_add_u32 s12, s12, s100
	s_addc_u32 s13, s13, s101
	global_load_dwordx4 v[92:95], v207, s[12:13]
	s_waitcnt vmcnt(15)
	v_cvt_scalef32_pk_bf16_fp4 v54, v96, 1.0
	v_cvt_scalef32_pk_bf16_fp4 v56, v96, 1.0 op_sel:[1,0,0]
	v_cvt_scalef32_pk_bf16_fp4 v58, v96, 1.0 op_sel:[0,1,0]
	v_cvt_scalef32_pk_bf16_fp4 v60, v96, 1.0 op_sel:[1,1,0]
	v_dot2_f32_bf16 v62, v54, v6, 0
	v_dot2_f32_bf16 v54, v56, v4, 0
	v_dot2_f32_bf16 v62, v58, v10, v62
	s_add_i32 s12, s28, -8
	v_dot2_f32_bf16 v54, v60, v8, v54
	v_cvt_scalef32_pk_bf16_fp4 v56, v97, 1.0
	v_cvt_scalef32_pk_bf16_fp4 v58, v97, 1.0 op_sel:[1,0,0]
	v_cvt_scalef32_pk_bf16_fp4 v60, v97, 1.0 op_sel:[0,1,0]
	v_cvt_scalef32_pk_bf16_fp4 v80, v97, 1.0 op_sel:[1,1,0]
	v_readlane_b32 s12, v46, s12
	v_dot2_f32_bf16 v62, v56, v14, v62
	v_dot2_f32_bf16 v54, v58, v12, v54
	s_lshr_b32 s12, s12, 7
	v_dot2_f32_bf16 v62, v60, v18, v62
	v_dot2_f32_bf16 v54, v80, v16, v54
	v_cvt_scalef32_pk_bf16_fp4 v56, v98, 1.0
	v_cvt_scalef32_pk_bf16_fp4 v58, v98, 1.0 op_sel:[1,0,0]
	v_cvt_scalef32_pk_bf16_fp4 v60, v98, 1.0 op_sel:[0,1,0]
	v_cvt_scalef32_pk_bf16_fp4 v80, v98, 1.0 op_sel:[1,1,0]
	s_mov_b32 s13, s86
	v_dot2_f32_bf16 v62, v56, v22, v62
	v_dot2_f32_bf16 v54, v58, v20, v54
	s_lshl_b64 s[12:13], s[12:13], 10
	v_dot2_f32_bf16 v62, v60, v26, v62
	v_dot2_f32_bf16 v54, v80, v24, v54
	v_cvt_scalef32_pk_bf16_fp4 v56, v99, 1.0
	v_cvt_scalef32_pk_bf16_fp4 v58, v99, 1.0 op_sel:[1,0,0]
	v_cvt_scalef32_pk_bf16_fp4 v60, v99, 1.0 op_sel:[0,1,0]
	v_cvt_scalef32_pk_bf16_fp4 v80, v99, 1.0 op_sel:[1,1,0]
	s_nop 0
	v_dot2_f32_bf16 v62, v56, v30, v62
	v_dot2_f32_bf16 v54, v58, v28, v54
	s_nop 0
	v_dot2_f32_bf16 v62, v60, v36, v62
	v_dot2_f32_bf16 v54, v80, v34, v54
	s_nop 2
	v_add_f32_e32 v54, v62, v54
	s_add_u32 s12, s12, s100
	s_addc_u32 s13, s13, s101
	global_load_dwordx4 v[96:99], v207, s[12:13]
	s_waitcnt vmcnt(15)
	v_cvt_scalef32_pk_bf16_fp4 v56, v100, 1.0
	v_cvt_scalef32_pk_bf16_fp4 v58, v100, 1.0 op_sel:[1,0,0]
	v_cvt_scalef32_pk_bf16_fp4 v60, v100, 1.0 op_sel:[0,1,0]
	v_cvt_scalef32_pk_bf16_fp4 v62, v100, 1.0 op_sel:[1,1,0]
	s_add_i32 s12, s28, -7
	v_dot2_f32_bf16 v80, v56, v6, 0
	v_dot2_f32_bf16 v56, v58, v4, 0
	v_dot2_f32_bf16 v80, v60, v10, v80
	v_readlane_b32 s12, v46, s12
	v_dot2_f32_bf16 v56, v62, v8, v56
	v_cvt_scalef32_pk_bf16_fp4 v58, v101, 1.0
	v_cvt_scalef32_pk_bf16_fp4 v60, v101, 1.0 op_sel:[1,0,0]
	v_cvt_scalef32_pk_bf16_fp4 v62, v101, 1.0 op_sel:[0,1,0]
	v_cvt_scalef32_pk_bf16_fp4 v82, v101, 1.0 op_sel:[1,1,0]
	s_lshr_b32 s12, s12, 7
	v_dot2_f32_bf16 v80, v58, v14, v80
	v_dot2_f32_bf16 v56, v60, v12, v56
	s_mov_b32 s13, s86
	v_dot2_f32_bf16 v80, v62, v18, v80
	v_dot2_f32_bf16 v56, v82, v16, v56
	v_cvt_scalef32_pk_bf16_fp4 v58, v102, 1.0
	v_cvt_scalef32_pk_bf16_fp4 v60, v102, 1.0 op_sel:[1,0,0]
	v_cvt_scalef32_pk_bf16_fp4 v62, v102, 1.0 op_sel:[0,1,0]
	v_cvt_scalef32_pk_bf16_fp4 v82, v102, 1.0 op_sel:[1,1,0]
	s_lshl_b64 s[12:13], s[12:13], 10
	v_dot2_f32_bf16 v80, v58, v22, v80
	v_dot2_f32_bf16 v56, v60, v20, v56
	s_nop 0
	v_dot2_f32_bf16 v80, v62, v26, v80
	v_dot2_f32_bf16 v56, v82, v24, v56
	v_cvt_scalef32_pk_bf16_fp4 v58, v103, 1.0
	v_cvt_scalef32_pk_bf16_fp4 v60, v103, 1.0 op_sel:[1,0,0]
	v_cvt_scalef32_pk_bf16_fp4 v62, v103, 1.0 op_sel:[0,1,0]
	v_cvt_scalef32_pk_bf16_fp4 v82, v103, 1.0 op_sel:[1,1,0]
	s_nop 0
	v_dot2_f32_bf16 v80, v58, v30, v80
	v_dot2_f32_bf16 v56, v60, v28, v56
	s_nop 0
	v_dot2_f32_bf16 v80, v62, v36, v80
	v_dot2_f32_bf16 v56, v82, v34, v56
	s_nop 0
	s_nop 2
	v_add_f32_e32 v55, v80, v56
	s_add_u32 s12, s12, s100
	s_addc_u32 s13, s13, s101
	global_load_dwordx4 v[100:103], v207, s[12:13]
	s_waitcnt vmcnt(15)
; #define P4_FOR16(M) M(0) M(1) M(2) M(3) M(4) M(5) M(6) M(7) M(8) M(9) M(10) M(11) M(12) M(13) M(14) M(15)
; #define P4_U(i) { P4_DOT(b##i, part[i]); const int nk_ = __builtin_amdgcn_readlane(ksel, nb + i); P4_LOAD(b##i, Ug, nk_); }
; #define P4_U(i) { P4_DOT(b##i, part[i]); const int nk_ = __builtin_amdgcn_readlane(kn, i); P4_LOAD(b##i, nbase, nk_); }
; __device__ __forceinline__ void peer_gather_f4p(const float* X, const int* __restrict__ IDX, const float* __restrict__ G, ...
;     ...
; #pragma unroll 1
;         for (int bt = 0; bt < 7; ++bt) {
;             const int ksel = (bt + 1 < 4) ? k0 : k1;
;             const int nb = (16 * (bt + 1)) & 63;
;     ...
;             P4_FOR16(P4_U)
;     ...
;             P4_RED(bt);
;         }
	v_cvt_scalef32_pk_bf16_fp4 v56, v104, 1.0
	v_cvt_scalef32_pk_bf16_fp4 v58, v104, 1.0 op_sel:[1,0,0]
	v_cvt_scalef32_pk_bf16_fp4 v60, v104, 1.0 op_sel:[0,1,0]
	v_cvt_scalef32_pk_bf16_fp4 v62, v104, 1.0 op_sel:[1,1,0]
	v_dot2_f32_bf16 v80, v56, v6, 0
	v_dot2_f32_bf16 v56, v58, v4, 0
	v_dot2_f32_bf16 v80, v60, v10, v80
	s_add_i32 s12, s28, -6
	v_dot2_f32_bf16 v56, v62, v8, v56
	v_cvt_scalef32_pk_bf16_fp4 v58, v105, 1.0
	v_cvt_scalef32_pk_bf16_fp4 v60, v105, 1.0 op_sel:[1,0,0]
	v_cvt_scalef32_pk_bf16_fp4 v62, v105, 1.0 op_sel:[0,1,0]
	v_cvt_scalef32_pk_bf16_fp4 v82, v105, 1.0 op_sel:[1,1,0]
	v_readlane_b32 s12, v46, s12
	v_dot2_f32_bf16 v80, v58, v14, v80
	v_dot2_f32_bf16 v56, v60, v12, v56
	s_lshr_b32 s12, s12, 7
	v_dot2_f32_bf16 v80, v62, v18, v80
	v_dot2_f32_bf16 v56, v82, v16, v56
	v_cvt_scalef32_pk_bf16_fp4 v58, v106, 1.0
	v_cvt_scalef32_pk_bf16_fp4 v60, v106, 1.0 op_sel:[1,0,0]
	v_cvt_scalef32_pk_bf16_fp4 v62, v106, 1.0 op_sel:[0,1,0]
	v_cvt_scalef32_pk_bf16_fp4 v82, v106, 1.0 op_sel:[1,1,0]
	s_mov_b32 s13, s86
	v_dot2_f32_bf16 v80, v58, v22, v80
	v_dot2_f32_bf16 v56, v60, v20, v56
	s_lshl_b64 s[12:13], s[12:13], 10
	v_dot2_f32_bf16 v80, v62, v26, v80
	v_dot2_f32_bf16 v56, v82, v24, v56
	v_cvt_scalef32_pk_bf16_fp4 v58, v107, 1.0
	v_cvt_scalef32_pk_bf16_fp4 v60, v107, 1.0 op_sel:[1,0,0]
	v_cvt_scalef32_pk_bf16_fp4 v62, v107, 1.0 op_sel:[0,1,0]
	v_cvt_scalef32_pk_bf16_fp4 v82, v107, 1.0 op_sel:[1,1,0]
	s_nop 0
	v_dot2_f32_bf16 v80, v58, v30, v80
	v_dot2_f32_bf16 v56, v60, v28, v56
	s_nop 0
	v_dot2_f32_bf16 v80, v62, v36, v80
	v_dot2_f32_bf16 v56, v82, v34, v56
	s_nop 2
	v_add_f32_e32 v56, v80, v56
	s_add_u32 s12, s12, s100
	s_addc_u32 s13, s13, s101
	global_load_dwordx4 v[104:107], v207, s[12:13]
	s_waitcnt vmcnt(15)
	v_cvt_scalef32_pk_bf16_fp4 v58, v108, 1.0
	v_cvt_scalef32_pk_bf16_fp4 v60, v108, 1.0 op_sel:[1,0,0]
	v_cvt_scalef32_pk_bf16_fp4 v62, v108, 1.0 op_sel:[0,1,0]
	v_cvt_scalef32_pk_bf16_fp4 v80, v108, 1.0 op_sel:[1,1,0]
	s_add_i32 s12, s28, -5
	v_dot2_f32_bf16 v82, v58, v6, 0
	v_dot2_f32_bf16 v58, v60, v4, 0
	v_dot2_f32_bf16 v82, v62, v10, v82
	v_readlane_b32 s12, v46, s12
	v_dot2_f32_bf16 v58, v80, v8, v58
	v_cvt_scalef32_pk_bf16_fp4 v60, v109, 1.0
	v_cvt_scalef32_pk_bf16_fp4 v62, v109, 1.0 op_sel:[1,0,0]
	v_cvt_scalef32_pk_bf16_fp4 v80, v109, 1.0 op_sel:[0,1,0]
	v_cvt_scalef32_pk_bf16_fp4 v108, v109, 1.0 op_sel:[1,1,0]
	s_lshr_b32 s12, s12, 7
	v_dot2_f32_bf16 v82, v60, v14, v82
	v_dot2_f32_bf16 v58, v62, v12, v58
	s_mov_b32 s13, s86
	v_dot2_f32_bf16 v82, v80, v18, v82
	v_dot2_f32_bf16 v58, v108, v16, v58
	v_cvt_scalef32_pk_bf16_fp4 v60, v110, 1.0
	v_cvt_scalef32_pk_bf16_fp4 v62, v110, 1.0 op_sel:[1,0,0]
	v_cvt_scalef32_pk_bf16_fp4 v80, v110, 1.0 op_sel:[0,1,0]
	v_cvt_scalef32_pk_bf16_fp4 v108, v110, 1.0 op_sel:[1,1,0]
	s_lshl_b64 s[12:13], s[12:13], 10
	v_dot2_f32_bf16 v82, v60, v22, v82
	v_dot2_f32_bf16 v58, v62, v20, v58
	s_nop 0
	v_dot2_f32_bf16 v82, v80, v26, v82
	v_dot2_f32_bf16 v58, v108, v24, v58
	v_cvt_scalef32_pk_bf16_fp4 v60, v111, 1.0
	v_cvt_scalef32_pk_bf16_fp4 v62, v111, 1.0 op_sel:[1,0,0]
	v_cvt_scalef32_pk_bf16_fp4 v80, v111, 1.0 op_sel:[0,1,0]
	v_cvt_scalef32_pk_bf16_fp4 v108, v111, 1.0 op_sel:[1,1,0]
	s_nop 0
	v_dot2_f32_bf16 v82, v60, v30, v82
	v_dot2_f32_bf16 v58, v62, v28, v58
	s_nop 0
	v_dot2_f32_bf16 v82, v80, v36, v82
	v_dot2_f32_bf16 v58, v108, v34, v58
	s_nop 0
	s_nop 2
	v_add_f32_e32 v57, v82, v58
	s_add_u32 s12, s12, s100
	s_addc_u32 s13, s13, s101
	global_load_dwordx4 v[108:111], v207, s[12:13]
	s_waitcnt vmcnt(15)
	v_cvt_scalef32_pk_bf16_fp4 v58, v112, 1.0
	v_cvt_scalef32_pk_bf16_fp4 v60, v112, 1.0 op_sel:[1,0,0]
	v_cvt_scalef32_pk_bf16_fp4 v62, v112, 1.0 op_sel:[0,1,0]
	v_cvt_scalef32_pk_bf16_fp4 v80, v112, 1.0 op_sel:[1,1,0]
	v_dot2_f32_bf16 v82, v58, v6, 0
	v_dot2_f32_bf16 v58, v60, v4, 0
	v_dot2_f32_bf16 v82, v62, v10, v82
	s_add_i32 s12, s28, -4
	v_dot2_f32_bf16 v58, v80, v8, v58
	v_cvt_scalef32_pk_bf16_fp4 v60, v113, 1.0
	v_cvt_scalef32_pk_bf16_fp4 v62, v113, 1.0 op_sel:[1,0,0]
	v_cvt_scalef32_pk_bf16_fp4 v80, v113, 1.0 op_sel:[0,1,0]
	v_cvt_scalef32_pk_bf16_fp4 v112, v113, 1.0 op_sel:[1,1,0]
	v_readlane_b32 s12, v46, s12
	v_dot2_f32_bf16 v82, v60, v14, v82
	v_dot2_f32_bf16 v58, v62, v12, v58
	s_lshr_b32 s12, s12, 7
	v_dot2_f32_bf16 v82, v80, v18, v82
	v_dot2_f32_bf16 v58, v112, v16, v58
	v_cvt_scalef32_pk_bf16_fp4 v60, v114, 1.0
	v_cvt_scalef32_pk_bf16_fp4 v62, v114, 1.0 op_sel:[1,0,0]
	v_cvt_scalef32_pk_bf16_fp4 v80, v114, 1.0 op_sel:[0,1,0]
	v_cvt_scalef32_pk_bf16_fp4 v112, v114, 1.0 op_sel:[1,1,0]
	s_mov_b32 s13, s86
	v_dot2_f32_bf16 v82, v60, v22, v82
	v_dot2_f32_bf16 v58, v62, v20, v58
	s_lshl_b64 s[12:13], s[12:13], 10
	v_dot2_f32_bf16 v82, v80, v26, v82
	v_dot2_f32_bf16 v58, v112, v24, v58
	v_cvt_scalef32_pk_bf16_fp4 v60, v115, 1.0
	v_cvt_scalef32_pk_bf16_fp4 v62, v115, 1.0 op_sel:[1,0,0]
	v_cvt_scalef32_pk_bf16_fp4 v80, v115, 1.0 op_sel:[0,1,0]
	v_cvt_scalef32_pk_bf16_fp4 v112, v115, 1.0 op_sel:[1,1,0]
	s_nop 0
	v_dot2_f32_bf16 v82, v60, v30, v82
	v_dot2_f32_bf16 v58, v62, v28, v58
	s_nop 0
	v_dot2_f32_bf16 v82, v80, v36, v82
	v_dot2_f32_bf16 v58, v112, v34, v58
	s_nop 0
	s_nop 2
	v_add_f32_e32 v132, v82, v58
	s_add_u32 s12, s12, s100
	s_addc_u32 s13, s13, s101
	global_load_dwordx4 v[112:115], v207, s[12:13]
	s_waitcnt vmcnt(15)
; #define P4_FOR16(M) M(0) M(1) M(2) M(3) M(4) M(5) M(6) M(7) M(8) M(9) M(10) M(11) M(12) M(13) M(14) M(15)
; #define P4_U(i) { P4_DOT(b##i, part[i]); const int nk_ = __builtin_amdgcn_readlane(ksel, nb + i); P4_LOAD(b##i, Ug, nk_); }
; #define P4_U(i) { P4_DOT(b##i, part[i]); const int nk_ = __builtin_amdgcn_readlane(kn, i); P4_LOAD(b##i, nbase, nk_); }
; __device__ __forceinline__ void peer_gather_f4p(const float* X, const int* __restrict__ IDX, const float* __restrict__ G, ...
;     ...
; #pragma unroll 1
;         for (int bt = 0; bt < 7; ++bt) {
;             const int ksel = (bt + 1 < 4) ? k0 : k1;
;             const int nb = (16 * (bt + 1)) & 63;
;     ...
;             P4_FOR16(P4_U)
;     ...
;             P4_RED(bt);
;         }
	v_cvt_scalef32_pk_bf16_fp4 v58, v116, 1.0
	v_cvt_scalef32_pk_bf16_fp4 v60, v116, 1.0 op_sel:[1,0,0]
	v_cvt_scalef32_pk_bf16_fp4 v62, v116, 1.0 op_sel:[0,1,0]
	v_cvt_scalef32_pk_bf16_fp4 v80, v116, 1.0 op_sel:[1,1,0]
	v_dot2_f32_bf16 v82, v58, v6, 0
	v_dot2_f32_bf16 v58, v60, v4, 0
	v_dot2_f32_bf16 v82, v62, v10, v82
	s_add_i32 s12, s28, -3
	v_dot2_f32_bf16 v58, v80, v8, v58
	v_cvt_scalef32_pk_bf16_fp4 v60, v117, 1.0
	v_cvt_scalef32_pk_bf16_fp4 v62, v117, 1.0 op_sel:[1,0,0]
	v_cvt_scalef32_pk_bf16_fp4 v80, v117, 1.0 op_sel:[0,1,0]
	v_cvt_scalef32_pk_bf16_fp4 v116, v117, 1.0 op_sel:[1,1,0]
	v_readlane_b32 s12, v46, s12
	v_dot2_f32_bf16 v82, v60, v14, v82
	v_dot2_f32_bf16 v58, v62, v12, v58
	s_lshr_b32 s12, s12, 7
	v_dot2_f32_bf16 v82, v80, v18, v82
	v_dot2_f32_bf16 v58, v116, v16, v58
	v_cvt_scalef32_pk_bf16_fp4 v60, v118, 1.0
	v_cvt_scalef32_pk_bf16_fp4 v62, v118, 1.0 op_sel:[1,0,0]
	v_cvt_scalef32_pk_bf16_fp4 v80, v118, 1.0 op_sel:[0,1,0]
	v_cvt_scalef32_pk_bf16_fp4 v116, v118, 1.0 op_sel:[1,1,0]
	s_mov_b32 s13, s86
	v_dot2_f32_bf16 v82, v60, v22, v82
	v_dot2_f32_bf16 v58, v62, v20, v58
	s_lshl_b64 s[12:13], s[12:13], 10
	v_dot2_f32_bf16 v82, v80, v26, v82
	v_dot2_f32_bf16 v58, v116, v24, v58
	v_cvt_scalef32_pk_bf16_fp4 v60, v119, 1.0
	v_cvt_scalef32_pk_bf16_fp4 v62, v119, 1.0 op_sel:[1,0,0]
	v_cvt_scalef32_pk_bf16_fp4 v80, v119, 1.0 op_sel:[0,1,0]
	v_cvt_scalef32_pk_bf16_fp4 v116, v119, 1.0 op_sel:[1,1,0]
	s_nop 0
	v_dot2_f32_bf16 v82, v60, v30, v82
	v_dot2_f32_bf16 v58, v62, v28, v58
	s_nop 0
	v_dot2_f32_bf16 v82, v80, v36, v82
	v_dot2_f32_bf16 v58, v116, v34, v58
	s_nop 0
	s_nop 2
	v_add_f32_e32 v133, v82, v58
	s_add_u32 s12, s12, s100
	s_addc_u32 s13, s13, s101
	global_load_dwordx4 v[116:119], v207, s[12:13]
	s_waitcnt vmcnt(15)
	v_cvt_scalef32_pk_bf16_fp4 v58, v120, 1.0
	v_cvt_scalef32_pk_bf16_fp4 v60, v120, 1.0 op_sel:[1,0,0]
	v_cvt_scalef32_pk_bf16_fp4 v62, v120, 1.0 op_sel:[0,1,0]
	v_cvt_scalef32_pk_bf16_fp4 v80, v120, 1.0 op_sel:[1,1,0]
	v_dot2_f32_bf16 v82, v58, v6, 0
	v_dot2_f32_bf16 v58, v60, v4, 0
	v_dot2_f32_bf16 v82, v62, v10, v82
	s_add_i32 s12, s28, -2
	v_dot2_f32_bf16 v58, v80, v8, v58
	v_cvt_scalef32_pk_bf16_fp4 v60, v121, 1.0
	v_cvt_scalef32_pk_bf16_fp4 v62, v121, 1.0 op_sel:[1,0,0]
	v_cvt_scalef32_pk_bf16_fp4 v80, v121, 1.0 op_sel:[0,1,0]
	v_cvt_scalef32_pk_bf16_fp4 v120, v121, 1.0 op_sel:[1,1,0]
	v_readlane_b32 s12, v46, s12
	v_dot2_f32_bf16 v82, v60, v14, v82
	v_dot2_f32_bf16 v58, v62, v12, v58
	s_lshr_b32 s12, s12, 7
	v_dot2_f32_bf16 v82, v80, v18, v82
	v_dot2_f32_bf16 v58, v120, v16, v58
	v_cvt_scalef32_pk_bf16_fp4 v60, v122, 1.0
	v_cvt_scalef32_pk_bf16_fp4 v62, v122, 1.0 op_sel:[1,0,0]
	v_cvt_scalef32_pk_bf16_fp4 v80, v122, 1.0 op_sel:[0,1,0]
	v_cvt_scalef32_pk_bf16_fp4 v120, v122, 1.0 op_sel:[1,1,0]
	s_mov_b32 s13, s86
	v_dot2_f32_bf16 v82, v60, v22, v82
	v_dot2_f32_bf16 v58, v62, v20, v58
	s_lshl_b64 s[12:13], s[12:13], 10
	v_dot2_f32_bf16 v82, v80, v26, v82
	v_dot2_f32_bf16 v58, v120, v24, v58
	v_cvt_scalef32_pk_bf16_fp4 v60, v123, 1.0
	v_cvt_scalef32_pk_bf16_fp4 v62, v123, 1.0 op_sel:[1,0,0]
	v_cvt_scalef32_pk_bf16_fp4 v80, v123, 1.0 op_sel:[0,1,0]
	v_cvt_scalef32_pk_bf16_fp4 v120, v123, 1.0 op_sel:[1,1,0]
	s_nop 0
	v_dot2_f32_bf16 v82, v60, v30, v82
	v_dot2_f32_bf16 v58, v62, v28, v58
	s_nop 0
	v_dot2_f32_bf16 v82, v80, v36, v82
	v_dot2_f32_bf16 v58, v120, v34, v58
	s_nop 0
	s_nop 2
	v_add_f32_e32 v134, v82, v58
	s_add_u32 s12, s12, s100
	s_addc_u32 s13, s13, s101
	global_load_dwordx4 v[120:123], v207, s[12:13]
	s_waitcnt vmcnt(15)
	v_cvt_scalef32_pk_bf16_fp4 v58, v124, 1.0
	v_cvt_scalef32_pk_bf16_fp4 v60, v124, 1.0 op_sel:[1,0,0]
	v_cvt_scalef32_pk_bf16_fp4 v62, v124, 1.0 op_sel:[0,1,0]
	v_cvt_scalef32_pk_bf16_fp4 v80, v124, 1.0 op_sel:[1,1,0]
	v_dot2_f32_bf16 v82, v58, v6, 0
	v_dot2_f32_bf16 v58, v60, v4, 0
	v_dot2_f32_bf16 v82, v62, v10, v82
	s_add_i32 s12, s28, -1
	v_dot2_f32_bf16 v58, v80, v8, v58
	v_cvt_scalef32_pk_bf16_fp4 v60, v125, 1.0
	v_cvt_scalef32_pk_bf16_fp4 v62, v125, 1.0 op_sel:[1,0,0]
	v_cvt_scalef32_pk_bf16_fp4 v80, v125, 1.0 op_sel:[0,1,0]
	v_cvt_scalef32_pk_bf16_fp4 v124, v125, 1.0 op_sel:[1,1,0]
	v_readlane_b32 s12, v46, s12
	v_dot2_f32_bf16 v82, v60, v14, v82
	v_dot2_f32_bf16 v58, v62, v12, v58
	s_lshr_b32 s12, s12, 7
	v_dot2_f32_bf16 v82, v80, v18, v82
	v_dot2_f32_bf16 v58, v124, v16, v58
	v_cvt_scalef32_pk_bf16_fp4 v60, v126, 1.0
	v_cvt_scalef32_pk_bf16_fp4 v62, v126, 1.0 op_sel:[1,0,0]
	v_cvt_scalef32_pk_bf16_fp4 v80, v126, 1.0 op_sel:[0,1,0]
	v_cvt_scalef32_pk_bf16_fp4 v124, v126, 1.0 op_sel:[1,1,0]
	s_mov_b32 s13, s86
	v_dot2_f32_bf16 v82, v60, v22, v82
	v_dot2_f32_bf16 v58, v62, v20, v58
	s_lshl_b64 s[12:13], s[12:13], 10
	v_dot2_f32_bf16 v82, v80, v26, v82
	v_dot2_f32_bf16 v58, v124, v24, v58
	v_cvt_scalef32_pk_bf16_fp4 v60, v127, 1.0
	v_cvt_scalef32_pk_bf16_fp4 v62, v127, 1.0 op_sel:[1,0,0]
	v_cvt_scalef32_pk_bf16_fp4 v80, v127, 1.0 op_sel:[0,1,0]
	v_cvt_scalef32_pk_bf16_fp4 v124, v127, 1.0 op_sel:[1,1,0]
	s_nop 0
	v_dot2_f32_bf16 v82, v60, v30, v82
	v_dot2_f32_bf16 v58, v62, v28, v58
	s_nop 0
	v_dot2_f32_bf16 v82, v80, v36, v82
	v_dot2_f32_bf16 v58, v124, v34, v58
	s_nop 0
	s_nop 2
	v_add_f32_e32 v135, v82, v58
	s_add_u32 s12, s12, s100
	s_addc_u32 s13, s13, s101
	global_load_dwordx4 v[124:127], v207, s[12:13]
	s_waitcnt vmcnt(15)
; __device__ __forceinline__ float gelu_tanh(float h) {
;     return 0.5f * h * (1.f + tanhf(0.7978845608028654f * (h + 0.044715f * h * h * h)));
	v_cvt_scalef32_pk_bf16_fp4 v58, v128, 1.0
	v_cvt_scalef32_pk_bf16_fp4 v60, v128, 1.0 op_sel:[1,0,0]
	v_cvt_scalef32_pk_bf16_fp4 v62, v128, 1.0 op_sel:[0,1,0]
	v_cvt_scalef32_pk_bf16_fp4 v80, v128, 1.0 op_sel:[1,1,0]
	v_readlane_b32 s12, v46, s28
	v_dot2_f32_bf16 v82, v58, v6, 0
	v_dot2c_f32_bf16_e32 v42, v60, v4
	s_lshr_b32 s12, s12, 7
	v_dot2_f32_bf16 v82, v62, v10, v82
	v_dot2c_f32_bf16_e32 v42, v80, v8
	v_cvt_scalef32_pk_bf16_fp4 v58, v129, 1.0
	v_cvt_scalef32_pk_bf16_fp4 v60, v129, 1.0 op_sel:[1,0,0]
	v_cvt_scalef32_pk_bf16_fp4 v62, v129, 1.0 op_sel:[0,1,0]
	v_cvt_scalef32_pk_bf16_fp4 v80, v129, 1.0 op_sel:[1,1,0]
	s_mov_b32 s13, s86
	v_dot2_f32_bf16 v82, v58, v14, v82
	v_dot2c_f32_bf16_e32 v42, v60, v12
	s_lshl_b64 s[12:13], s[12:13], 10
	v_dot2_f32_bf16 v82, v62, v18, v82
	v_dot2c_f32_bf16_e32 v42, v80, v16
	v_cvt_scalef32_pk_bf16_fp4 v58, v130, 1.0
	v_cvt_scalef32_pk_bf16_fp4 v60, v130, 1.0 op_sel:[1,0,0]
	v_cvt_scalef32_pk_bf16_fp4 v62, v130, 1.0 op_sel:[0,1,0]
	v_cvt_scalef32_pk_bf16_fp4 v80, v130, 1.0 op_sel:[1,1,0]
	v_cndmask_b32_e64 v46, v48, v56, s[46:47]
	v_dot2_f32_bf16 v82, v58, v22, v82
	v_dot2c_f32_bf16_e32 v42, v60, v20
	ds_swizzle_b32 v46, v46 offset:swizzle(SWAP,8)
	v_dot2_f32_bf16 v82, v62, v26, v82
	v_dot2c_f32_bf16_e32 v42, v80, v24
	v_cvt_scalef32_pk_bf16_fp4 v58, v131, 1.0
	v_cvt_scalef32_pk_bf16_fp4 v60, v131, 1.0 op_sel:[1,0,0]
	v_cvt_scalef32_pk_bf16_fp4 v62, v131, 1.0 op_sel:[0,1,0]
	v_cvt_scalef32_pk_bf16_fp4 v80, v131, 1.0 op_sel:[1,1,0]
	s_nop 0
	v_dot2_f32_bf16 v82, v58, v30, v82
	v_dot2c_f32_bf16_e32 v42, v60, v28
	s_nop 0
	v_dot2_f32_bf16 v82, v62, v36, v82
	v_dot2c_f32_bf16_e32 v42, v80, v34
	s_nop 0
	s_nop 2
	v_add_f32_e32 v58, v82, v42
	v_lshl_add_u64 v[42:43], v[40:41], 0, s[12:13]
	global_load_dwordx4 v[128:131], v[42:43], off
	v_cndmask_b32_e64 v43, v47, v55, s[46:47]
	ds_swizzle_b32 v43, v43 offset:swizzle(SWAP,8)
	v_cndmask_b32_e64 v42, v55, v47, s[46:47]
	v_cndmask_b32_e64 v47, v49, v57, s[46:47]
	ds_swizzle_b32 v47, v47 offset:swizzle(SWAP,8)
	s_waitcnt lgkmcnt(1)
	v_add_f32_e32 v42, v42, v43
	v_cndmask_b32_e64 v43, v56, v48, s[46:47]
	v_cndmask_b32_e64 v48, v50, v132, s[46:47]
	v_add_f32_e32 v43, v43, v46
	v_cndmask_b32_e64 v46, v57, v49, s[46:47]
	ds_swizzle_b32 v48, v48 offset:swizzle(SWAP,8)
	v_cndmask_b32_e64 v49, v51, v133, s[46:47]
	ds_swizzle_b32 v49, v49 offset:swizzle(SWAP,8)
	s_waitcnt lgkmcnt(2)
	v_add_f32_e32 v46, v46, v47
	v_cndmask_b32_e64 v47, v132, v50, s[46:47]
	v_cndmask_b32_e64 v50, v52, v134, s[46:47]
	ds_swizzle_b32 v50, v50 offset:swizzle(SWAP,8)
	s_waitcnt lgkmcnt(2)
	v_add_f32_e32 v47, v47, v48
	v_cndmask_b32_e64 v48, v133, v51, s[46:47]
	v_cndmask_b32_e64 v51, v53, v135, s[46:47]
	s_waitcnt lgkmcnt(1)
	v_add_f32_e32 v48, v48, v49
	v_cndmask_b32_e64 v49, v134, v52, s[46:47]
	ds_swizzle_b32 v51, v51 offset:swizzle(SWAP,8)
	v_cndmask_b32_e64 v52, v54, v58, s[46:47]
	ds_swizzle_b32 v52, v52 offset:swizzle(SWAP,8)
	s_waitcnt lgkmcnt(2)
	v_add_f32_e32 v49, v49, v50
	v_cndmask_b32_e64 v50, v135, v53, s[46:47]
	s_waitcnt lgkmcnt(1)
	v_add_f32_e32 v50, v50, v51
	v_cndmask_b32_e64 v51, v58, v54, s[46:47]
	s_waitcnt lgkmcnt(0)
	v_add_f32_e32 v51, v51, v52
	v_cndmask_b32_e64 v53, v42, v48, s[44:45]
	v_cndmask_b32_e64 v42, v48, v42, s[44:45]
	v_cndmask_b32_e64 v48, v49, v43, s[44:45]
	v_cndmask_b32_e64 v43, v43, v49, s[44:45]
	v_cndmask_b32_e64 v49, v46, v50, s[44:45]
	v_cndmask_b32_e64 v52, v47, v51, s[44:45]
	ds_swizzle_b32 v53, v53 offset:swizzle(SWAP,4)
	ds_swizzle_b32 v43, v43 offset:swizzle(SWAP,4)
	ds_swizzle_b32 v49, v49 offset:swizzle(SWAP,4)
	ds_swizzle_b32 v52, v52 offset:swizzle(SWAP,4)
	v_cndmask_b32_e64 v46, v50, v46, s[44:45]
	v_cndmask_b32_e64 v47, v51, v47, s[44:45]
	s_waitcnt lgkmcnt(3)
	v_add_f32_e32 v42, v42, v53
	s_waitcnt lgkmcnt(2)
	v_add_f32_e32 v43, v48, v43
	s_waitcnt lgkmcnt(1)
	v_add_f32_e32 v46, v46, v49
	s_waitcnt lgkmcnt(0)
	v_add_f32_e32 v47, v47, v52
	v_cndmask_b32_e64 v48, v42, v46, s[42:43]
	v_cndmask_b32_e64 v49, v43, v47, s[42:43]
	ds_swizzle_b32 v48, v48 offset:swizzle(SWAP,2)
	ds_swizzle_b32 v49, v49 offset:swizzle(SWAP,2)
	v_cndmask_b32_e64 v42, v46, v42, s[42:43]
	v_cndmask_b32_e64 v43, v47, v43, s[42:43]
	s_waitcnt lgkmcnt(1)
	v_add_f32_e32 v42, v42, v48
	s_waitcnt lgkmcnt(0)
	v_add_f32_e32 v43, v43, v49
	v_cndmask_b32_e64 v46, v42, v43, s[40:41]
	ds_swizzle_b32 v46, v46 offset:swizzle(SWAP,1)
	v_cndmask_b32_e64 v42, v43, v42, s[40:41]
	s_waitcnt lgkmcnt(0)
	v_add_f32_e32 v42, v42, v46
	ds_swizzle_b32 v43, v42 offset:swizzle(SWAP,16)
	s_waitcnt lgkmcnt(0)
	v_add_f32_e32 v46, v42, v43
	ds_read2st64_b32 v[42:43], v45 offset1:8
	v_mov_b32_e32 v47, v46
	s_nop 1
	v_permlane32_swap_b32_e32 v46, v47
	v_add_f32_e32 v46, v46, v47
	s_waitcnt lgkmcnt(0)
	v_mul_f32_e32 v42, v42, v46
	v_mul_f32_e32 v46, 0x3d372713, v42
	v_mul_f32_e32 v46, v42, v46
	v_fma_f32 v46, v42, v46, v42
	v_mul_f32_e32 v46, 0x3f4c422a, v46
	v_cmp_nlt_f32_e64 s[12:13], |v46|, s25
	s_and_saveexec_b64 s[48:49], s[12:13]
	s_xor_b64 s[12:13], exec, s[48:49]
	s_cbranch_execz .LBB0_1233
	v_add_f32_e64 v47, |v46|, |v46|
	v_mul_f32_e32 v48, 0x3fb8aa3b, v47
	v_rndne_f32_e32 v49, v48
	v_sub_f32_e32 v50, v48, v49
	v_fma_f32 v48, v47, s70, -v48
	v_fmac_f32_e32 v48, 0x32a5705f, v47
	v_add_f32_e32 v48, v50, v48
	v_cvt_i32_f32_e32 v49, v49
	v_exp_f32_e32 v48, v48
	v_cmp_ngt_f32_e64 s[48:49], s67, v47
	v_ldexp_f32 v48, v48, v49
	s_nop 0
	v_cndmask_b32_e64 v48, 0, v48, s[48:49]
	v_cmp_nlt_f32_e64 s[48:49], s68, v47
	s_nop 1
	v_cndmask_b32_e64 v47, v205, v48, s[48:49]
	v_add_f32_e32 v47, 1.0, v47
	v_rcp_f32_e32 v47, v47
	s_nop 0
	v_fma_f32 v47, v47, -2.0, 1.0
	s_andn2_saveexec_b64 s[12:13], s[12:13]
	s_cbranch_execnz .LBB0_1234

; #define P4_FOR16(M) M(0) M(1) M(2) M(3) M(4) M(5) M(6) M(7) M(8) M(9) M(10) M(11) M(12) M(13) M(14) M(15)
; #define P4_V(i) { const unsigned wu_ = (unsigned)__builtin_amdgcn_readlane((int)__float_as_uint(wreg), i); const unsigned long long wp_ = ((unsigned long long)wu_ << 32) | wu_; \
;               P4_ACC(b##i, wp_); const int nk_ = __builtin_amdgcn_readlane(ksel, nb + i); P4_LOAD(b##i, Vg, nk_); }
; #define P4_V(i) { const unsigned wu_ = (unsigned)__builtin_amdgcn_readlane((int)__float_as_uint(wreg), i); const unsigned long long wp_ = ((unsigned long long)wu_ << 32) | wu_; \
;               P4_ACC(b##i, wp_); const int nk_ = __builtin_amdgcn_readlane(kn, i); P4_LOAD(b##i, Vg, nk_); }
; #define P4_V(i) { const unsigned wu_ = (unsigned)__builtin_amdgcn_readlane((int)__float_as_uint(wreg), i); const unsigned long long wp_ = ((unsigned long long)wu_ << 32) | wu_; \
;               P4_ACC(b##i, wp_); }
; __device__ __forceinline__ void peer_gather_f4p(const float* X, const int* __restrict__ IDX, const float* __restrict__ G, ...
;     ...
; #pragma unroll 1
;         for (int bt = 0; bt < 7; ++bt) {
;             const int ksel = (bt + 1 < 4) ? k0 : k1;
;             const int nb = (16 * (bt + 1)) & 63;
;             const float wreg = wbuf[kt * 128 + bt * 16 + (lane & 15)];
;     ...
;             P4_FOR16(P4_V)
;     ...
;         }
.LBB0_1247:
	ds_read_b32 v65, v171
	s_waitcnt vmcnt(15)
	v_cvt_scalef32_pk_f32_fp4 v[66:67], v4, 1.0
	v_cvt_scalef32_pk_f32_fp4 v[68:69], v4, 1.0 op_sel:[1,0,0]
	v_cvt_scalef32_pk_f32_fp4 v[70:71], v4, 1.0 op_sel:[0,1,0]
	s_cmp_lt_u32 s28, 3
	s_waitcnt lgkmcnt(0)
	v_readlane_b32 s16, v65, 0
	s_mov_b32 s17, s16
	v_cvt_scalef32_pk_f32_fp4 v[72:73], v4, 1.0 op_sel:[1,1,0]
	v_pk_fma_f32 v[132:133], s[16:17], v[66:67], v[132:133]
	v_pk_fma_f32 v[162:163], s[16:17], v[68:69], v[162:163]
	v_pk_fma_f32 v[160:161], s[16:17], v[70:71], v[160:161]
	s_cselect_b64 vcc, -1, 0
	v_pk_fma_f32 v[158:159], s[16:17], v[72:73], v[158:159]
	v_cvt_scalef32_pk_f32_fp4 v[66:67], v5, 1.0
	v_cvt_scalef32_pk_f32_fp4 v[68:69], v5, 1.0 op_sel:[1,0,0]
	v_cvt_scalef32_pk_f32_fp4 v[70:71], v5, 1.0 op_sel:[0,1,0]
	v_cvt_scalef32_pk_f32_fp4 v[4:5], v5, 1.0 op_sel:[1,1,0]
	v_cndmask_b32_e32 v64, v167, v166, vcc
	v_pk_fma_f32 v[156:157], s[16:17], v[66:67], v[156:157]
	v_pk_fma_f32 v[154:155], s[16:17], v[68:69], v[154:155]
	v_pk_fma_f32 v[152:153], s[16:17], v[70:71], v[152:153]
	v_pk_fma_f32 v[150:151], s[16:17], v[4:5], v[150:151]
	v_cvt_scalef32_pk_f32_fp4 v[4:5], v6, 1.0
	v_cvt_scalef32_pk_f32_fp4 v[66:67], v6, 1.0 op_sel:[1,0,0]
	v_cvt_scalef32_pk_f32_fp4 v[68:69], v6, 1.0 op_sel:[0,1,0]
	v_cvt_scalef32_pk_f32_fp4 v[70:71], v6, 1.0 op_sel:[1,1,0]
	s_mov_b32 s41, s86
	v_pk_fma_f32 v[148:149], s[16:17], v[4:5], v[148:149]
	v_pk_fma_f32 v[146:147], s[16:17], v[66:67], v[146:147]
	v_pk_fma_f32 v[144:145], s[16:17], v[68:69], v[144:145]
	v_pk_fma_f32 v[142:143], s[16:17], v[70:71], v[142:143]
	v_cvt_scalef32_pk_f32_fp4 v[4:5], v7, 1.0
	v_cvt_scalef32_pk_f32_fp4 v[66:67], v7, 1.0 op_sel:[1,0,0]
	v_cvt_scalef32_pk_f32_fp4 v[68:69], v7, 1.0 op_sel:[0,1,0]
	v_cvt_scalef32_pk_f32_fp4 v[6:7], v7, 1.0 op_sel:[1,1,0]
	s_add_i32 s28, s28, 1
	v_pk_fma_f32 v[140:141], s[16:17], v[4:5], v[140:141]
	v_pk_fma_f32 v[138:139], s[16:17], v[66:67], v[138:139]
	v_pk_fma_f32 v[136:137], s[16:17], v[68:69], v[136:137]
	v_pk_fma_f32 v[134:135], s[16:17], v[6:7], v[134:135]
	s_add_i32 s16, s27, -15
	v_readlane_b32 s16, v64, s16
	s_lshr_b32 s40, s16, 7
	v_readfirstlane_b32 s100, v168
	v_readfirstlane_b32 s101, v169
	v_subrev_u32_e32 v207, s100, v168
	s_lshl_b64 s[16:17], s[40:41], 10
	s_add_u32 s16, s16, s100
	s_addc_u32 s17, s17, s101
	global_load_dwordx4 v[4:7], v207, s[16:17]
	v_readlane_b32 s16, v65, 1
	s_waitcnt vmcnt(15)
	v_cvt_scalef32_pk_f32_fp4 v[66:67], v8, 1.0
	v_cvt_scalef32_pk_f32_fp4 v[68:69], v8, 1.0 op_sel:[1,0,0]
	v_cvt_scalef32_pk_f32_fp4 v[70:71], v8, 1.0 op_sel:[0,1,0]
	s_mov_b32 s17, s16
	v_cvt_scalef32_pk_f32_fp4 v[72:73], v8, 1.0 op_sel:[1,1,0]
	v_pk_fma_f32 v[132:133], s[16:17], v[66:67], v[132:133]
	v_pk_fma_f32 v[162:163], s[16:17], v[68:69], v[162:163]
	v_pk_fma_f32 v[160:161], s[16:17], v[70:71], v[160:161]
	v_add_u32_e32 v171, 64, v171
	v_pk_fma_f32 v[158:159], s[16:17], v[72:73], v[158:159]
	v_cvt_scalef32_pk_f32_fp4 v[66:67], v9, 1.0
	v_cvt_scalef32_pk_f32_fp4 v[68:69], v9, 1.0 op_sel:[1,0,0]
	v_cvt_scalef32_pk_f32_fp4 v[70:71], v9, 1.0 op_sel:[0,1,0]
	v_cvt_scalef32_pk_f32_fp4 v[8:9], v9, 1.0 op_sel:[1,1,0]
	s_nop 0
	v_pk_fma_f32 v[156:157], s[16:17], v[66:67], v[156:157]
	v_pk_fma_f32 v[154:155], s[16:17], v[68:69], v[154:155]
	v_pk_fma_f32 v[152:153], s[16:17], v[70:71], v[152:153]
	v_pk_fma_f32 v[150:151], s[16:17], v[8:9], v[150:151]
	v_cvt_scalef32_pk_f32_fp4 v[8:9], v10, 1.0
	v_cvt_scalef32_pk_f32_fp4 v[66:67], v10, 1.0 op_sel:[1,0,0]
	v_cvt_scalef32_pk_f32_fp4 v[68:69], v10, 1.0 op_sel:[0,1,0]
	v_cvt_scalef32_pk_f32_fp4 v[70:71], v10, 1.0 op_sel:[1,1,0]
	s_nop 0
	v_pk_fma_f32 v[148:149], s[16:17], v[8:9], v[148:149]
	v_pk_fma_f32 v[146:147], s[16:17], v[66:67], v[146:147]
	v_pk_fma_f32 v[144:145], s[16:17], v[68:69], v[144:145]
	v_pk_fma_f32 v[142:143], s[16:17], v[70:71], v[142:143]
	v_cvt_scalef32_pk_f32_fp4 v[8:9], v11, 1.0
	v_cvt_scalef32_pk_f32_fp4 v[66:67], v11, 1.0 op_sel:[1,0,0]
	v_cvt_scalef32_pk_f32_fp4 v[68:69], v11, 1.0 op_sel:[0,1,0]
	v_cvt_scalef32_pk_f32_fp4 v[10:11], v11, 1.0 op_sel:[1,1,0]
	s_nop 0
	v_pk_fma_f32 v[140:141], s[16:17], v[8:9], v[140:141]
	v_pk_fma_f32 v[138:139], s[16:17], v[66:67], v[138:139]
	v_pk_fma_f32 v[136:137], s[16:17], v[68:69], v[136:137]
	v_pk_fma_f32 v[134:135], s[16:17], v[10:11], v[134:135]
	s_add_i32 s16, s27, -14
	v_readlane_b32 s16, v64, s16
	s_lshr_b32 s40, s16, 7
	s_lshl_b64 s[16:17], s[40:41], 10
	s_add_u32 s16, s16, s100
	s_addc_u32 s17, s17, s101
	global_load_dwordx4 v[8:11], v207, s[16:17]
	v_readlane_b32 s16, v65, 2
	s_waitcnt vmcnt(15)
	v_cvt_scalef32_pk_f32_fp4 v[66:67], v12, 1.0
	v_cvt_scalef32_pk_f32_fp4 v[68:69], v12, 1.0 op_sel:[1,0,0]
	v_cvt_scalef32_pk_f32_fp4 v[70:71], v12, 1.0 op_sel:[0,1,0]
	s_mov_b32 s17, s16
	v_cvt_scalef32_pk_f32_fp4 v[72:73], v12, 1.0 op_sel:[1,1,0]
	v_pk_fma_f32 v[132:133], s[16:17], v[66:67], v[132:133]
	v_pk_fma_f32 v[162:163], s[16:17], v[68:69], v[162:163]
	v_pk_fma_f32 v[160:161], s[16:17], v[70:71], v[160:161]
	s_nop 0
	v_pk_fma_f32 v[158:159], s[16:17], v[72:73], v[158:159]
	v_cvt_scalef32_pk_f32_fp4 v[66:67], v13, 1.0
	v_cvt_scalef32_pk_f32_fp4 v[68:69], v13, 1.0 op_sel:[1,0,0]
	v_cvt_scalef32_pk_f32_fp4 v[70:71], v13, 1.0 op_sel:[0,1,0]
	v_cvt_scalef32_pk_f32_fp4 v[12:13], v13, 1.0 op_sel:[1,1,0]
	s_nop 0
	v_pk_fma_f32 v[156:157], s[16:17], v[66:67], v[156:157]
	v_pk_fma_f32 v[154:155], s[16:17], v[68:69], v[154:155]
	v_pk_fma_f32 v[152:153], s[16:17], v[70:71], v[152:153]
	v_pk_fma_f32 v[150:151], s[16:17], v[12:13], v[150:151]
	v_cvt_scalef32_pk_f32_fp4 v[12:13], v14, 1.0
	v_cvt_scalef32_pk_f32_fp4 v[66:67], v14, 1.0 op_sel:[1,0,0]
	v_cvt_scalef32_pk_f32_fp4 v[68:69], v14, 1.0 op_sel:[0,1,0]
	v_cvt_scalef32_pk_f32_fp4 v[70:71], v14, 1.0 op_sel:[1,1,0]
	s_nop 0
	v_pk_fma_f32 v[148:149], s[16:17], v[12:13], v[148:149]
	v_pk_fma_f32 v[146:147], s[16:17], v[66:67], v[146:147]
	v_pk_fma_f32 v[144:145], s[16:17], v[68:69], v[144:145]
	v_pk_fma_f32 v[142:143], s[16:17], v[70:71], v[142:143]
	v_cvt_scalef32_pk_f32_fp4 v[12:13], v15, 1.0
	v_cvt_scalef32_pk_f32_fp4 v[66:67], v15, 1.0 op_sel:[1,0,0]
	v_cvt_scalef32_pk_f32_fp4 v[68:69], v15, 1.0 op_sel:[0,1,0]
	v_cvt_scalef32_pk_f32_fp4 v[14:15], v15, 1.0 op_sel:[1,1,0]
	s_nop 0
	v_pk_fma_f32 v[140:141], s[16:17], v[12:13], v[140:141]
	v_pk_fma_f32 v[138:139], s[16:17], v[66:67], v[138:139]
	v_pk_fma_f32 v[136:137], s[16:17], v[68:69], v[136:137]
	v_pk_fma_f32 v[134:135], s[16:17], v[14:15], v[134:135]
	s_add_i32 s16, s27, -13
	v_readlane_b32 s16, v64, s16
	s_lshr_b32 s40, s16, 7
	s_lshl_b64 s[16:17], s[40:41], 10
	s_add_u32 s16, s16, s100
	s_addc_u32 s17, s17, s101
	global_load_dwordx4 v[12:15], v207, s[16:17]
	v_readlane_b32 s16, v65, 3
	s_waitcnt vmcnt(15)
; #define P4_FOR16(M) M(0) M(1) M(2) M(3) M(4) M(5) M(6) M(7) M(8) M(9) M(10) M(11) M(12) M(13) M(14) M(15)
; #define P4_V(i) { const unsigned wu_ = (unsigned)__builtin_amdgcn_readlane((int)__float_as_uint(wreg), i); const unsigned long long wp_ = ((unsigned long long)wu_ << 32) | wu_; \
;               P4_ACC(b##i, wp_); const int nk_ = __builtin_amdgcn_readlane(ksel, nb + i); P4_LOAD(b##i, Vg, nk_); }
; #define P4_V(i) { const unsigned wu_ = (unsigned)__builtin_amdgcn_readlane((int)__float_as_uint(wreg), i); const unsigned long long wp_ = ((unsigned long long)wu_ << 32) | wu_; \
;               P4_ACC(b##i, wp_); const int nk_ = __builtin_amdgcn_readlane(kn, i); P4_LOAD(b##i, Vg, nk_); }
; #define P4_V(i) { const unsigned wu_ = (unsigned)__builtin_amdgcn_readlane((int)__float_as_uint(wreg), i); const unsigned long long wp_ = ((unsigned long long)wu_ << 32) | wu_; \
;               P4_ACC(b##i, wp_); }
; __device__ __forceinline__ void peer_gather_f4p(const float* X, const int* __restrict__ IDX, const float* __restrict__ G, ...
;     ...
; #pragma unroll 1
;         for (int bt = 0; bt < 7; ++bt) {
;             const int ksel = (bt + 1 < 4) ? k0 : k1;
;             const int nb = (16 * (bt + 1)) & 63;
;             const float wreg = wbuf[kt * 128 + bt * 16 + (lane & 15)];
;     ...
;             P4_FOR16(P4_V)
;     ...
;         }
	v_cvt_scalef32_pk_f32_fp4 v[66:67], v16, 1.0
	v_cvt_scalef32_pk_f32_fp4 v[68:69], v16, 1.0 op_sel:[1,0,0]
	v_cvt_scalef32_pk_f32_fp4 v[70:71], v16, 1.0 op_sel:[0,1,0]
	s_mov_b32 s17, s16
	v_cvt_scalef32_pk_f32_fp4 v[72:73], v16, 1.0 op_sel:[1,1,0]
	v_pk_fma_f32 v[132:133], s[16:17], v[66:67], v[132:133]
	v_pk_fma_f32 v[162:163], s[16:17], v[68:69], v[162:163]
	v_pk_fma_f32 v[160:161], s[16:17], v[70:71], v[160:161]
	s_nop 0
	v_pk_fma_f32 v[158:159], s[16:17], v[72:73], v[158:159]
	v_cvt_scalef32_pk_f32_fp4 v[66:67], v17, 1.0
	v_cvt_scalef32_pk_f32_fp4 v[68:69], v17, 1.0 op_sel:[1,0,0]
	v_cvt_scalef32_pk_f32_fp4 v[70:71], v17, 1.0 op_sel:[0,1,0]
	v_cvt_scalef32_pk_f32_fp4 v[16:17], v17, 1.0 op_sel:[1,1,0]
	s_nop 0
	v_pk_fma_f32 v[156:157], s[16:17], v[66:67], v[156:157]
	v_pk_fma_f32 v[154:155], s[16:17], v[68:69], v[154:155]
	v_pk_fma_f32 v[152:153], s[16:17], v[70:71], v[152:153]
	v_pk_fma_f32 v[150:151], s[16:17], v[16:17], v[150:151]
	v_cvt_scalef32_pk_f32_fp4 v[16:17], v18, 1.0
	v_cvt_scalef32_pk_f32_fp4 v[66:67], v18, 1.0 op_sel:[1,0,0]
	v_cvt_scalef32_pk_f32_fp4 v[68:69], v18, 1.0 op_sel:[0,1,0]
	v_cvt_scalef32_pk_f32_fp4 v[70:71], v18, 1.0 op_sel:[1,1,0]
	s_nop 0
	v_pk_fma_f32 v[148:149], s[16:17], v[16:17], v[148:149]
	v_pk_fma_f32 v[146:147], s[16:17], v[66:67], v[146:147]
	v_pk_fma_f32 v[144:145], s[16:17], v[68:69], v[144:145]
	v_pk_fma_f32 v[142:143], s[16:17], v[70:71], v[142:143]
	v_cvt_scalef32_pk_f32_fp4 v[16:17], v19, 1.0
	v_cvt_scalef32_pk_f32_fp4 v[66:67], v19, 1.0 op_sel:[1,0,0]
	v_cvt_scalef32_pk_f32_fp4 v[68:69], v19, 1.0 op_sel:[0,1,0]
	v_cvt_scalef32_pk_f32_fp4 v[18:19], v19, 1.0 op_sel:[1,1,0]
	s_nop 0
	v_pk_fma_f32 v[140:141], s[16:17], v[16:17], v[140:141]
	v_pk_fma_f32 v[138:139], s[16:17], v[66:67], v[138:139]
	v_pk_fma_f32 v[136:137], s[16:17], v[68:69], v[136:137]
	v_pk_fma_f32 v[134:135], s[16:17], v[18:19], v[134:135]
	s_add_i32 s16, s27, -12
	v_readlane_b32 s16, v64, s16
	s_lshr_b32 s40, s16, 7
	s_lshl_b64 s[16:17], s[40:41], 10
	s_add_u32 s16, s16, s100
	s_addc_u32 s17, s17, s101
	global_load_dwordx4 v[16:19], v207, s[16:17]
	v_readlane_b32 s16, v65, 4
	s_waitcnt vmcnt(15)
	v_cvt_scalef32_pk_f32_fp4 v[66:67], v20, 1.0
	v_cvt_scalef32_pk_f32_fp4 v[68:69], v20, 1.0 op_sel:[1,0,0]
	v_cvt_scalef32_pk_f32_fp4 v[70:71], v20, 1.0 op_sel:[0,1,0]
	s_mov_b32 s17, s16
	v_cvt_scalef32_pk_f32_fp4 v[72:73], v20, 1.0 op_sel:[1,1,0]
	v_pk_fma_f32 v[132:133], s[16:17], v[66:67], v[132:133]
	v_pk_fma_f32 v[162:163], s[16:17], v[68:69], v[162:163]
	v_pk_fma_f32 v[160:161], s[16:17], v[70:71], v[160:161]
	s_nop 0
	v_pk_fma_f32 v[158:159], s[16:17], v[72:73], v[158:159]
	v_cvt_scalef32_pk_f32_fp4 v[66:67], v21, 1.0
	v_cvt_scalef32_pk_f32_fp4 v[68:69], v21, 1.0 op_sel:[1,0,0]
	v_cvt_scalef32_pk_f32_fp4 v[70:71], v21, 1.0 op_sel:[0,1,0]
	v_cvt_scalef32_pk_f32_fp4 v[20:21], v21, 1.0 op_sel:[1,1,0]
	s_nop 0
	v_pk_fma_f32 v[156:157], s[16:17], v[66:67], v[156:157]
	v_pk_fma_f32 v[154:155], s[16:17], v[68:69], v[154:155]
	v_pk_fma_f32 v[152:153], s[16:17], v[70:71], v[152:153]
	v_pk_fma_f32 v[150:151], s[16:17], v[20:21], v[150:151]
	v_cvt_scalef32_pk_f32_fp4 v[20:21], v22, 1.0
	v_cvt_scalef32_pk_f32_fp4 v[66:67], v22, 1.0 op_sel:[1,0,0]
	v_cvt_scalef32_pk_f32_fp4 v[68:69], v22, 1.0 op_sel:[0,1,0]
	v_cvt_scalef32_pk_f32_fp4 v[70:71], v22, 1.0 op_sel:[1,1,0]
	s_nop 0
	v_pk_fma_f32 v[148:149], s[16:17], v[20:21], v[148:149]
	v_pk_fma_f32 v[146:147], s[16:17], v[66:67], v[146:147]
	v_pk_fma_f32 v[144:145], s[16:17], v[68:69], v[144:145]
	v_pk_fma_f32 v[142:143], s[16:17], v[70:71], v[142:143]
	v_cvt_scalef32_pk_f32_fp4 v[20:21], v23, 1.0
	v_cvt_scalef32_pk_f32_fp4 v[66:67], v23, 1.0 op_sel:[1,0,0]
	v_cvt_scalef32_pk_f32_fp4 v[68:69], v23, 1.0 op_sel:[0,1,0]
	v_cvt_scalef32_pk_f32_fp4 v[22:23], v23, 1.0 op_sel:[1,1,0]
	s_nop 0
	v_pk_fma_f32 v[140:141], s[16:17], v[20:21], v[140:141]
	v_pk_fma_f32 v[138:139], s[16:17], v[66:67], v[138:139]
	v_pk_fma_f32 v[136:137], s[16:17], v[68:69], v[136:137]
	v_pk_fma_f32 v[134:135], s[16:17], v[22:23], v[134:135]
	s_add_i32 s16, s27, -11
	v_readlane_b32 s16, v64, s16
	s_lshr_b32 s40, s16, 7
	s_lshl_b64 s[16:17], s[40:41], 10
	s_add_u32 s16, s16, s100
	s_addc_u32 s17, s17, s101
	global_load_dwordx4 v[20:23], v207, s[16:17]
	v_readlane_b32 s16, v65, 5
	s_waitcnt vmcnt(15)
	v_cvt_scalef32_pk_f32_fp4 v[66:67], v24, 1.0
	v_cvt_scalef32_pk_f32_fp4 v[68:69], v24, 1.0 op_sel:[1,0,0]
	v_cvt_scalef32_pk_f32_fp4 v[70:71], v24, 1.0 op_sel:[0,1,0]
	s_mov_b32 s17, s16
	v_cvt_scalef32_pk_f32_fp4 v[72:73], v24, 1.0 op_sel:[1,1,0]
	v_pk_fma_f32 v[132:133], s[16:17], v[66:67], v[132:133]
	v_pk_fma_f32 v[162:163], s[16:17], v[68:69], v[162:163]
	v_pk_fma_f32 v[160:161], s[16:17], v[70:71], v[160:161]
	s_nop 0
	v_pk_fma_f32 v[158:159], s[16:17], v[72:73], v[158:159]
	v_cvt_scalef32_pk_f32_fp4 v[66:67], v25, 1.0
	v_cvt_scalef32_pk_f32_fp4 v[68:69], v25, 1.0 op_sel:[1,0,0]
	v_cvt_scalef32_pk_f32_fp4 v[70:71], v25, 1.0 op_sel:[0,1,0]
	v_cvt_scalef32_pk_f32_fp4 v[24:25], v25, 1.0 op_sel:[1,1,0]
	s_nop 0
	v_pk_fma_f32 v[156:157], s[16:17], v[66:67], v[156:157]
	v_pk_fma_f32 v[154:155], s[16:17], v[68:69], v[154:155]
	v_pk_fma_f32 v[152:153], s[16:17], v[70:71], v[152:153]
	v_pk_fma_f32 v[150:151], s[16:17], v[24:25], v[150:151]
	v_cvt_scalef32_pk_f32_fp4 v[24:25], v26, 1.0
	v_cvt_scalef32_pk_f32_fp4 v[66:67], v26, 1.0 op_sel:[1,0,0]
	v_cvt_scalef32_pk_f32_fp4 v[68:69], v26, 1.0 op_sel:[0,1,0]
	v_cvt_scalef32_pk_f32_fp4 v[70:71], v26, 1.0 op_sel:[1,1,0]
	s_nop 0
	v_pk_fma_f32 v[148:149], s[16:17], v[24:25], v[148:149]
	v_pk_fma_f32 v[146:147], s[16:17], v[66:67], v[146:147]
	v_pk_fma_f32 v[144:145], s[16:17], v[68:69], v[144:145]
	v_pk_fma_f32 v[142:143], s[16:17], v[70:71], v[142:143]
	v_cvt_scalef32_pk_f32_fp4 v[24:25], v27, 1.0
	v_cvt_scalef32_pk_f32_fp4 v[66:67], v27, 1.0 op_sel:[1,0,0]
	v_cvt_scalef32_pk_f32_fp4 v[68:69], v27, 1.0 op_sel:[0,1,0]
	v_cvt_scalef32_pk_f32_fp4 v[26:27], v27, 1.0 op_sel:[1,1,0]
	s_nop 0
	v_pk_fma_f32 v[140:141], s[16:17], v[24:25], v[140:141]
	v_pk_fma_f32 v[138:139], s[16:17], v[66:67], v[138:139]
	v_pk_fma_f32 v[136:137], s[16:17], v[68:69], v[136:137]
	v_pk_fma_f32 v[134:135], s[16:17], v[26:27], v[134:135]
	s_add_i32 s16, s27, -10
	v_readlane_b32 s16, v64, s16
	s_lshr_b32 s40, s16, 7
	s_lshl_b64 s[16:17], s[40:41], 10
	s_add_u32 s16, s16, s100
	s_addc_u32 s17, s17, s101
	global_load_dwordx4 v[24:27], v207, s[16:17]
	v_readlane_b32 s16, v65, 6
	s_waitcnt vmcnt(15)
; #define P4_FOR16(M) M(0) M(1) M(2) M(3) M(4) M(5) M(6) M(7) M(8) M(9) M(10) M(11) M(12) M(13) M(14) M(15)
; #define P4_V(i) { const unsigned wu_ = (unsigned)__builtin_amdgcn_readlane((int)__float_as_uint(wreg), i); const unsigned long long wp_ = ((unsigned long long)wu_ << 32) | wu_; \
;               P4_ACC(b##i, wp_); const int nk_ = __builtin_amdgcn_readlane(ksel, nb + i); P4_LOAD(b##i, Vg, nk_); }
; #define P4_V(i) { const unsigned wu_ = (unsigned)__builtin_amdgcn_readlane((int)__float_as_uint(wreg), i); const unsigned long long wp_ = ((unsigned long long)wu_ << 32) | wu_; \
;               P4_ACC(b##i, wp_); const int nk_ = __builtin_amdgcn_readlane(kn, i); P4_LOAD(b##i, Vg, nk_); }
; #define P4_V(i) { const unsigned wu_ = (unsigned)__builtin_amdgcn_readlane((int)__float_as_uint(wreg), i); const unsigned long long wp_ = ((unsigned long long)wu_ << 32) | wu_; \
;               P4_ACC(b##i, wp_); }
; __device__ __forceinline__ void peer_gather_f4p(const float* X, const int* __restrict__ IDX, const float* __restrict__ G, ...
;     ...
; #pragma unroll 1
;         for (int bt = 0; bt < 7; ++bt) {
;             const int ksel = (bt + 1 < 4) ? k0 : k1;
;             const int nb = (16 * (bt + 1)) & 63;
;             const float wreg = wbuf[kt * 128 + bt * 16 + (lane & 15)];
;     ...
;             P4_FOR16(P4_V)
;     ...
;         }
	v_cvt_scalef32_pk_f32_fp4 v[66:67], v28, 1.0
	v_cvt_scalef32_pk_f32_fp4 v[68:69], v28, 1.0 op_sel:[1,0,0]
	v_cvt_scalef32_pk_f32_fp4 v[70:71], v28, 1.0 op_sel:[0,1,0]
	s_mov_b32 s17, s16
	v_cvt_scalef32_pk_f32_fp4 v[72:73], v28, 1.0 op_sel:[1,1,0]
	v_pk_fma_f32 v[132:133], s[16:17], v[66:67], v[132:133]
	v_pk_fma_f32 v[162:163], s[16:17], v[68:69], v[162:163]
	v_pk_fma_f32 v[160:161], s[16:17], v[70:71], v[160:161]
	s_nop 0
	v_pk_fma_f32 v[158:159], s[16:17], v[72:73], v[158:159]
	v_cvt_scalef32_pk_f32_fp4 v[66:67], v29, 1.0
	v_cvt_scalef32_pk_f32_fp4 v[68:69], v29, 1.0 op_sel:[1,0,0]
	v_cvt_scalef32_pk_f32_fp4 v[70:71], v29, 1.0 op_sel:[0,1,0]
	v_cvt_scalef32_pk_f32_fp4 v[28:29], v29, 1.0 op_sel:[1,1,0]
	s_nop 0
	v_pk_fma_f32 v[156:157], s[16:17], v[66:67], v[156:157]
	v_pk_fma_f32 v[154:155], s[16:17], v[68:69], v[154:155]
	v_pk_fma_f32 v[152:153], s[16:17], v[70:71], v[152:153]
	v_pk_fma_f32 v[150:151], s[16:17], v[28:29], v[150:151]
	v_cvt_scalef32_pk_f32_fp4 v[28:29], v30, 1.0
	v_cvt_scalef32_pk_f32_fp4 v[66:67], v30, 1.0 op_sel:[1,0,0]
	v_cvt_scalef32_pk_f32_fp4 v[68:69], v30, 1.0 op_sel:[0,1,0]
	v_cvt_scalef32_pk_f32_fp4 v[70:71], v30, 1.0 op_sel:[1,1,0]
	s_nop 0
	v_pk_fma_f32 v[148:149], s[16:17], v[28:29], v[148:149]
	v_pk_fma_f32 v[146:147], s[16:17], v[66:67], v[146:147]
	v_pk_fma_f32 v[144:145], s[16:17], v[68:69], v[144:145]
	v_pk_fma_f32 v[142:143], s[16:17], v[70:71], v[142:143]
	v_cvt_scalef32_pk_f32_fp4 v[28:29], v31, 1.0
	v_cvt_scalef32_pk_f32_fp4 v[66:67], v31, 1.0 op_sel:[1,0,0]
	v_cvt_scalef32_pk_f32_fp4 v[68:69], v31, 1.0 op_sel:[0,1,0]
	v_cvt_scalef32_pk_f32_fp4 v[30:31], v31, 1.0 op_sel:[1,1,0]
	s_nop 0
	v_pk_fma_f32 v[140:141], s[16:17], v[28:29], v[140:141]
	v_pk_fma_f32 v[138:139], s[16:17], v[66:67], v[138:139]
	v_pk_fma_f32 v[136:137], s[16:17], v[68:69], v[136:137]
	v_pk_fma_f32 v[134:135], s[16:17], v[30:31], v[134:135]
	s_add_i32 s16, s27, -9
	v_readlane_b32 s16, v64, s16
	s_lshr_b32 s40, s16, 7
	s_lshl_b64 s[16:17], s[40:41], 10
	s_add_u32 s16, s16, s100
	s_addc_u32 s17, s17, s101
	global_load_dwordx4 v[28:31], v207, s[16:17]
	v_readlane_b32 s16, v65, 7
	s_waitcnt vmcnt(15)
	v_cvt_scalef32_pk_f32_fp4 v[66:67], v32, 1.0
	v_cvt_scalef32_pk_f32_fp4 v[68:69], v32, 1.0 op_sel:[1,0,0]
	v_cvt_scalef32_pk_f32_fp4 v[70:71], v32, 1.0 op_sel:[0,1,0]
	s_mov_b32 s17, s16
	v_cvt_scalef32_pk_f32_fp4 v[72:73], v32, 1.0 op_sel:[1,1,0]
	v_pk_fma_f32 v[132:133], s[16:17], v[66:67], v[132:133]
	v_pk_fma_f32 v[162:163], s[16:17], v[68:69], v[162:163]
	v_pk_fma_f32 v[160:161], s[16:17], v[70:71], v[160:161]
	s_nop 0
	v_pk_fma_f32 v[158:159], s[16:17], v[72:73], v[158:159]
	v_cvt_scalef32_pk_f32_fp4 v[66:67], v33, 1.0
	v_cvt_scalef32_pk_f32_fp4 v[68:69], v33, 1.0 op_sel:[1,0,0]
	v_cvt_scalef32_pk_f32_fp4 v[70:71], v33, 1.0 op_sel:[0,1,0]
	v_cvt_scalef32_pk_f32_fp4 v[32:33], v33, 1.0 op_sel:[1,1,0]
	s_nop 0
	v_pk_fma_f32 v[156:157], s[16:17], v[66:67], v[156:157]
	v_pk_fma_f32 v[154:155], s[16:17], v[68:69], v[154:155]
	v_pk_fma_f32 v[152:153], s[16:17], v[70:71], v[152:153]
	v_pk_fma_f32 v[150:151], s[16:17], v[32:33], v[150:151]
	v_cvt_scalef32_pk_f32_fp4 v[32:33], v34, 1.0
	v_cvt_scalef32_pk_f32_fp4 v[66:67], v34, 1.0 op_sel:[1,0,0]
	v_cvt_scalef32_pk_f32_fp4 v[68:69], v34, 1.0 op_sel:[0,1,0]
	v_cvt_scalef32_pk_f32_fp4 v[70:71], v34, 1.0 op_sel:[1,1,0]
	s_nop 0
	v_pk_fma_f32 v[148:149], s[16:17], v[32:33], v[148:149]
	v_pk_fma_f32 v[146:147], s[16:17], v[66:67], v[146:147]
	v_pk_fma_f32 v[144:145], s[16:17], v[68:69], v[144:145]
	v_pk_fma_f32 v[142:143], s[16:17], v[70:71], v[142:143]
	v_cvt_scalef32_pk_f32_fp4 v[32:33], v35, 1.0
	v_cvt_scalef32_pk_f32_fp4 v[66:67], v35, 1.0 op_sel:[1,0,0]
	v_cvt_scalef32_pk_f32_fp4 v[68:69], v35, 1.0 op_sel:[0,1,0]
	v_cvt_scalef32_pk_f32_fp4 v[34:35], v35, 1.0 op_sel:[1,1,0]
	s_nop 0
	v_pk_fma_f32 v[140:141], s[16:17], v[32:33], v[140:141]
	v_pk_fma_f32 v[138:139], s[16:17], v[66:67], v[138:139]
	v_pk_fma_f32 v[136:137], s[16:17], v[68:69], v[136:137]
	v_pk_fma_f32 v[134:135], s[16:17], v[34:35], v[134:135]
	s_add_i32 s16, s27, -8
	v_readlane_b32 s16, v64, s16
	s_lshr_b32 s40, s16, 7
	s_lshl_b64 s[16:17], s[40:41], 10
	s_add_u32 s16, s16, s100
	s_addc_u32 s17, s17, s101
	global_load_dwordx4 v[32:35], v207, s[16:17]
	v_readlane_b32 s16, v65, 8
	s_waitcnt vmcnt(15)
	v_cvt_scalef32_pk_f32_fp4 v[66:67], v36, 1.0
	v_cvt_scalef32_pk_f32_fp4 v[68:69], v36, 1.0 op_sel:[1,0,0]
	v_cvt_scalef32_pk_f32_fp4 v[70:71], v36, 1.0 op_sel:[0,1,0]
	s_mov_b32 s17, s16
	v_cvt_scalef32_pk_f32_fp4 v[72:73], v36, 1.0 op_sel:[1,1,0]
	v_pk_fma_f32 v[132:133], s[16:17], v[66:67], v[132:133]
	v_pk_fma_f32 v[162:163], s[16:17], v[68:69], v[162:163]
	v_pk_fma_f32 v[160:161], s[16:17], v[70:71], v[160:161]
	s_nop 0
	v_pk_fma_f32 v[158:159], s[16:17], v[72:73], v[158:159]
	v_cvt_scalef32_pk_f32_fp4 v[66:67], v37, 1.0
	v_cvt_scalef32_pk_f32_fp4 v[68:69], v37, 1.0 op_sel:[1,0,0]
	v_cvt_scalef32_pk_f32_fp4 v[70:71], v37, 1.0 op_sel:[0,1,0]
	v_cvt_scalef32_pk_f32_fp4 v[36:37], v37, 1.0 op_sel:[1,1,0]
	s_nop 0
	v_pk_fma_f32 v[156:157], s[16:17], v[66:67], v[156:157]
	v_pk_fma_f32 v[154:155], s[16:17], v[68:69], v[154:155]
	v_pk_fma_f32 v[152:153], s[16:17], v[70:71], v[152:153]
	v_pk_fma_f32 v[150:151], s[16:17], v[36:37], v[150:151]
	v_cvt_scalef32_pk_f32_fp4 v[36:37], v38, 1.0
	v_cvt_scalef32_pk_f32_fp4 v[66:67], v38, 1.0 op_sel:[1,0,0]
	v_cvt_scalef32_pk_f32_fp4 v[68:69], v38, 1.0 op_sel:[0,1,0]
	v_cvt_scalef32_pk_f32_fp4 v[70:71], v38, 1.0 op_sel:[1,1,0]
	s_nop 0
	v_pk_fma_f32 v[148:149], s[16:17], v[36:37], v[148:149]
	v_pk_fma_f32 v[146:147], s[16:17], v[66:67], v[146:147]
	v_pk_fma_f32 v[144:145], s[16:17], v[68:69], v[144:145]
	v_pk_fma_f32 v[142:143], s[16:17], v[70:71], v[142:143]
	v_cvt_scalef32_pk_f32_fp4 v[36:37], v39, 1.0
	v_cvt_scalef32_pk_f32_fp4 v[66:67], v39, 1.0 op_sel:[1,0,0]
	v_cvt_scalef32_pk_f32_fp4 v[68:69], v39, 1.0 op_sel:[0,1,0]
	v_cvt_scalef32_pk_f32_fp4 v[38:39], v39, 1.0 op_sel:[1,1,0]
	s_nop 0
	v_pk_fma_f32 v[140:141], s[16:17], v[36:37], v[140:141]
	v_pk_fma_f32 v[138:139], s[16:17], v[66:67], v[138:139]
	v_pk_fma_f32 v[136:137], s[16:17], v[68:69], v[136:137]
	v_pk_fma_f32 v[134:135], s[16:17], v[38:39], v[134:135]
	s_add_i32 s16, s27, -7
	v_readlane_b32 s16, v64, s16
	s_lshr_b32 s40, s16, 7
	s_lshl_b64 s[16:17], s[40:41], 10
	s_add_u32 s16, s16, s100
	s_addc_u32 s17, s17, s101
	global_load_dwordx4 v[36:39], v207, s[16:17]
	v_readlane_b32 s16, v65, 9
	s_waitcnt vmcnt(15)
; #define P4_FOR16(M) M(0) M(1) M(2) M(3) M(4) M(5) M(6) M(7) M(8) M(9) M(10) M(11) M(12) M(13) M(14) M(15)
; #define P4_V(i) { const unsigned wu_ = (unsigned)__builtin_amdgcn_readlane((int)__float_as_uint(wreg), i); const unsigned long long wp_ = ((unsigned long long)wu_ << 32) | wu_; \
;               P4_ACC(b##i, wp_); const int nk_ = __builtin_amdgcn_readlane(ksel, nb + i); P4_LOAD(b##i, Vg, nk_); }
; #define P4_V(i) { const unsigned wu_ = (unsigned)__builtin_amdgcn_readlane((int)__float_as_uint(wreg), i); const unsigned long long wp_ = ((unsigned long long)wu_ << 32) | wu_; \
;               P4_ACC(b##i, wp_); const int nk_ = __builtin_amdgcn_readlane(kn, i); P4_LOAD(b##i, Vg, nk_); }
; #define P4_V(i) { const unsigned wu_ = (unsigned)__builtin_amdgcn_readlane((int)__float_as_uint(wreg), i); const unsigned long long wp_ = ((unsigned long long)wu_ << 32) | wu_; \
;               P4_ACC(b##i, wp_); }
; __device__ __forceinline__ void peer_gather_f4p(const float* X, const int* __restrict__ IDX, const float* __restrict__ G, ...
;     ...
; #pragma unroll 1
;         for (int bt = 0; bt < 7; ++bt) {
;             const int ksel = (bt + 1 < 4) ? k0 : k1;
;             const int nb = (16 * (bt + 1)) & 63;
;             const float wreg = wbuf[kt * 128 + bt * 16 + (lane & 15)];
;     ...
;             P4_FOR16(P4_V)
;     ...
;         }
	v_cvt_scalef32_pk_f32_fp4 v[66:67], v40, 1.0
	v_cvt_scalef32_pk_f32_fp4 v[68:69], v40, 1.0 op_sel:[1,0,0]
	v_cvt_scalef32_pk_f32_fp4 v[70:71], v40, 1.0 op_sel:[0,1,0]
	s_mov_b32 s17, s16
	v_cvt_scalef32_pk_f32_fp4 v[72:73], v40, 1.0 op_sel:[1,1,0]
	v_pk_fma_f32 v[132:133], s[16:17], v[66:67], v[132:133]
	v_pk_fma_f32 v[162:163], s[16:17], v[68:69], v[162:163]
	v_pk_fma_f32 v[160:161], s[16:17], v[70:71], v[160:161]
	s_nop 0
	v_pk_fma_f32 v[158:159], s[16:17], v[72:73], v[158:159]
	v_cvt_scalef32_pk_f32_fp4 v[66:67], v41, 1.0
	v_cvt_scalef32_pk_f32_fp4 v[68:69], v41, 1.0 op_sel:[1,0,0]
	v_cvt_scalef32_pk_f32_fp4 v[70:71], v41, 1.0 op_sel:[0,1,0]
	v_cvt_scalef32_pk_f32_fp4 v[40:41], v41, 1.0 op_sel:[1,1,0]
	s_nop 0
	v_pk_fma_f32 v[156:157], s[16:17], v[66:67], v[156:157]
	v_pk_fma_f32 v[154:155], s[16:17], v[68:69], v[154:155]
	v_pk_fma_f32 v[152:153], s[16:17], v[70:71], v[152:153]
	v_pk_fma_f32 v[150:151], s[16:17], v[40:41], v[150:151]
	v_cvt_scalef32_pk_f32_fp4 v[40:41], v42, 1.0
	v_cvt_scalef32_pk_f32_fp4 v[66:67], v42, 1.0 op_sel:[1,0,0]
	v_cvt_scalef32_pk_f32_fp4 v[68:69], v42, 1.0 op_sel:[0,1,0]
	v_cvt_scalef32_pk_f32_fp4 v[70:71], v42, 1.0 op_sel:[1,1,0]
	s_nop 0
	v_pk_fma_f32 v[148:149], s[16:17], v[40:41], v[148:149]
	v_pk_fma_f32 v[146:147], s[16:17], v[66:67], v[146:147]
	v_pk_fma_f32 v[144:145], s[16:17], v[68:69], v[144:145]
	v_pk_fma_f32 v[142:143], s[16:17], v[70:71], v[142:143]
	v_cvt_scalef32_pk_f32_fp4 v[40:41], v43, 1.0
	v_cvt_scalef32_pk_f32_fp4 v[66:67], v43, 1.0 op_sel:[1,0,0]
	v_cvt_scalef32_pk_f32_fp4 v[68:69], v43, 1.0 op_sel:[0,1,0]
	v_cvt_scalef32_pk_f32_fp4 v[42:43], v43, 1.0 op_sel:[1,1,0]
	s_nop 0
	v_pk_fma_f32 v[140:141], s[16:17], v[40:41], v[140:141]
	v_pk_fma_f32 v[138:139], s[16:17], v[66:67], v[138:139]
	v_pk_fma_f32 v[136:137], s[16:17], v[68:69], v[136:137]
	v_pk_fma_f32 v[134:135], s[16:17], v[42:43], v[134:135]
	s_add_i32 s16, s27, -6
	v_readlane_b32 s16, v64, s16
	s_lshr_b32 s40, s16, 7
	s_lshl_b64 s[16:17], s[40:41], 10
	s_add_u32 s16, s16, s100
	s_addc_u32 s17, s17, s101
	global_load_dwordx4 v[40:43], v207, s[16:17]
	v_readlane_b32 s16, v65, 10
	s_waitcnt vmcnt(15)
	v_cvt_scalef32_pk_f32_fp4 v[66:67], v44, 1.0
	v_cvt_scalef32_pk_f32_fp4 v[68:69], v44, 1.0 op_sel:[1,0,0]
	v_cvt_scalef32_pk_f32_fp4 v[70:71], v44, 1.0 op_sel:[0,1,0]
	s_mov_b32 s17, s16
	v_cvt_scalef32_pk_f32_fp4 v[72:73], v44, 1.0 op_sel:[1,1,0]
	v_pk_fma_f32 v[132:133], s[16:17], v[66:67], v[132:133]
	v_pk_fma_f32 v[162:163], s[16:17], v[68:69], v[162:163]
	v_pk_fma_f32 v[160:161], s[16:17], v[70:71], v[160:161]
	s_nop 0
	v_pk_fma_f32 v[158:159], s[16:17], v[72:73], v[158:159]
	v_cvt_scalef32_pk_f32_fp4 v[66:67], v45, 1.0
	v_cvt_scalef32_pk_f32_fp4 v[68:69], v45, 1.0 op_sel:[1,0,0]
	v_cvt_scalef32_pk_f32_fp4 v[70:71], v45, 1.0 op_sel:[0,1,0]
	v_cvt_scalef32_pk_f32_fp4 v[44:45], v45, 1.0 op_sel:[1,1,0]
	s_nop 0
	v_pk_fma_f32 v[156:157], s[16:17], v[66:67], v[156:157]
	v_pk_fma_f32 v[154:155], s[16:17], v[68:69], v[154:155]
	v_pk_fma_f32 v[152:153], s[16:17], v[70:71], v[152:153]
	v_pk_fma_f32 v[150:151], s[16:17], v[44:45], v[150:151]
	v_cvt_scalef32_pk_f32_fp4 v[44:45], v46, 1.0
	v_cvt_scalef32_pk_f32_fp4 v[66:67], v46, 1.0 op_sel:[1,0,0]
	v_cvt_scalef32_pk_f32_fp4 v[68:69], v46, 1.0 op_sel:[0,1,0]
	v_cvt_scalef32_pk_f32_fp4 v[70:71], v46, 1.0 op_sel:[1,1,0]
	s_nop 0
	v_pk_fma_f32 v[148:149], s[16:17], v[44:45], v[148:149]
	v_pk_fma_f32 v[146:147], s[16:17], v[66:67], v[146:147]
	v_pk_fma_f32 v[144:145], s[16:17], v[68:69], v[144:145]
	v_pk_fma_f32 v[142:143], s[16:17], v[70:71], v[142:143]
	v_cvt_scalef32_pk_f32_fp4 v[44:45], v47, 1.0
	v_cvt_scalef32_pk_f32_fp4 v[66:67], v47, 1.0 op_sel:[1,0,0]
	v_cvt_scalef32_pk_f32_fp4 v[68:69], v47, 1.0 op_sel:[0,1,0]
	v_cvt_scalef32_pk_f32_fp4 v[46:47], v47, 1.0 op_sel:[1,1,0]
	s_nop 0
	v_pk_fma_f32 v[140:141], s[16:17], v[44:45], v[140:141]
	v_pk_fma_f32 v[138:139], s[16:17], v[66:67], v[138:139]
	v_pk_fma_f32 v[136:137], s[16:17], v[68:69], v[136:137]
	v_pk_fma_f32 v[134:135], s[16:17], v[46:47], v[134:135]
	s_add_i32 s16, s27, -5
	v_readlane_b32 s16, v64, s16
	s_lshr_b32 s40, s16, 7
	s_lshl_b64 s[16:17], s[40:41], 10
	s_add_u32 s16, s16, s100
	s_addc_u32 s17, s17, s101
	global_load_dwordx4 v[44:47], v207, s[16:17]
	v_readlane_b32 s16, v65, 11
	s_waitcnt vmcnt(15)
	v_cvt_scalef32_pk_f32_fp4 v[66:67], v48, 1.0
	v_cvt_scalef32_pk_f32_fp4 v[68:69], v48, 1.0 op_sel:[1,0,0]
	v_cvt_scalef32_pk_f32_fp4 v[70:71], v48, 1.0 op_sel:[0,1,0]
	s_mov_b32 s17, s16
	v_cvt_scalef32_pk_f32_fp4 v[72:73], v48, 1.0 op_sel:[1,1,0]
	v_pk_fma_f32 v[132:133], s[16:17], v[66:67], v[132:133]
	v_pk_fma_f32 v[162:163], s[16:17], v[68:69], v[162:163]
	v_pk_fma_f32 v[160:161], s[16:17], v[70:71], v[160:161]
	s_nop 0
	v_pk_fma_f32 v[158:159], s[16:17], v[72:73], v[158:159]
	v_cvt_scalef32_pk_f32_fp4 v[66:67], v49, 1.0
	v_cvt_scalef32_pk_f32_fp4 v[68:69], v49, 1.0 op_sel:[1,0,0]
	v_cvt_scalef32_pk_f32_fp4 v[70:71], v49, 1.0 op_sel:[0,1,0]
	v_cvt_scalef32_pk_f32_fp4 v[48:49], v49, 1.0 op_sel:[1,1,0]
	s_nop 0
	v_pk_fma_f32 v[156:157], s[16:17], v[66:67], v[156:157]
	v_pk_fma_f32 v[154:155], s[16:17], v[68:69], v[154:155]
	v_pk_fma_f32 v[152:153], s[16:17], v[70:71], v[152:153]
	v_pk_fma_f32 v[150:151], s[16:17], v[48:49], v[150:151]
	v_cvt_scalef32_pk_f32_fp4 v[48:49], v50, 1.0
	v_cvt_scalef32_pk_f32_fp4 v[66:67], v50, 1.0 op_sel:[1,0,0]
	v_cvt_scalef32_pk_f32_fp4 v[68:69], v50, 1.0 op_sel:[0,1,0]
	v_cvt_scalef32_pk_f32_fp4 v[70:71], v50, 1.0 op_sel:[1,1,0]
	s_nop 0
	v_pk_fma_f32 v[148:149], s[16:17], v[48:49], v[148:149]
	v_pk_fma_f32 v[146:147], s[16:17], v[66:67], v[146:147]
	v_pk_fma_f32 v[144:145], s[16:17], v[68:69], v[144:145]
	v_pk_fma_f32 v[142:143], s[16:17], v[70:71], v[142:143]
	v_cvt_scalef32_pk_f32_fp4 v[48:49], v51, 1.0
	v_cvt_scalef32_pk_f32_fp4 v[66:67], v51, 1.0 op_sel:[1,0,0]
	v_cvt_scalef32_pk_f32_fp4 v[68:69], v51, 1.0 op_sel:[0,1,0]
	v_cvt_scalef32_pk_f32_fp4 v[50:51], v51, 1.0 op_sel:[1,1,0]
	s_nop 0
	v_pk_fma_f32 v[140:141], s[16:17], v[48:49], v[140:141]
	v_pk_fma_f32 v[138:139], s[16:17], v[66:67], v[138:139]
	v_pk_fma_f32 v[136:137], s[16:17], v[68:69], v[136:137]
	v_pk_fma_f32 v[134:135], s[16:17], v[50:51], v[134:135]
	s_add_i32 s16, s27, -4
	v_readlane_b32 s16, v64, s16
	s_lshr_b32 s40, s16, 7
	s_lshl_b64 s[16:17], s[40:41], 10
	s_add_u32 s16, s16, s100
	s_addc_u32 s17, s17, s101
	global_load_dwordx4 v[48:51], v207, s[16:17]
	v_readlane_b32 s16, v65, 12
	s_waitcnt vmcnt(15)
; #define P4_FOR16(M) M(0) M(1) M(2) M(3) M(4) M(5) M(6) M(7) M(8) M(9) M(10) M(11) M(12) M(13) M(14) M(15)
; #define P4_V(i) { const unsigned wu_ = (unsigned)__builtin_amdgcn_readlane((int)__float_as_uint(wreg), i); const unsigned long long wp_ = ((unsigned long long)wu_ << 32) | wu_; \
;               P4_ACC(b##i, wp_); const int nk_ = __builtin_amdgcn_readlane(ksel, nb + i); P4_LOAD(b##i, Vg, nk_); }
; #define P4_V(i) { const unsigned wu_ = (unsigned)__builtin_amdgcn_readlane((int)__float_as_uint(wreg), i); const unsigned long long wp_ = ((unsigned long long)wu_ << 32) | wu_; \
;               P4_ACC(b##i, wp_); const int nk_ = __builtin_amdgcn_readlane(kn, i); P4_LOAD(b##i, Vg, nk_); }
; #define P4_V(i) { const unsigned wu_ = (unsigned)__builtin_amdgcn_readlane((int)__float_as_uint(wreg), i); const unsigned long long wp_ = ((unsigned long long)wu_ << 32) | wu_; \
;               P4_ACC(b##i, wp_); }
; __device__ __forceinline__ void peer_gather_f4p(const float* X, const int* __restrict__ IDX, const float* __restrict__ G, ...
;     ...
; #pragma unroll 1
;         for (int bt = 0; bt < 7; ++bt) {
;             const int ksel = (bt + 1 < 4) ? k0 : k1;
;             const int nb = (16 * (bt + 1)) & 63;
;             const float wreg = wbuf[kt * 128 + bt * 16 + (lane & 15)];
;     ...
;             P4_FOR16(P4_V)
;     ...
;         }
	v_cvt_scalef32_pk_f32_fp4 v[66:67], v52, 1.0
	v_cvt_scalef32_pk_f32_fp4 v[68:69], v52, 1.0 op_sel:[1,0,0]
	v_cvt_scalef32_pk_f32_fp4 v[70:71], v52, 1.0 op_sel:[0,1,0]
	s_mov_b32 s17, s16
	v_cvt_scalef32_pk_f32_fp4 v[72:73], v52, 1.0 op_sel:[1,1,0]
	v_pk_fma_f32 v[132:133], s[16:17], v[66:67], v[132:133]
	v_pk_fma_f32 v[162:163], s[16:17], v[68:69], v[162:163]
	v_pk_fma_f32 v[160:161], s[16:17], v[70:71], v[160:161]
	s_nop 0
	v_pk_fma_f32 v[158:159], s[16:17], v[72:73], v[158:159]
	v_cvt_scalef32_pk_f32_fp4 v[66:67], v53, 1.0
	v_cvt_scalef32_pk_f32_fp4 v[68:69], v53, 1.0 op_sel:[1,0,0]
	v_cvt_scalef32_pk_f32_fp4 v[70:71], v53, 1.0 op_sel:[0,1,0]
	v_cvt_scalef32_pk_f32_fp4 v[52:53], v53, 1.0 op_sel:[1,1,0]
	s_nop 0
	v_pk_fma_f32 v[156:157], s[16:17], v[66:67], v[156:157]
	v_pk_fma_f32 v[154:155], s[16:17], v[68:69], v[154:155]
	v_pk_fma_f32 v[152:153], s[16:17], v[70:71], v[152:153]
	v_pk_fma_f32 v[150:151], s[16:17], v[52:53], v[150:151]
	v_cvt_scalef32_pk_f32_fp4 v[52:53], v54, 1.0
	v_cvt_scalef32_pk_f32_fp4 v[66:67], v54, 1.0 op_sel:[1,0,0]
	v_cvt_scalef32_pk_f32_fp4 v[68:69], v54, 1.0 op_sel:[0,1,0]
	v_cvt_scalef32_pk_f32_fp4 v[70:71], v54, 1.0 op_sel:[1,1,0]
	s_nop 0
	v_pk_fma_f32 v[148:149], s[16:17], v[52:53], v[148:149]
	v_pk_fma_f32 v[146:147], s[16:17], v[66:67], v[146:147]
	v_pk_fma_f32 v[144:145], s[16:17], v[68:69], v[144:145]
	v_pk_fma_f32 v[142:143], s[16:17], v[70:71], v[142:143]
	v_cvt_scalef32_pk_f32_fp4 v[52:53], v55, 1.0
	v_cvt_scalef32_pk_f32_fp4 v[66:67], v55, 1.0 op_sel:[1,0,0]
	v_cvt_scalef32_pk_f32_fp4 v[68:69], v55, 1.0 op_sel:[0,1,0]
	v_cvt_scalef32_pk_f32_fp4 v[54:55], v55, 1.0 op_sel:[1,1,0]
	s_nop 0
	v_pk_fma_f32 v[140:141], s[16:17], v[52:53], v[140:141]
	v_pk_fma_f32 v[138:139], s[16:17], v[66:67], v[138:139]
	v_pk_fma_f32 v[136:137], s[16:17], v[68:69], v[136:137]
	v_pk_fma_f32 v[134:135], s[16:17], v[54:55], v[134:135]
	s_add_i32 s16, s27, -3
	v_readlane_b32 s16, v64, s16
	s_lshr_b32 s40, s16, 7
	s_lshl_b64 s[16:17], s[40:41], 10
	s_add_u32 s16, s16, s100
	s_addc_u32 s17, s17, s101
	global_load_dwordx4 v[52:55], v207, s[16:17]
	v_readlane_b32 s16, v65, 13
	s_waitcnt vmcnt(15)
	v_cvt_scalef32_pk_f32_fp4 v[66:67], v56, 1.0
	v_cvt_scalef32_pk_f32_fp4 v[68:69], v56, 1.0 op_sel:[1,0,0]
	v_cvt_scalef32_pk_f32_fp4 v[70:71], v56, 1.0 op_sel:[0,1,0]
	s_mov_b32 s17, s16
	v_cvt_scalef32_pk_f32_fp4 v[72:73], v56, 1.0 op_sel:[1,1,0]
	v_pk_fma_f32 v[132:133], s[16:17], v[66:67], v[132:133]
	v_pk_fma_f32 v[162:163], s[16:17], v[68:69], v[162:163]
	v_pk_fma_f32 v[160:161], s[16:17], v[70:71], v[160:161]
	s_nop 0
	v_pk_fma_f32 v[158:159], s[16:17], v[72:73], v[158:159]
	v_cvt_scalef32_pk_f32_fp4 v[66:67], v57, 1.0
	v_cvt_scalef32_pk_f32_fp4 v[68:69], v57, 1.0 op_sel:[1,0,0]
	v_cvt_scalef32_pk_f32_fp4 v[70:71], v57, 1.0 op_sel:[0,1,0]
	v_cvt_scalef32_pk_f32_fp4 v[56:57], v57, 1.0 op_sel:[1,1,0]
	s_nop 0
	v_pk_fma_f32 v[156:157], s[16:17], v[66:67], v[156:157]
	v_pk_fma_f32 v[154:155], s[16:17], v[68:69], v[154:155]
	v_pk_fma_f32 v[152:153], s[16:17], v[70:71], v[152:153]
	v_pk_fma_f32 v[150:151], s[16:17], v[56:57], v[150:151]
	v_cvt_scalef32_pk_f32_fp4 v[56:57], v58, 1.0
	v_cvt_scalef32_pk_f32_fp4 v[66:67], v58, 1.0 op_sel:[1,0,0]
	v_cvt_scalef32_pk_f32_fp4 v[68:69], v58, 1.0 op_sel:[0,1,0]
	v_cvt_scalef32_pk_f32_fp4 v[70:71], v58, 1.0 op_sel:[1,1,0]
	s_nop 0
	v_pk_fma_f32 v[148:149], s[16:17], v[56:57], v[148:149]
	v_pk_fma_f32 v[146:147], s[16:17], v[66:67], v[146:147]
	v_pk_fma_f32 v[144:145], s[16:17], v[68:69], v[144:145]
	v_pk_fma_f32 v[142:143], s[16:17], v[70:71], v[142:143]
	v_cvt_scalef32_pk_f32_fp4 v[56:57], v59, 1.0
	v_cvt_scalef32_pk_f32_fp4 v[66:67], v59, 1.0 op_sel:[1,0,0]
	v_cvt_scalef32_pk_f32_fp4 v[68:69], v59, 1.0 op_sel:[0,1,0]
	v_cvt_scalef32_pk_f32_fp4 v[58:59], v59, 1.0 op_sel:[1,1,0]
	s_nop 0
	v_pk_fma_f32 v[140:141], s[16:17], v[56:57], v[140:141]
	v_pk_fma_f32 v[138:139], s[16:17], v[66:67], v[138:139]
	v_pk_fma_f32 v[136:137], s[16:17], v[68:69], v[136:137]
	v_pk_fma_f32 v[134:135], s[16:17], v[58:59], v[134:135]
	s_add_i32 s16, s27, -2
	v_readlane_b32 s16, v64, s16
	s_lshr_b32 s40, s16, 7
	s_lshl_b64 s[16:17], s[40:41], 10
	s_add_u32 s16, s16, s100
	s_addc_u32 s17, s17, s101
	global_load_dwordx4 v[56:59], v207, s[16:17]
	v_readlane_b32 s16, v65, 14
	s_waitcnt vmcnt(15)
	v_cvt_scalef32_pk_f32_fp4 v[66:67], v60, 1.0
	v_cvt_scalef32_pk_f32_fp4 v[68:69], v60, 1.0 op_sel:[1,0,0]
	v_cvt_scalef32_pk_f32_fp4 v[70:71], v60, 1.0 op_sel:[0,1,0]
	s_mov_b32 s17, s16
	v_cvt_scalef32_pk_f32_fp4 v[72:73], v60, 1.0 op_sel:[1,1,0]
	v_pk_fma_f32 v[132:133], s[16:17], v[66:67], v[132:133]
	v_pk_fma_f32 v[162:163], s[16:17], v[68:69], v[162:163]
	v_pk_fma_f32 v[160:161], s[16:17], v[70:71], v[160:161]
	s_nop 0
	v_pk_fma_f32 v[158:159], s[16:17], v[72:73], v[158:159]
	v_cvt_scalef32_pk_f32_fp4 v[66:67], v61, 1.0
	v_cvt_scalef32_pk_f32_fp4 v[68:69], v61, 1.0 op_sel:[1,0,0]
	v_cvt_scalef32_pk_f32_fp4 v[70:71], v61, 1.0 op_sel:[0,1,0]
	v_cvt_scalef32_pk_f32_fp4 v[60:61], v61, 1.0 op_sel:[1,1,0]
	s_nop 0
	v_pk_fma_f32 v[156:157], s[16:17], v[66:67], v[156:157]
	v_pk_fma_f32 v[154:155], s[16:17], v[68:69], v[154:155]
	v_pk_fma_f32 v[152:153], s[16:17], v[70:71], v[152:153]
	v_pk_fma_f32 v[150:151], s[16:17], v[60:61], v[150:151]
	v_cvt_scalef32_pk_f32_fp4 v[60:61], v62, 1.0
	v_cvt_scalef32_pk_f32_fp4 v[66:67], v62, 1.0 op_sel:[1,0,0]
	v_cvt_scalef32_pk_f32_fp4 v[68:69], v62, 1.0 op_sel:[0,1,0]
	v_cvt_scalef32_pk_f32_fp4 v[70:71], v62, 1.0 op_sel:[1,1,0]
	s_nop 0
	v_pk_fma_f32 v[148:149], s[16:17], v[60:61], v[148:149]
	v_pk_fma_f32 v[146:147], s[16:17], v[66:67], v[146:147]
	v_pk_fma_f32 v[144:145], s[16:17], v[68:69], v[144:145]
	v_pk_fma_f32 v[142:143], s[16:17], v[70:71], v[142:143]
	v_cvt_scalef32_pk_f32_fp4 v[60:61], v63, 1.0
	v_cvt_scalef32_pk_f32_fp4 v[66:67], v63, 1.0 op_sel:[1,0,0]
	v_cvt_scalef32_pk_f32_fp4 v[68:69], v63, 1.0 op_sel:[0,1,0]
	v_cvt_scalef32_pk_f32_fp4 v[62:63], v63, 1.0 op_sel:[1,1,0]
	s_nop 0
	v_pk_fma_f32 v[140:141], s[16:17], v[60:61], v[140:141]
	v_pk_fma_f32 v[138:139], s[16:17], v[66:67], v[138:139]
	v_pk_fma_f32 v[136:137], s[16:17], v[68:69], v[136:137]
	v_pk_fma_f32 v[134:135], s[16:17], v[62:63], v[134:135]
	s_add_i32 s16, s27, -1
	v_readlane_b32 s16, v64, s16
	s_lshr_b32 s40, s16, 7
	s_lshl_b64 s[16:17], s[40:41], 10
	s_add_u32 s16, s16, s100
	s_addc_u32 s17, s17, s101
	global_load_dwordx4 v[60:63], v207, s[16:17]
	v_readlane_b32 s16, v65, 15
	s_waitcnt vmcnt(15)
; #define P4_FOR16(M) M(0) M(1) M(2) M(3) M(4) M(5) M(6) M(7) M(8) M(9) M(10) M(11) M(12) M(13) M(14) M(15)
; #define P4_V(i) { const unsigned wu_ = (unsigned)__builtin_amdgcn_readlane((int)__float_as_uint(wreg), i); const unsigned long long wp_ = ((unsigned long long)wu_ << 32) | wu_; \
;               P4_ACC(b##i, wp_); const int nk_ = __builtin_amdgcn_readlane(ksel, nb + i); P4_LOAD(b##i, Vg, nk_); }
; #define P4_V(i) { const unsigned wu_ = (unsigned)__builtin_amdgcn_readlane((int)__float_as_uint(wreg), i); const unsigned long long wp_ = ((unsigned long long)wu_ << 32) | wu_; \
;               P4_ACC(b##i, wp_); const int nk_ = __builtin_amdgcn_readlane(kn, i); P4_LOAD(b##i, Vg, nk_); }
; #define P4_V(i) { const unsigned wu_ = (unsigned)__builtin_amdgcn_readlane((int)__float_as_uint(wreg), i); const unsigned long long wp_ = ((unsigned long long)wu_ << 32) | wu_; \
;               P4_ACC(b##i, wp_); }
; __device__ __forceinline__ void peer_gather_f4p(const float* X, const int* __restrict__ IDX, const float* __restrict__ G, ...
;     ...
; #pragma unroll 1
;         for (int bt = 0; bt < 7; ++bt) {
;             const int ksel = (bt + 1 < 4) ? k0 : k1;
;             const int nb = (16 * (bt + 1)) & 63;
;             const float wreg = wbuf[kt * 128 + bt * 16 + (lane & 15)];
;     ...
;             P4_FOR16(P4_V)
;     ...
;         }
;         {
;             const float wreg = wbuf[kt * 128 + 7 * 16 + (lane & 15)];
;             if (kt < 3) {
;     ...
;                 P4_FOR16(P4_V)
	v_cvt_scalef32_pk_f32_fp4 v[66:67], v80, 1.0
	v_cvt_scalef32_pk_f32_fp4 v[68:69], v80, 1.0 op_sel:[1,0,0]
	v_cvt_scalef32_pk_f32_fp4 v[70:71], v80, 1.0 op_sel:[0,1,0]
	v_cvt_scalef32_pk_f32_fp4 v[72:73], v80, 1.0 op_sel:[1,1,0]
	s_mov_b32 s17, s16
	v_pk_fma_f32 v[132:133], s[16:17], v[66:67], v[132:133]
	v_pk_fma_f32 v[162:163], s[16:17], v[68:69], v[162:163]
	v_pk_fma_f32 v[160:161], s[16:17], v[70:71], v[160:161]
	v_pk_fma_f32 v[158:159], s[16:17], v[72:73], v[158:159]
	v_cvt_scalef32_pk_f32_fp4 v[66:67], v81, 1.0
	v_cvt_scalef32_pk_f32_fp4 v[68:69], v81, 1.0 op_sel:[1,0,0]
	v_cvt_scalef32_pk_f32_fp4 v[70:71], v81, 1.0 op_sel:[0,1,0]
	v_cvt_scalef32_pk_f32_fp4 v[72:73], v81, 1.0 op_sel:[1,1,0]
	s_nop 0
	v_pk_fma_f32 v[156:157], s[16:17], v[66:67], v[156:157]
	v_pk_fma_f32 v[154:155], s[16:17], v[68:69], v[154:155]
	v_pk_fma_f32 v[152:153], s[16:17], v[70:71], v[152:153]
	v_pk_fma_f32 v[150:151], s[16:17], v[72:73], v[150:151]
	v_cvt_scalef32_pk_f32_fp4 v[66:67], v82, 1.0
	v_cvt_scalef32_pk_f32_fp4 v[68:69], v82, 1.0 op_sel:[1,0,0]
	v_cvt_scalef32_pk_f32_fp4 v[70:71], v82, 1.0 op_sel:[0,1,0]
	v_cvt_scalef32_pk_f32_fp4 v[72:73], v82, 1.0 op_sel:[1,1,0]
	s_nop 0
	v_pk_fma_f32 v[148:149], s[16:17], v[66:67], v[148:149]
	v_pk_fma_f32 v[146:147], s[16:17], v[68:69], v[146:147]
	v_pk_fma_f32 v[144:145], s[16:17], v[70:71], v[144:145]
	v_pk_fma_f32 v[142:143], s[16:17], v[72:73], v[142:143]
	v_cvt_scalef32_pk_f32_fp4 v[66:67], v83, 1.0
	v_cvt_scalef32_pk_f32_fp4 v[68:69], v83, 1.0 op_sel:[1,0,0]
	v_cvt_scalef32_pk_f32_fp4 v[70:71], v83, 1.0 op_sel:[0,1,0]
	v_cvt_scalef32_pk_f32_fp4 v[72:73], v83, 1.0 op_sel:[1,1,0]
	s_nop 0
	v_pk_fma_f32 v[140:141], s[16:17], v[66:67], v[140:141]
	v_pk_fma_f32 v[138:139], s[16:17], v[68:69], v[138:139]
	v_pk_fma_f32 v[136:137], s[16:17], v[70:71], v[136:137]
	v_pk_fma_f32 v[134:135], s[16:17], v[72:73], v[134:135]
	v_readlane_b32 s16, v64, s27
	s_lshr_b32 s40, s16, 7
	s_lshl_b64 s[40:41], s[40:41], 10
	s_add_u32 s40, s40, s100
	s_addc_u32 s41, s41, s101
	global_load_dwordx4 v[80:83], v207, s[40:41]
	s_add_i32 s27, s27, 16
	s_cmpk_eq_i32 s27, 0x8f
	s_cbranch_scc0 .LBB0_1247
	v_lshl_add_u32 v64, v170, 2, s26
	ds_read_b32 v209, v64 offset:4544
	s_cmp_lg_u32 s19, 3
	s_mov_b64 s[40:41], -1
	s_cbranch_scc0 .LBB0_1250
	v_readlane_b32 s16, v208, 0
	s_waitcnt lgkmcnt(0)
	v_readlane_b32 s40, v209, 0
	s_waitcnt vmcnt(15)
	v_cvt_scalef32_pk_f32_fp4 v[64:65], v4, 1.0
	v_mov_b64_e32 v[166:167], v[132:133]
	v_mov_b64_e32 v[168:169], v[162:163]
	v_mov_b64_e32 v[170:171], v[160:161]
	v_mov_b64_e32 v[172:173], v[158:159]
	s_lshr_b32 s16, s16, 7
	s_mov_b32 s17, s86
	s_mov_b32 s41, s40
	v_cvt_scalef32_pk_f32_fp4 v[66:67], v4, 1.0 op_sel:[1,0,0]
	v_cvt_scalef32_pk_f32_fp4 v[68:69], v4, 1.0 op_sel:[0,1,0]
	v_cvt_scalef32_pk_f32_fp4 v[70:71], v4, 1.0 op_sel:[1,1,0]
	v_pk_fma_f32 v[166:167], s[40:41], v[64:65], v[166:167]
	v_mov_b64_e32 v[174:175], v[156:157]
	v_pk_fma_f32 v[168:169], s[40:41], v[66:67], v[168:169]
	v_pk_fma_f32 v[170:171], s[40:41], v[68:69], v[170:171]
	v_pk_fma_f32 v[172:173], s[40:41], v[70:71], v[172:173]
	v_cvt_scalef32_pk_f32_fp4 v[64:65], v5, 1.0
	v_mov_b64_e32 v[176:177], v[154:155]
	v_mov_b64_e32 v[178:179], v[152:153]
	v_mov_b64_e32 v[180:181], v[150:151]
	s_lshl_b64 s[16:17], s[16:17], 10
	v_cvt_scalef32_pk_f32_fp4 v[66:67], v5, 1.0 op_sel:[1,0,0]
	v_cvt_scalef32_pk_f32_fp4 v[68:69], v5, 1.0 op_sel:[0,1,0]
	v_cvt_scalef32_pk_f32_fp4 v[70:71], v5, 1.0 op_sel:[1,1,0]
	v_pk_fma_f32 v[174:175], s[40:41], v[64:65], v[174:175]
	v_mov_b64_e32 v[182:183], v[148:149]
	v_pk_fma_f32 v[176:177], s[40:41], v[66:67], v[176:177]
	v_pk_fma_f32 v[178:179], s[40:41], v[68:69], v[178:179]
	v_pk_fma_f32 v[180:181], s[40:41], v[70:71], v[180:181]
	v_cvt_scalef32_pk_f32_fp4 v[64:65], v6, 1.0
	v_mov_b64_e32 v[184:185], v[146:147]
	v_mov_b64_e32 v[186:187], v[144:145]
	v_mov_b64_e32 v[188:189], v[142:143]
	s_add_u32 s16, s52, s16
	v_cvt_scalef32_pk_f32_fp4 v[66:67], v6, 1.0 op_sel:[1,0,0]
	v_cvt_scalef32_pk_f32_fp4 v[68:69], v6, 1.0 op_sel:[0,1,0]
	v_cvt_scalef32_pk_f32_fp4 v[70:71], v6, 1.0 op_sel:[1,1,0]
	v_pk_fma_f32 v[182:183], s[40:41], v[64:65], v[182:183]
	v_mov_b64_e32 v[190:191], v[140:141]
	v_pk_fma_f32 v[184:185], s[40:41], v[66:67], v[184:185]
	v_pk_fma_f32 v[186:187], s[40:41], v[68:69], v[186:187]
	v_pk_fma_f32 v[188:189], s[40:41], v[70:71], v[188:189]
	v_cvt_scalef32_pk_f32_fp4 v[64:65], v7, 1.0
	s_addc_u32 s17, s53, s17
	v_cvt_scalef32_pk_f32_fp4 v[66:67], v7, 1.0 op_sel:[1,0,0]
	v_cvt_scalef32_pk_f32_fp4 v[68:69], v7, 1.0 op_sel:[0,1,0]
	v_cvt_scalef32_pk_f32_fp4 v[70:71], v7, 1.0 op_sel:[1,1,0]
	v_pk_fma_f32 v[190:191], s[40:41], v[64:65], v[190:191]
	v_mov_b64_e32 v[192:193], v[138:139]
	v_mov_b64_e32 v[194:195], v[136:137]
	v_mov_b64_e32 v[196:197], v[134:135]
	v_lshl_add_u64 v[64:65], s[16:17], 0, v[164:165]
	v_readlane_b32 s16, v208, 1
	v_pk_fma_f32 v[192:193], s[40:41], v[66:67], v[192:193]
	v_pk_fma_f32 v[194:195], s[40:41], v[68:69], v[194:195]
	v_pk_fma_f32 v[196:197], s[40:41], v[70:71], v[196:197]
	global_load_dwordx4 v[64:67], v[64:65], off
	v_readlane_b32 s40, v209, 1
	s_waitcnt vmcnt(15)
; #define P4_FOR16(M) M(0) M(1) M(2) M(3) M(4) M(5) M(6) M(7) M(8) M(9) M(10) M(11) M(12) M(13) M(14) M(15)
; #define P4_V(i) { const unsigned wu_ = (unsigned)__builtin_amdgcn_readlane((int)__float_as_uint(wreg), i); const unsigned long long wp_ = ((unsigned long long)wu_ << 32) | wu_; \
;               P4_ACC(b##i, wp_); const int nk_ = __builtin_amdgcn_readlane(ksel, nb + i); P4_LOAD(b##i, Vg, nk_); }
; #define P4_V(i) { const unsigned wu_ = (unsigned)__builtin_amdgcn_readlane((int)__float_as_uint(wreg), i); const unsigned long long wp_ = ((unsigned long long)wu_ << 32) | wu_; \
;               P4_ACC(b##i, wp_); const int nk_ = __builtin_amdgcn_readlane(kn, i); P4_LOAD(b##i, Vg, nk_); }
; #define P4_V(i) { const unsigned wu_ = (unsigned)__builtin_amdgcn_readlane((int)__float_as_uint(wreg), i); const unsigned long long wp_ = ((unsigned long long)wu_ << 32) | wu_; \
;               P4_ACC(b##i, wp_); }
; __device__ __forceinline__ void peer_gather_f4p(const float* X, const int* __restrict__ IDX, const float* __restrict__ G, ...
;     ...
;             if (kt < 3) {
;     ...
;                 P4_FOR16(P4_V)
	v_cvt_scalef32_pk_f32_fp4 v[68:69], v8, 1.0
	s_lshr_b32 s16, s16, 7
	s_mov_b32 s17, s86
	s_mov_b32 s41, s40
	v_cvt_scalef32_pk_f32_fp4 v[70:71], v8, 1.0 op_sel:[1,0,0]
	v_cvt_scalef32_pk_f32_fp4 v[72:73], v8, 1.0 op_sel:[0,1,0]
	v_cvt_scalef32_pk_f32_fp4 v[74:75], v8, 1.0 op_sel:[1,1,0]
	v_pk_fma_f32 v[166:167], s[40:41], v[68:69], v[166:167]
	s_lshl_b64 s[16:17], s[16:17], 10
	v_pk_fma_f32 v[168:169], s[40:41], v[70:71], v[168:169]
	v_pk_fma_f32 v[170:171], s[40:41], v[72:73], v[170:171]
	v_pk_fma_f32 v[172:173], s[40:41], v[74:75], v[172:173]
	v_cvt_scalef32_pk_f32_fp4 v[68:69], v9, 1.0
	v_cvt_scalef32_pk_f32_fp4 v[70:71], v9, 1.0 op_sel:[1,0,0]
	v_cvt_scalef32_pk_f32_fp4 v[72:73], v9, 1.0 op_sel:[0,1,0]
	v_cvt_scalef32_pk_f32_fp4 v[74:75], v9, 1.0 op_sel:[1,1,0]
	s_add_u32 s16, s52, s16
	v_pk_fma_f32 v[174:175], s[40:41], v[68:69], v[174:175]
	v_pk_fma_f32 v[176:177], s[40:41], v[70:71], v[176:177]
	v_pk_fma_f32 v[178:179], s[40:41], v[72:73], v[178:179]
	v_pk_fma_f32 v[180:181], s[40:41], v[74:75], v[180:181]
	v_cvt_scalef32_pk_f32_fp4 v[68:69], v10, 1.0
	v_cvt_scalef32_pk_f32_fp4 v[70:71], v10, 1.0 op_sel:[1,0,0]
	v_cvt_scalef32_pk_f32_fp4 v[72:73], v10, 1.0 op_sel:[0,1,0]
	v_cvt_scalef32_pk_f32_fp4 v[74:75], v10, 1.0 op_sel:[1,1,0]
	s_addc_u32 s17, s53, s17
	v_pk_fma_f32 v[182:183], s[40:41], v[68:69], v[182:183]
	v_pk_fma_f32 v[184:185], s[40:41], v[70:71], v[184:185]
	v_pk_fma_f32 v[186:187], s[40:41], v[72:73], v[186:187]
	v_pk_fma_f32 v[188:189], s[40:41], v[74:75], v[188:189]
	v_cvt_scalef32_pk_f32_fp4 v[68:69], v11, 1.0
	v_cvt_scalef32_pk_f32_fp4 v[70:71], v11, 1.0 op_sel:[1,0,0]
	v_cvt_scalef32_pk_f32_fp4 v[72:73], v11, 1.0 op_sel:[0,1,0]
	v_cvt_scalef32_pk_f32_fp4 v[74:75], v11, 1.0 op_sel:[1,1,0]
	s_nop 0
	v_pk_fma_f32 v[190:191], s[40:41], v[68:69], v[190:191]
	v_lshl_add_u64 v[68:69], s[16:17], 0, v[164:165]
	v_readlane_b32 s16, v208, 2
	v_pk_fma_f32 v[192:193], s[40:41], v[70:71], v[192:193]
	v_pk_fma_f32 v[194:195], s[40:41], v[72:73], v[194:195]
	v_pk_fma_f32 v[196:197], s[40:41], v[74:75], v[196:197]
	global_load_dwordx4 v[68:71], v[68:69], off
	v_readlane_b32 s40, v209, 2
	s_waitcnt vmcnt(15)
	v_cvt_scalef32_pk_f32_fp4 v[72:73], v12, 1.0
	s_lshr_b32 s16, s16, 7
	s_mov_b32 s17, s86
	s_mov_b32 s41, s40
	v_cvt_scalef32_pk_f32_fp4 v[74:75], v12, 1.0 op_sel:[1,0,0]
	v_cvt_scalef32_pk_f32_fp4 v[76:77], v12, 1.0 op_sel:[0,1,0]
	v_cvt_scalef32_pk_f32_fp4 v[78:79], v12, 1.0 op_sel:[1,1,0]
	v_pk_fma_f32 v[166:167], s[40:41], v[72:73], v[166:167]
	s_lshl_b64 s[16:17], s[16:17], 10
	v_pk_fma_f32 v[168:169], s[40:41], v[74:75], v[168:169]
	v_pk_fma_f32 v[170:171], s[40:41], v[76:77], v[170:171]
	v_pk_fma_f32 v[172:173], s[40:41], v[78:79], v[172:173]
	v_cvt_scalef32_pk_f32_fp4 v[72:73], v13, 1.0
	v_cvt_scalef32_pk_f32_fp4 v[74:75], v13, 1.0 op_sel:[1,0,0]
	v_cvt_scalef32_pk_f32_fp4 v[76:77], v13, 1.0 op_sel:[0,1,0]
	v_cvt_scalef32_pk_f32_fp4 v[78:79], v13, 1.0 op_sel:[1,1,0]
	s_add_u32 s16, s52, s16
	v_pk_fma_f32 v[174:175], s[40:41], v[72:73], v[174:175]
	v_pk_fma_f32 v[176:177], s[40:41], v[74:75], v[176:177]
	v_pk_fma_f32 v[178:179], s[40:41], v[76:77], v[178:179]
	v_pk_fma_f32 v[180:181], s[40:41], v[78:79], v[180:181]
	v_cvt_scalef32_pk_f32_fp4 v[72:73], v14, 1.0
	v_cvt_scalef32_pk_f32_fp4 v[74:75], v14, 1.0 op_sel:[1,0,0]
	v_cvt_scalef32_pk_f32_fp4 v[76:77], v14, 1.0 op_sel:[0,1,0]
	v_cvt_scalef32_pk_f32_fp4 v[78:79], v14, 1.0 op_sel:[1,1,0]
	s_addc_u32 s17, s53, s17
	v_pk_fma_f32 v[182:183], s[40:41], v[72:73], v[182:183]
	v_pk_fma_f32 v[184:185], s[40:41], v[74:75], v[184:185]
	v_pk_fma_f32 v[186:187], s[40:41], v[76:77], v[186:187]
	v_pk_fma_f32 v[188:189], s[40:41], v[78:79], v[188:189]
	v_cvt_scalef32_pk_f32_fp4 v[72:73], v15, 1.0
	v_cvt_scalef32_pk_f32_fp4 v[74:75], v15, 1.0 op_sel:[1,0,0]
	v_cvt_scalef32_pk_f32_fp4 v[76:77], v15, 1.0 op_sel:[0,1,0]
	v_cvt_scalef32_pk_f32_fp4 v[78:79], v15, 1.0 op_sel:[1,1,0]
	s_nop 0
	v_pk_fma_f32 v[190:191], s[40:41], v[72:73], v[190:191]
	v_lshl_add_u64 v[72:73], s[16:17], 0, v[164:165]
	v_readlane_b32 s16, v208, 3
	v_pk_fma_f32 v[192:193], s[40:41], v[74:75], v[192:193]
	v_pk_fma_f32 v[194:195], s[40:41], v[76:77], v[194:195]
	v_pk_fma_f32 v[196:197], s[40:41], v[78:79], v[196:197]
	global_load_dwordx4 v[72:75], v[72:73], off
	v_readlane_b32 s40, v209, 3
	s_waitcnt vmcnt(15)
	v_cvt_scalef32_pk_f32_fp4 v[76:77], v16, 1.0
	s_lshr_b32 s16, s16, 7
	s_mov_b32 s17, s86
	s_mov_b32 s41, s40
	v_cvt_scalef32_pk_f32_fp4 v[78:79], v16, 1.0 op_sel:[1,0,0]
	v_cvt_scalef32_pk_f32_fp4 v[84:85], v16, 1.0 op_sel:[0,1,0]
	v_cvt_scalef32_pk_f32_fp4 v[86:87], v16, 1.0 op_sel:[1,1,0]
	v_pk_fma_f32 v[166:167], s[40:41], v[76:77], v[166:167]
	s_lshl_b64 s[16:17], s[16:17], 10
	v_pk_fma_f32 v[168:169], s[40:41], v[78:79], v[168:169]
	v_pk_fma_f32 v[170:171], s[40:41], v[84:85], v[170:171]
	v_pk_fma_f32 v[172:173], s[40:41], v[86:87], v[172:173]
	v_cvt_scalef32_pk_f32_fp4 v[76:77], v17, 1.0
	v_cvt_scalef32_pk_f32_fp4 v[78:79], v17, 1.0 op_sel:[1,0,0]
	v_cvt_scalef32_pk_f32_fp4 v[84:85], v17, 1.0 op_sel:[0,1,0]
	v_cvt_scalef32_pk_f32_fp4 v[86:87], v17, 1.0 op_sel:[1,1,0]
	s_add_u32 s16, s52, s16
	v_pk_fma_f32 v[174:175], s[40:41], v[76:77], v[174:175]
	v_pk_fma_f32 v[176:177], s[40:41], v[78:79], v[176:177]
	v_pk_fma_f32 v[178:179], s[40:41], v[84:85], v[178:179]
	v_pk_fma_f32 v[180:181], s[40:41], v[86:87], v[180:181]
	v_cvt_scalef32_pk_f32_fp4 v[76:77], v18, 1.0
	v_cvt_scalef32_pk_f32_fp4 v[78:79], v18, 1.0 op_sel:[1,0,0]
	v_cvt_scalef32_pk_f32_fp4 v[84:85], v18, 1.0 op_sel:[0,1,0]
	v_cvt_scalef32_pk_f32_fp4 v[86:87], v18, 1.0 op_sel:[1,1,0]
	s_addc_u32 s17, s53, s17
	v_pk_fma_f32 v[182:183], s[40:41], v[76:77], v[182:183]
	v_pk_fma_f32 v[184:185], s[40:41], v[78:79], v[184:185]
	v_pk_fma_f32 v[186:187], s[40:41], v[84:85], v[186:187]
	v_pk_fma_f32 v[188:189], s[40:41], v[86:87], v[188:189]
	v_cvt_scalef32_pk_f32_fp4 v[76:77], v19, 1.0
	v_cvt_scalef32_pk_f32_fp4 v[78:79], v19, 1.0 op_sel:[1,0,0]
	v_cvt_scalef32_pk_f32_fp4 v[84:85], v19, 1.0 op_sel:[0,1,0]
	v_cvt_scalef32_pk_f32_fp4 v[86:87], v19, 1.0 op_sel:[1,1,0]
	s_nop 0
	v_pk_fma_f32 v[190:191], s[40:41], v[76:77], v[190:191]
	v_lshl_add_u64 v[76:77], s[16:17], 0, v[164:165]
	v_readlane_b32 s16, v208, 4
	v_pk_fma_f32 v[192:193], s[40:41], v[78:79], v[192:193]
	v_pk_fma_f32 v[194:195], s[40:41], v[84:85], v[194:195]
	v_pk_fma_f32 v[196:197], s[40:41], v[86:87], v[196:197]
	global_load_dwordx4 v[76:79], v[76:77], off
	v_readlane_b32 s40, v209, 4
	s_waitcnt vmcnt(15)
; #define P4_FOR16(M) M(0) M(1) M(2) M(3) M(4) M(5) M(6) M(7) M(8) M(9) M(10) M(11) M(12) M(13) M(14) M(15)
; #define P4_V(i) { const unsigned wu_ = (unsigned)__builtin_amdgcn_readlane((int)__float_as_uint(wreg), i); const unsigned long long wp_ = ((unsigned long long)wu_ << 32) | wu_; \
;               P4_ACC(b##i, wp_); const int nk_ = __builtin_amdgcn_readlane(ksel, nb + i); P4_LOAD(b##i, Vg, nk_); }
; #define P4_V(i) { const unsigned wu_ = (unsigned)__builtin_amdgcn_readlane((int)__float_as_uint(wreg), i); const unsigned long long wp_ = ((unsigned long long)wu_ << 32) | wu_; \
;               P4_ACC(b##i, wp_); const int nk_ = __builtin_amdgcn_readlane(kn, i); P4_LOAD(b##i, Vg, nk_); }
; #define P4_V(i) { const unsigned wu_ = (unsigned)__builtin_amdgcn_readlane((int)__float_as_uint(wreg), i); const unsigned long long wp_ = ((unsigned long long)wu_ << 32) | wu_; \
;               P4_ACC(b##i, wp_); }
; __device__ __forceinline__ void peer_gather_f4p(const float* X, const int* __restrict__ IDX, const float* __restrict__ G, ...
;     ...
;             if (kt < 3) {
;     ...
;                 P4_FOR16(P4_V)
	v_cvt_scalef32_pk_f32_fp4 v[84:85], v20, 1.0
	s_lshr_b32 s16, s16, 7
	s_mov_b32 s17, s86
	s_mov_b32 s41, s40
	v_cvt_scalef32_pk_f32_fp4 v[86:87], v20, 1.0 op_sel:[1,0,0]
	v_cvt_scalef32_pk_f32_fp4 v[88:89], v20, 1.0 op_sel:[0,1,0]
	v_cvt_scalef32_pk_f32_fp4 v[90:91], v20, 1.0 op_sel:[1,1,0]
	v_pk_fma_f32 v[166:167], s[40:41], v[84:85], v[166:167]
	s_lshl_b64 s[16:17], s[16:17], 10
	v_pk_fma_f32 v[168:169], s[40:41], v[86:87], v[168:169]
	v_pk_fma_f32 v[170:171], s[40:41], v[88:89], v[170:171]
	v_pk_fma_f32 v[172:173], s[40:41], v[90:91], v[172:173]
	v_cvt_scalef32_pk_f32_fp4 v[84:85], v21, 1.0
	v_cvt_scalef32_pk_f32_fp4 v[86:87], v21, 1.0 op_sel:[1,0,0]
	v_cvt_scalef32_pk_f32_fp4 v[88:89], v21, 1.0 op_sel:[0,1,0]
	v_cvt_scalef32_pk_f32_fp4 v[90:91], v21, 1.0 op_sel:[1,1,0]
	s_add_u32 s16, s52, s16
	v_pk_fma_f32 v[174:175], s[40:41], v[84:85], v[174:175]
	v_pk_fma_f32 v[176:177], s[40:41], v[86:87], v[176:177]
	v_pk_fma_f32 v[178:179], s[40:41], v[88:89], v[178:179]
	v_pk_fma_f32 v[180:181], s[40:41], v[90:91], v[180:181]
	v_cvt_scalef32_pk_f32_fp4 v[84:85], v22, 1.0
	v_cvt_scalef32_pk_f32_fp4 v[86:87], v22, 1.0 op_sel:[1,0,0]
	v_cvt_scalef32_pk_f32_fp4 v[88:89], v22, 1.0 op_sel:[0,1,0]
	v_cvt_scalef32_pk_f32_fp4 v[90:91], v22, 1.0 op_sel:[1,1,0]
	s_addc_u32 s17, s53, s17
	v_pk_fma_f32 v[182:183], s[40:41], v[84:85], v[182:183]
	v_pk_fma_f32 v[184:185], s[40:41], v[86:87], v[184:185]
	v_pk_fma_f32 v[186:187], s[40:41], v[88:89], v[186:187]
	v_pk_fma_f32 v[188:189], s[40:41], v[90:91], v[188:189]
	v_cvt_scalef32_pk_f32_fp4 v[84:85], v23, 1.0
	v_cvt_scalef32_pk_f32_fp4 v[86:87], v23, 1.0 op_sel:[1,0,0]
	v_cvt_scalef32_pk_f32_fp4 v[88:89], v23, 1.0 op_sel:[0,1,0]
	v_cvt_scalef32_pk_f32_fp4 v[90:91], v23, 1.0 op_sel:[1,1,0]
	s_nop 0
	v_pk_fma_f32 v[190:191], s[40:41], v[84:85], v[190:191]
	v_lshl_add_u64 v[84:85], s[16:17], 0, v[164:165]
	v_readlane_b32 s16, v208, 5
	v_pk_fma_f32 v[192:193], s[40:41], v[86:87], v[192:193]
	v_pk_fma_f32 v[194:195], s[40:41], v[88:89], v[194:195]
	v_pk_fma_f32 v[196:197], s[40:41], v[90:91], v[196:197]
	global_load_dwordx4 v[84:87], v[84:85], off
	v_readlane_b32 s40, v209, 5
	s_waitcnt vmcnt(15)
	v_cvt_scalef32_pk_f32_fp4 v[88:89], v24, 1.0
	s_lshr_b32 s16, s16, 7
	s_mov_b32 s17, s86
	s_mov_b32 s41, s40
	v_cvt_scalef32_pk_f32_fp4 v[90:91], v24, 1.0 op_sel:[1,0,0]
	v_cvt_scalef32_pk_f32_fp4 v[92:93], v24, 1.0 op_sel:[0,1,0]
	v_cvt_scalef32_pk_f32_fp4 v[94:95], v24, 1.0 op_sel:[1,1,0]
	v_pk_fma_f32 v[166:167], s[40:41], v[88:89], v[166:167]
	s_lshl_b64 s[16:17], s[16:17], 10
	v_pk_fma_f32 v[168:169], s[40:41], v[90:91], v[168:169]
	v_pk_fma_f32 v[170:171], s[40:41], v[92:93], v[170:171]
	v_pk_fma_f32 v[172:173], s[40:41], v[94:95], v[172:173]
	v_cvt_scalef32_pk_f32_fp4 v[88:89], v25, 1.0
	v_cvt_scalef32_pk_f32_fp4 v[90:91], v25, 1.0 op_sel:[1,0,0]
	v_cvt_scalef32_pk_f32_fp4 v[92:93], v25, 1.0 op_sel:[0,1,0]
	v_cvt_scalef32_pk_f32_fp4 v[94:95], v25, 1.0 op_sel:[1,1,0]
	s_add_u32 s16, s52, s16
	v_pk_fma_f32 v[174:175], s[40:41], v[88:89], v[174:175]
	v_pk_fma_f32 v[176:177], s[40:41], v[90:91], v[176:177]
	v_pk_fma_f32 v[178:179], s[40:41], v[92:93], v[178:179]
	v_pk_fma_f32 v[180:181], s[40:41], v[94:95], v[180:181]
	v_cvt_scalef32_pk_f32_fp4 v[88:89], v26, 1.0
	v_cvt_scalef32_pk_f32_fp4 v[90:91], v26, 1.0 op_sel:[1,0,0]
	v_cvt_scalef32_pk_f32_fp4 v[92:93], v26, 1.0 op_sel:[0,1,0]
	v_cvt_scalef32_pk_f32_fp4 v[94:95], v26, 1.0 op_sel:[1,1,0]
	s_addc_u32 s17, s53, s17
	v_pk_fma_f32 v[182:183], s[40:41], v[88:89], v[182:183]
	v_pk_fma_f32 v[184:185], s[40:41], v[90:91], v[184:185]
	v_pk_fma_f32 v[186:187], s[40:41], v[92:93], v[186:187]
	v_pk_fma_f32 v[188:189], s[40:41], v[94:95], v[188:189]
	v_cvt_scalef32_pk_f32_fp4 v[88:89], v27, 1.0
	v_cvt_scalef32_pk_f32_fp4 v[90:91], v27, 1.0 op_sel:[1,0,0]
	v_cvt_scalef32_pk_f32_fp4 v[92:93], v27, 1.0 op_sel:[0,1,0]
	v_cvt_scalef32_pk_f32_fp4 v[94:95], v27, 1.0 op_sel:[1,1,0]
	s_nop 0
	v_pk_fma_f32 v[190:191], s[40:41], v[88:89], v[190:191]
	v_lshl_add_u64 v[88:89], s[16:17], 0, v[164:165]
	v_readlane_b32 s16, v208, 6
	v_pk_fma_f32 v[192:193], s[40:41], v[90:91], v[192:193]
	v_pk_fma_f32 v[194:195], s[40:41], v[92:93], v[194:195]
	v_pk_fma_f32 v[196:197], s[40:41], v[94:95], v[196:197]
	global_load_dwordx4 v[88:91], v[88:89], off
	v_readlane_b32 s40, v209, 6
	s_waitcnt vmcnt(15)
	v_cvt_scalef32_pk_f32_fp4 v[92:93], v28, 1.0
	s_lshr_b32 s16, s16, 7
	s_mov_b32 s17, s86
	s_mov_b32 s41, s40
	v_cvt_scalef32_pk_f32_fp4 v[94:95], v28, 1.0 op_sel:[1,0,0]
	v_cvt_scalef32_pk_f32_fp4 v[96:97], v28, 1.0 op_sel:[0,1,0]
	v_cvt_scalef32_pk_f32_fp4 v[98:99], v28, 1.0 op_sel:[1,1,0]
	v_pk_fma_f32 v[166:167], s[40:41], v[92:93], v[166:167]
	s_lshl_b64 s[16:17], s[16:17], 10
	v_pk_fma_f32 v[168:169], s[40:41], v[94:95], v[168:169]
	v_pk_fma_f32 v[170:171], s[40:41], v[96:97], v[170:171]
	v_pk_fma_f32 v[172:173], s[40:41], v[98:99], v[172:173]
	v_cvt_scalef32_pk_f32_fp4 v[92:93], v29, 1.0
	v_cvt_scalef32_pk_f32_fp4 v[94:95], v29, 1.0 op_sel:[1,0,0]
	v_cvt_scalef32_pk_f32_fp4 v[96:97], v29, 1.0 op_sel:[0,1,0]
	v_cvt_scalef32_pk_f32_fp4 v[98:99], v29, 1.0 op_sel:[1,1,0]
	s_add_u32 s16, s52, s16
	v_pk_fma_f32 v[174:175], s[40:41], v[92:93], v[174:175]
	v_pk_fma_f32 v[176:177], s[40:41], v[94:95], v[176:177]
	v_pk_fma_f32 v[178:179], s[40:41], v[96:97], v[178:179]
	v_pk_fma_f32 v[180:181], s[40:41], v[98:99], v[180:181]
	v_cvt_scalef32_pk_f32_fp4 v[92:93], v30, 1.0
	v_cvt_scalef32_pk_f32_fp4 v[94:95], v30, 1.0 op_sel:[1,0,0]
	v_cvt_scalef32_pk_f32_fp4 v[96:97], v30, 1.0 op_sel:[0,1,0]
	v_cvt_scalef32_pk_f32_fp4 v[98:99], v30, 1.0 op_sel:[1,1,0]
	s_addc_u32 s17, s53, s17
	v_pk_fma_f32 v[182:183], s[40:41], v[92:93], v[182:183]
	v_pk_fma_f32 v[184:185], s[40:41], v[94:95], v[184:185]
	v_pk_fma_f32 v[186:187], s[40:41], v[96:97], v[186:187]
	v_pk_fma_f32 v[188:189], s[40:41], v[98:99], v[188:189]
	v_cvt_scalef32_pk_f32_fp4 v[92:93], v31, 1.0
	v_cvt_scalef32_pk_f32_fp4 v[94:95], v31, 1.0 op_sel:[1,0,0]
	v_cvt_scalef32_pk_f32_fp4 v[96:97], v31, 1.0 op_sel:[0,1,0]
	v_cvt_scalef32_pk_f32_fp4 v[98:99], v31, 1.0 op_sel:[1,1,0]
	s_nop 0
	v_pk_fma_f32 v[190:191], s[40:41], v[92:93], v[190:191]
	v_lshl_add_u64 v[92:93], s[16:17], 0, v[164:165]
	v_readlane_b32 s16, v208, 7
	v_pk_fma_f32 v[192:193], s[40:41], v[94:95], v[192:193]
	v_pk_fma_f32 v[194:195], s[40:41], v[96:97], v[194:195]
	v_pk_fma_f32 v[196:197], s[40:41], v[98:99], v[196:197]
	global_load_dwordx4 v[92:95], v[92:93], off
	v_readlane_b32 s40, v209, 7
	s_waitcnt vmcnt(15)
; #define P4_FOR16(M) M(0) M(1) M(2) M(3) M(4) M(5) M(6) M(7) M(8) M(9) M(10) M(11) M(12) M(13) M(14) M(15)
; #define P4_V(i) { const unsigned wu_ = (unsigned)__builtin_amdgcn_readlane((int)__float_as_uint(wreg), i); const unsigned long long wp_ = ((unsigned long long)wu_ << 32) | wu_; \
;               P4_ACC(b##i, wp_); const int nk_ = __builtin_amdgcn_readlane(ksel, nb + i); P4_LOAD(b##i, Vg, nk_); }
; #define P4_V(i) { const unsigned wu_ = (unsigned)__builtin_amdgcn_readlane((int)__float_as_uint(wreg), i); const unsigned long long wp_ = ((unsigned long long)wu_ << 32) | wu_; \
;               P4_ACC(b##i, wp_); const int nk_ = __builtin_amdgcn_readlane(kn, i); P4_LOAD(b##i, Vg, nk_); }
; #define P4_V(i) { const unsigned wu_ = (unsigned)__builtin_amdgcn_readlane((int)__float_as_uint(wreg), i); const unsigned long long wp_ = ((unsigned long long)wu_ << 32) | wu_; \
;               P4_ACC(b##i, wp_); }
; __device__ __forceinline__ void peer_gather_f4p(const float* X, const int* __restrict__ IDX, const float* __restrict__ G, ...
;     ...
;             if (kt < 3) {
;     ...
;                 P4_FOR16(P4_V)
	v_cvt_scalef32_pk_f32_fp4 v[96:97], v32, 1.0
	s_lshr_b32 s16, s16, 7
	s_mov_b32 s17, s86
	s_mov_b32 s41, s40
	v_cvt_scalef32_pk_f32_fp4 v[98:99], v32, 1.0 op_sel:[1,0,0]
	v_cvt_scalef32_pk_f32_fp4 v[100:101], v32, 1.0 op_sel:[0,1,0]
	v_cvt_scalef32_pk_f32_fp4 v[102:103], v32, 1.0 op_sel:[1,1,0]
	v_pk_fma_f32 v[166:167], s[40:41], v[96:97], v[166:167]
	s_lshl_b64 s[16:17], s[16:17], 10
	v_pk_fma_f32 v[168:169], s[40:41], v[98:99], v[168:169]
	v_pk_fma_f32 v[170:171], s[40:41], v[100:101], v[170:171]
	v_pk_fma_f32 v[172:173], s[40:41], v[102:103], v[172:173]
	v_cvt_scalef32_pk_f32_fp4 v[96:97], v33, 1.0
	v_cvt_scalef32_pk_f32_fp4 v[98:99], v33, 1.0 op_sel:[1,0,0]
	v_cvt_scalef32_pk_f32_fp4 v[100:101], v33, 1.0 op_sel:[0,1,0]
	v_cvt_scalef32_pk_f32_fp4 v[102:103], v33, 1.0 op_sel:[1,1,0]
	s_add_u32 s16, s52, s16
	v_pk_fma_f32 v[174:175], s[40:41], v[96:97], v[174:175]
	v_pk_fma_f32 v[176:177], s[40:41], v[98:99], v[176:177]
	v_pk_fma_f32 v[178:179], s[40:41], v[100:101], v[178:179]
	v_pk_fma_f32 v[180:181], s[40:41], v[102:103], v[180:181]
	v_cvt_scalef32_pk_f32_fp4 v[96:97], v34, 1.0
	v_cvt_scalef32_pk_f32_fp4 v[98:99], v34, 1.0 op_sel:[1,0,0]
	v_cvt_scalef32_pk_f32_fp4 v[100:101], v34, 1.0 op_sel:[0,1,0]
	v_cvt_scalef32_pk_f32_fp4 v[102:103], v34, 1.0 op_sel:[1,1,0]
	s_addc_u32 s17, s53, s17
	v_pk_fma_f32 v[182:183], s[40:41], v[96:97], v[182:183]
	v_pk_fma_f32 v[184:185], s[40:41], v[98:99], v[184:185]
	v_pk_fma_f32 v[186:187], s[40:41], v[100:101], v[186:187]
	v_pk_fma_f32 v[188:189], s[40:41], v[102:103], v[188:189]
	v_cvt_scalef32_pk_f32_fp4 v[96:97], v35, 1.0
	v_cvt_scalef32_pk_f32_fp4 v[98:99], v35, 1.0 op_sel:[1,0,0]
	v_cvt_scalef32_pk_f32_fp4 v[100:101], v35, 1.0 op_sel:[0,1,0]
	v_cvt_scalef32_pk_f32_fp4 v[102:103], v35, 1.0 op_sel:[1,1,0]
	s_nop 0
	v_pk_fma_f32 v[190:191], s[40:41], v[96:97], v[190:191]
	v_lshl_add_u64 v[96:97], s[16:17], 0, v[164:165]
	v_readlane_b32 s16, v208, 8
	v_pk_fma_f32 v[192:193], s[40:41], v[98:99], v[192:193]
	v_pk_fma_f32 v[194:195], s[40:41], v[100:101], v[194:195]
	v_pk_fma_f32 v[196:197], s[40:41], v[102:103], v[196:197]
	global_load_dwordx4 v[96:99], v[96:97], off
	v_readlane_b32 s40, v209, 8
	s_waitcnt vmcnt(15)
	v_cvt_scalef32_pk_f32_fp4 v[100:101], v36, 1.0
	s_lshr_b32 s16, s16, 7
	s_mov_b32 s17, s86
	s_mov_b32 s41, s40
	v_cvt_scalef32_pk_f32_fp4 v[102:103], v36, 1.0 op_sel:[1,0,0]
	v_cvt_scalef32_pk_f32_fp4 v[104:105], v36, 1.0 op_sel:[0,1,0]
	v_cvt_scalef32_pk_f32_fp4 v[106:107], v36, 1.0 op_sel:[1,1,0]
	v_pk_fma_f32 v[166:167], s[40:41], v[100:101], v[166:167]
	s_lshl_b64 s[16:17], s[16:17], 10
	v_pk_fma_f32 v[168:169], s[40:41], v[102:103], v[168:169]
	v_pk_fma_f32 v[170:171], s[40:41], v[104:105], v[170:171]
	v_pk_fma_f32 v[172:173], s[40:41], v[106:107], v[172:173]
	v_cvt_scalef32_pk_f32_fp4 v[100:101], v37, 1.0
	v_cvt_scalef32_pk_f32_fp4 v[102:103], v37, 1.0 op_sel:[1,0,0]
	v_cvt_scalef32_pk_f32_fp4 v[104:105], v37, 1.0 op_sel:[0,1,0]
	v_cvt_scalef32_pk_f32_fp4 v[106:107], v37, 1.0 op_sel:[1,1,0]
	s_add_u32 s16, s52, s16
	v_pk_fma_f32 v[174:175], s[40:41], v[100:101], v[174:175]
	v_pk_fma_f32 v[176:177], s[40:41], v[102:103], v[176:177]
	v_pk_fma_f32 v[178:179], s[40:41], v[104:105], v[178:179]
	v_pk_fma_f32 v[180:181], s[40:41], v[106:107], v[180:181]
	v_cvt_scalef32_pk_f32_fp4 v[100:101], v38, 1.0
	v_cvt_scalef32_pk_f32_fp4 v[102:103], v38, 1.0 op_sel:[1,0,0]
	v_cvt_scalef32_pk_f32_fp4 v[104:105], v38, 1.0 op_sel:[0,1,0]
	v_cvt_scalef32_pk_f32_fp4 v[106:107], v38, 1.0 op_sel:[1,1,0]
	s_addc_u32 s17, s53, s17
	v_pk_fma_f32 v[182:183], s[40:41], v[100:101], v[182:183]
	v_pk_fma_f32 v[184:185], s[40:41], v[102:103], v[184:185]
	v_pk_fma_f32 v[186:187], s[40:41], v[104:105], v[186:187]
	v_pk_fma_f32 v[188:189], s[40:41], v[106:107], v[188:189]
	v_cvt_scalef32_pk_f32_fp4 v[100:101], v39, 1.0
	v_cvt_scalef32_pk_f32_fp4 v[102:103], v39, 1.0 op_sel:[1,0,0]
	v_cvt_scalef32_pk_f32_fp4 v[104:105], v39, 1.0 op_sel:[0,1,0]
	v_cvt_scalef32_pk_f32_fp4 v[106:107], v39, 1.0 op_sel:[1,1,0]
	s_nop 0
	v_pk_fma_f32 v[190:191], s[40:41], v[100:101], v[190:191]
	v_lshl_add_u64 v[100:101], s[16:17], 0, v[164:165]
	v_readlane_b32 s16, v208, 9
	v_pk_fma_f32 v[192:193], s[40:41], v[102:103], v[192:193]
	v_pk_fma_f32 v[194:195], s[40:41], v[104:105], v[194:195]
	v_pk_fma_f32 v[196:197], s[40:41], v[106:107], v[196:197]
	global_load_dwordx4 v[100:103], v[100:101], off
	v_readlane_b32 s40, v209, 9
	s_waitcnt vmcnt(15)
	v_cvt_scalef32_pk_f32_fp4 v[104:105], v40, 1.0
	s_lshr_b32 s16, s16, 7
	s_mov_b32 s17, s86
	s_mov_b32 s41, s40
	v_cvt_scalef32_pk_f32_fp4 v[106:107], v40, 1.0 op_sel:[1,0,0]
	v_cvt_scalef32_pk_f32_fp4 v[108:109], v40, 1.0 op_sel:[0,1,0]
	v_cvt_scalef32_pk_f32_fp4 v[110:111], v40, 1.0 op_sel:[1,1,0]
	v_pk_fma_f32 v[166:167], s[40:41], v[104:105], v[166:167]
	s_lshl_b64 s[16:17], s[16:17], 10
	v_pk_fma_f32 v[168:169], s[40:41], v[106:107], v[168:169]
	v_pk_fma_f32 v[170:171], s[40:41], v[108:109], v[170:171]
	v_pk_fma_f32 v[172:173], s[40:41], v[110:111], v[172:173]
	v_cvt_scalef32_pk_f32_fp4 v[104:105], v41, 1.0
	v_cvt_scalef32_pk_f32_fp4 v[106:107], v41, 1.0 op_sel:[1,0,0]
	v_cvt_scalef32_pk_f32_fp4 v[108:109], v41, 1.0 op_sel:[0,1,0]
	v_cvt_scalef32_pk_f32_fp4 v[110:111], v41, 1.0 op_sel:[1,1,0]
	s_add_u32 s16, s52, s16
	v_pk_fma_f32 v[174:175], s[40:41], v[104:105], v[174:175]
	v_pk_fma_f32 v[176:177], s[40:41], v[106:107], v[176:177]
	v_pk_fma_f32 v[178:179], s[40:41], v[108:109], v[178:179]
	v_pk_fma_f32 v[180:181], s[40:41], v[110:111], v[180:181]
	v_cvt_scalef32_pk_f32_fp4 v[104:105], v42, 1.0
	v_cvt_scalef32_pk_f32_fp4 v[106:107], v42, 1.0 op_sel:[1,0,0]
	v_cvt_scalef32_pk_f32_fp4 v[108:109], v42, 1.0 op_sel:[0,1,0]
	v_cvt_scalef32_pk_f32_fp4 v[110:111], v42, 1.0 op_sel:[1,1,0]
	s_addc_u32 s17, s53, s17
	v_pk_fma_f32 v[182:183], s[40:41], v[104:105], v[182:183]
	v_pk_fma_f32 v[184:185], s[40:41], v[106:107], v[184:185]
	v_pk_fma_f32 v[186:187], s[40:41], v[108:109], v[186:187]
	v_pk_fma_f32 v[188:189], s[40:41], v[110:111], v[188:189]
	v_cvt_scalef32_pk_f32_fp4 v[104:105], v43, 1.0
	v_cvt_scalef32_pk_f32_fp4 v[106:107], v43, 1.0 op_sel:[1,0,0]
	v_cvt_scalef32_pk_f32_fp4 v[108:109], v43, 1.0 op_sel:[0,1,0]
	v_cvt_scalef32_pk_f32_fp4 v[110:111], v43, 1.0 op_sel:[1,1,0]
	s_nop 0
	v_pk_fma_f32 v[190:191], s[40:41], v[104:105], v[190:191]
	v_lshl_add_u64 v[104:105], s[16:17], 0, v[164:165]
	v_readlane_b32 s16, v208, 10
	v_pk_fma_f32 v[192:193], s[40:41], v[106:107], v[192:193]
	v_pk_fma_f32 v[194:195], s[40:41], v[108:109], v[194:195]
	v_pk_fma_f32 v[196:197], s[40:41], v[110:111], v[196:197]
	global_load_dwordx4 v[104:107], v[104:105], off
	v_readlane_b32 s40, v209, 10
	s_waitcnt vmcnt(15)
; #define P4_FOR16(M) M(0) M(1) M(2) M(3) M(4) M(5) M(6) M(7) M(8) M(9) M(10) M(11) M(12) M(13) M(14) M(15)
; #define P4_V(i) { const unsigned wu_ = (unsigned)__builtin_amdgcn_readlane((int)__float_as_uint(wreg), i); const unsigned long long wp_ = ((unsigned long long)wu_ << 32) | wu_; \
;               P4_ACC(b##i, wp_); const int nk_ = __builtin_amdgcn_readlane(ksel, nb + i); P4_LOAD(b##i, Vg, nk_); }
; #define P4_V(i) { const unsigned wu_ = (unsigned)__builtin_amdgcn_readlane((int)__float_as_uint(wreg), i); const unsigned long long wp_ = ((unsigned long long)wu_ << 32) | wu_; \
;               P4_ACC(b##i, wp_); const int nk_ = __builtin_amdgcn_readlane(kn, i); P4_LOAD(b##i, Vg, nk_); }
; #define P4_V(i) { const unsigned wu_ = (unsigned)__builtin_amdgcn_readlane((int)__float_as_uint(wreg), i); const unsigned long long wp_ = ((unsigned long long)wu_ << 32) | wu_; \
;               P4_ACC(b##i, wp_); }
; __device__ __forceinline__ void peer_gather_f4p(const float* X, const int* __restrict__ IDX, const float* __restrict__ G, ...
;     ...
;             if (kt < 3) {
;     ...
;                 P4_FOR16(P4_V)
	v_cvt_scalef32_pk_f32_fp4 v[108:109], v44, 1.0
	s_lshr_b32 s16, s16, 7
	s_mov_b32 s17, s86
	s_mov_b32 s41, s40
	v_cvt_scalef32_pk_f32_fp4 v[110:111], v44, 1.0 op_sel:[1,0,0]
	v_cvt_scalef32_pk_f32_fp4 v[112:113], v44, 1.0 op_sel:[0,1,0]
	v_cvt_scalef32_pk_f32_fp4 v[114:115], v44, 1.0 op_sel:[1,1,0]
	v_pk_fma_f32 v[166:167], s[40:41], v[108:109], v[166:167]
	s_lshl_b64 s[16:17], s[16:17], 10
	v_pk_fma_f32 v[168:169], s[40:41], v[110:111], v[168:169]
	v_pk_fma_f32 v[170:171], s[40:41], v[112:113], v[170:171]
	v_pk_fma_f32 v[172:173], s[40:41], v[114:115], v[172:173]
	v_cvt_scalef32_pk_f32_fp4 v[108:109], v45, 1.0
	v_cvt_scalef32_pk_f32_fp4 v[110:111], v45, 1.0 op_sel:[1,0,0]
	v_cvt_scalef32_pk_f32_fp4 v[112:113], v45, 1.0 op_sel:[0,1,0]
	v_cvt_scalef32_pk_f32_fp4 v[114:115], v45, 1.0 op_sel:[1,1,0]
	s_add_u32 s16, s52, s16
	v_pk_fma_f32 v[174:175], s[40:41], v[108:109], v[174:175]
	v_pk_fma_f32 v[176:177], s[40:41], v[110:111], v[176:177]
	v_pk_fma_f32 v[178:179], s[40:41], v[112:113], v[178:179]
	v_pk_fma_f32 v[180:181], s[40:41], v[114:115], v[180:181]
	v_cvt_scalef32_pk_f32_fp4 v[108:109], v46, 1.0
	v_cvt_scalef32_pk_f32_fp4 v[110:111], v46, 1.0 op_sel:[1,0,0]
	v_cvt_scalef32_pk_f32_fp4 v[112:113], v46, 1.0 op_sel:[0,1,0]
	v_cvt_scalef32_pk_f32_fp4 v[114:115], v46, 1.0 op_sel:[1,1,0]
	s_addc_u32 s17, s53, s17
	v_pk_fma_f32 v[182:183], s[40:41], v[108:109], v[182:183]
	v_pk_fma_f32 v[184:185], s[40:41], v[110:111], v[184:185]
	v_pk_fma_f32 v[186:187], s[40:41], v[112:113], v[186:187]
	v_pk_fma_f32 v[188:189], s[40:41], v[114:115], v[188:189]
	v_cvt_scalef32_pk_f32_fp4 v[108:109], v47, 1.0
	v_cvt_scalef32_pk_f32_fp4 v[110:111], v47, 1.0 op_sel:[1,0,0]
	v_cvt_scalef32_pk_f32_fp4 v[112:113], v47, 1.0 op_sel:[0,1,0]
	v_cvt_scalef32_pk_f32_fp4 v[114:115], v47, 1.0 op_sel:[1,1,0]
	s_nop 0
	v_pk_fma_f32 v[190:191], s[40:41], v[108:109], v[190:191]
	v_lshl_add_u64 v[108:109], s[16:17], 0, v[164:165]
	v_readlane_b32 s16, v208, 11
	v_pk_fma_f32 v[192:193], s[40:41], v[110:111], v[192:193]
	v_pk_fma_f32 v[194:195], s[40:41], v[112:113], v[194:195]
	v_pk_fma_f32 v[196:197], s[40:41], v[114:115], v[196:197]
	global_load_dwordx4 v[108:111], v[108:109], off
	v_readlane_b32 s40, v209, 11
	s_waitcnt vmcnt(15)
	v_cvt_scalef32_pk_f32_fp4 v[112:113], v48, 1.0
	s_lshr_b32 s16, s16, 7
	s_mov_b32 s17, s86
	s_mov_b32 s41, s40
	v_cvt_scalef32_pk_f32_fp4 v[114:115], v48, 1.0 op_sel:[1,0,0]
	v_cvt_scalef32_pk_f32_fp4 v[116:117], v48, 1.0 op_sel:[0,1,0]
	v_cvt_scalef32_pk_f32_fp4 v[118:119], v48, 1.0 op_sel:[1,1,0]
	v_pk_fma_f32 v[166:167], s[40:41], v[112:113], v[166:167]
	s_lshl_b64 s[16:17], s[16:17], 10
	v_pk_fma_f32 v[168:169], s[40:41], v[114:115], v[168:169]
	v_pk_fma_f32 v[170:171], s[40:41], v[116:117], v[170:171]
	v_pk_fma_f32 v[172:173], s[40:41], v[118:119], v[172:173]
	v_cvt_scalef32_pk_f32_fp4 v[112:113], v49, 1.0
	v_cvt_scalef32_pk_f32_fp4 v[114:115], v49, 1.0 op_sel:[1,0,0]
	v_cvt_scalef32_pk_f32_fp4 v[116:117], v49, 1.0 op_sel:[0,1,0]
	v_cvt_scalef32_pk_f32_fp4 v[118:119], v49, 1.0 op_sel:[1,1,0]
	s_add_u32 s16, s52, s16
	v_pk_fma_f32 v[174:175], s[40:41], v[112:113], v[174:175]
	v_pk_fma_f32 v[176:177], s[40:41], v[114:115], v[176:177]
	v_pk_fma_f32 v[178:179], s[40:41], v[116:117], v[178:179]
	v_pk_fma_f32 v[180:181], s[40:41], v[118:119], v[180:181]
	v_cvt_scalef32_pk_f32_fp4 v[112:113], v50, 1.0
	v_cvt_scalef32_pk_f32_fp4 v[114:115], v50, 1.0 op_sel:[1,0,0]
	v_cvt_scalef32_pk_f32_fp4 v[116:117], v50, 1.0 op_sel:[0,1,0]
	v_cvt_scalef32_pk_f32_fp4 v[118:119], v50, 1.0 op_sel:[1,1,0]
	s_addc_u32 s17, s53, s17
	v_pk_fma_f32 v[182:183], s[40:41], v[112:113], v[182:183]
	v_pk_fma_f32 v[184:185], s[40:41], v[114:115], v[184:185]
	v_pk_fma_f32 v[186:187], s[40:41], v[116:117], v[186:187]
	v_pk_fma_f32 v[188:189], s[40:41], v[118:119], v[188:189]
	v_cvt_scalef32_pk_f32_fp4 v[112:113], v51, 1.0
	v_cvt_scalef32_pk_f32_fp4 v[114:115], v51, 1.0 op_sel:[1,0,0]
	v_cvt_scalef32_pk_f32_fp4 v[116:117], v51, 1.0 op_sel:[0,1,0]
	v_cvt_scalef32_pk_f32_fp4 v[118:119], v51, 1.0 op_sel:[1,1,0]
	s_nop 0
	v_pk_fma_f32 v[190:191], s[40:41], v[112:113], v[190:191]
	v_lshl_add_u64 v[112:113], s[16:17], 0, v[164:165]
	v_readlane_b32 s16, v208, 12
	v_pk_fma_f32 v[192:193], s[40:41], v[114:115], v[192:193]
	v_pk_fma_f32 v[194:195], s[40:41], v[116:117], v[194:195]
	v_pk_fma_f32 v[196:197], s[40:41], v[118:119], v[196:197]
	global_load_dwordx4 v[112:115], v[112:113], off
	v_readlane_b32 s40, v209, 12
	s_waitcnt vmcnt(15)
	v_cvt_scalef32_pk_f32_fp4 v[116:117], v52, 1.0
	s_lshr_b32 s16, s16, 7
	s_mov_b32 s17, s86
	s_mov_b32 s41, s40
	v_cvt_scalef32_pk_f32_fp4 v[118:119], v52, 1.0 op_sel:[1,0,0]
	v_cvt_scalef32_pk_f32_fp4 v[120:121], v52, 1.0 op_sel:[0,1,0]
	v_cvt_scalef32_pk_f32_fp4 v[122:123], v52, 1.0 op_sel:[1,1,0]
	v_pk_fma_f32 v[166:167], s[40:41], v[116:117], v[166:167]
	s_lshl_b64 s[16:17], s[16:17], 10
	v_pk_fma_f32 v[168:169], s[40:41], v[118:119], v[168:169]
	v_pk_fma_f32 v[170:171], s[40:41], v[120:121], v[170:171]
	v_pk_fma_f32 v[172:173], s[40:41], v[122:123], v[172:173]
	v_cvt_scalef32_pk_f32_fp4 v[116:117], v53, 1.0
	v_cvt_scalef32_pk_f32_fp4 v[118:119], v53, 1.0 op_sel:[1,0,0]
	v_cvt_scalef32_pk_f32_fp4 v[120:121], v53, 1.0 op_sel:[0,1,0]
	v_cvt_scalef32_pk_f32_fp4 v[122:123], v53, 1.0 op_sel:[1,1,0]
	s_add_u32 s16, s52, s16
	v_pk_fma_f32 v[174:175], s[40:41], v[116:117], v[174:175]
	v_pk_fma_f32 v[176:177], s[40:41], v[118:119], v[176:177]
	v_pk_fma_f32 v[178:179], s[40:41], v[120:121], v[178:179]
	v_pk_fma_f32 v[180:181], s[40:41], v[122:123], v[180:181]
	v_cvt_scalef32_pk_f32_fp4 v[116:117], v54, 1.0
	v_cvt_scalef32_pk_f32_fp4 v[118:119], v54, 1.0 op_sel:[1,0,0]
	v_cvt_scalef32_pk_f32_fp4 v[120:121], v54, 1.0 op_sel:[0,1,0]
	v_cvt_scalef32_pk_f32_fp4 v[122:123], v54, 1.0 op_sel:[1,1,0]
	s_addc_u32 s17, s53, s17
	v_pk_fma_f32 v[182:183], s[40:41], v[116:117], v[182:183]
	v_pk_fma_f32 v[184:185], s[40:41], v[118:119], v[184:185]
	v_pk_fma_f32 v[186:187], s[40:41], v[120:121], v[186:187]
	v_pk_fma_f32 v[188:189], s[40:41], v[122:123], v[188:189]
	v_cvt_scalef32_pk_f32_fp4 v[116:117], v55, 1.0
	v_cvt_scalef32_pk_f32_fp4 v[118:119], v55, 1.0 op_sel:[1,0,0]
	v_cvt_scalef32_pk_f32_fp4 v[120:121], v55, 1.0 op_sel:[0,1,0]
	v_cvt_scalef32_pk_f32_fp4 v[122:123], v55, 1.0 op_sel:[1,1,0]
	s_nop 0
	v_pk_fma_f32 v[190:191], s[40:41], v[116:117], v[190:191]
	v_lshl_add_u64 v[116:117], s[16:17], 0, v[164:165]
	v_readlane_b32 s16, v208, 13
	v_pk_fma_f32 v[192:193], s[40:41], v[118:119], v[192:193]
	v_pk_fma_f32 v[194:195], s[40:41], v[120:121], v[194:195]
	v_pk_fma_f32 v[196:197], s[40:41], v[122:123], v[196:197]
	global_load_dwordx4 v[116:119], v[116:117], off
	v_readlane_b32 s40, v209, 13
	s_waitcnt vmcnt(15)
; #define P4_FOR16(M) M(0) M(1) M(2) M(3) M(4) M(5) M(6) M(7) M(8) M(9) M(10) M(11) M(12) M(13) M(14) M(15)
; #define P4_V(i) { const unsigned wu_ = (unsigned)__builtin_amdgcn_readlane((int)__float_as_uint(wreg), i); const unsigned long long wp_ = ((unsigned long long)wu_ << 32) | wu_; \
;               P4_ACC(b##i, wp_); const int nk_ = __builtin_amdgcn_readlane(ksel, nb + i); P4_LOAD(b##i, Vg, nk_); }
; #define P4_V(i) { const unsigned wu_ = (unsigned)__builtin_amdgcn_readlane((int)__float_as_uint(wreg), i); const unsigned long long wp_ = ((unsigned long long)wu_ << 32) | wu_; \
;               P4_ACC(b##i, wp_); const int nk_ = __builtin_amdgcn_readlane(kn, i); P4_LOAD(b##i, Vg, nk_); }
; #define P4_V(i) { const unsigned wu_ = (unsigned)__builtin_amdgcn_readlane((int)__float_as_uint(wreg), i); const unsigned long long wp_ = ((unsigned long long)wu_ << 32) | wu_; \
;               P4_ACC(b##i, wp_); }
; __device__ __forceinline__ void peer_gather_f4p(const float* X, const int* __restrict__ IDX, const float* __restrict__ G, ...
;     ...
;             if (kt < 3) {
;     ...
;                 P4_FOR16(P4_V)
	v_cvt_scalef32_pk_f32_fp4 v[120:121], v56, 1.0
	s_lshr_b32 s16, s16, 7
	s_mov_b32 s17, s86
	s_mov_b32 s41, s40
	v_cvt_scalef32_pk_f32_fp4 v[122:123], v56, 1.0 op_sel:[1,0,0]
	v_cvt_scalef32_pk_f32_fp4 v[124:125], v56, 1.0 op_sel:[0,1,0]
	v_cvt_scalef32_pk_f32_fp4 v[126:127], v56, 1.0 op_sel:[1,1,0]
	v_pk_fma_f32 v[166:167], s[40:41], v[120:121], v[166:167]
	s_lshl_b64 s[16:17], s[16:17], 10
	v_pk_fma_f32 v[168:169], s[40:41], v[122:123], v[168:169]
	v_pk_fma_f32 v[170:171], s[40:41], v[124:125], v[170:171]
	v_pk_fma_f32 v[172:173], s[40:41], v[126:127], v[172:173]
	v_cvt_scalef32_pk_f32_fp4 v[120:121], v57, 1.0
	v_cvt_scalef32_pk_f32_fp4 v[122:123], v57, 1.0 op_sel:[1,0,0]
	v_cvt_scalef32_pk_f32_fp4 v[124:125], v57, 1.0 op_sel:[0,1,0]
	v_cvt_scalef32_pk_f32_fp4 v[126:127], v57, 1.0 op_sel:[1,1,0]
	s_add_u32 s16, s52, s16
	v_pk_fma_f32 v[174:175], s[40:41], v[120:121], v[174:175]
	v_pk_fma_f32 v[176:177], s[40:41], v[122:123], v[176:177]
	v_pk_fma_f32 v[178:179], s[40:41], v[124:125], v[178:179]
	v_pk_fma_f32 v[180:181], s[40:41], v[126:127], v[180:181]
	v_cvt_scalef32_pk_f32_fp4 v[120:121], v58, 1.0
	v_cvt_scalef32_pk_f32_fp4 v[122:123], v58, 1.0 op_sel:[1,0,0]
	v_cvt_scalef32_pk_f32_fp4 v[124:125], v58, 1.0 op_sel:[0,1,0]
	v_cvt_scalef32_pk_f32_fp4 v[126:127], v58, 1.0 op_sel:[1,1,0]
	s_addc_u32 s17, s53, s17
	v_pk_fma_f32 v[182:183], s[40:41], v[120:121], v[182:183]
	v_pk_fma_f32 v[184:185], s[40:41], v[122:123], v[184:185]
	v_pk_fma_f32 v[186:187], s[40:41], v[124:125], v[186:187]
	v_pk_fma_f32 v[188:189], s[40:41], v[126:127], v[188:189]
	v_cvt_scalef32_pk_f32_fp4 v[120:121], v59, 1.0
	v_cvt_scalef32_pk_f32_fp4 v[122:123], v59, 1.0 op_sel:[1,0,0]
	v_cvt_scalef32_pk_f32_fp4 v[124:125], v59, 1.0 op_sel:[0,1,0]
	v_cvt_scalef32_pk_f32_fp4 v[126:127], v59, 1.0 op_sel:[1,1,0]
	s_nop 0
	v_pk_fma_f32 v[190:191], s[40:41], v[120:121], v[190:191]
	v_lshl_add_u64 v[120:121], s[16:17], 0, v[164:165]
	v_readlane_b32 s16, v208, 14
	v_pk_fma_f32 v[192:193], s[40:41], v[122:123], v[192:193]
	v_pk_fma_f32 v[194:195], s[40:41], v[124:125], v[194:195]
	v_pk_fma_f32 v[196:197], s[40:41], v[126:127], v[196:197]
	global_load_dwordx4 v[120:123], v[120:121], off
	v_readlane_b32 s40, v209, 14
	s_waitcnt vmcnt(15)
	v_cvt_scalef32_pk_f32_fp4 v[124:125], v60, 1.0
	s_lshr_b32 s16, s16, 7
	s_mov_b32 s17, s86
	s_mov_b32 s41, s40
	v_cvt_scalef32_pk_f32_fp4 v[126:127], v60, 1.0 op_sel:[1,0,0]
	v_cvt_scalef32_pk_f32_fp4 v[128:129], v60, 1.0 op_sel:[0,1,0]
	v_cvt_scalef32_pk_f32_fp4 v[130:131], v60, 1.0 op_sel:[1,1,0]
	v_pk_fma_f32 v[166:167], s[40:41], v[124:125], v[166:167]
	s_lshl_b64 s[16:17], s[16:17], 10
	v_pk_fma_f32 v[168:169], s[40:41], v[126:127], v[168:169]
	v_pk_fma_f32 v[170:171], s[40:41], v[128:129], v[170:171]
	v_pk_fma_f32 v[172:173], s[40:41], v[130:131], v[172:173]
	v_cvt_scalef32_pk_f32_fp4 v[124:125], v61, 1.0
	v_cvt_scalef32_pk_f32_fp4 v[126:127], v61, 1.0 op_sel:[1,0,0]
	v_cvt_scalef32_pk_f32_fp4 v[128:129], v61, 1.0 op_sel:[0,1,0]
	v_cvt_scalef32_pk_f32_fp4 v[130:131], v61, 1.0 op_sel:[1,1,0]
	s_add_u32 s16, s52, s16
	v_pk_fma_f32 v[174:175], s[40:41], v[124:125], v[174:175]
	v_pk_fma_f32 v[176:177], s[40:41], v[126:127], v[176:177]
	v_pk_fma_f32 v[178:179], s[40:41], v[128:129], v[178:179]
	v_pk_fma_f32 v[180:181], s[40:41], v[130:131], v[180:181]
	v_cvt_scalef32_pk_f32_fp4 v[124:125], v62, 1.0
	v_cvt_scalef32_pk_f32_fp4 v[126:127], v62, 1.0 op_sel:[1,0,0]
	v_cvt_scalef32_pk_f32_fp4 v[128:129], v62, 1.0 op_sel:[0,1,0]
	v_cvt_scalef32_pk_f32_fp4 v[130:131], v62, 1.0 op_sel:[1,1,0]
	s_addc_u32 s17, s53, s17
	v_pk_fma_f32 v[182:183], s[40:41], v[124:125], v[182:183]
	v_pk_fma_f32 v[184:185], s[40:41], v[126:127], v[184:185]
	v_pk_fma_f32 v[186:187], s[40:41], v[128:129], v[186:187]
	v_pk_fma_f32 v[188:189], s[40:41], v[130:131], v[188:189]
	v_cvt_scalef32_pk_f32_fp4 v[124:125], v63, 1.0
	v_cvt_scalef32_pk_f32_fp4 v[126:127], v63, 1.0 op_sel:[1,0,0]
	v_cvt_scalef32_pk_f32_fp4 v[128:129], v63, 1.0 op_sel:[0,1,0]
	v_cvt_scalef32_pk_f32_fp4 v[130:131], v63, 1.0 op_sel:[1,1,0]
	s_nop 0
	v_pk_fma_f32 v[190:191], s[40:41], v[124:125], v[190:191]
	v_lshl_add_u64 v[124:125], s[16:17], 0, v[164:165]
	v_readlane_b32 s16, v208, 15
	v_pk_fma_f32 v[192:193], s[40:41], v[126:127], v[192:193]
	v_pk_fma_f32 v[194:195], s[40:41], v[128:129], v[194:195]
	v_pk_fma_f32 v[196:197], s[40:41], v[130:131], v[196:197]
	global_load_dwordx4 v[124:127], v[124:125], off
	v_readlane_b32 s40, v209, 15
	s_waitcnt vmcnt(15)
	v_cvt_scalef32_pk_f32_fp4 v[128:129], v80, 1.0
	s_lshr_b32 s16, s16, 7
	s_mov_b32 s17, s86
	s_mov_b32 s41, s40
	v_cvt_scalef32_pk_f32_fp4 v[130:131], v80, 1.0 op_sel:[1,0,0]
	v_cvt_scalef32_pk_f32_fp4 v[210:211], v80, 1.0 op_sel:[0,1,0]
	v_cvt_scalef32_pk_f32_fp4 v[212:213], v80, 1.0 op_sel:[1,1,0]
	v_pk_fma_f32 v[166:167], s[40:41], v[128:129], v[166:167]
	s_lshl_b64 s[16:17], s[16:17], 10
	v_pk_fma_f32 v[168:169], s[40:41], v[130:131], v[168:169]
	v_pk_fma_f32 v[170:171], s[40:41], v[210:211], v[170:171]
	v_pk_fma_f32 v[172:173], s[40:41], v[212:213], v[172:173]
	v_cvt_scalef32_pk_f32_fp4 v[128:129], v81, 1.0
	v_cvt_scalef32_pk_f32_fp4 v[130:131], v81, 1.0 op_sel:[1,0,0]
	v_cvt_scalef32_pk_f32_fp4 v[210:211], v81, 1.0 op_sel:[0,1,0]
	v_cvt_scalef32_pk_f32_fp4 v[212:213], v81, 1.0 op_sel:[1,1,0]
	s_add_u32 s16, s52, s16
	v_pk_fma_f32 v[174:175], s[40:41], v[128:129], v[174:175]
	v_pk_fma_f32 v[176:177], s[40:41], v[130:131], v[176:177]
	v_pk_fma_f32 v[178:179], s[40:41], v[210:211], v[178:179]
	v_pk_fma_f32 v[180:181], s[40:41], v[212:213], v[180:181]
	v_cvt_scalef32_pk_f32_fp4 v[128:129], v82, 1.0
	v_cvt_scalef32_pk_f32_fp4 v[130:131], v82, 1.0 op_sel:[1,0,0]
	v_cvt_scalef32_pk_f32_fp4 v[210:211], v82, 1.0 op_sel:[0,1,0]
	v_cvt_scalef32_pk_f32_fp4 v[212:213], v82, 1.0 op_sel:[1,1,0]
	s_addc_u32 s17, s53, s17
	v_pk_fma_f32 v[182:183], s[40:41], v[128:129], v[182:183]
	v_pk_fma_f32 v[184:185], s[40:41], v[130:131], v[184:185]
	v_pk_fma_f32 v[186:187], s[40:41], v[210:211], v[186:187]
	v_pk_fma_f32 v[188:189], s[40:41], v[212:213], v[188:189]
	v_cvt_scalef32_pk_f32_fp4 v[128:129], v83, 1.0
	v_cvt_scalef32_pk_f32_fp4 v[130:131], v83, 1.0 op_sel:[1,0,0]
	v_cvt_scalef32_pk_f32_fp4 v[210:211], v83, 1.0 op_sel:[0,1,0]
	v_cvt_scalef32_pk_f32_fp4 v[212:213], v83, 1.0 op_sel:[1,1,0]
	s_nop 0
	v_pk_fma_f32 v[190:191], s[40:41], v[128:129], v[190:191]
	v_lshl_add_u64 v[128:129], s[16:17], 0, v[164:165]
	v_pk_fma_f32 v[192:193], s[40:41], v[130:131], v[192:193]
	v_pk_fma_f32 v[194:195], s[40:41], v[210:211], v[194:195]
	v_pk_fma_f32 v[196:197], s[40:41], v[212:213], v[196:197]
	global_load_dwordx4 v[128:131], v[128:129], off
	s_mov_b64 s[40:41], 0
